# v25 + the per-MFMA-block s_setprio 1/0 flips removed from all eight GEMM K-loops (both half-workgroups run at equal priority)
# speedup vs baseline: 1.0127x; 1.0035x over previous
; #define PG8_STAGE(bufoff, gbase, voff) do { _Pragma("unroll") for (int _i = 0; _i < 2; ++_i) \
;         __builtin_amdgcn_global_load_lds((const unsigned*)((const char*)(gbase) + (voff)[_i]), (PG8_LAS unsigned*)(lds + (bufoff) + ldsw + _i * 8192), 16, 0, 0); } while (0)
; #define PG8_LDA(dst, b, h) do { _Pragma("unroll") for (int m = 0; m < 4; ++m) _Pragma("unroll") for (int k = 0; k < 2; ++k) dst[m][k] = *(const PG8_LAS bf16x8*)(lds + PG8_SA(b, h) + aoff + m * 2048 + k * 1024); } while (0)
; #define PG8_LDB(dst, b, h) do { _Pragma("unroll") for (int n = 0; n < 2; ++n) _Pragma("unroll") for (int k = 0; k < 2; ++k) dst[n][k] = *(const PG8_LAS bf16x8*)(lds + PG8_SB(b, h) + boff + n * 2048 + k * 1024); } while (0)
; #define PG8_MMA(ai, bj, At, Bt) do { __builtin_amdgcn_s_setprio(1); _Pragma("unroll") for (int m = 0; m < 4; ++m) _Pragma("unroll") for (int n = 0; n < 2; ++n) _Pragma("unroll") for (int k = 0; k < 2; ++k) \
;         acc[ai][bj][m][n] = __builtin_amdgcn_mfma_f32_16x16x32_bf16(Bt[n][k], At[m][k], acc[ai][bj][m][n], 0, 0, 0); __builtin_amdgcn_s_setprio(0); } while (0)
; #define PG8_WAIT_V(n) asm volatile("s_waitcnt vmcnt(" #n ")" ::: "memory")
; #define PG8_BAR __builtin_amdgcn_s_barrier()
; template <class Epi, class Sched, bool ALIGN_EPI = false, bool SP2 = false>
; __device__ __forceinline__ void gemm_phase(PG8_LAS unsigned char* lds, const Gemm g, const Sched& S, const Epi& E, int tid_in) {
;     ...
;         for (int t = 0; t < nt; t += 2) {
;             const bool last = (t == nt - 2);
;             const char* a1 = cA + (size_t)(t + 1) * kstep;
;             const char* a2 = last ? nA : cA + (size_t)(t + 2) * kstep; const char* b2 = last ? nB : cB + (size_t)(t + 2) * kstep;
;             const char* a3 = a2 + kstep; const char* b3 = b2 + kstep;
;             if (last && has_next) S.a_ready(nxt);
;             if constexpr (SP2) {
;             PG8_LDB(B0, 0, 0); PG8_LDB(B1, 0, 1); PG8_SCHED; PG8_LDA(At, 0, 0); PG8_STAGE(PG8_SA(1, 1), a1 + hstep, voffA);
;             PG8_WAIT_V(8); PG8_WAIT_L(0); PG8_BAR; PG8_MMA(0, 0, At, B0); PG8_MMA(0, 1, At, B1); PG8_BAR; PG8_SCHED;
;             PG8_LDA(At, 0, 1); PG8_STAGE(PG8_SB(0, 0), b2, voffB); PG8_STAGE(PG8_SB(0, 1), b2 + hstepB, voffB); PG8_STAGE(PG8_SA(0, 0), a2, voffA);
;             PG8_WAIT_V(8); PG8_WAIT_L(0); PG8_BAR; PG8_MMA(1, 0, At, B0); PG8_MMA(1, 1, At, B1); PG8_BAR; PG8_SCHED;
.Lkb_skip_0:
	ds_read_b128 v[156:159], v150
	ds_read_b128 v[160:163], v150 offset:1024
	ds_read_b128 v[164:167], v150 offset:2048
	ds_read_b128 v[168:171], v150 offset:3072
	ds_read_b128 v[172:175], v151
	ds_read_b128 v[176:179], v151 offset:1024
	ds_read_b128 v[180:183], v151 offset:2048
	ds_read_b128 v[184:187], v151 offset:3072
	s_add_u32 s26, s48, 0xfff80080
	s_addc_u32 s27, s49, -1
	s_cmp_eq_u32 s76, 28
	s_cselect_b32 s53, s41, s27
	s_cselect_b32 s52, s70, s26
	s_cselect_b32 s51, s39, s75
	s_cselect_b32 s50, s71, s74
	s_add_i32 m0, s47, 0xc000
	ds_read_b128 v[188:191], v152
	ds_read_b128 v[192:195], v152 offset:1024
	ds_read_b128 v[196:199], v152 offset:2048
	ds_read_b128 v[200:203], v152 offset:3072
	ds_read_b128 v[212:215], v152 offset:4096
	ds_read_b128 v[216:219], v152 offset:5120
	ds_read_b128 v[220:223], v152 offset:6144
	ds_read_b128 v[224:227], v152 offset:7168
	global_load_lds_dwordx4 v138, s[48:49]
	s_add_i32 m0, s47, 0xe000
	s_nop 0
	global_load_lds_dwordx4 v140, s[48:49]
	s_waitcnt vmcnt(8)
	s_waitcnt lgkmcnt(0)
	s_barrier
	s_waitcnt lgkmcnt(0)
	v_mfma_f32_16x16x32_bf16 v[124:127], v[156:159], v[188:191], 0
	v_mfma_f32_16x16x32_bf16 v[120:123], v[164:167], v[188:191], 0
	v_mfma_f32_16x16x32_bf16 v[108:111], v[156:159], v[196:199], 0
	v_mfma_f32_16x16x32_bf16 v[104:107], v[164:167], v[196:199], 0
	v_mfma_f32_16x16x32_bf16 v[92:95], v[156:159], v[212:215], 0
	v_mfma_f32_16x16x32_bf16 v[88:91], v[164:167], v[212:215], 0
	v_mfma_f32_16x16x32_bf16 v[76:79], v[156:159], v[220:223], 0
	v_mfma_f32_16x16x32_bf16 v[72:75], v[164:167], v[220:223], 0
	v_mfma_f32_16x16x32_bf16 v[124:127], v[160:163], v[192:195], v[124:127]
	v_mfma_f32_16x16x32_bf16 v[120:123], v[168:171], v[192:195], v[120:123]
	v_mfma_f32_16x16x32_bf16 v[108:111], v[160:163], v[200:203], v[108:111]
	v_mfma_f32_16x16x32_bf16 v[104:107], v[168:171], v[200:203], v[104:107]
	v_mfma_f32_16x16x32_bf16 v[92:95], v[160:163], v[216:219], v[92:95]
	v_mfma_f32_16x16x32_bf16 v[88:91], v[168:171], v[216:219], v[88:91]
	v_mfma_f32_16x16x32_bf16 v[76:79], v[160:163], v[224:227], v[76:79]
	v_mfma_f32_16x16x32_bf16 v[72:75], v[168:171], v[224:227], v[72:75]
	v_mfma_f32_16x16x32_bf16 v[116:119], v[172:175], v[188:191], 0
	v_mfma_f32_16x16x32_bf16 v[112:115], v[180:183], v[188:191], 0
	v_mfma_f32_16x16x32_bf16 v[100:103], v[172:175], v[196:199], 0
	v_mfma_f32_16x16x32_bf16 v[96:99], v[180:183], v[196:199], 0
	v_mfma_f32_16x16x32_bf16 v[84:87], v[172:175], v[212:215], 0
	v_mfma_f32_16x16x32_bf16 v[80:83], v[180:183], v[212:215], 0
	v_mfma_f32_16x16x32_bf16 v[68:71], v[172:175], v[220:223], 0
	v_mfma_f32_16x16x32_bf16 v[64:67], v[180:183], v[220:223], 0
	v_mfma_f32_16x16x32_bf16 v[116:119], v[176:179], v[192:195], v[116:119]
	v_mfma_f32_16x16x32_bf16 v[112:115], v[184:187], v[192:195], v[112:115]
	v_mfma_f32_16x16x32_bf16 v[100:103], v[176:179], v[200:203], v[100:103]
	v_mfma_f32_16x16x32_bf16 v[96:99], v[184:187], v[200:203], v[96:99]
	v_mfma_f32_16x16x32_bf16 v[84:87], v[176:179], v[216:219], v[84:87]
	v_mfma_f32_16x16x32_bf16 v[80:83], v[184:187], v[216:219], v[80:83]
	v_mfma_f32_16x16x32_bf16 v[68:71], v[176:179], v[224:227], v[68:71]
	v_mfma_f32_16x16x32_bf16 v[64:67], v[184:187], v[224:227], v[64:67]
	s_barrier
	s_add_i32 s26, s67, s54
	s_mov_b32 m0, s26
	ds_read_b128 v[188:191], v152 offset:16384
	ds_read_b128 v[192:195], v152 offset:17408
	ds_read_b128 v[196:199], v152 offset:18432
	ds_read_b128 v[200:203], v152 offset:19456
	ds_read_b128 v[212:215], v152 offset:20480
	ds_read_b128 v[216:219], v152 offset:21504
	ds_read_b128 v[220:223], v152 offset:22528
	ds_read_b128 v[224:227], v152 offset:23552
	global_load_lds_dwordx4 v132, s[50:51]
	s_add_i32 m0, s26, 0x2000
	s_add_u32 s26, s50, 0x20000
	s_addc_u32 s27, s51, 0
	s_add_i32 s33, s68, s54
	global_load_lds_dwordx4 v128, s[50:51]
	s_mov_b32 m0, s33
	s_nop 0
	global_load_lds_dwordx4 v132, s[26:27]
	s_add_i32 m0, s33, 0x2000
	s_nop 0
	global_load_lds_dwordx4 v128, s[26:27]
	s_mov_b32 m0, s47
	s_nop 0
	global_load_lds_dwordx4 v134, s[52:53]
	s_mov_b32 m0, s56
	s_nop 0
	global_load_lds_dwordx4 v130, s[52:53]
	s_waitcnt vmcnt(8)
	s_waitcnt lgkmcnt(0)
	s_barrier
	s_waitcnt lgkmcnt(0)
	v_mfma_f32_16x16x32_bf16 v[60:63], v[156:159], v[188:191], 0
	v_mfma_f32_16x16x32_bf16 v[56:59], v[164:167], v[188:191], 0
	v_mfma_f32_16x16x32_bf16 v[44:47], v[156:159], v[196:199], 0
	v_mfma_f32_16x16x32_bf16 v[40:43], v[164:167], v[196:199], 0
	v_mfma_f32_16x16x32_bf16 v[28:31], v[156:159], v[212:215], 0
	v_mfma_f32_16x16x32_bf16 v[24:27], v[164:167], v[212:215], 0
	v_mfma_f32_16x16x32_bf16 v[12:15], v[156:159], v[220:223], 0
	v_mfma_f32_16x16x32_bf16 v[8:11], v[164:167], v[220:223], 0
	v_mfma_f32_16x16x32_bf16 v[60:63], v[160:163], v[192:195], v[60:63]
	v_mfma_f32_16x16x32_bf16 v[56:59], v[168:171], v[192:195], v[56:59]
	v_mfma_f32_16x16x32_bf16 v[44:47], v[160:163], v[200:203], v[44:47]
	v_mfma_f32_16x16x32_bf16 v[40:43], v[168:171], v[200:203], v[40:43]
	v_mfma_f32_16x16x32_bf16 v[28:31], v[160:163], v[216:219], v[28:31]
	v_mfma_f32_16x16x32_bf16 v[24:27], v[168:171], v[216:219], v[24:27]
	v_mfma_f32_16x16x32_bf16 v[12:15], v[160:163], v[224:227], v[12:15]
	v_mfma_f32_16x16x32_bf16 v[8:11], v[168:171], v[224:227], v[8:11]
	v_mfma_f32_16x16x32_bf16 v[52:55], v[172:175], v[188:191], 0
	v_mfma_f32_16x16x32_bf16 v[48:51], v[180:183], v[188:191], 0
	v_mfma_f32_16x16x32_bf16 v[36:39], v[172:175], v[196:199], 0
	v_mfma_f32_16x16x32_bf16 v[32:35], v[180:183], v[196:199], 0
	v_mfma_f32_16x16x32_bf16 v[20:23], v[172:175], v[212:215], 0
	v_mfma_f32_16x16x32_bf16 v[16:19], v[180:183], v[212:215], 0
	v_mfma_f32_16x16x32_bf16 v[4:7], v[172:175], v[220:223], 0
	v_mfma_f32_16x16x32_bf16 v[0:3], v[180:183], v[220:223], 0
	v_mfma_f32_16x16x32_bf16 v[52:55], v[176:179], v[192:195], v[52:55]
	v_mfma_f32_16x16x32_bf16 v[48:51], v[184:187], v[192:195], v[48:51]
	v_mfma_f32_16x16x32_bf16 v[36:39], v[176:179], v[200:203], v[36:39]
	v_mfma_f32_16x16x32_bf16 v[32:35], v[184:187], v[200:203], v[32:35]
	v_mfma_f32_16x16x32_bf16 v[20:23], v[176:179], v[216:219], v[20:23]
	v_mfma_f32_16x16x32_bf16 v[16:19], v[184:187], v[216:219], v[16:19]
	v_mfma_f32_16x16x32_bf16 v[4:7], v[176:179], v[224:227], v[4:7]
	v_mfma_f32_16x16x32_bf16 v[0:3], v[184:187], v[224:227], v[0:3]
	s_barrier
; #define PG8_STAGE(bufoff, gbase, voff) do { _Pragma("unroll") for (int _i = 0; _i < 2; ++_i) \
;         __builtin_amdgcn_global_load_lds((const unsigned*)((const char*)(gbase) + (voff)[_i]), (PG8_LAS unsigned*)(lds + (bufoff) + ldsw + _i * 8192), 16, 0, 0); } while (0)
; #define PG8_LDA(dst, b, h) do { _Pragma("unroll") for (int m = 0; m < 4; ++m) _Pragma("unroll") for (int k = 0; k < 2; ++k) dst[m][k] = *(const PG8_LAS bf16x8*)(lds + PG8_SA(b, h) + aoff + m * 2048 + k * 1024); } while (0)
; #define PG8_LDB(dst, b, h) do { _Pragma("unroll") for (int n = 0; n < 2; ++n) _Pragma("unroll") for (int k = 0; k < 2; ++k) dst[n][k] = *(const PG8_LAS bf16x8*)(lds + PG8_SB(b, h) + boff + n * 2048 + k * 1024); } while (0)
; #define PG8_MMA(ai, bj, At, Bt) do { __builtin_amdgcn_s_setprio(1); _Pragma("unroll") for (int m = 0; m < 4; ++m) _Pragma("unroll") for (int n = 0; n < 2; ++n) _Pragma("unroll") for (int k = 0; k < 2; ++k) \
;         acc[ai][bj][m][n] = __builtin_amdgcn_mfma_f32_16x16x32_bf16(Bt[n][k], At[m][k], acc[ai][bj][m][n], 0, 0, 0); __builtin_amdgcn_s_setprio(0); } while (0)
; #define PG8_WAIT_V(n) asm volatile("s_waitcnt vmcnt(" #n ")" ::: "memory")
; #define PG8_WAIT_L(n) asm volatile("s_waitcnt lgkmcnt(" #n ")" ::: "memory")
; #define PG8_BAR __builtin_amdgcn_s_barrier()
; #define PG8_SCHED __builtin_amdgcn_sched_barrier(0)
; template <class Epi, class Sched, bool ALIGN_EPI = false, bool SP2 = false>
; __device__ __forceinline__ void gemm_phase(PG8_LAS unsigned char* lds, const Gemm g, const Sched& S, const Epi& E, int tid_in) {
;     ...
;             PG8_LDB(B0, 1, 0); PG8_LDB(B1, 1, 1); PG8_SCHED; PG8_LDA(At, 1, 0); PG8_STAGE(PG8_SA(0, 1), a2 + hstep, voffA);
;             PG8_WAIT_V(8); PG8_WAIT_L(0); PG8_BAR; PG8_MMA(0, 0, At, B0); PG8_MMA(0, 1, At, B1); PG8_BAR; PG8_SCHED;
;             PG8_LDA(At, 1, 1); PG8_STAGE(PG8_SB(1, 0), b3, voffB); PG8_STAGE(PG8_SB(1, 1), b3 + hstepB, voffB); PG8_STAGE(PG8_SA(1, 0), a3, voffA);
;             PG8_WAIT_V(8); PG8_WAIT_L(0); PG8_BAR; PG8_MMA(1, 0, At, B0); PG8_MMA(1, 1, At, B1); PG8_BAR; PG8_SCHED;
	s_add_i32 s33, 0, 0x18000
	v_add_u32_e32 v155, s33, v146
	s_add_i32 s77, 0, 0x1c000
	ds_read_b128 v[156:159], v155
	ds_read_b128 v[160:163], v155 offset:1024
	ds_read_b128 v[164:167], v155 offset:2048
	ds_read_b128 v[168:171], v155 offset:3072
	v_add_u32_e32 v155, s77, v146
	ds_read_b128 v[172:175], v155
	ds_read_b128 v[176:179], v155 offset:1024
	ds_read_b128 v[180:183], v155 offset:2048
	ds_read_b128 v[184:187], v155 offset:3072
	s_add_u32 s26, s52, 0x80000
	s_addc_u32 s27, s53, 0
	s_mov_b32 m0, s57
	ds_read_b128 v[188:191], v152 offset:32768
	ds_read_b128 v[192:195], v152 offset:33792
	ds_read_b128 v[196:199], v152 offset:34816
	ds_read_b128 v[200:203], v152 offset:35840
	ds_read_b128 v[212:215], v152 offset:36864
	ds_read_b128 v[216:219], v152 offset:37888
	ds_read_b128 v[220:223], v152 offset:38912
	ds_read_b128 v[224:227], v152 offset:39936
	global_load_lds_dwordx4 v134, s[26:27]
	s_mov_b32 m0, s58
	s_nop 0
	global_load_lds_dwordx4 v130, s[26:27]
	s_waitcnt vmcnt(8)
	s_waitcnt lgkmcnt(0)
	s_barrier
	s_waitcnt lgkmcnt(0)
	v_mfma_f32_16x16x32_bf16 v[124:127], v[156:159], v[188:191], v[124:127]
	v_mfma_f32_16x16x32_bf16 v[120:123], v[164:167], v[188:191], v[120:123]
	v_mfma_f32_16x16x32_bf16 v[108:111], v[156:159], v[196:199], v[108:111]
	v_mfma_f32_16x16x32_bf16 v[104:107], v[164:167], v[196:199], v[104:107]
	v_mfma_f32_16x16x32_bf16 v[92:95], v[156:159], v[212:215], v[92:95]
	v_mfma_f32_16x16x32_bf16 v[88:91], v[164:167], v[212:215], v[88:91]
	v_mfma_f32_16x16x32_bf16 v[76:79], v[156:159], v[220:223], v[76:79]
	v_mfma_f32_16x16x32_bf16 v[72:75], v[164:167], v[220:223], v[72:75]
	v_mfma_f32_16x16x32_bf16 v[124:127], v[160:163], v[192:195], v[124:127]
	v_mfma_f32_16x16x32_bf16 v[120:123], v[168:171], v[192:195], v[120:123]
	v_mfma_f32_16x16x32_bf16 v[108:111], v[160:163], v[200:203], v[108:111]
	v_mfma_f32_16x16x32_bf16 v[104:107], v[168:171], v[200:203], v[104:107]
	v_mfma_f32_16x16x32_bf16 v[92:95], v[160:163], v[216:219], v[92:95]
	v_mfma_f32_16x16x32_bf16 v[88:91], v[168:171], v[216:219], v[88:91]
	v_mfma_f32_16x16x32_bf16 v[76:79], v[160:163], v[224:227], v[76:79]
	v_mfma_f32_16x16x32_bf16 v[72:75], v[168:171], v[224:227], v[72:75]
	v_mfma_f32_16x16x32_bf16 v[116:119], v[172:175], v[188:191], v[116:119]
	v_mfma_f32_16x16x32_bf16 v[112:115], v[180:183], v[188:191], v[112:115]
	v_mfma_f32_16x16x32_bf16 v[100:103], v[172:175], v[196:199], v[100:103]
	v_mfma_f32_16x16x32_bf16 v[96:99], v[180:183], v[196:199], v[96:99]
	v_mfma_f32_16x16x32_bf16 v[84:87], v[172:175], v[212:215], v[84:87]
	v_mfma_f32_16x16x32_bf16 v[80:83], v[180:183], v[212:215], v[80:83]
	v_mfma_f32_16x16x32_bf16 v[68:71], v[172:175], v[220:223], v[68:71]
	v_mfma_f32_16x16x32_bf16 v[64:67], v[180:183], v[220:223], v[64:67]
	v_mfma_f32_16x16x32_bf16 v[116:119], v[176:179], v[192:195], v[116:119]
	v_mfma_f32_16x16x32_bf16 v[112:115], v[184:187], v[192:195], v[112:115]
	v_mfma_f32_16x16x32_bf16 v[100:103], v[176:179], v[200:203], v[100:103]
	v_mfma_f32_16x16x32_bf16 v[96:99], v[184:187], v[200:203], v[96:99]
	v_mfma_f32_16x16x32_bf16 v[84:87], v[176:179], v[216:219], v[84:87]
	v_mfma_f32_16x16x32_bf16 v[80:83], v[184:187], v[216:219], v[80:83]
	v_mfma_f32_16x16x32_bf16 v[68:71], v[176:179], v[224:227], v[68:71]
	v_mfma_f32_16x16x32_bf16 v[64:67], v[184:187], v[224:227], v[64:67]
	s_barrier
	s_add_i32 s26, s33, s54
	s_add_i32 m0, s26, 0xffffff80
	ds_read_b128 v[188:191], v152 offset:49152
	ds_read_b128 v[192:195], v152 offset:50176
	ds_read_b128 v[196:199], v152 offset:51200
	ds_read_b128 v[200:203], v152 offset:52224
	ds_read_b128 v[212:215], v152 offset:53248
	ds_read_b128 v[216:219], v152 offset:54272
	ds_read_b128 v[220:223], v152 offset:55296
	ds_read_b128 v[224:227], v152 offset:56320
	global_load_lds_dwordx4 v132, s[50:51] offset:128
	s_add_i32 m0, s26, 0x1f80
	s_add_u32 s26, s50, 0x20080
	s_addc_u32 s27, s51, 0
	s_add_i32 s33, s77, s54
	global_load_lds_dwordx4 v128, s[50:51] offset:128
	s_mov_b32 m0, s33
	s_nop 0
	global_load_lds_dwordx4 v132, s[26:27]
	s_add_i32 m0, s33, 0x2000
	s_nop 0
	global_load_lds_dwordx4 v128, s[26:27]
	s_add_i32 m0, s61, 0xffffff80
	s_nop 0
	global_load_lds_dwordx4 v134, s[52:53] offset:128
	s_add_i32 m0, s62, 0xffffff80
	s_nop 0
	global_load_lds_dwordx4 v130, s[52:53] offset:128
	s_waitcnt vmcnt(8)
	s_waitcnt lgkmcnt(0)
	s_barrier
	s_waitcnt lgkmcnt(0)
	v_mfma_f32_16x16x32_bf16 v[60:63], v[156:159], v[188:191], v[60:63]
	v_mfma_f32_16x16x32_bf16 v[56:59], v[164:167], v[188:191], v[56:59]
	v_mfma_f32_16x16x32_bf16 v[44:47], v[156:159], v[196:199], v[44:47]
	v_mfma_f32_16x16x32_bf16 v[40:43], v[164:167], v[196:199], v[40:43]
	v_mfma_f32_16x16x32_bf16 v[28:31], v[156:159], v[212:215], v[28:31]
	v_mfma_f32_16x16x32_bf16 v[24:27], v[164:167], v[212:215], v[24:27]
	v_mfma_f32_16x16x32_bf16 v[12:15], v[156:159], v[220:223], v[12:15]
	v_mfma_f32_16x16x32_bf16 v[8:11], v[164:167], v[220:223], v[8:11]
	v_mfma_f32_16x16x32_bf16 v[60:63], v[160:163], v[192:195], v[60:63]
	v_mfma_f32_16x16x32_bf16 v[56:59], v[168:171], v[192:195], v[56:59]
	v_mfma_f32_16x16x32_bf16 v[44:47], v[160:163], v[200:203], v[44:47]
	v_mfma_f32_16x16x32_bf16 v[40:43], v[168:171], v[200:203], v[40:43]
	v_mfma_f32_16x16x32_bf16 v[28:31], v[160:163], v[216:219], v[28:31]
	v_mfma_f32_16x16x32_bf16 v[24:27], v[168:171], v[216:219], v[24:27]
	v_mfma_f32_16x16x32_bf16 v[12:15], v[160:163], v[224:227], v[12:15]
	v_mfma_f32_16x16x32_bf16 v[8:11], v[168:171], v[224:227], v[8:11]
	v_mfma_f32_16x16x32_bf16 v[52:55], v[172:175], v[188:191], v[52:55]
	v_mfma_f32_16x16x32_bf16 v[48:51], v[180:183], v[188:191], v[48:51]
	v_mfma_f32_16x16x32_bf16 v[36:39], v[172:175], v[196:199], v[36:39]
	v_mfma_f32_16x16x32_bf16 v[32:35], v[180:183], v[196:199], v[32:35]
	v_mfma_f32_16x16x32_bf16 v[20:23], v[172:175], v[212:215], v[20:23]
	v_mfma_f32_16x16x32_bf16 v[16:19], v[180:183], v[212:215], v[16:19]
	v_mfma_f32_16x16x32_bf16 v[4:7], v[172:175], v[220:223], v[4:7]
	v_mfma_f32_16x16x32_bf16 v[0:3], v[180:183], v[220:223], v[0:3]
	v_mfma_f32_16x16x32_bf16 v[52:55], v[176:179], v[192:195], v[52:55]
	v_mfma_f32_16x16x32_bf16 v[48:51], v[184:187], v[192:195], v[48:51]
	v_mfma_f32_16x16x32_bf16 v[36:39], v[176:179], v[200:203], v[36:39]
	v_mfma_f32_16x16x32_bf16 v[32:35], v[184:187], v[200:203], v[32:35]
	v_mfma_f32_16x16x32_bf16 v[20:23], v[176:179], v[216:219], v[20:23]
	v_mfma_f32_16x16x32_bf16 v[16:19], v[184:187], v[216:219], v[16:19]
	v_mfma_f32_16x16x32_bf16 v[4:7], v[176:179], v[224:227], v[4:7]
	v_mfma_f32_16x16x32_bf16 v[0:3], v[184:187], v[224:227], v[0:3]
	s_barrier
	s_add_i32 s76, s76, 2
	s_add_u32 s48, s48, 0x100
	s_addc_u32 s49, s49, 0
	s_add_u32 s74, s74, 0x100
	s_addc_u32 s75, s75, 0
	s_cmp_gt_u32 s76, 29
; #define PG8_STAGE(bufoff, gbase, voff) do { _Pragma("unroll") for (int _i = 0; _i < 2; ++_i) \
;         __builtin_amdgcn_global_load_lds((const unsigned*)((const char*)(gbase) + (voff)[_i]), (PG8_LAS unsigned*)(lds + (bufoff) + ldsw + _i * 8192), 16, 0, 0); } while (0)
; #define PG8_LDA(dst, b, h) do { _Pragma("unroll") for (int m = 0; m < 4; ++m) _Pragma("unroll") for (int k = 0; k < 2; ++k) dst[m][k] = *(const PG8_LAS bf16x8*)(lds + PG8_SA(b, h) + aoff + m * 2048 + k * 1024); } while (0)
; #define PG8_LDB(dst, b, h) do { _Pragma("unroll") for (int n = 0; n < 2; ++n) _Pragma("unroll") for (int k = 0; k < 2; ++k) dst[n][k] = *(const PG8_LAS bf16x8*)(lds + PG8_SB(b, h) + boff + n * 2048 + k * 1024); } while (0)
; #define PG8_MMA(ai, bj, At, Bt) do { __builtin_amdgcn_s_setprio(1); _Pragma("unroll") for (int m = 0; m < 4; ++m) _Pragma("unroll") for (int n = 0; n < 2; ++n) _Pragma("unroll") for (int k = 0; k < 2; ++k) \
;         acc[ai][bj][m][n] = __builtin_amdgcn_mfma_f32_16x16x32_bf16(Bt[n][k], At[m][k], acc[ai][bj][m][n], 0, 0, 0); __builtin_amdgcn_s_setprio(0); } while (0)
; #define PG8_WAIT_V(n) asm volatile("s_waitcnt vmcnt(" #n ")" ::: "memory")
; #define PG8_BAR __builtin_amdgcn_s_barrier()
; template <class Epi, class Sched, bool ALIGN_EPI = false, bool SP2 = false>
; __device__ __forceinline__ void gemm_phase(PG8_LAS unsigned char* lds, const Gemm g, const Sched& S, const Epi& E, int tid_in) {
;     ...
;         for (int t = 0; t < nt; t += 2) {
;             const bool last = (t == nt - 2);
;             const char* a1 = cA + (size_t)(t + 1) * kstep;
;             const char* a2 = last ? nA : cA + (size_t)(t + 2) * kstep; const char* b2 = last ? nB : cB + (size_t)(t + 2) * kstep;
;             const char* a3 = a2 + kstep; const char* b3 = b2 + kstep;
;             if (last && has_next) S.a_ready(nxt);
;             if constexpr (SP2) {
;             PG8_LDB(B0, 0, 0); PG8_LDB(B1, 0, 1); PG8_SCHED; PG8_LDA(At, 0, 0); PG8_STAGE(PG8_SA(1, 1), a1 + hstep, voffA);
;             PG8_WAIT_V(8); PG8_WAIT_L(0); PG8_BAR; PG8_MMA(0, 0, At, B0); PG8_MMA(0, 1, At, B1); PG8_BAR; PG8_SCHED;
;             PG8_LDA(At, 0, 1); PG8_STAGE(PG8_SB(0, 0), b2, voffB); PG8_STAGE(PG8_SB(0, 1), b2 + hstepB, voffB); PG8_STAGE(PG8_SA(0, 0), a2, voffA);
;             PG8_WAIT_V(8); PG8_WAIT_L(0); PG8_BAR; PG8_MMA(1, 0, At, B0); PG8_MMA(1, 1, At, B1); PG8_BAR; PG8_SCHED;
.LBB0_80:
	ds_read_b128 v[156:159], v150
	ds_read_b128 v[160:163], v150 offset:1024
	ds_read_b128 v[164:167], v150 offset:2048
	ds_read_b128 v[168:171], v150 offset:3072
	ds_read_b128 v[172:175], v151
	ds_read_b128 v[176:179], v151 offset:1024
	ds_read_b128 v[180:183], v151 offset:2048
	ds_read_b128 v[184:187], v151 offset:3072
	s_add_u32 s26, s48, 0xfff80080
	s_addc_u32 s27, s49, -1
	s_cmp_eq_u32 s76, 28
	s_cselect_b32 s53, s41, s27
	s_cselect_b32 s52, s70, s26
	s_cselect_b32 s51, s39, s75
	s_cselect_b32 s50, s71, s74
	s_add_i32 m0, s47, 0xc000
	ds_read_b128 v[188:191], v152
	ds_read_b128 v[192:195], v152 offset:1024
	ds_read_b128 v[196:199], v152 offset:2048
	ds_read_b128 v[200:203], v152 offset:3072
	ds_read_b128 v[212:215], v152 offset:4096
	ds_read_b128 v[216:219], v152 offset:5120
	ds_read_b128 v[220:223], v152 offset:6144
	ds_read_b128 v[224:227], v152 offset:7168
	global_load_lds_dwordx4 v138, s[48:49]
	s_add_i32 m0, s47, 0xe000
	s_nop 0
	global_load_lds_dwordx4 v140, s[48:49]
	s_waitcnt vmcnt(8)
	s_waitcnt lgkmcnt(0)
	s_barrier
	s_waitcnt lgkmcnt(0)
	v_mfma_f32_16x16x32_bf16 v[124:127], v[156:159], v[188:191], v[124:127]
	v_mfma_f32_16x16x32_bf16 v[120:123], v[164:167], v[188:191], v[120:123]
	v_mfma_f32_16x16x32_bf16 v[108:111], v[156:159], v[196:199], v[108:111]
	v_mfma_f32_16x16x32_bf16 v[104:107], v[164:167], v[196:199], v[104:107]
	v_mfma_f32_16x16x32_bf16 v[92:95], v[156:159], v[212:215], v[92:95]
	v_mfma_f32_16x16x32_bf16 v[88:91], v[164:167], v[212:215], v[88:91]
	v_mfma_f32_16x16x32_bf16 v[76:79], v[156:159], v[220:223], v[76:79]
	v_mfma_f32_16x16x32_bf16 v[72:75], v[164:167], v[220:223], v[72:75]
	v_mfma_f32_16x16x32_bf16 v[124:127], v[160:163], v[192:195], v[124:127]
	v_mfma_f32_16x16x32_bf16 v[120:123], v[168:171], v[192:195], v[120:123]
	v_mfma_f32_16x16x32_bf16 v[108:111], v[160:163], v[200:203], v[108:111]
	v_mfma_f32_16x16x32_bf16 v[104:107], v[168:171], v[200:203], v[104:107]
	v_mfma_f32_16x16x32_bf16 v[92:95], v[160:163], v[216:219], v[92:95]
	v_mfma_f32_16x16x32_bf16 v[88:91], v[168:171], v[216:219], v[88:91]
	v_mfma_f32_16x16x32_bf16 v[76:79], v[160:163], v[224:227], v[76:79]
	v_mfma_f32_16x16x32_bf16 v[72:75], v[168:171], v[224:227], v[72:75]
	v_mfma_f32_16x16x32_bf16 v[116:119], v[172:175], v[188:191], v[116:119]
	v_mfma_f32_16x16x32_bf16 v[112:115], v[180:183], v[188:191], v[112:115]
	v_mfma_f32_16x16x32_bf16 v[100:103], v[172:175], v[196:199], v[100:103]
	v_mfma_f32_16x16x32_bf16 v[96:99], v[180:183], v[196:199], v[96:99]
	v_mfma_f32_16x16x32_bf16 v[84:87], v[172:175], v[212:215], v[84:87]
	v_mfma_f32_16x16x32_bf16 v[80:83], v[180:183], v[212:215], v[80:83]
	v_mfma_f32_16x16x32_bf16 v[68:71], v[172:175], v[220:223], v[68:71]
	v_mfma_f32_16x16x32_bf16 v[64:67], v[180:183], v[220:223], v[64:67]
	v_mfma_f32_16x16x32_bf16 v[116:119], v[176:179], v[192:195], v[116:119]
	v_mfma_f32_16x16x32_bf16 v[112:115], v[184:187], v[192:195], v[112:115]
	v_mfma_f32_16x16x32_bf16 v[100:103], v[176:179], v[200:203], v[100:103]
	v_mfma_f32_16x16x32_bf16 v[96:99], v[184:187], v[200:203], v[96:99]
	v_mfma_f32_16x16x32_bf16 v[84:87], v[176:179], v[216:219], v[84:87]
	v_mfma_f32_16x16x32_bf16 v[80:83], v[184:187], v[216:219], v[80:83]
	v_mfma_f32_16x16x32_bf16 v[68:71], v[176:179], v[224:227], v[68:71]
	v_mfma_f32_16x16x32_bf16 v[64:67], v[184:187], v[224:227], v[64:67]
	s_barrier
	s_add_i32 s26, s67, s54
	s_mov_b32 m0, s26
	ds_read_b128 v[188:191], v152 offset:16384
	ds_read_b128 v[192:195], v152 offset:17408
	ds_read_b128 v[196:199], v152 offset:18432
	ds_read_b128 v[200:203], v152 offset:19456
	ds_read_b128 v[212:215], v152 offset:20480
	ds_read_b128 v[216:219], v152 offset:21504
	ds_read_b128 v[220:223], v152 offset:22528
	ds_read_b128 v[224:227], v152 offset:23552
	global_load_lds_dwordx4 v132, s[50:51]
	s_add_i32 m0, s26, 0x2000
	s_add_u32 s26, s50, 0x20000
	s_addc_u32 s27, s51, 0
	s_add_i32 s33, s68, s54
	global_load_lds_dwordx4 v128, s[50:51]
	s_mov_b32 m0, s33
	s_nop 0
	global_load_lds_dwordx4 v132, s[26:27]
	s_add_i32 m0, s33, 0x2000
	s_nop 0
	global_load_lds_dwordx4 v128, s[26:27]
	s_mov_b32 m0, s47
	s_nop 0
	global_load_lds_dwordx4 v134, s[52:53]
	s_mov_b32 m0, s56
	s_nop 0
	global_load_lds_dwordx4 v130, s[52:53]
	s_waitcnt vmcnt(8)
	s_waitcnt lgkmcnt(0)
	s_barrier
	s_waitcnt lgkmcnt(0)
	v_mfma_f32_16x16x32_bf16 v[60:63], v[156:159], v[188:191], v[60:63]
	v_mfma_f32_16x16x32_bf16 v[56:59], v[164:167], v[188:191], v[56:59]
	v_mfma_f32_16x16x32_bf16 v[44:47], v[156:159], v[196:199], v[44:47]
	v_mfma_f32_16x16x32_bf16 v[40:43], v[164:167], v[196:199], v[40:43]
	v_mfma_f32_16x16x32_bf16 v[28:31], v[156:159], v[212:215], v[28:31]
	v_mfma_f32_16x16x32_bf16 v[24:27], v[164:167], v[212:215], v[24:27]
	v_mfma_f32_16x16x32_bf16 v[12:15], v[156:159], v[220:223], v[12:15]
	v_mfma_f32_16x16x32_bf16 v[8:11], v[164:167], v[220:223], v[8:11]
	v_mfma_f32_16x16x32_bf16 v[60:63], v[160:163], v[192:195], v[60:63]
	v_mfma_f32_16x16x32_bf16 v[56:59], v[168:171], v[192:195], v[56:59]
	v_mfma_f32_16x16x32_bf16 v[44:47], v[160:163], v[200:203], v[44:47]
	v_mfma_f32_16x16x32_bf16 v[40:43], v[168:171], v[200:203], v[40:43]
	v_mfma_f32_16x16x32_bf16 v[28:31], v[160:163], v[216:219], v[28:31]
	v_mfma_f32_16x16x32_bf16 v[24:27], v[168:171], v[216:219], v[24:27]
	v_mfma_f32_16x16x32_bf16 v[12:15], v[160:163], v[224:227], v[12:15]
	v_mfma_f32_16x16x32_bf16 v[8:11], v[168:171], v[224:227], v[8:11]
	v_mfma_f32_16x16x32_bf16 v[52:55], v[172:175], v[188:191], v[52:55]
	v_mfma_f32_16x16x32_bf16 v[48:51], v[180:183], v[188:191], v[48:51]
	v_mfma_f32_16x16x32_bf16 v[36:39], v[172:175], v[196:199], v[36:39]
	v_mfma_f32_16x16x32_bf16 v[32:35], v[180:183], v[196:199], v[32:35]
	v_mfma_f32_16x16x32_bf16 v[20:23], v[172:175], v[212:215], v[20:23]
	v_mfma_f32_16x16x32_bf16 v[16:19], v[180:183], v[212:215], v[16:19]
	v_mfma_f32_16x16x32_bf16 v[4:7], v[172:175], v[220:223], v[4:7]
	v_mfma_f32_16x16x32_bf16 v[0:3], v[180:183], v[220:223], v[0:3]
	v_mfma_f32_16x16x32_bf16 v[52:55], v[176:179], v[192:195], v[52:55]
	v_mfma_f32_16x16x32_bf16 v[48:51], v[184:187], v[192:195], v[48:51]
	v_mfma_f32_16x16x32_bf16 v[36:39], v[176:179], v[200:203], v[36:39]
	v_mfma_f32_16x16x32_bf16 v[32:35], v[184:187], v[200:203], v[32:35]
	v_mfma_f32_16x16x32_bf16 v[20:23], v[176:179], v[216:219], v[20:23]
	v_mfma_f32_16x16x32_bf16 v[16:19], v[184:187], v[216:219], v[16:19]
	v_mfma_f32_16x16x32_bf16 v[4:7], v[176:179], v[224:227], v[4:7]
	v_mfma_f32_16x16x32_bf16 v[0:3], v[184:187], v[224:227], v[0:3]
	s_barrier
; #define PG8_STAGE(bufoff, gbase, voff) do { _Pragma("unroll") for (int _i = 0; _i < 2; ++_i) \
;         __builtin_amdgcn_global_load_lds((const unsigned*)((const char*)(gbase) + (voff)[_i]), (PG8_LAS unsigned*)(lds + (bufoff) + ldsw + _i * 8192), 16, 0, 0); } while (0)
; #define PG8_LDA(dst, b, h) do { _Pragma("unroll") for (int m = 0; m < 4; ++m) _Pragma("unroll") for (int k = 0; k < 2; ++k) dst[m][k] = *(const PG8_LAS bf16x8*)(lds + PG8_SA(b, h) + aoff + m * 2048 + k * 1024); } while (0)
; #define PG8_LDB(dst, b, h) do { _Pragma("unroll") for (int n = 0; n < 2; ++n) _Pragma("unroll") for (int k = 0; k < 2; ++k) dst[n][k] = *(const PG8_LAS bf16x8*)(lds + PG8_SB(b, h) + boff + n * 2048 + k * 1024); } while (0)
; #define PG8_MMA(ai, bj, At, Bt) do { __builtin_amdgcn_s_setprio(1); _Pragma("unroll") for (int m = 0; m < 4; ++m) _Pragma("unroll") for (int n = 0; n < 2; ++n) _Pragma("unroll") for (int k = 0; k < 2; ++k) \
;         acc[ai][bj][m][n] = __builtin_amdgcn_mfma_f32_16x16x32_bf16(Bt[n][k], At[m][k], acc[ai][bj][m][n], 0, 0, 0); __builtin_amdgcn_s_setprio(0); } while (0)
; #define PG8_WAIT_V(n) asm volatile("s_waitcnt vmcnt(" #n ")" ::: "memory")
; #define PG8_WAIT_L(n) asm volatile("s_waitcnt lgkmcnt(" #n ")" ::: "memory")
; #define PG8_BAR __builtin_amdgcn_s_barrier()
; #define PG8_SCHED __builtin_amdgcn_sched_barrier(0)
; template <class Epi, class Sched, bool ALIGN_EPI = false, bool SP2 = false>
; __device__ __forceinline__ void gemm_phase(PG8_LAS unsigned char* lds, const Gemm g, const Sched& S, const Epi& E, int tid_in) {
;     ...
;             PG8_LDB(B0, 1, 0); PG8_LDB(B1, 1, 1); PG8_SCHED; PG8_LDA(At, 1, 0); PG8_STAGE(PG8_SA(0, 1), a2 + hstep, voffA);
;             PG8_WAIT_V(8); PG8_WAIT_L(0); PG8_BAR; PG8_MMA(0, 0, At, B0); PG8_MMA(0, 1, At, B1); PG8_BAR; PG8_SCHED;
;             PG8_LDA(At, 1, 1); PG8_STAGE(PG8_SB(1, 0), b3, voffB); PG8_STAGE(PG8_SB(1, 1), b3 + hstepB, voffB); PG8_STAGE(PG8_SA(1, 0), a3, voffA);
;             PG8_WAIT_V(8); PG8_WAIT_L(0); PG8_BAR; PG8_MMA(1, 0, At, B0); PG8_MMA(1, 1, At, B1); PG8_BAR; PG8_SCHED;
;     ...
;         if constexpr (ALIGN_EPI) { if (wr == 0) PG8_BAR; }
	s_add_i32 s33, 0, 0x18000
	v_add_u32_e32 v155, s33, v146
	s_add_i32 s77, 0, 0x1c000
	ds_read_b128 v[156:159], v155
	ds_read_b128 v[160:163], v155 offset:1024
	ds_read_b128 v[164:167], v155 offset:2048
	ds_read_b128 v[168:171], v155 offset:3072
	v_add_u32_e32 v155, s77, v146
	ds_read_b128 v[172:175], v155
	ds_read_b128 v[176:179], v155 offset:1024
	ds_read_b128 v[180:183], v155 offset:2048
	ds_read_b128 v[184:187], v155 offset:3072
	s_add_u32 s26, s52, 0x80000
	s_addc_u32 s27, s53, 0
	s_mov_b32 m0, s57
	ds_read_b128 v[188:191], v152 offset:32768
	ds_read_b128 v[192:195], v152 offset:33792
	ds_read_b128 v[196:199], v152 offset:34816
	ds_read_b128 v[200:203], v152 offset:35840
	ds_read_b128 v[212:215], v152 offset:36864
	ds_read_b128 v[216:219], v152 offset:37888
	ds_read_b128 v[220:223], v152 offset:38912
	ds_read_b128 v[224:227], v152 offset:39936
	global_load_lds_dwordx4 v134, s[26:27]
	s_mov_b32 m0, s58
	s_nop 0
	global_load_lds_dwordx4 v130, s[26:27]
	s_waitcnt vmcnt(8)
	s_waitcnt lgkmcnt(0)
	s_barrier
	s_waitcnt lgkmcnt(0)
	v_mfma_f32_16x16x32_bf16 v[124:127], v[156:159], v[188:191], v[124:127]
	v_mfma_f32_16x16x32_bf16 v[120:123], v[164:167], v[188:191], v[120:123]
	v_mfma_f32_16x16x32_bf16 v[108:111], v[156:159], v[196:199], v[108:111]
	v_mfma_f32_16x16x32_bf16 v[104:107], v[164:167], v[196:199], v[104:107]
	v_mfma_f32_16x16x32_bf16 v[92:95], v[156:159], v[212:215], v[92:95]
	v_mfma_f32_16x16x32_bf16 v[88:91], v[164:167], v[212:215], v[88:91]
	v_mfma_f32_16x16x32_bf16 v[76:79], v[156:159], v[220:223], v[76:79]
	v_mfma_f32_16x16x32_bf16 v[72:75], v[164:167], v[220:223], v[72:75]
	v_mfma_f32_16x16x32_bf16 v[124:127], v[160:163], v[192:195], v[124:127]
	v_mfma_f32_16x16x32_bf16 v[120:123], v[168:171], v[192:195], v[120:123]
	v_mfma_f32_16x16x32_bf16 v[108:111], v[160:163], v[200:203], v[108:111]
	v_mfma_f32_16x16x32_bf16 v[104:107], v[168:171], v[200:203], v[104:107]
	v_mfma_f32_16x16x32_bf16 v[92:95], v[160:163], v[216:219], v[92:95]
	v_mfma_f32_16x16x32_bf16 v[88:91], v[168:171], v[216:219], v[88:91]
	v_mfma_f32_16x16x32_bf16 v[76:79], v[160:163], v[224:227], v[76:79]
	v_mfma_f32_16x16x32_bf16 v[72:75], v[168:171], v[224:227], v[72:75]
	v_mfma_f32_16x16x32_bf16 v[116:119], v[172:175], v[188:191], v[116:119]
	v_mfma_f32_16x16x32_bf16 v[112:115], v[180:183], v[188:191], v[112:115]
	v_mfma_f32_16x16x32_bf16 v[100:103], v[172:175], v[196:199], v[100:103]
	v_mfma_f32_16x16x32_bf16 v[96:99], v[180:183], v[196:199], v[96:99]
	v_mfma_f32_16x16x32_bf16 v[84:87], v[172:175], v[212:215], v[84:87]
	v_mfma_f32_16x16x32_bf16 v[80:83], v[180:183], v[212:215], v[80:83]
	v_mfma_f32_16x16x32_bf16 v[68:71], v[172:175], v[220:223], v[68:71]
	v_mfma_f32_16x16x32_bf16 v[64:67], v[180:183], v[220:223], v[64:67]
	v_mfma_f32_16x16x32_bf16 v[116:119], v[176:179], v[192:195], v[116:119]
	v_mfma_f32_16x16x32_bf16 v[112:115], v[184:187], v[192:195], v[112:115]
	v_mfma_f32_16x16x32_bf16 v[100:103], v[176:179], v[200:203], v[100:103]
	v_mfma_f32_16x16x32_bf16 v[96:99], v[184:187], v[200:203], v[96:99]
	v_mfma_f32_16x16x32_bf16 v[84:87], v[176:179], v[216:219], v[84:87]
	v_mfma_f32_16x16x32_bf16 v[80:83], v[184:187], v[216:219], v[80:83]
	v_mfma_f32_16x16x32_bf16 v[68:71], v[176:179], v[224:227], v[68:71]
	v_mfma_f32_16x16x32_bf16 v[64:67], v[184:187], v[224:227], v[64:67]
	s_barrier
	s_add_i32 s26, s33, s54
	s_add_i32 m0, s26, 0xffffff80
	ds_read_b128 v[188:191], v152 offset:49152
	ds_read_b128 v[192:195], v152 offset:50176
	ds_read_b128 v[196:199], v152 offset:51200
	ds_read_b128 v[200:203], v152 offset:52224
	ds_read_b128 v[212:215], v152 offset:53248
	ds_read_b128 v[216:219], v152 offset:54272
	ds_read_b128 v[220:223], v152 offset:55296
	ds_read_b128 v[224:227], v152 offset:56320
	global_load_lds_dwordx4 v132, s[50:51] offset:128
	s_add_i32 m0, s26, 0x1f80
	s_add_u32 s26, s50, 0x20080
	s_addc_u32 s27, s51, 0
	s_add_i32 s33, s77, s54
	global_load_lds_dwordx4 v128, s[50:51] offset:128
	s_mov_b32 m0, s33
	s_nop 0
	global_load_lds_dwordx4 v132, s[26:27]
	s_add_i32 m0, s33, 0x2000
	s_nop 0
	global_load_lds_dwordx4 v128, s[26:27]
	s_add_i32 m0, s61, 0xffffff80
	s_nop 0
	global_load_lds_dwordx4 v134, s[52:53] offset:128
	s_add_i32 m0, s62, 0xffffff80
	s_nop 0
	global_load_lds_dwordx4 v130, s[52:53] offset:128
	s_waitcnt vmcnt(8)
	s_waitcnt lgkmcnt(0)
	s_barrier
	s_waitcnt lgkmcnt(0)
	v_mfma_f32_16x16x32_bf16 v[60:63], v[156:159], v[188:191], v[60:63]
	v_mfma_f32_16x16x32_bf16 v[56:59], v[164:167], v[188:191], v[56:59]
	v_mfma_f32_16x16x32_bf16 v[44:47], v[156:159], v[196:199], v[44:47]
	v_mfma_f32_16x16x32_bf16 v[40:43], v[164:167], v[196:199], v[40:43]
	v_mfma_f32_16x16x32_bf16 v[28:31], v[156:159], v[212:215], v[28:31]
	v_mfma_f32_16x16x32_bf16 v[24:27], v[164:167], v[212:215], v[24:27]
	v_mfma_f32_16x16x32_bf16 v[12:15], v[156:159], v[220:223], v[12:15]
	v_mfma_f32_16x16x32_bf16 v[8:11], v[164:167], v[220:223], v[8:11]
	v_mfma_f32_16x16x32_bf16 v[60:63], v[160:163], v[192:195], v[60:63]
	v_mfma_f32_16x16x32_bf16 v[56:59], v[168:171], v[192:195], v[56:59]
	v_mfma_f32_16x16x32_bf16 v[44:47], v[160:163], v[200:203], v[44:47]
	v_mfma_f32_16x16x32_bf16 v[40:43], v[168:171], v[200:203], v[40:43]
	v_mfma_f32_16x16x32_bf16 v[28:31], v[160:163], v[216:219], v[28:31]
	v_mfma_f32_16x16x32_bf16 v[24:27], v[168:171], v[216:219], v[24:27]
	v_mfma_f32_16x16x32_bf16 v[12:15], v[160:163], v[224:227], v[12:15]
	v_mfma_f32_16x16x32_bf16 v[8:11], v[168:171], v[224:227], v[8:11]
	v_mfma_f32_16x16x32_bf16 v[52:55], v[172:175], v[188:191], v[52:55]
	v_mfma_f32_16x16x32_bf16 v[48:51], v[180:183], v[188:191], v[48:51]
	v_mfma_f32_16x16x32_bf16 v[36:39], v[172:175], v[196:199], v[36:39]
	v_mfma_f32_16x16x32_bf16 v[32:35], v[180:183], v[196:199], v[32:35]
	v_mfma_f32_16x16x32_bf16 v[20:23], v[172:175], v[212:215], v[20:23]
	v_mfma_f32_16x16x32_bf16 v[16:19], v[180:183], v[212:215], v[16:19]
	v_mfma_f32_16x16x32_bf16 v[4:7], v[172:175], v[220:223], v[4:7]
	v_mfma_f32_16x16x32_bf16 v[0:3], v[180:183], v[220:223], v[0:3]
	v_mfma_f32_16x16x32_bf16 v[52:55], v[176:179], v[192:195], v[52:55]
	v_mfma_f32_16x16x32_bf16 v[48:51], v[184:187], v[192:195], v[48:51]
	v_mfma_f32_16x16x32_bf16 v[36:39], v[176:179], v[200:203], v[36:39]
	v_mfma_f32_16x16x32_bf16 v[32:35], v[184:187], v[200:203], v[32:35]
	v_mfma_f32_16x16x32_bf16 v[20:23], v[176:179], v[216:219], v[20:23]
	v_mfma_f32_16x16x32_bf16 v[16:19], v[184:187], v[216:219], v[16:19]
	v_mfma_f32_16x16x32_bf16 v[4:7], v[176:179], v[224:227], v[4:7]
	v_mfma_f32_16x16x32_bf16 v[0:3], v[184:187], v[224:227], v[0:3]
	s_barrier
	s_add_i32 s76, s76, 2
	s_add_u32 s48, s48, 0x100
	s_addc_u32 s49, s49, 0
	s_add_u32 s74, s74, 0x100
	s_addc_u32 s75, s75, 0
	s_cmp_gt_u32 s76, 29
	s_cbranch_scc0 .LBB0_80
	s_and_b64 vcc, exec, s[14:15]
	s_cbranch_vccz .LBB0_83
	s_barrier

; #define PG8_STAGE(bufoff, gbase, voff) do { _Pragma("unroll") for (int _i = 0; _i < 2; ++_i) \
;         __builtin_amdgcn_global_load_lds((const unsigned*)((const char*)(gbase) + (voff)[_i]), (PG8_LAS unsigned*)(lds + (bufoff) + ldsw + _i * 8192), 16, 0, 0); } while (0)
; #define PG8_LDA(dst, b, h) do { _Pragma("unroll") for (int m = 0; m < 4; ++m) _Pragma("unroll") for (int k = 0; k < 2; ++k) dst[m][k] = *(const PG8_LAS bf16x8*)(lds + PG8_SA(b, h) + aoff + m * 2048 + k * 1024); } while (0)
; #define PG8_LDB(dst, b, h) do { _Pragma("unroll") for (int n = 0; n < 2; ++n) _Pragma("unroll") for (int k = 0; k < 2; ++k) dst[n][k] = *(const PG8_LAS bf16x8*)(lds + PG8_SB(b, h) + boff + n * 2048 + k * 1024); } while (0)
; #define PG8_MMA(ai, bj, At, Bt) do { __builtin_amdgcn_s_setprio(1); _Pragma("unroll") for (int m = 0; m < 4; ++m) _Pragma("unroll") for (int n = 0; n < 2; ++n) _Pragma("unroll") for (int k = 0; k < 2; ++k) \
;         acc[ai][bj][m][n] = __builtin_amdgcn_mfma_f32_16x16x32_bf16(Bt[n][k], At[m][k], acc[ai][bj][m][n], 0, 0, 0); __builtin_amdgcn_s_setprio(0); } while (0)
; #define PG8_WAIT_V(n) asm volatile("s_waitcnt vmcnt(" #n ")" ::: "memory")
; #define PG8_BAR __builtin_amdgcn_s_barrier()
; template <class Epi, class Sched, bool ALIGN_EPI = false, bool SP2 = false>
; __device__ __forceinline__ void gemm_phase(PG8_LAS unsigned char* lds, const Gemm g, const Sched& S, const Epi& E, int tid_in) {
;     ...
;         for (int t = 0; t < nt; t += 2) {
;             const bool last = (t == nt - 2);
;             const char* a1 = cA + (size_t)(t + 1) * kstep;
;             const char* a2 = last ? nA : cA + (size_t)(t + 2) * kstep; const char* b2 = last ? nB : cB + (size_t)(t + 2) * kstep;
;             const char* a3 = a2 + kstep; const char* b3 = b2 + kstep;
;             if (last && has_next) S.a_ready(nxt);
;             if constexpr (SP2) {
;             PG8_LDB(B0, 0, 0); PG8_LDB(B1, 0, 1); PG8_SCHED; PG8_LDA(At, 0, 0); PG8_STAGE(PG8_SA(1, 1), a1 + hstep, voffA);
;             PG8_WAIT_V(8); PG8_WAIT_L(0); PG8_BAR; PG8_MMA(0, 0, At, B0); PG8_MMA(0, 1, At, B1); PG8_BAR; PG8_SCHED;
;             PG8_LDA(At, 0, 1); PG8_STAGE(PG8_SB(0, 0), b2, voffB); PG8_STAGE(PG8_SB(0, 1), b2 + hstepB, voffB); PG8_STAGE(PG8_SA(0, 0), a2, voffA);
;             PG8_WAIT_V(8); PG8_WAIT_L(0); PG8_BAR; PG8_MMA(1, 0, At, B0); PG8_MMA(1, 1, At, B1); PG8_BAR; PG8_SCHED;
.Lkb_skip_1:
	ds_read_b128 v[146:149], v153
	ds_read_b128 v[158:161], v153 offset:1024
	ds_read_b128 v[162:165], v153 offset:2048
	ds_read_b128 v[166:169], v153 offset:3072
	ds_read_b128 v[170:173], v154
	ds_read_b128 v[174:177], v154 offset:1024
	ds_read_b128 v[178:181], v154 offset:2048
	ds_read_b128 v[182:185], v154 offset:3072
	s_add_u32 s26, s58, 0xfff80080
	s_addc_u32 s27, s59, -1
	s_cmp_eq_u32 s79, 28
	s_cselect_b32 s63, s49, s27
	s_cselect_b32 s62, s55, s26
	s_cselect_b32 s61, s47, s77
	s_cselect_b32 s60, s75, s76
	s_add_i32 m0, s57, 0xc000
	ds_read_b128 v[186:189], v155
	ds_read_b128 v[190:193], v155 offset:1024
	ds_read_b128 v[194:197], v155 offset:2048
	ds_read_b128 v[198:201], v155 offset:3072
	ds_read_b128 v[202:205], v155 offset:4096
	ds_read_b128 v[206:209], v155 offset:5120
	ds_read_b128 v[212:215], v155 offset:6144
	ds_read_b128 v[216:219], v155 offset:7168
	global_load_lds_dwordx4 v138, s[58:59]
	s_add_i32 m0, s57, 0xe000
	s_nop 0
	global_load_lds_dwordx4 v140, s[58:59]
	s_waitcnt vmcnt(8)
	s_waitcnt lgkmcnt(0)
	s_barrier
	s_waitcnt lgkmcnt(0)
	v_mfma_f32_16x16x32_bf16 v[124:127], v[146:149], v[186:189], 0
	v_mfma_f32_16x16x32_bf16 v[120:123], v[162:165], v[186:189], 0
	v_mfma_f32_16x16x32_bf16 v[108:111], v[146:149], v[194:197], 0
	v_mfma_f32_16x16x32_bf16 v[104:107], v[162:165], v[194:197], 0
	v_mfma_f32_16x16x32_bf16 v[92:95], v[146:149], v[202:205], 0
	v_mfma_f32_16x16x32_bf16 v[88:91], v[162:165], v[202:205], 0
	v_mfma_f32_16x16x32_bf16 v[76:79], v[146:149], v[212:215], 0
	v_mfma_f32_16x16x32_bf16 v[72:75], v[162:165], v[212:215], 0
	v_mfma_f32_16x16x32_bf16 v[124:127], v[158:161], v[190:193], v[124:127]
	v_mfma_f32_16x16x32_bf16 v[120:123], v[166:169], v[190:193], v[120:123]
	v_mfma_f32_16x16x32_bf16 v[108:111], v[158:161], v[198:201], v[108:111]
	v_mfma_f32_16x16x32_bf16 v[104:107], v[166:169], v[198:201], v[104:107]
	v_mfma_f32_16x16x32_bf16 v[92:95], v[158:161], v[206:209], v[92:95]
	v_mfma_f32_16x16x32_bf16 v[88:91], v[166:169], v[206:209], v[88:91]
	v_mfma_f32_16x16x32_bf16 v[76:79], v[158:161], v[216:219], v[76:79]
	v_mfma_f32_16x16x32_bf16 v[72:75], v[166:169], v[216:219], v[72:75]
	v_mfma_f32_16x16x32_bf16 v[116:119], v[170:173], v[186:189], 0
	v_mfma_f32_16x16x32_bf16 v[112:115], v[178:181], v[186:189], 0
	v_mfma_f32_16x16x32_bf16 v[100:103], v[170:173], v[194:197], 0
	v_mfma_f32_16x16x32_bf16 v[96:99], v[178:181], v[194:197], 0
	v_mfma_f32_16x16x32_bf16 v[84:87], v[170:173], v[202:205], 0
	v_mfma_f32_16x16x32_bf16 v[80:83], v[178:181], v[202:205], 0
	v_mfma_f32_16x16x32_bf16 v[68:71], v[170:173], v[212:215], 0
	v_mfma_f32_16x16x32_bf16 v[64:67], v[178:181], v[212:215], 0
	v_mfma_f32_16x16x32_bf16 v[116:119], v[174:177], v[190:193], v[116:119]
	v_mfma_f32_16x16x32_bf16 v[112:115], v[182:185], v[190:193], v[112:115]
	v_mfma_f32_16x16x32_bf16 v[100:103], v[174:177], v[198:201], v[100:103]
	v_mfma_f32_16x16x32_bf16 v[96:99], v[182:185], v[198:201], v[96:99]
	v_mfma_f32_16x16x32_bf16 v[84:87], v[174:177], v[206:209], v[84:87]
	v_mfma_f32_16x16x32_bf16 v[80:83], v[182:185], v[206:209], v[80:83]
	v_mfma_f32_16x16x32_bf16 v[68:71], v[174:177], v[216:219], v[68:71]
	v_mfma_f32_16x16x32_bf16 v[64:67], v[182:185], v[216:219], v[64:67]
	s_barrier
	s_add_i32 s26, s73, s66
	s_mov_b32 m0, s26
	ds_read_b128 v[186:189], v155 offset:16384
	ds_read_b128 v[190:193], v155 offset:17408
	ds_read_b128 v[194:197], v155 offset:18432
	ds_read_b128 v[198:201], v155 offset:19456
	ds_read_b128 v[202:205], v155 offset:20480
	ds_read_b128 v[206:209], v155 offset:21504
	ds_read_b128 v[212:215], v155 offset:22528
	ds_read_b128 v[216:219], v155 offset:23552
	global_load_lds_dwordx4 v130, s[60:61]
	s_add_i32 m0, s26, 0x2000
	s_add_u32 s26, s60, 0x20000
	s_addc_u32 s27, s61, 0
	s_add_i32 s33, s74, s66
	global_load_lds_dwordx4 v134, s[60:61]
	s_mov_b32 m0, s33
	s_nop 0
	global_load_lds_dwordx4 v130, s[26:27]
	s_add_i32 m0, s33, 0x2000
	s_nop 0
	global_load_lds_dwordx4 v134, s[26:27]
	s_mov_b32 m0, s57
	s_nop 0
	global_load_lds_dwordx4 v128, s[62:63]
	s_mov_b32 m0, s67
	s_nop 0
	global_load_lds_dwordx4 v132, s[62:63]
	s_waitcnt vmcnt(8)
	s_waitcnt lgkmcnt(0)
	s_barrier
	s_waitcnt lgkmcnt(0)
	v_mfma_f32_16x16x32_bf16 v[60:63], v[146:149], v[186:189], 0
	v_mfma_f32_16x16x32_bf16 v[56:59], v[162:165], v[186:189], 0
	v_mfma_f32_16x16x32_bf16 v[44:47], v[146:149], v[194:197], 0
	v_mfma_f32_16x16x32_bf16 v[40:43], v[162:165], v[194:197], 0
	v_mfma_f32_16x16x32_bf16 v[28:31], v[146:149], v[202:205], 0
	v_mfma_f32_16x16x32_bf16 v[24:27], v[162:165], v[202:205], 0
	v_mfma_f32_16x16x32_bf16 v[12:15], v[146:149], v[212:215], 0
	v_mfma_f32_16x16x32_bf16 v[8:11], v[162:165], v[212:215], 0
	v_mfma_f32_16x16x32_bf16 v[60:63], v[158:161], v[190:193], v[60:63]
	v_mfma_f32_16x16x32_bf16 v[56:59], v[166:169], v[190:193], v[56:59]
	v_mfma_f32_16x16x32_bf16 v[44:47], v[158:161], v[198:201], v[44:47]
	v_mfma_f32_16x16x32_bf16 v[40:43], v[166:169], v[198:201], v[40:43]
	v_mfma_f32_16x16x32_bf16 v[28:31], v[158:161], v[206:209], v[28:31]
	v_mfma_f32_16x16x32_bf16 v[24:27], v[166:169], v[206:209], v[24:27]
	v_mfma_f32_16x16x32_bf16 v[12:15], v[158:161], v[216:219], v[12:15]
	v_mfma_f32_16x16x32_bf16 v[8:11], v[166:169], v[216:219], v[8:11]
	v_mfma_f32_16x16x32_bf16 v[52:55], v[170:173], v[186:189], 0
	v_mfma_f32_16x16x32_bf16 v[48:51], v[178:181], v[186:189], 0
	v_mfma_f32_16x16x32_bf16 v[36:39], v[170:173], v[194:197], 0
	v_mfma_f32_16x16x32_bf16 v[32:35], v[178:181], v[194:197], 0
	v_mfma_f32_16x16x32_bf16 v[20:23], v[170:173], v[202:205], 0
	v_mfma_f32_16x16x32_bf16 v[16:19], v[178:181], v[202:205], 0
	v_mfma_f32_16x16x32_bf16 v[4:7], v[170:173], v[212:215], 0
	v_mfma_f32_16x16x32_bf16 v[0:3], v[178:181], v[212:215], 0
	v_mfma_f32_16x16x32_bf16 v[52:55], v[174:177], v[190:193], v[52:55]
	v_mfma_f32_16x16x32_bf16 v[48:51], v[182:185], v[190:193], v[48:51]
	v_mfma_f32_16x16x32_bf16 v[36:39], v[174:177], v[198:201], v[36:39]
	v_mfma_f32_16x16x32_bf16 v[32:35], v[182:185], v[198:201], v[32:35]
	v_mfma_f32_16x16x32_bf16 v[20:23], v[174:177], v[206:209], v[20:23]
	v_mfma_f32_16x16x32_bf16 v[16:19], v[182:185], v[206:209], v[16:19]
	v_mfma_f32_16x16x32_bf16 v[4:7], v[174:177], v[216:219], v[4:7]
	v_mfma_f32_16x16x32_bf16 v[0:3], v[182:185], v[216:219], v[0:3]
	s_barrier
; #define PG8_STAGE(bufoff, gbase, voff) do { _Pragma("unroll") for (int _i = 0; _i < 2; ++_i) \
;         __builtin_amdgcn_global_load_lds((const unsigned*)((const char*)(gbase) + (voff)[_i]), (PG8_LAS unsigned*)(lds + (bufoff) + ldsw + _i * 8192), 16, 0, 0); } while (0)
; #define PG8_LDA(dst, b, h) do { _Pragma("unroll") for (int m = 0; m < 4; ++m) _Pragma("unroll") for (int k = 0; k < 2; ++k) dst[m][k] = *(const PG8_LAS bf16x8*)(lds + PG8_SA(b, h) + aoff + m * 2048 + k * 1024); } while (0)
; #define PG8_LDB(dst, b, h) do { _Pragma("unroll") for (int n = 0; n < 2; ++n) _Pragma("unroll") for (int k = 0; k < 2; ++k) dst[n][k] = *(const PG8_LAS bf16x8*)(lds + PG8_SB(b, h) + boff + n * 2048 + k * 1024); } while (0)
; #define PG8_MMA(ai, bj, At, Bt) do { __builtin_amdgcn_s_setprio(1); _Pragma("unroll") for (int m = 0; m < 4; ++m) _Pragma("unroll") for (int n = 0; n < 2; ++n) _Pragma("unroll") for (int k = 0; k < 2; ++k) \
;         acc[ai][bj][m][n] = __builtin_amdgcn_mfma_f32_16x16x32_bf16(Bt[n][k], At[m][k], acc[ai][bj][m][n], 0, 0, 0); __builtin_amdgcn_s_setprio(0); } while (0)
; #define PG8_WAIT_V(n) asm volatile("s_waitcnt vmcnt(" #n ")" ::: "memory")
; #define PG8_WAIT_L(n) asm volatile("s_waitcnt lgkmcnt(" #n ")" ::: "memory")
; #define PG8_BAR __builtin_amdgcn_s_barrier()
; #define PG8_SCHED __builtin_amdgcn_sched_barrier(0)
; template <class Epi, class Sched, bool ALIGN_EPI = false, bool SP2 = false>
; __device__ __forceinline__ void gemm_phase(PG8_LAS unsigned char* lds, const Gemm g, const Sched& S, const Epi& E, int tid_in) {
;     ...
;             PG8_LDB(B0, 1, 0); PG8_LDB(B1, 1, 1); PG8_SCHED; PG8_LDA(At, 1, 0); PG8_STAGE(PG8_SA(0, 1), a2 + hstep, voffA);
;             PG8_WAIT_V(8); PG8_WAIT_L(0); PG8_BAR; PG8_MMA(0, 0, At, B0); PG8_MMA(0, 1, At, B1); PG8_BAR; PG8_SCHED;
;             PG8_LDA(At, 1, 1); PG8_STAGE(PG8_SB(1, 0), b3, voffB); PG8_STAGE(PG8_SB(1, 1), b3 + hstepB, voffB); PG8_STAGE(PG8_SA(1, 0), a3, voffA);
;             PG8_WAIT_V(8); PG8_WAIT_L(0); PG8_BAR; PG8_MMA(1, 0, At, B0); PG8_MMA(1, 1, At, B1); PG8_BAR; PG8_SCHED;
	s_add_i32 s33, 0, 0x18000
	s_add_i32 s84, 0, 0x1c000
	v_add_u32_e32 v166, s33, v137
	v_add_u32_e32 v182, s84, v137
	ds_read_b128 v[146:149], v166
	ds_read_b128 v[158:161], v166 offset:1024
	ds_read_b128 v[162:165], v166 offset:2048
	ds_read_b128 v[166:169], v166 offset:3072
	ds_read_b128 v[170:173], v182
	ds_read_b128 v[174:177], v182 offset:1024
	ds_read_b128 v[178:181], v182 offset:2048
	ds_read_b128 v[182:185], v182 offset:3072
	s_add_u32 s26, s62, 0x80000
	s_addc_u32 s27, s63, 0
	s_mov_b32 m0, s68
	ds_read_b128 v[186:189], v155 offset:32768
	ds_read_b128 v[190:193], v155 offset:33792
	ds_read_b128 v[194:197], v155 offset:34816
	ds_read_b128 v[198:201], v155 offset:35840
	ds_read_b128 v[202:205], v155 offset:36864
	ds_read_b128 v[206:209], v155 offset:37888
	ds_read_b128 v[212:215], v155 offset:38912
	ds_read_b128 v[216:219], v155 offset:39936
	global_load_lds_dwordx4 v128, s[26:27]
	s_mov_b32 m0, s69
	s_nop 0
	global_load_lds_dwordx4 v132, s[26:27]
	s_waitcnt vmcnt(8)
	s_waitcnt lgkmcnt(0)
	s_barrier
	s_waitcnt lgkmcnt(0)
	v_mfma_f32_16x16x32_bf16 v[124:127], v[146:149], v[186:189], v[124:127]
	v_mfma_f32_16x16x32_bf16 v[120:123], v[162:165], v[186:189], v[120:123]
	v_mfma_f32_16x16x32_bf16 v[108:111], v[146:149], v[194:197], v[108:111]
	v_mfma_f32_16x16x32_bf16 v[104:107], v[162:165], v[194:197], v[104:107]
	v_mfma_f32_16x16x32_bf16 v[92:95], v[146:149], v[202:205], v[92:95]
	v_mfma_f32_16x16x32_bf16 v[88:91], v[162:165], v[202:205], v[88:91]
	v_mfma_f32_16x16x32_bf16 v[76:79], v[146:149], v[212:215], v[76:79]
	v_mfma_f32_16x16x32_bf16 v[72:75], v[162:165], v[212:215], v[72:75]
	v_mfma_f32_16x16x32_bf16 v[124:127], v[158:161], v[190:193], v[124:127]
	v_mfma_f32_16x16x32_bf16 v[120:123], v[166:169], v[190:193], v[120:123]
	v_mfma_f32_16x16x32_bf16 v[108:111], v[158:161], v[198:201], v[108:111]
	v_mfma_f32_16x16x32_bf16 v[104:107], v[166:169], v[198:201], v[104:107]
	v_mfma_f32_16x16x32_bf16 v[92:95], v[158:161], v[206:209], v[92:95]
	v_mfma_f32_16x16x32_bf16 v[88:91], v[166:169], v[206:209], v[88:91]
	v_mfma_f32_16x16x32_bf16 v[76:79], v[158:161], v[216:219], v[76:79]
	v_mfma_f32_16x16x32_bf16 v[72:75], v[166:169], v[216:219], v[72:75]
	v_mfma_f32_16x16x32_bf16 v[116:119], v[170:173], v[186:189], v[116:119]
	v_mfma_f32_16x16x32_bf16 v[112:115], v[178:181], v[186:189], v[112:115]
	v_mfma_f32_16x16x32_bf16 v[100:103], v[170:173], v[194:197], v[100:103]
	v_mfma_f32_16x16x32_bf16 v[96:99], v[178:181], v[194:197], v[96:99]
	v_mfma_f32_16x16x32_bf16 v[84:87], v[170:173], v[202:205], v[84:87]
	v_mfma_f32_16x16x32_bf16 v[80:83], v[178:181], v[202:205], v[80:83]
	v_mfma_f32_16x16x32_bf16 v[68:71], v[170:173], v[212:215], v[68:71]
	v_mfma_f32_16x16x32_bf16 v[64:67], v[178:181], v[212:215], v[64:67]
	v_mfma_f32_16x16x32_bf16 v[116:119], v[174:177], v[190:193], v[116:119]
	v_mfma_f32_16x16x32_bf16 v[112:115], v[182:185], v[190:193], v[112:115]
	v_mfma_f32_16x16x32_bf16 v[100:103], v[174:177], v[198:201], v[100:103]
	v_mfma_f32_16x16x32_bf16 v[96:99], v[182:185], v[198:201], v[96:99]
	v_mfma_f32_16x16x32_bf16 v[84:87], v[174:177], v[206:209], v[84:87]
	v_mfma_f32_16x16x32_bf16 v[80:83], v[182:185], v[206:209], v[80:83]
	v_mfma_f32_16x16x32_bf16 v[68:71], v[174:177], v[216:219], v[68:71]
	v_mfma_f32_16x16x32_bf16 v[64:67], v[182:185], v[216:219], v[64:67]
	s_barrier
	s_add_i32 s26, s33, s66
	s_add_i32 m0, s26, 0xffffff80
	ds_read_b128 v[186:189], v155 offset:49152
	ds_read_b128 v[190:193], v155 offset:50176
	ds_read_b128 v[194:197], v155 offset:51200
	ds_read_b128 v[198:201], v155 offset:52224
	ds_read_b128 v[202:205], v155 offset:53248
	ds_read_b128 v[206:209], v155 offset:54272
	ds_read_b128 v[212:215], v155 offset:55296
	ds_read_b128 v[216:219], v155 offset:56320
	global_load_lds_dwordx4 v130, s[60:61] offset:128
	s_add_i32 m0, s26, 0x1f80
	s_add_u32 s26, s60, 0x20080
	s_addc_u32 s27, s61, 0
	s_add_i32 s33, s84, s66
	global_load_lds_dwordx4 v134, s[60:61] offset:128
	s_mov_b32 m0, s33
	s_nop 0
	global_load_lds_dwordx4 v130, s[26:27]
	s_add_i32 m0, s33, 0x2000
	s_nop 0
	global_load_lds_dwordx4 v134, s[26:27]
	s_add_i32 m0, s71, 0xffffff80
	s_nop 0
	global_load_lds_dwordx4 v128, s[62:63] offset:128
	s_add_i32 m0, s72, 0xffffff80
	s_nop 0
	global_load_lds_dwordx4 v132, s[62:63] offset:128
	s_waitcnt vmcnt(8)
	s_waitcnt lgkmcnt(0)
	s_barrier
	s_waitcnt lgkmcnt(0)
	v_mfma_f32_16x16x32_bf16 v[60:63], v[146:149], v[186:189], v[60:63]
	v_mfma_f32_16x16x32_bf16 v[56:59], v[162:165], v[186:189], v[56:59]
	v_mfma_f32_16x16x32_bf16 v[44:47], v[146:149], v[194:197], v[44:47]
	v_mfma_f32_16x16x32_bf16 v[40:43], v[162:165], v[194:197], v[40:43]
	v_mfma_f32_16x16x32_bf16 v[28:31], v[146:149], v[202:205], v[28:31]
	v_mfma_f32_16x16x32_bf16 v[24:27], v[162:165], v[202:205], v[24:27]
	v_mfma_f32_16x16x32_bf16 v[12:15], v[146:149], v[212:215], v[12:15]
	v_mfma_f32_16x16x32_bf16 v[8:11], v[162:165], v[212:215], v[8:11]
	v_mfma_f32_16x16x32_bf16 v[60:63], v[158:161], v[190:193], v[60:63]
	v_mfma_f32_16x16x32_bf16 v[56:59], v[166:169], v[190:193], v[56:59]
	v_mfma_f32_16x16x32_bf16 v[44:47], v[158:161], v[198:201], v[44:47]
	v_mfma_f32_16x16x32_bf16 v[40:43], v[166:169], v[198:201], v[40:43]
	v_mfma_f32_16x16x32_bf16 v[28:31], v[158:161], v[206:209], v[28:31]
	v_mfma_f32_16x16x32_bf16 v[24:27], v[166:169], v[206:209], v[24:27]
	v_mfma_f32_16x16x32_bf16 v[12:15], v[158:161], v[216:219], v[12:15]
	v_mfma_f32_16x16x32_bf16 v[8:11], v[166:169], v[216:219], v[8:11]
	v_mfma_f32_16x16x32_bf16 v[52:55], v[170:173], v[186:189], v[52:55]
	v_mfma_f32_16x16x32_bf16 v[48:51], v[178:181], v[186:189], v[48:51]
	v_mfma_f32_16x16x32_bf16 v[36:39], v[170:173], v[194:197], v[36:39]
	v_mfma_f32_16x16x32_bf16 v[32:35], v[178:181], v[194:197], v[32:35]
	v_mfma_f32_16x16x32_bf16 v[20:23], v[170:173], v[202:205], v[20:23]
	v_mfma_f32_16x16x32_bf16 v[16:19], v[178:181], v[202:205], v[16:19]
	v_mfma_f32_16x16x32_bf16 v[4:7], v[170:173], v[212:215], v[4:7]
	v_mfma_f32_16x16x32_bf16 v[0:3], v[178:181], v[212:215], v[0:3]
	v_mfma_f32_16x16x32_bf16 v[52:55], v[174:177], v[190:193], v[52:55]
	v_mfma_f32_16x16x32_bf16 v[48:51], v[182:185], v[190:193], v[48:51]
	v_mfma_f32_16x16x32_bf16 v[36:39], v[174:177], v[198:201], v[36:39]
	v_mfma_f32_16x16x32_bf16 v[32:35], v[182:185], v[198:201], v[32:35]
	v_mfma_f32_16x16x32_bf16 v[20:23], v[174:177], v[206:209], v[20:23]
	v_mfma_f32_16x16x32_bf16 v[16:19], v[182:185], v[206:209], v[16:19]
	v_mfma_f32_16x16x32_bf16 v[4:7], v[174:177], v[216:219], v[4:7]
	v_mfma_f32_16x16x32_bf16 v[0:3], v[182:185], v[216:219], v[0:3]
	s_barrier
	s_add_i32 s79, s79, 2
	s_add_u32 s58, s58, 0x100
	s_addc_u32 s59, s59, 0
	s_add_u32 s76, s76, 0x100
	s_addc_u32 s77, s77, 0
	s_cmp_gt_u32 s79, 29
; #define PG8_STAGE(bufoff, gbase, voff) do { _Pragma("unroll") for (int _i = 0; _i < 2; ++_i) \
;         __builtin_amdgcn_global_load_lds((const unsigned*)((const char*)(gbase) + (voff)[_i]), (PG8_LAS unsigned*)(lds + (bufoff) + ldsw + _i * 8192), 16, 0, 0); } while (0)
; #define PG8_LDA(dst, b, h) do { _Pragma("unroll") for (int m = 0; m < 4; ++m) _Pragma("unroll") for (int k = 0; k < 2; ++k) dst[m][k] = *(const PG8_LAS bf16x8*)(lds + PG8_SA(b, h) + aoff + m * 2048 + k * 1024); } while (0)
; #define PG8_LDB(dst, b, h) do { _Pragma("unroll") for (int n = 0; n < 2; ++n) _Pragma("unroll") for (int k = 0; k < 2; ++k) dst[n][k] = *(const PG8_LAS bf16x8*)(lds + PG8_SB(b, h) + boff + n * 2048 + k * 1024); } while (0)
; #define PG8_MMA(ai, bj, At, Bt) do { __builtin_amdgcn_s_setprio(1); _Pragma("unroll") for (int m = 0; m < 4; ++m) _Pragma("unroll") for (int n = 0; n < 2; ++n) _Pragma("unroll") for (int k = 0; k < 2; ++k) \
;         acc[ai][bj][m][n] = __builtin_amdgcn_mfma_f32_16x16x32_bf16(Bt[n][k], At[m][k], acc[ai][bj][m][n], 0, 0, 0); __builtin_amdgcn_s_setprio(0); } while (0)
; #define PG8_WAIT_V(n) asm volatile("s_waitcnt vmcnt(" #n ")" ::: "memory")
; #define PG8_BAR __builtin_amdgcn_s_barrier()
; template <class Epi, class Sched, bool ALIGN_EPI = false, bool SP2 = false>
; __device__ __forceinline__ void gemm_phase(PG8_LAS unsigned char* lds, const Gemm g, const Sched& S, const Epi& E, int tid_in) {
;     ...
;         for (int t = 0; t < nt; t += 2) {
;             const bool last = (t == nt - 2);
;             const char* a1 = cA + (size_t)(t + 1) * kstep;
;             const char* a2 = last ? nA : cA + (size_t)(t + 2) * kstep; const char* b2 = last ? nB : cB + (size_t)(t + 2) * kstep;
;             const char* a3 = a2 + kstep; const char* b3 = b2 + kstep;
;             if (last && has_next) S.a_ready(nxt);
;             if constexpr (SP2) {
;             PG8_LDB(B0, 0, 0); PG8_LDB(B1, 0, 1); PG8_SCHED; PG8_LDA(At, 0, 0); PG8_STAGE(PG8_SA(1, 1), a1 + hstep, voffA);
;             PG8_WAIT_V(8); PG8_WAIT_L(0); PG8_BAR; PG8_MMA(0, 0, At, B0); PG8_MMA(0, 1, At, B1); PG8_BAR; PG8_SCHED;
;             PG8_LDA(At, 0, 1); PG8_STAGE(PG8_SB(0, 0), b2, voffB); PG8_STAGE(PG8_SB(0, 1), b2 + hstepB, voffB); PG8_STAGE(PG8_SA(0, 0), a2, voffA);
;             PG8_WAIT_V(8); PG8_WAIT_L(0); PG8_BAR; PG8_MMA(1, 0, At, B0); PG8_MMA(1, 1, At, B1); PG8_BAR; PG8_SCHED;
.LBB0_292:
	ds_read_b128 v[146:149], v153
	ds_read_b128 v[158:161], v153 offset:1024
	ds_read_b128 v[162:165], v153 offset:2048
	ds_read_b128 v[166:169], v153 offset:3072
	ds_read_b128 v[170:173], v154
	ds_read_b128 v[174:177], v154 offset:1024
	ds_read_b128 v[178:181], v154 offset:2048
	ds_read_b128 v[182:185], v154 offset:3072
	s_add_u32 s26, s58, 0xfff80080
	s_addc_u32 s27, s59, -1
	s_cmp_eq_u32 s79, 28
	s_cselect_b32 s63, s49, s27
	s_cselect_b32 s62, s55, s26
	s_cselect_b32 s61, s47, s77
	s_cselect_b32 s60, s75, s76
	s_add_i32 m0, s57, 0xc000
	ds_read_b128 v[186:189], v155
	ds_read_b128 v[190:193], v155 offset:1024
	ds_read_b128 v[194:197], v155 offset:2048
	ds_read_b128 v[198:201], v155 offset:3072
	ds_read_b128 v[202:205], v155 offset:4096
	ds_read_b128 v[206:209], v155 offset:5120
	ds_read_b128 v[212:215], v155 offset:6144
	ds_read_b128 v[216:219], v155 offset:7168
	global_load_lds_dwordx4 v138, s[58:59]
	s_add_i32 m0, s57, 0xe000
	s_nop 0
	global_load_lds_dwordx4 v140, s[58:59]
	s_waitcnt vmcnt(8)
	s_waitcnt lgkmcnt(0)
	s_barrier
	s_waitcnt lgkmcnt(0)
	v_mfma_f32_16x16x32_bf16 v[124:127], v[146:149], v[186:189], v[124:127]
	v_mfma_f32_16x16x32_bf16 v[120:123], v[162:165], v[186:189], v[120:123]
	v_mfma_f32_16x16x32_bf16 v[108:111], v[146:149], v[194:197], v[108:111]
	v_mfma_f32_16x16x32_bf16 v[104:107], v[162:165], v[194:197], v[104:107]
	v_mfma_f32_16x16x32_bf16 v[92:95], v[146:149], v[202:205], v[92:95]
	v_mfma_f32_16x16x32_bf16 v[88:91], v[162:165], v[202:205], v[88:91]
	v_mfma_f32_16x16x32_bf16 v[76:79], v[146:149], v[212:215], v[76:79]
	v_mfma_f32_16x16x32_bf16 v[72:75], v[162:165], v[212:215], v[72:75]
	v_mfma_f32_16x16x32_bf16 v[124:127], v[158:161], v[190:193], v[124:127]
	v_mfma_f32_16x16x32_bf16 v[120:123], v[166:169], v[190:193], v[120:123]
	v_mfma_f32_16x16x32_bf16 v[108:111], v[158:161], v[198:201], v[108:111]
	v_mfma_f32_16x16x32_bf16 v[104:107], v[166:169], v[198:201], v[104:107]
	v_mfma_f32_16x16x32_bf16 v[92:95], v[158:161], v[206:209], v[92:95]
	v_mfma_f32_16x16x32_bf16 v[88:91], v[166:169], v[206:209], v[88:91]
	v_mfma_f32_16x16x32_bf16 v[76:79], v[158:161], v[216:219], v[76:79]
	v_mfma_f32_16x16x32_bf16 v[72:75], v[166:169], v[216:219], v[72:75]
	v_mfma_f32_16x16x32_bf16 v[116:119], v[170:173], v[186:189], v[116:119]
	v_mfma_f32_16x16x32_bf16 v[112:115], v[178:181], v[186:189], v[112:115]
	v_mfma_f32_16x16x32_bf16 v[100:103], v[170:173], v[194:197], v[100:103]
	v_mfma_f32_16x16x32_bf16 v[96:99], v[178:181], v[194:197], v[96:99]
	v_mfma_f32_16x16x32_bf16 v[84:87], v[170:173], v[202:205], v[84:87]
	v_mfma_f32_16x16x32_bf16 v[80:83], v[178:181], v[202:205], v[80:83]
	v_mfma_f32_16x16x32_bf16 v[68:71], v[170:173], v[212:215], v[68:71]
	v_mfma_f32_16x16x32_bf16 v[64:67], v[178:181], v[212:215], v[64:67]
	v_mfma_f32_16x16x32_bf16 v[116:119], v[174:177], v[190:193], v[116:119]
	v_mfma_f32_16x16x32_bf16 v[112:115], v[182:185], v[190:193], v[112:115]
	v_mfma_f32_16x16x32_bf16 v[100:103], v[174:177], v[198:201], v[100:103]
	v_mfma_f32_16x16x32_bf16 v[96:99], v[182:185], v[198:201], v[96:99]
	v_mfma_f32_16x16x32_bf16 v[84:87], v[174:177], v[206:209], v[84:87]
	v_mfma_f32_16x16x32_bf16 v[80:83], v[182:185], v[206:209], v[80:83]
	v_mfma_f32_16x16x32_bf16 v[68:71], v[174:177], v[216:219], v[68:71]
	v_mfma_f32_16x16x32_bf16 v[64:67], v[182:185], v[216:219], v[64:67]
	s_barrier
	s_add_i32 s26, s73, s66
	s_mov_b32 m0, s26
	ds_read_b128 v[186:189], v155 offset:16384
	ds_read_b128 v[190:193], v155 offset:17408
	ds_read_b128 v[194:197], v155 offset:18432
	ds_read_b128 v[198:201], v155 offset:19456
	ds_read_b128 v[202:205], v155 offset:20480
	ds_read_b128 v[206:209], v155 offset:21504
	ds_read_b128 v[212:215], v155 offset:22528
	ds_read_b128 v[216:219], v155 offset:23552
	global_load_lds_dwordx4 v130, s[60:61]
	s_add_i32 m0, s26, 0x2000
	s_add_u32 s26, s60, 0x20000
	s_addc_u32 s27, s61, 0
	s_add_i32 s33, s74, s66
	global_load_lds_dwordx4 v134, s[60:61]
	s_mov_b32 m0, s33
	s_nop 0
	global_load_lds_dwordx4 v130, s[26:27]
	s_add_i32 m0, s33, 0x2000
	s_nop 0
	global_load_lds_dwordx4 v134, s[26:27]
	s_mov_b32 m0, s57
	s_nop 0
	global_load_lds_dwordx4 v128, s[62:63]
	s_mov_b32 m0, s67
	s_nop 0
	global_load_lds_dwordx4 v132, s[62:63]
	s_waitcnt vmcnt(8)
	s_waitcnt lgkmcnt(0)
	s_barrier
	s_waitcnt lgkmcnt(0)
	v_mfma_f32_16x16x32_bf16 v[60:63], v[146:149], v[186:189], v[60:63]
	v_mfma_f32_16x16x32_bf16 v[56:59], v[162:165], v[186:189], v[56:59]
	v_mfma_f32_16x16x32_bf16 v[44:47], v[146:149], v[194:197], v[44:47]
	v_mfma_f32_16x16x32_bf16 v[40:43], v[162:165], v[194:197], v[40:43]
	v_mfma_f32_16x16x32_bf16 v[28:31], v[146:149], v[202:205], v[28:31]
	v_mfma_f32_16x16x32_bf16 v[24:27], v[162:165], v[202:205], v[24:27]
	v_mfma_f32_16x16x32_bf16 v[12:15], v[146:149], v[212:215], v[12:15]
	v_mfma_f32_16x16x32_bf16 v[8:11], v[162:165], v[212:215], v[8:11]
	v_mfma_f32_16x16x32_bf16 v[60:63], v[158:161], v[190:193], v[60:63]
	v_mfma_f32_16x16x32_bf16 v[56:59], v[166:169], v[190:193], v[56:59]
	v_mfma_f32_16x16x32_bf16 v[44:47], v[158:161], v[198:201], v[44:47]
	v_mfma_f32_16x16x32_bf16 v[40:43], v[166:169], v[198:201], v[40:43]
	v_mfma_f32_16x16x32_bf16 v[28:31], v[158:161], v[206:209], v[28:31]
	v_mfma_f32_16x16x32_bf16 v[24:27], v[166:169], v[206:209], v[24:27]
	v_mfma_f32_16x16x32_bf16 v[12:15], v[158:161], v[216:219], v[12:15]
	v_mfma_f32_16x16x32_bf16 v[8:11], v[166:169], v[216:219], v[8:11]
	v_mfma_f32_16x16x32_bf16 v[52:55], v[170:173], v[186:189], v[52:55]
	v_mfma_f32_16x16x32_bf16 v[48:51], v[178:181], v[186:189], v[48:51]
	v_mfma_f32_16x16x32_bf16 v[36:39], v[170:173], v[194:197], v[36:39]
	v_mfma_f32_16x16x32_bf16 v[32:35], v[178:181], v[194:197], v[32:35]
	v_mfma_f32_16x16x32_bf16 v[20:23], v[170:173], v[202:205], v[20:23]
	v_mfma_f32_16x16x32_bf16 v[16:19], v[178:181], v[202:205], v[16:19]
	v_mfma_f32_16x16x32_bf16 v[4:7], v[170:173], v[212:215], v[4:7]
	v_mfma_f32_16x16x32_bf16 v[0:3], v[178:181], v[212:215], v[0:3]
	v_mfma_f32_16x16x32_bf16 v[52:55], v[174:177], v[190:193], v[52:55]
	v_mfma_f32_16x16x32_bf16 v[48:51], v[182:185], v[190:193], v[48:51]
	v_mfma_f32_16x16x32_bf16 v[36:39], v[174:177], v[198:201], v[36:39]
	v_mfma_f32_16x16x32_bf16 v[32:35], v[182:185], v[198:201], v[32:35]
	v_mfma_f32_16x16x32_bf16 v[20:23], v[174:177], v[206:209], v[20:23]
	v_mfma_f32_16x16x32_bf16 v[16:19], v[182:185], v[206:209], v[16:19]
	v_mfma_f32_16x16x32_bf16 v[4:7], v[174:177], v[216:219], v[4:7]
	v_mfma_f32_16x16x32_bf16 v[0:3], v[182:185], v[216:219], v[0:3]
	s_barrier
; #define PG8_STAGE(bufoff, gbase, voff) do { _Pragma("unroll") for (int _i = 0; _i < 2; ++_i) \
;         __builtin_amdgcn_global_load_lds((const unsigned*)((const char*)(gbase) + (voff)[_i]), (PG8_LAS unsigned*)(lds + (bufoff) + ldsw + _i * 8192), 16, 0, 0); } while (0)
; #define PG8_LDA(dst, b, h) do { _Pragma("unroll") for (int m = 0; m < 4; ++m) _Pragma("unroll") for (int k = 0; k < 2; ++k) dst[m][k] = *(const PG8_LAS bf16x8*)(lds + PG8_SA(b, h) + aoff + m * 2048 + k * 1024); } while (0)
; #define PG8_LDB(dst, b, h) do { _Pragma("unroll") for (int n = 0; n < 2; ++n) _Pragma("unroll") for (int k = 0; k < 2; ++k) dst[n][k] = *(const PG8_LAS bf16x8*)(lds + PG8_SB(b, h) + boff + n * 2048 + k * 1024); } while (0)
; #define PG8_MMA(ai, bj, At, Bt) do { __builtin_amdgcn_s_setprio(1); _Pragma("unroll") for (int m = 0; m < 4; ++m) _Pragma("unroll") for (int n = 0; n < 2; ++n) _Pragma("unroll") for (int k = 0; k < 2; ++k) \
;         acc[ai][bj][m][n] = __builtin_amdgcn_mfma_f32_16x16x32_bf16(Bt[n][k], At[m][k], acc[ai][bj][m][n], 0, 0, 0); __builtin_amdgcn_s_setprio(0); } while (0)
; #define PG8_WAIT_V(n) asm volatile("s_waitcnt vmcnt(" #n ")" ::: "memory")
; #define PG8_WAIT_L(n) asm volatile("s_waitcnt lgkmcnt(" #n ")" ::: "memory")
; #define PG8_BAR __builtin_amdgcn_s_barrier()
; #define PG8_SCHED __builtin_amdgcn_sched_barrier(0)
; template <class Epi, class Sched, bool ALIGN_EPI = false, bool SP2 = false>
; __device__ __forceinline__ void gemm_phase(PG8_LAS unsigned char* lds, const Gemm g, const Sched& S, const Epi& E, int tid_in) {
;     ...
;             PG8_LDB(B0, 1, 0); PG8_LDB(B1, 1, 1); PG8_SCHED; PG8_LDA(At, 1, 0); PG8_STAGE(PG8_SA(0, 1), a2 + hstep, voffA);
;             PG8_WAIT_V(8); PG8_WAIT_L(0); PG8_BAR; PG8_MMA(0, 0, At, B0); PG8_MMA(0, 1, At, B1); PG8_BAR; PG8_SCHED;
;             PG8_LDA(At, 1, 1); PG8_STAGE(PG8_SB(1, 0), b3, voffB); PG8_STAGE(PG8_SB(1, 1), b3 + hstepB, voffB); PG8_STAGE(PG8_SA(1, 0), a3, voffA);
	s_add_i32 s33, 0, 0x18000
	s_add_i32 s84, 0, 0x1c000
	v_add_u32_e32 v166, s33, v137
	v_add_u32_e32 v182, s84, v137
	ds_read_b128 v[146:149], v166
	ds_read_b128 v[158:161], v166 offset:1024
	ds_read_b128 v[162:165], v166 offset:2048
	ds_read_b128 v[166:169], v166 offset:3072
	ds_read_b128 v[170:173], v182
	ds_read_b128 v[174:177], v182 offset:1024
	ds_read_b128 v[178:181], v182 offset:2048
	ds_read_b128 v[182:185], v182 offset:3072
	s_add_u32 s26, s62, 0x80000
	s_addc_u32 s27, s63, 0
	s_mov_b32 m0, s68
	ds_read_b128 v[186:189], v155 offset:32768
	ds_read_b128 v[190:193], v155 offset:33792
	ds_read_b128 v[194:197], v155 offset:34816
	ds_read_b128 v[198:201], v155 offset:35840
	ds_read_b128 v[202:205], v155 offset:36864
	ds_read_b128 v[206:209], v155 offset:37888
	ds_read_b128 v[212:215], v155 offset:38912
	ds_read_b128 v[216:219], v155 offset:39936
	global_load_lds_dwordx4 v128, s[26:27]
	s_mov_b32 m0, s69
	s_nop 0
	global_load_lds_dwordx4 v132, s[26:27]
	s_waitcnt vmcnt(8)
	s_waitcnt lgkmcnt(0)
	s_barrier
	s_waitcnt lgkmcnt(0)
	v_mfma_f32_16x16x32_bf16 v[124:127], v[146:149], v[186:189], v[124:127]
	v_mfma_f32_16x16x32_bf16 v[120:123], v[162:165], v[186:189], v[120:123]
	v_mfma_f32_16x16x32_bf16 v[108:111], v[146:149], v[194:197], v[108:111]
	v_mfma_f32_16x16x32_bf16 v[104:107], v[162:165], v[194:197], v[104:107]
	v_mfma_f32_16x16x32_bf16 v[92:95], v[146:149], v[202:205], v[92:95]
	v_mfma_f32_16x16x32_bf16 v[88:91], v[162:165], v[202:205], v[88:91]
	v_mfma_f32_16x16x32_bf16 v[76:79], v[146:149], v[212:215], v[76:79]
	v_mfma_f32_16x16x32_bf16 v[72:75], v[162:165], v[212:215], v[72:75]
	v_mfma_f32_16x16x32_bf16 v[124:127], v[158:161], v[190:193], v[124:127]
	v_mfma_f32_16x16x32_bf16 v[120:123], v[166:169], v[190:193], v[120:123]
	v_mfma_f32_16x16x32_bf16 v[108:111], v[158:161], v[198:201], v[108:111]
	v_mfma_f32_16x16x32_bf16 v[104:107], v[166:169], v[198:201], v[104:107]
	v_mfma_f32_16x16x32_bf16 v[92:95], v[158:161], v[206:209], v[92:95]
	v_mfma_f32_16x16x32_bf16 v[88:91], v[166:169], v[206:209], v[88:91]
	v_mfma_f32_16x16x32_bf16 v[76:79], v[158:161], v[216:219], v[76:79]
	v_mfma_f32_16x16x32_bf16 v[72:75], v[166:169], v[216:219], v[72:75]
	v_mfma_f32_16x16x32_bf16 v[116:119], v[170:173], v[186:189], v[116:119]
	v_mfma_f32_16x16x32_bf16 v[112:115], v[178:181], v[186:189], v[112:115]
	v_mfma_f32_16x16x32_bf16 v[100:103], v[170:173], v[194:197], v[100:103]
	v_mfma_f32_16x16x32_bf16 v[96:99], v[178:181], v[194:197], v[96:99]
	v_mfma_f32_16x16x32_bf16 v[84:87], v[170:173], v[202:205], v[84:87]
	v_mfma_f32_16x16x32_bf16 v[80:83], v[178:181], v[202:205], v[80:83]
	v_mfma_f32_16x16x32_bf16 v[68:71], v[170:173], v[212:215], v[68:71]
	v_mfma_f32_16x16x32_bf16 v[64:67], v[178:181], v[212:215], v[64:67]
	v_mfma_f32_16x16x32_bf16 v[116:119], v[174:177], v[190:193], v[116:119]
	v_mfma_f32_16x16x32_bf16 v[112:115], v[182:185], v[190:193], v[112:115]
	v_mfma_f32_16x16x32_bf16 v[100:103], v[174:177], v[198:201], v[100:103]
	v_mfma_f32_16x16x32_bf16 v[96:99], v[182:185], v[198:201], v[96:99]
	v_mfma_f32_16x16x32_bf16 v[84:87], v[174:177], v[206:209], v[84:87]
	v_mfma_f32_16x16x32_bf16 v[80:83], v[182:185], v[206:209], v[80:83]
	v_mfma_f32_16x16x32_bf16 v[68:71], v[174:177], v[216:219], v[68:71]
	v_mfma_f32_16x16x32_bf16 v[64:67], v[182:185], v[216:219], v[64:67]
	s_barrier
	s_add_i32 s26, s33, s66
	s_add_i32 m0, s26, 0xffffff80
	ds_read_b128 v[186:189], v155 offset:49152
	ds_read_b128 v[190:193], v155 offset:50176
	ds_read_b128 v[194:197], v155 offset:51200
	ds_read_b128 v[198:201], v155 offset:52224
	ds_read_b128 v[202:205], v155 offset:53248
	ds_read_b128 v[206:209], v155 offset:54272
	ds_read_b128 v[212:215], v155 offset:55296
	ds_read_b128 v[216:219], v155 offset:56320
	global_load_lds_dwordx4 v130, s[60:61] offset:128
	s_add_i32 m0, s26, 0x1f80
	s_add_u32 s26, s60, 0x20080
	s_addc_u32 s27, s61, 0
	s_add_i32 s33, s84, s66
	global_load_lds_dwordx4 v134, s[60:61] offset:128
	s_mov_b32 m0, s33
	s_nop 0
	global_load_lds_dwordx4 v130, s[26:27]
	s_add_i32 m0, s33, 0x2000
	s_nop 0
	global_load_lds_dwordx4 v134, s[26:27]
	s_add_i32 m0, s71, 0xffffff80
	s_nop 0
	global_load_lds_dwordx4 v128, s[62:63] offset:128
	s_add_i32 m0, s72, 0xffffff80
	s_nop 0
	global_load_lds_dwordx4 v132, s[62:63] offset:128
	s_waitcnt vmcnt(8)
	s_waitcnt lgkmcnt(0)
	s_barrier
; #define PG8_WAIT_V(n) asm volatile("s_waitcnt vmcnt(" #n ")" ::: "memory")
; #define PG8_BAR __builtin_amdgcn_s_barrier()
; template <class Epi, class Sched, bool ALIGN_EPI = false, bool SP2 = false>
; __device__ __forceinline__ void gemm_phase(PG8_LAS unsigned char* lds, const Gemm g, const Sched& S, const Epi& E, int tid_in) {
;     ...
;             PG8_WAIT_V(8); PG8_WAIT_L(0); PG8_BAR; PG8_MMA(1, 0, At, B0); PG8_MMA(1, 1, At, B1); PG8_BAR; PG8_SCHED;
;             } else {
;             PG8_LDB(B0, 0, 0); PG8_SCHED; PG8_LDA(At, 0, 0); PG8_STAGE(PG8_SA(1, 1), a1 + hstep, voffA);
;             PG8_WAIT_L(8); PG8_BAR; PG8_WAIT_L(0); PG8_MMA(0, 0, At, B0); PG8_BAR; PG8_SCHED;
;             PG8_LDB(B1, 0, 1); PG8_STAGE(PG8_SB(0, 0), b2, voffB);
;             PG8_BAR; PG8_WAIT_L(0); PG8_MMA(0, 1, At, B1); PG8_BAR;
;             PG8_LDA(At, 0, 1); PG8_STAGE(PG8_SA(0, 0), a2, voffA);
;             PG8_BAR; PG8_WAIT_L(0); PG8_MMA(1, 0, At, B0); PG8_BAR; PG8_SCHED;
;             PG8_STAGE(PG8_SB(0, 1), b2 + hstepB, voffB);
;             PG8_WAIT_V(6); PG8_BAR; PG8_MMA(1, 1, At, B1); PG8_BAR;
;             PG8_LDB(B0, 1, 0); PG8_SCHED; PG8_LDA(At, 1, 0); PG8_STAGE(PG8_SA(0, 1), a2 + hstep, voffA);
;             PG8_WAIT_L(8); PG8_BAR; PG8_WAIT_L(0); PG8_MMA(0, 0, At, B0); PG8_BAR; PG8_SCHED;
;             PG8_LDB(B1, 1, 1); PG8_STAGE(PG8_SB(1, 0), b3, voffB);
;             PG8_BAR; PG8_WAIT_L(0); PG8_MMA(0, 1, At, B1); PG8_BAR;
;             PG8_LDA(At, 1, 1); PG8_STAGE(PG8_SA(1, 0), a3, voffA);
;             PG8_BAR; PG8_WAIT_L(0); PG8_MMA(1, 0, At, B0); PG8_BAR; PG8_SCHED;
;             PG8_STAGE(PG8_SB(1, 1), b3 + hstepB, voffB);
;             PG8_WAIT_V(6); PG8_BAR; PG8_MMA(1, 1, At, B1); PG8_BAR;
;             }
;         }
;         if constexpr (ALIGN_EPI) { if (wr == 0) PG8_BAR; }
;     __device__ __forceinline__ void operator()(const f32x4 (&acc)[2][2][4][2], const Unit& u, int wr, int wc, int fr, int fq) const {
;     ...
;                 const int row = u.pm * BM + ai * HALF + wr * 64 + m * 16 + r; float q = 0.f;
; #pragma unroll
;                 for (int bj = 0; bj < 2; ++bj) {
;                     const size_t off = (size_t)row * 2048 + u.pn * BM + wc * 64 + bj * 32 + 8 * p;
;                     f32x4 b0, b1;
;                     if (BASE_F32) { b0 = *(const f32x4*)((const float*)base + off); b1 = *(const f32x4*)((const float*)base + off + 4); }
	s_waitcnt lgkmcnt(0)
	v_mfma_f32_16x16x32_bf16 v[60:63], v[146:149], v[186:189], v[60:63]
	v_mfma_f32_16x16x32_bf16 v[56:59], v[162:165], v[186:189], v[56:59]
	v_mfma_f32_16x16x32_bf16 v[44:47], v[146:149], v[194:197], v[44:47]
	v_mfma_f32_16x16x32_bf16 v[40:43], v[162:165], v[194:197], v[40:43]
	v_mfma_f32_16x16x32_bf16 v[28:31], v[146:149], v[202:205], v[28:31]
	v_mfma_f32_16x16x32_bf16 v[24:27], v[162:165], v[202:205], v[24:27]
	v_mfma_f32_16x16x32_bf16 v[12:15], v[146:149], v[212:215], v[12:15]
	v_mfma_f32_16x16x32_bf16 v[8:11], v[162:165], v[212:215], v[8:11]
	v_mfma_f32_16x16x32_bf16 v[60:63], v[158:161], v[190:193], v[60:63]
	v_mfma_f32_16x16x32_bf16 v[56:59], v[166:169], v[190:193], v[56:59]
	v_mfma_f32_16x16x32_bf16 v[44:47], v[158:161], v[198:201], v[44:47]
	v_mfma_f32_16x16x32_bf16 v[40:43], v[166:169], v[198:201], v[40:43]
	v_mfma_f32_16x16x32_bf16 v[28:31], v[158:161], v[206:209], v[28:31]
	v_mfma_f32_16x16x32_bf16 v[24:27], v[166:169], v[206:209], v[24:27]
	v_mfma_f32_16x16x32_bf16 v[12:15], v[158:161], v[216:219], v[12:15]
	v_mfma_f32_16x16x32_bf16 v[8:11], v[166:169], v[216:219], v[8:11]
	v_mfma_f32_16x16x32_bf16 v[52:55], v[170:173], v[186:189], v[52:55]
	v_mfma_f32_16x16x32_bf16 v[48:51], v[178:181], v[186:189], v[48:51]
	v_mfma_f32_16x16x32_bf16 v[36:39], v[170:173], v[194:197], v[36:39]
	v_mfma_f32_16x16x32_bf16 v[32:35], v[178:181], v[194:197], v[32:35]
	v_mfma_f32_16x16x32_bf16 v[20:23], v[170:173], v[202:205], v[20:23]
	v_mfma_f32_16x16x32_bf16 v[16:19], v[178:181], v[202:205], v[16:19]
	v_mfma_f32_16x16x32_bf16 v[4:7], v[170:173], v[212:215], v[4:7]
	v_mfma_f32_16x16x32_bf16 v[0:3], v[178:181], v[212:215], v[0:3]
	v_mfma_f32_16x16x32_bf16 v[52:55], v[174:177], v[190:193], v[52:55]
	v_mfma_f32_16x16x32_bf16 v[48:51], v[182:185], v[190:193], v[48:51]
	v_mfma_f32_16x16x32_bf16 v[36:39], v[174:177], v[198:201], v[36:39]
	v_mfma_f32_16x16x32_bf16 v[32:35], v[182:185], v[198:201], v[32:35]
	v_mfma_f32_16x16x32_bf16 v[20:23], v[174:177], v[206:209], v[20:23]
	v_mfma_f32_16x16x32_bf16 v[16:19], v[182:185], v[206:209], v[16:19]
	v_mfma_f32_16x16x32_bf16 v[4:7], v[174:177], v[216:219], v[4:7]
	v_mfma_f32_16x16x32_bf16 v[0:3], v[182:185], v[216:219], v[0:3]
	s_barrier
	s_add_i32 s79, s79, 2
	s_add_u32 s58, s58, 0x100
	s_addc_u32 s59, s59, 0
	s_add_u32 s76, s76, 0x100
	s_addc_u32 s77, s77, 0
	s_cmp_gt_u32 s79, 29
	s_cbranch_scc0 .LBB0_292
	v_lshl_add_u32 v148, s54, 8, v150
	v_lshl_or_b32 v146, s56, 8, v136
	v_lshl_add_u32 v147, v148, 11, v146
	v_lshlrev_b32_e32 v159, 1, v147
	v_lshlrev_b32_e32 v158, 2, v147
	v_lshlrev_b32_e32 v208, 3, v148
	global_load_dwordx4 v[160:163], v158, s[12:13]
	global_load_dwordx4 v[164:167], v158, s[12:13] offset:16
	global_load_dwordx4 v[168:171], v158, s[12:13] offset:128
	global_load_dwordx4 v[172:175], v158, s[12:13] offset:144
	v_add_u32_e32 v149, 0x20000, v158
	global_load_dwordx4 v[176:179], v149, s[12:13]
	global_load_dwordx4 v[180:183], v149, s[12:13] offset:16
	global_load_dwordx4 v[184:187], v149, s[12:13] offset:128
	global_load_dwordx4 v[188:191], v149, s[12:13] offset:144
	v_add_u32_e32 v209, 0x40000, v158
	global_load_dwordx4 v[192:195], v209, s[12:13]
	global_load_dwordx4 v[196:199], v209, s[12:13] offset:16
	global_load_dwordx4 v[200:203], v209, s[12:13] offset:128
	global_load_dwordx4 v[204:207], v209, s[12:13] offset:144
	v_add_u32_e32 v149, 0x60000, v158
	global_load_dwordx4 v[212:215], v149, s[12:13]
	global_load_dwordx4 v[216:219], v149, s[12:13] offset:16
	global_load_dwordx4 v[220:223], v149, s[12:13] offset:128
	global_load_dwordx4 v[224:227], v149, s[12:13] offset:144
	v_add_u32_e32 v209, 0x100000, v158
	global_load_dwordx4 v[228:231], v209, s[12:13]
	global_load_dwordx4 v[232:235], v209, s[12:13] offset:16
	global_load_dwordx4 v[236:239], v209, s[12:13] offset:128
	global_load_dwordx4 v[240:243], v209, s[12:13] offset:144
	s_and_b64 vcc, exec, s[44:45]
	s_cbranch_vccz .LBB0_295
	s_barrier

; #define PG8_STAGE(bufoff, gbase, voff) do { _Pragma("unroll") for (int _i = 0; _i < 2; ++_i) \
;         __builtin_amdgcn_global_load_lds((const unsigned*)((const char*)(gbase) + (voff)[_i]), (PG8_LAS unsigned*)(lds + (bufoff) + ldsw + _i * 8192), 16, 0, 0); } while (0)
; #define PG8_LDA(dst, b, h) do { _Pragma("unroll") for (int m = 0; m < 4; ++m) _Pragma("unroll") for (int k = 0; k < 2; ++k) dst[m][k] = *(const PG8_LAS bf16x8*)(lds + PG8_SA(b, h) + aoff + m * 2048 + k * 1024); } while (0)
; #define PG8_LDB(dst, b, h) do { _Pragma("unroll") for (int n = 0; n < 2; ++n) _Pragma("unroll") for (int k = 0; k < 2; ++k) dst[n][k] = *(const PG8_LAS bf16x8*)(lds + PG8_SB(b, h) + boff + n * 2048 + k * 1024); } while (0)
; #define PG8_MMA(ai, bj, At, Bt) do { __builtin_amdgcn_s_setprio(1); _Pragma("unroll") for (int m = 0; m < 4; ++m) _Pragma("unroll") for (int n = 0; n < 2; ++n) _Pragma("unroll") for (int k = 0; k < 2; ++k) \
;         acc[ai][bj][m][n] = __builtin_amdgcn_mfma_f32_16x16x32_bf16(Bt[n][k], At[m][k], acc[ai][bj][m][n], 0, 0, 0); __builtin_amdgcn_s_setprio(0); } while (0)
; #define PG8_WAIT_V(n) asm volatile("s_waitcnt vmcnt(" #n ")" ::: "memory")
; #define PG8_BAR __builtin_amdgcn_s_barrier()
; template <class Epi, class Sched, bool ALIGN_EPI = false, bool SP2 = false>
; __device__ __forceinline__ void gemm_phase(PG8_LAS unsigned char* lds, const Gemm g, const Sched& S, const Epi& E, int tid_in) {
;     ...
;         for (int t = 0; t < nt; t += 2) {
;             const bool last = (t == nt - 2);
;             const char* a1 = cA + (size_t)(t + 1) * kstep;
;             const char* a2 = last ? nA : cA + (size_t)(t + 2) * kstep; const char* b2 = last ? nB : cB + (size_t)(t + 2) * kstep;
;             const char* a3 = a2 + kstep; const char* b3 = b2 + kstep;
;             if (last && has_next) S.a_ready(nxt);
;             if constexpr (SP2) {
;             PG8_LDB(B0, 0, 0); PG8_LDB(B1, 0, 1); PG8_SCHED; PG8_LDA(At, 0, 0); PG8_STAGE(PG8_SA(1, 1), a1 + hstep, voffA);
;             PG8_WAIT_V(8); PG8_WAIT_L(0); PG8_BAR; PG8_MMA(0, 0, At, B0); PG8_MMA(0, 1, At, B1); PG8_BAR; PG8_SCHED;
;             PG8_LDA(At, 0, 1); PG8_STAGE(PG8_SB(0, 0), b2, voffB); PG8_STAGE(PG8_SB(0, 1), b2 + hstepB, voffB); PG8_STAGE(PG8_SA(0, 0), a2, voffA);
;             PG8_WAIT_V(8); PG8_WAIT_L(0); PG8_BAR; PG8_MMA(1, 0, At, B0); PG8_MMA(1, 1, At, B1); PG8_BAR; PG8_SCHED;
.Lkb_skip_2:
	ds_read_b128 v[156:159], v150
	ds_read_b128 v[160:163], v150 offset:1024
	ds_read_b128 v[164:167], v150 offset:2048
	ds_read_b128 v[168:171], v150 offset:3072
	ds_read_b128 v[172:175], v151
	ds_read_b128 v[176:179], v151 offset:1024
	ds_read_b128 v[180:183], v151 offset:2048
	ds_read_b128 v[184:187], v151 offset:3072
	s_add_u32 s26, s52, 0xfff80080
	s_addc_u32 s27, s53, -1
	s_cmp_eq_u32 s76, 28
	s_cselect_b32 s57, s45, s27
	s_cselect_b32 s56, s72, s26
	s_cselect_b32 s55, s43, s75
	s_cselect_b32 s54, s73, s74
	s_add_i32 m0, s51, 0xc000
	ds_read_b128 v[188:191], v152
	ds_read_b128 v[192:195], v152 offset:1024
	ds_read_b128 v[196:199], v152 offset:2048
	ds_read_b128 v[200:203], v152 offset:3072
	ds_read_b128 v[204:207], v152 offset:4096
	ds_read_b128 v[212:215], v152 offset:5120
	ds_read_b128 v[216:219], v152 offset:6144
	ds_read_b128 v[220:223], v152 offset:7168
	global_load_lds_dwordx4 v138, s[52:53]
	s_add_i32 m0, s51, 0xe000
	s_nop 0
	global_load_lds_dwordx4 v140, s[52:53]
	s_waitcnt vmcnt(8)
	s_waitcnt lgkmcnt(0)
	s_barrier
	s_waitcnt lgkmcnt(0)
	v_mfma_f32_16x16x32_bf16 v[124:127], v[156:159], v[188:191], 0
	v_mfma_f32_16x16x32_bf16 v[120:123], v[164:167], v[188:191], 0
	v_mfma_f32_16x16x32_bf16 v[108:111], v[156:159], v[196:199], 0
	v_mfma_f32_16x16x32_bf16 v[104:107], v[164:167], v[196:199], 0
	v_mfma_f32_16x16x32_bf16 v[92:95], v[156:159], v[204:207], 0
	v_mfma_f32_16x16x32_bf16 v[88:91], v[164:167], v[204:207], 0
	v_mfma_f32_16x16x32_bf16 v[76:79], v[156:159], v[216:219], 0
	v_mfma_f32_16x16x32_bf16 v[72:75], v[164:167], v[216:219], 0
	v_mfma_f32_16x16x32_bf16 v[124:127], v[160:163], v[192:195], v[124:127]
	v_mfma_f32_16x16x32_bf16 v[120:123], v[168:171], v[192:195], v[120:123]
	v_mfma_f32_16x16x32_bf16 v[108:111], v[160:163], v[200:203], v[108:111]
	v_mfma_f32_16x16x32_bf16 v[104:107], v[168:171], v[200:203], v[104:107]
	v_mfma_f32_16x16x32_bf16 v[92:95], v[160:163], v[212:215], v[92:95]
	v_mfma_f32_16x16x32_bf16 v[88:91], v[168:171], v[212:215], v[88:91]
	v_mfma_f32_16x16x32_bf16 v[76:79], v[160:163], v[220:223], v[76:79]
	v_mfma_f32_16x16x32_bf16 v[72:75], v[168:171], v[220:223], v[72:75]
	v_mfma_f32_16x16x32_bf16 v[116:119], v[172:175], v[188:191], 0
	v_mfma_f32_16x16x32_bf16 v[112:115], v[180:183], v[188:191], 0
	v_mfma_f32_16x16x32_bf16 v[100:103], v[172:175], v[196:199], 0
	v_mfma_f32_16x16x32_bf16 v[96:99], v[180:183], v[196:199], 0
	v_mfma_f32_16x16x32_bf16 v[84:87], v[172:175], v[204:207], 0
	v_mfma_f32_16x16x32_bf16 v[80:83], v[180:183], v[204:207], 0
	v_mfma_f32_16x16x32_bf16 v[68:71], v[172:175], v[216:219], 0
	v_mfma_f32_16x16x32_bf16 v[64:67], v[180:183], v[216:219], 0
	v_mfma_f32_16x16x32_bf16 v[116:119], v[176:179], v[192:195], v[116:119]
	v_mfma_f32_16x16x32_bf16 v[112:115], v[184:187], v[192:195], v[112:115]
	v_mfma_f32_16x16x32_bf16 v[100:103], v[176:179], v[200:203], v[100:103]
	v_mfma_f32_16x16x32_bf16 v[96:99], v[184:187], v[200:203], v[96:99]
	v_mfma_f32_16x16x32_bf16 v[84:87], v[176:179], v[212:215], v[84:87]
	v_mfma_f32_16x16x32_bf16 v[80:83], v[184:187], v[212:215], v[80:83]
	v_mfma_f32_16x16x32_bf16 v[68:71], v[176:179], v[220:223], v[68:71]
	v_mfma_f32_16x16x32_bf16 v[64:67], v[184:187], v[220:223], v[64:67]
	s_barrier
	s_add_i32 s26, s68, s60
	s_mov_b32 m0, s26
	ds_read_b128 v[188:191], v152 offset:16384
	ds_read_b128 v[192:195], v152 offset:17408
	ds_read_b128 v[196:199], v152 offset:18432
	ds_read_b128 v[200:203], v152 offset:19456
	ds_read_b128 v[204:207], v152 offset:20480
	ds_read_b128 v[212:215], v152 offset:21504
	ds_read_b128 v[216:219], v152 offset:22528
	ds_read_b128 v[220:223], v152 offset:23552
	global_load_lds_dwordx4 v130, s[54:55]
	s_add_i32 m0, s26, 0x2000
	s_add_u32 s26, s54, 0x20000
	s_addc_u32 s27, s55, 0
	s_add_i32 s33, s69, s60
	global_load_lds_dwordx4 v134, s[54:55]
	s_mov_b32 m0, s33
	s_nop 0
	global_load_lds_dwordx4 v130, s[26:27]
	s_add_i32 m0, s33, 0x2000
	s_nop 0
	global_load_lds_dwordx4 v134, s[26:27]
	s_mov_b32 m0, s51
	s_nop 0
	global_load_lds_dwordx4 v128, s[56:57]
	s_mov_b32 m0, s61
	s_nop 0
	global_load_lds_dwordx4 v132, s[56:57]
	s_waitcnt vmcnt(8)
	s_waitcnt lgkmcnt(0)
	s_barrier
	s_waitcnt lgkmcnt(0)
	v_mfma_f32_16x16x32_bf16 v[60:63], v[156:159], v[188:191], 0
	v_mfma_f32_16x16x32_bf16 v[56:59], v[164:167], v[188:191], 0
	v_mfma_f32_16x16x32_bf16 v[44:47], v[156:159], v[196:199], 0
	v_mfma_f32_16x16x32_bf16 v[40:43], v[164:167], v[196:199], 0
	v_mfma_f32_16x16x32_bf16 v[28:31], v[156:159], v[204:207], 0
	v_mfma_f32_16x16x32_bf16 v[24:27], v[164:167], v[204:207], 0
	v_mfma_f32_16x16x32_bf16 v[12:15], v[156:159], v[216:219], 0
	v_mfma_f32_16x16x32_bf16 v[8:11], v[164:167], v[216:219], 0
	v_mfma_f32_16x16x32_bf16 v[60:63], v[160:163], v[192:195], v[60:63]
	v_mfma_f32_16x16x32_bf16 v[56:59], v[168:171], v[192:195], v[56:59]
	v_mfma_f32_16x16x32_bf16 v[44:47], v[160:163], v[200:203], v[44:47]
	v_mfma_f32_16x16x32_bf16 v[40:43], v[168:171], v[200:203], v[40:43]
	v_mfma_f32_16x16x32_bf16 v[28:31], v[160:163], v[212:215], v[28:31]
	v_mfma_f32_16x16x32_bf16 v[24:27], v[168:171], v[212:215], v[24:27]
	v_mfma_f32_16x16x32_bf16 v[12:15], v[160:163], v[220:223], v[12:15]
	v_mfma_f32_16x16x32_bf16 v[8:11], v[168:171], v[220:223], v[8:11]
	v_mfma_f32_16x16x32_bf16 v[52:55], v[172:175], v[188:191], 0
	v_mfma_f32_16x16x32_bf16 v[48:51], v[180:183], v[188:191], 0
	v_mfma_f32_16x16x32_bf16 v[36:39], v[172:175], v[196:199], 0
	v_mfma_f32_16x16x32_bf16 v[32:35], v[180:183], v[196:199], 0
	v_mfma_f32_16x16x32_bf16 v[20:23], v[172:175], v[204:207], 0
	v_mfma_f32_16x16x32_bf16 v[16:19], v[180:183], v[204:207], 0
	v_mfma_f32_16x16x32_bf16 v[4:7], v[172:175], v[216:219], 0
	v_mfma_f32_16x16x32_bf16 v[0:3], v[180:183], v[216:219], 0
	v_mfma_f32_16x16x32_bf16 v[52:55], v[176:179], v[192:195], v[52:55]
	v_mfma_f32_16x16x32_bf16 v[48:51], v[184:187], v[192:195], v[48:51]
	v_mfma_f32_16x16x32_bf16 v[36:39], v[176:179], v[200:203], v[36:39]
	v_mfma_f32_16x16x32_bf16 v[32:35], v[184:187], v[200:203], v[32:35]
	v_mfma_f32_16x16x32_bf16 v[20:23], v[176:179], v[212:215], v[20:23]
	v_mfma_f32_16x16x32_bf16 v[16:19], v[184:187], v[212:215], v[16:19]
	v_mfma_f32_16x16x32_bf16 v[4:7], v[176:179], v[220:223], v[4:7]
	v_mfma_f32_16x16x32_bf16 v[0:3], v[184:187], v[220:223], v[0:3]
	s_barrier
; #define PG8_STAGE(bufoff, gbase, voff) do { _Pragma("unroll") for (int _i = 0; _i < 2; ++_i) \
;         __builtin_amdgcn_global_load_lds((const unsigned*)((const char*)(gbase) + (voff)[_i]), (PG8_LAS unsigned*)(lds + (bufoff) + ldsw + _i * 8192), 16, 0, 0); } while (0)
; #define PG8_LDA(dst, b, h) do { _Pragma("unroll") for (int m = 0; m < 4; ++m) _Pragma("unroll") for (int k = 0; k < 2; ++k) dst[m][k] = *(const PG8_LAS bf16x8*)(lds + PG8_SA(b, h) + aoff + m * 2048 + k * 1024); } while (0)
; #define PG8_LDB(dst, b, h) do { _Pragma("unroll") for (int n = 0; n < 2; ++n) _Pragma("unroll") for (int k = 0; k < 2; ++k) dst[n][k] = *(const PG8_LAS bf16x8*)(lds + PG8_SB(b, h) + boff + n * 2048 + k * 1024); } while (0)
; #define PG8_MMA(ai, bj, At, Bt) do { __builtin_amdgcn_s_setprio(1); _Pragma("unroll") for (int m = 0; m < 4; ++m) _Pragma("unroll") for (int n = 0; n < 2; ++n) _Pragma("unroll") for (int k = 0; k < 2; ++k) \
;         acc[ai][bj][m][n] = __builtin_amdgcn_mfma_f32_16x16x32_bf16(Bt[n][k], At[m][k], acc[ai][bj][m][n], 0, 0, 0); __builtin_amdgcn_s_setprio(0); } while (0)
; #define PG8_WAIT_V(n) asm volatile("s_waitcnt vmcnt(" #n ")" ::: "memory")
; #define PG8_WAIT_L(n) asm volatile("s_waitcnt lgkmcnt(" #n ")" ::: "memory")
; #define PG8_BAR __builtin_amdgcn_s_barrier()
; #define PG8_SCHED __builtin_amdgcn_sched_barrier(0)
; template <class Epi, class Sched, bool ALIGN_EPI = false, bool SP2 = false>
; __device__ __forceinline__ void gemm_phase(PG8_LAS unsigned char* lds, const Gemm g, const Sched& S, const Epi& E, int tid_in) {
;     ...
;             PG8_LDB(B0, 1, 0); PG8_LDB(B1, 1, 1); PG8_SCHED; PG8_LDA(At, 1, 0); PG8_STAGE(PG8_SA(0, 1), a2 + hstep, voffA);
;             PG8_WAIT_V(8); PG8_WAIT_L(0); PG8_BAR; PG8_MMA(0, 0, At, B0); PG8_MMA(0, 1, At, B1); PG8_BAR; PG8_SCHED;
;             PG8_LDA(At, 1, 1); PG8_STAGE(PG8_SB(1, 0), b3, voffB); PG8_STAGE(PG8_SB(1, 1), b3 + hstepB, voffB); PG8_STAGE(PG8_SA(1, 0), a3, voffA);
;             PG8_WAIT_V(8); PG8_WAIT_L(0); PG8_BAR; PG8_MMA(1, 0, At, B0); PG8_MMA(1, 1, At, B1); PG8_BAR; PG8_SCHED;
	s_add_i32 s33, 0, 0x18000
	v_add_u32_e32 v155, s33, v146
	s_add_i32 s77, 0, 0x1c000
	ds_read_b128 v[156:159], v155
	ds_read_b128 v[160:163], v155 offset:1024
	ds_read_b128 v[164:167], v155 offset:2048
	ds_read_b128 v[168:171], v155 offset:3072
	v_add_u32_e32 v155, s77, v146
	ds_read_b128 v[172:175], v155
	ds_read_b128 v[176:179], v155 offset:1024
	ds_read_b128 v[180:183], v155 offset:2048
	ds_read_b128 v[184:187], v155 offset:3072
	s_add_u32 s26, s56, 0x80000
	s_addc_u32 s27, s57, 0
	s_mov_b32 m0, s62
	ds_read_b128 v[188:191], v152 offset:32768
	ds_read_b128 v[192:195], v152 offset:33792
	ds_read_b128 v[196:199], v152 offset:34816
	ds_read_b128 v[200:203], v152 offset:35840
	ds_read_b128 v[204:207], v152 offset:36864
	ds_read_b128 v[212:215], v152 offset:37888
	ds_read_b128 v[216:219], v152 offset:38912
	ds_read_b128 v[220:223], v152 offset:39936
	global_load_lds_dwordx4 v128, s[26:27]
	s_mov_b32 m0, s63
	s_nop 0
	global_load_lds_dwordx4 v132, s[26:27]
	s_waitcnt vmcnt(8)
	s_waitcnt lgkmcnt(0)
	s_barrier
	s_waitcnt lgkmcnt(0)
	v_mfma_f32_16x16x32_bf16 v[124:127], v[156:159], v[188:191], v[124:127]
	v_mfma_f32_16x16x32_bf16 v[120:123], v[164:167], v[188:191], v[120:123]
	v_mfma_f32_16x16x32_bf16 v[108:111], v[156:159], v[196:199], v[108:111]
	v_mfma_f32_16x16x32_bf16 v[104:107], v[164:167], v[196:199], v[104:107]
	v_mfma_f32_16x16x32_bf16 v[92:95], v[156:159], v[204:207], v[92:95]
	v_mfma_f32_16x16x32_bf16 v[88:91], v[164:167], v[204:207], v[88:91]
	v_mfma_f32_16x16x32_bf16 v[76:79], v[156:159], v[216:219], v[76:79]
	v_mfma_f32_16x16x32_bf16 v[72:75], v[164:167], v[216:219], v[72:75]
	v_mfma_f32_16x16x32_bf16 v[124:127], v[160:163], v[192:195], v[124:127]
	v_mfma_f32_16x16x32_bf16 v[120:123], v[168:171], v[192:195], v[120:123]
	v_mfma_f32_16x16x32_bf16 v[108:111], v[160:163], v[200:203], v[108:111]
	v_mfma_f32_16x16x32_bf16 v[104:107], v[168:171], v[200:203], v[104:107]
	v_mfma_f32_16x16x32_bf16 v[92:95], v[160:163], v[212:215], v[92:95]
	v_mfma_f32_16x16x32_bf16 v[88:91], v[168:171], v[212:215], v[88:91]
	v_mfma_f32_16x16x32_bf16 v[76:79], v[160:163], v[220:223], v[76:79]
	v_mfma_f32_16x16x32_bf16 v[72:75], v[168:171], v[220:223], v[72:75]
	v_mfma_f32_16x16x32_bf16 v[116:119], v[172:175], v[188:191], v[116:119]
	v_mfma_f32_16x16x32_bf16 v[112:115], v[180:183], v[188:191], v[112:115]
	v_mfma_f32_16x16x32_bf16 v[100:103], v[172:175], v[196:199], v[100:103]
	v_mfma_f32_16x16x32_bf16 v[96:99], v[180:183], v[196:199], v[96:99]
	v_mfma_f32_16x16x32_bf16 v[84:87], v[172:175], v[204:207], v[84:87]
	v_mfma_f32_16x16x32_bf16 v[80:83], v[180:183], v[204:207], v[80:83]
	v_mfma_f32_16x16x32_bf16 v[68:71], v[172:175], v[216:219], v[68:71]
	v_mfma_f32_16x16x32_bf16 v[64:67], v[180:183], v[216:219], v[64:67]
	v_mfma_f32_16x16x32_bf16 v[116:119], v[176:179], v[192:195], v[116:119]
	v_mfma_f32_16x16x32_bf16 v[112:115], v[184:187], v[192:195], v[112:115]
	v_mfma_f32_16x16x32_bf16 v[100:103], v[176:179], v[200:203], v[100:103]
	v_mfma_f32_16x16x32_bf16 v[96:99], v[184:187], v[200:203], v[96:99]
	v_mfma_f32_16x16x32_bf16 v[84:87], v[176:179], v[212:215], v[84:87]
	v_mfma_f32_16x16x32_bf16 v[80:83], v[184:187], v[212:215], v[80:83]
	v_mfma_f32_16x16x32_bf16 v[68:71], v[176:179], v[220:223], v[68:71]
	v_mfma_f32_16x16x32_bf16 v[64:67], v[184:187], v[220:223], v[64:67]
	s_barrier
	s_add_i32 s26, s33, s60
	s_add_i32 m0, s26, 0xffffff80
	ds_read_b128 v[188:191], v152 offset:49152
	ds_read_b128 v[192:195], v152 offset:50176
	ds_read_b128 v[196:199], v152 offset:51200
	ds_read_b128 v[200:203], v152 offset:52224
	ds_read_b128 v[204:207], v152 offset:53248
	ds_read_b128 v[212:215], v152 offset:54272
	ds_read_b128 v[216:219], v152 offset:55296
	ds_read_b128 v[220:223], v152 offset:56320
	global_load_lds_dwordx4 v130, s[54:55] offset:128
	s_add_i32 m0, s26, 0x1f80
	s_add_u32 s26, s54, 0x20080
	s_addc_u32 s27, s55, 0
	s_add_i32 s33, s77, s60
	global_load_lds_dwordx4 v134, s[54:55] offset:128
	s_mov_b32 m0, s33
	s_nop 0
	global_load_lds_dwordx4 v130, s[26:27]
	s_add_i32 m0, s33, 0x2000
	s_nop 0
	global_load_lds_dwordx4 v134, s[26:27]
	s_add_i32 m0, s66, 0xffffff80
	s_nop 0
	global_load_lds_dwordx4 v128, s[56:57] offset:128
	s_add_i32 m0, s67, 0xffffff80
	s_nop 0
	global_load_lds_dwordx4 v132, s[56:57] offset:128
	s_waitcnt vmcnt(8)
	s_waitcnt lgkmcnt(0)
	s_barrier
	s_waitcnt lgkmcnt(0)
	v_mfma_f32_16x16x32_bf16 v[60:63], v[156:159], v[188:191], v[60:63]
	v_mfma_f32_16x16x32_bf16 v[56:59], v[164:167], v[188:191], v[56:59]
	v_mfma_f32_16x16x32_bf16 v[44:47], v[156:159], v[196:199], v[44:47]
	v_mfma_f32_16x16x32_bf16 v[40:43], v[164:167], v[196:199], v[40:43]
	v_mfma_f32_16x16x32_bf16 v[28:31], v[156:159], v[204:207], v[28:31]
	v_mfma_f32_16x16x32_bf16 v[24:27], v[164:167], v[204:207], v[24:27]
	v_mfma_f32_16x16x32_bf16 v[12:15], v[156:159], v[216:219], v[12:15]
	v_mfma_f32_16x16x32_bf16 v[8:11], v[164:167], v[216:219], v[8:11]
	v_mfma_f32_16x16x32_bf16 v[60:63], v[160:163], v[192:195], v[60:63]
	v_mfma_f32_16x16x32_bf16 v[56:59], v[168:171], v[192:195], v[56:59]
	v_mfma_f32_16x16x32_bf16 v[44:47], v[160:163], v[200:203], v[44:47]
	v_mfma_f32_16x16x32_bf16 v[40:43], v[168:171], v[200:203], v[40:43]
	v_mfma_f32_16x16x32_bf16 v[28:31], v[160:163], v[212:215], v[28:31]
	v_mfma_f32_16x16x32_bf16 v[24:27], v[168:171], v[212:215], v[24:27]
	v_mfma_f32_16x16x32_bf16 v[12:15], v[160:163], v[220:223], v[12:15]
	v_mfma_f32_16x16x32_bf16 v[8:11], v[168:171], v[220:223], v[8:11]
	v_mfma_f32_16x16x32_bf16 v[52:55], v[172:175], v[188:191], v[52:55]
	v_mfma_f32_16x16x32_bf16 v[48:51], v[180:183], v[188:191], v[48:51]
	v_mfma_f32_16x16x32_bf16 v[36:39], v[172:175], v[196:199], v[36:39]
	v_mfma_f32_16x16x32_bf16 v[32:35], v[180:183], v[196:199], v[32:35]
	v_mfma_f32_16x16x32_bf16 v[20:23], v[172:175], v[204:207], v[20:23]
	v_mfma_f32_16x16x32_bf16 v[16:19], v[180:183], v[204:207], v[16:19]
	v_mfma_f32_16x16x32_bf16 v[4:7], v[172:175], v[216:219], v[4:7]
	v_mfma_f32_16x16x32_bf16 v[0:3], v[180:183], v[216:219], v[0:3]
	v_mfma_f32_16x16x32_bf16 v[52:55], v[176:179], v[192:195], v[52:55]
	v_mfma_f32_16x16x32_bf16 v[48:51], v[184:187], v[192:195], v[48:51]
	v_mfma_f32_16x16x32_bf16 v[36:39], v[176:179], v[200:203], v[36:39]
	v_mfma_f32_16x16x32_bf16 v[32:35], v[184:187], v[200:203], v[32:35]
	v_mfma_f32_16x16x32_bf16 v[20:23], v[176:179], v[212:215], v[20:23]
	v_mfma_f32_16x16x32_bf16 v[16:19], v[184:187], v[212:215], v[16:19]
	v_mfma_f32_16x16x32_bf16 v[4:7], v[176:179], v[220:223], v[4:7]
	v_mfma_f32_16x16x32_bf16 v[0:3], v[184:187], v[220:223], v[0:3]
	s_barrier
	s_add_i32 s76, s76, 2
	s_add_u32 s52, s52, 0x100
	s_addc_u32 s53, s53, 0
	s_add_u32 s74, s74, 0x100
	s_addc_u32 s75, s75, 0
	s_cmp_gt_u32 s76, 29
; #define PG8_STAGE(bufoff, gbase, voff) do { _Pragma("unroll") for (int _i = 0; _i < 2; ++_i) \
;         __builtin_amdgcn_global_load_lds((const unsigned*)((const char*)(gbase) + (voff)[_i]), (PG8_LAS unsigned*)(lds + (bufoff) + ldsw + _i * 8192), 16, 0, 0); } while (0)
; #define PG8_LDA(dst, b, h) do { _Pragma("unroll") for (int m = 0; m < 4; ++m) _Pragma("unroll") for (int k = 0; k < 2; ++k) dst[m][k] = *(const PG8_LAS bf16x8*)(lds + PG8_SA(b, h) + aoff + m * 2048 + k * 1024); } while (0)
; #define PG8_LDB(dst, b, h) do { _Pragma("unroll") for (int n = 0; n < 2; ++n) _Pragma("unroll") for (int k = 0; k < 2; ++k) dst[n][k] = *(const PG8_LAS bf16x8*)(lds + PG8_SB(b, h) + boff + n * 2048 + k * 1024); } while (0)
; #define PG8_MMA(ai, bj, At, Bt) do { __builtin_amdgcn_s_setprio(1); _Pragma("unroll") for (int m = 0; m < 4; ++m) _Pragma("unroll") for (int n = 0; n < 2; ++n) _Pragma("unroll") for (int k = 0; k < 2; ++k) \
;         acc[ai][bj][m][n] = __builtin_amdgcn_mfma_f32_16x16x32_bf16(Bt[n][k], At[m][k], acc[ai][bj][m][n], 0, 0, 0); __builtin_amdgcn_s_setprio(0); } while (0)
; #define PG8_WAIT_V(n) asm volatile("s_waitcnt vmcnt(" #n ")" ::: "memory")
; #define PG8_BAR __builtin_amdgcn_s_barrier()
; template <class Epi, class Sched, bool ALIGN_EPI = false, bool SP2 = false>
; __device__ __forceinline__ void gemm_phase(PG8_LAS unsigned char* lds, const Gemm g, const Sched& S, const Epi& E, int tid_in) {
;     ...
;         for (int t = 0; t < nt; t += 2) {
;             const bool last = (t == nt - 2);
;             const char* a1 = cA + (size_t)(t + 1) * kstep;
;             const char* a2 = last ? nA : cA + (size_t)(t + 2) * kstep; const char* b2 = last ? nB : cB + (size_t)(t + 2) * kstep;
;             const char* a3 = a2 + kstep; const char* b3 = b2 + kstep;
;             if (last && has_next) S.a_ready(nxt);
;             if constexpr (SP2) {
;             PG8_LDB(B0, 0, 0); PG8_LDB(B1, 0, 1); PG8_SCHED; PG8_LDA(At, 0, 0); PG8_STAGE(PG8_SA(1, 1), a1 + hstep, voffA);
;             PG8_WAIT_V(8); PG8_WAIT_L(0); PG8_BAR; PG8_MMA(0, 0, At, B0); PG8_MMA(0, 1, At, B1); PG8_BAR; PG8_SCHED;
;             PG8_LDA(At, 0, 1); PG8_STAGE(PG8_SB(0, 0), b2, voffB); PG8_STAGE(PG8_SB(0, 1), b2 + hstepB, voffB); PG8_STAGE(PG8_SA(0, 0), a2, voffA);
;             PG8_WAIT_V(8); PG8_WAIT_L(0); PG8_BAR; PG8_MMA(1, 0, At, B0); PG8_MMA(1, 1, At, B1); PG8_BAR; PG8_SCHED;
.LBB0_394:
	ds_read_b128 v[156:159], v150
	ds_read_b128 v[160:163], v150 offset:1024
	ds_read_b128 v[164:167], v150 offset:2048
	ds_read_b128 v[168:171], v150 offset:3072
	ds_read_b128 v[172:175], v151
	ds_read_b128 v[176:179], v151 offset:1024
	ds_read_b128 v[180:183], v151 offset:2048
	ds_read_b128 v[184:187], v151 offset:3072
	s_add_u32 s26, s52, 0xfff80080
	s_addc_u32 s27, s53, -1
	s_cmp_eq_u32 s76, 28
	s_cselect_b32 s57, s45, s27
	s_cselect_b32 s56, s72, s26
	s_cselect_b32 s55, s43, s75
	s_cselect_b32 s54, s73, s74
	s_add_i32 m0, s51, 0xc000
	ds_read_b128 v[188:191], v152
	ds_read_b128 v[192:195], v152 offset:1024
	ds_read_b128 v[196:199], v152 offset:2048
	ds_read_b128 v[200:203], v152 offset:3072
	ds_read_b128 v[204:207], v152 offset:4096
	ds_read_b128 v[212:215], v152 offset:5120
	ds_read_b128 v[216:219], v152 offset:6144
	ds_read_b128 v[220:223], v152 offset:7168
	global_load_lds_dwordx4 v138, s[52:53]
	s_add_i32 m0, s51, 0xe000
	s_nop 0
	global_load_lds_dwordx4 v140, s[52:53]
	s_waitcnt vmcnt(8)
	s_waitcnt lgkmcnt(0)
	s_barrier
	s_waitcnt lgkmcnt(0)
	v_mfma_f32_16x16x32_bf16 v[124:127], v[156:159], v[188:191], v[124:127]
	v_mfma_f32_16x16x32_bf16 v[120:123], v[164:167], v[188:191], v[120:123]
	v_mfma_f32_16x16x32_bf16 v[108:111], v[156:159], v[196:199], v[108:111]
	v_mfma_f32_16x16x32_bf16 v[104:107], v[164:167], v[196:199], v[104:107]
	v_mfma_f32_16x16x32_bf16 v[92:95], v[156:159], v[204:207], v[92:95]
	v_mfma_f32_16x16x32_bf16 v[88:91], v[164:167], v[204:207], v[88:91]
	v_mfma_f32_16x16x32_bf16 v[76:79], v[156:159], v[216:219], v[76:79]
	v_mfma_f32_16x16x32_bf16 v[72:75], v[164:167], v[216:219], v[72:75]
	v_mfma_f32_16x16x32_bf16 v[124:127], v[160:163], v[192:195], v[124:127]
	v_mfma_f32_16x16x32_bf16 v[120:123], v[168:171], v[192:195], v[120:123]
	v_mfma_f32_16x16x32_bf16 v[108:111], v[160:163], v[200:203], v[108:111]
	v_mfma_f32_16x16x32_bf16 v[104:107], v[168:171], v[200:203], v[104:107]
	v_mfma_f32_16x16x32_bf16 v[92:95], v[160:163], v[212:215], v[92:95]
	v_mfma_f32_16x16x32_bf16 v[88:91], v[168:171], v[212:215], v[88:91]
	v_mfma_f32_16x16x32_bf16 v[76:79], v[160:163], v[220:223], v[76:79]
	v_mfma_f32_16x16x32_bf16 v[72:75], v[168:171], v[220:223], v[72:75]
	v_mfma_f32_16x16x32_bf16 v[116:119], v[172:175], v[188:191], v[116:119]
	v_mfma_f32_16x16x32_bf16 v[112:115], v[180:183], v[188:191], v[112:115]
	v_mfma_f32_16x16x32_bf16 v[100:103], v[172:175], v[196:199], v[100:103]
	v_mfma_f32_16x16x32_bf16 v[96:99], v[180:183], v[196:199], v[96:99]
	v_mfma_f32_16x16x32_bf16 v[84:87], v[172:175], v[204:207], v[84:87]
	v_mfma_f32_16x16x32_bf16 v[80:83], v[180:183], v[204:207], v[80:83]
	v_mfma_f32_16x16x32_bf16 v[68:71], v[172:175], v[216:219], v[68:71]
	v_mfma_f32_16x16x32_bf16 v[64:67], v[180:183], v[216:219], v[64:67]
	v_mfma_f32_16x16x32_bf16 v[116:119], v[176:179], v[192:195], v[116:119]
	v_mfma_f32_16x16x32_bf16 v[112:115], v[184:187], v[192:195], v[112:115]
	v_mfma_f32_16x16x32_bf16 v[100:103], v[176:179], v[200:203], v[100:103]
	v_mfma_f32_16x16x32_bf16 v[96:99], v[184:187], v[200:203], v[96:99]
	v_mfma_f32_16x16x32_bf16 v[84:87], v[176:179], v[212:215], v[84:87]
	v_mfma_f32_16x16x32_bf16 v[80:83], v[184:187], v[212:215], v[80:83]
	v_mfma_f32_16x16x32_bf16 v[68:71], v[176:179], v[220:223], v[68:71]
	v_mfma_f32_16x16x32_bf16 v[64:67], v[184:187], v[220:223], v[64:67]
	s_barrier
	s_add_i32 s26, s68, s60
	s_mov_b32 m0, s26
	ds_read_b128 v[188:191], v152 offset:16384
	ds_read_b128 v[192:195], v152 offset:17408
	ds_read_b128 v[196:199], v152 offset:18432
	ds_read_b128 v[200:203], v152 offset:19456
	ds_read_b128 v[204:207], v152 offset:20480
	ds_read_b128 v[212:215], v152 offset:21504
	ds_read_b128 v[216:219], v152 offset:22528
	ds_read_b128 v[220:223], v152 offset:23552
	global_load_lds_dwordx4 v130, s[54:55]
	s_add_i32 m0, s26, 0x2000
	s_add_u32 s26, s54, 0x20000
	s_addc_u32 s27, s55, 0
	s_add_i32 s33, s69, s60
	global_load_lds_dwordx4 v134, s[54:55]
	s_mov_b32 m0, s33
	s_nop 0
	global_load_lds_dwordx4 v130, s[26:27]
	s_add_i32 m0, s33, 0x2000
	s_nop 0
	global_load_lds_dwordx4 v134, s[26:27]
	s_mov_b32 m0, s51
	s_nop 0
	global_load_lds_dwordx4 v128, s[56:57]
	s_mov_b32 m0, s61
	s_nop 0
	global_load_lds_dwordx4 v132, s[56:57]
	s_waitcnt vmcnt(8)
	s_waitcnt lgkmcnt(0)
	s_barrier
	s_waitcnt lgkmcnt(0)
	v_mfma_f32_16x16x32_bf16 v[60:63], v[156:159], v[188:191], v[60:63]
	v_mfma_f32_16x16x32_bf16 v[56:59], v[164:167], v[188:191], v[56:59]
	v_mfma_f32_16x16x32_bf16 v[44:47], v[156:159], v[196:199], v[44:47]
	v_mfma_f32_16x16x32_bf16 v[40:43], v[164:167], v[196:199], v[40:43]
	v_mfma_f32_16x16x32_bf16 v[28:31], v[156:159], v[204:207], v[28:31]
	v_mfma_f32_16x16x32_bf16 v[24:27], v[164:167], v[204:207], v[24:27]
	v_mfma_f32_16x16x32_bf16 v[12:15], v[156:159], v[216:219], v[12:15]
	v_mfma_f32_16x16x32_bf16 v[8:11], v[164:167], v[216:219], v[8:11]
	v_mfma_f32_16x16x32_bf16 v[60:63], v[160:163], v[192:195], v[60:63]
	v_mfma_f32_16x16x32_bf16 v[56:59], v[168:171], v[192:195], v[56:59]
	v_mfma_f32_16x16x32_bf16 v[44:47], v[160:163], v[200:203], v[44:47]
	v_mfma_f32_16x16x32_bf16 v[40:43], v[168:171], v[200:203], v[40:43]
	v_mfma_f32_16x16x32_bf16 v[28:31], v[160:163], v[212:215], v[28:31]
	v_mfma_f32_16x16x32_bf16 v[24:27], v[168:171], v[212:215], v[24:27]
	v_mfma_f32_16x16x32_bf16 v[12:15], v[160:163], v[220:223], v[12:15]
	v_mfma_f32_16x16x32_bf16 v[8:11], v[168:171], v[220:223], v[8:11]
	v_mfma_f32_16x16x32_bf16 v[52:55], v[172:175], v[188:191], v[52:55]
	v_mfma_f32_16x16x32_bf16 v[48:51], v[180:183], v[188:191], v[48:51]
	v_mfma_f32_16x16x32_bf16 v[36:39], v[172:175], v[196:199], v[36:39]
	v_mfma_f32_16x16x32_bf16 v[32:35], v[180:183], v[196:199], v[32:35]
	v_mfma_f32_16x16x32_bf16 v[20:23], v[172:175], v[204:207], v[20:23]
	v_mfma_f32_16x16x32_bf16 v[16:19], v[180:183], v[204:207], v[16:19]
	v_mfma_f32_16x16x32_bf16 v[4:7], v[172:175], v[216:219], v[4:7]
	v_mfma_f32_16x16x32_bf16 v[0:3], v[180:183], v[216:219], v[0:3]
	v_mfma_f32_16x16x32_bf16 v[52:55], v[176:179], v[192:195], v[52:55]
	v_mfma_f32_16x16x32_bf16 v[48:51], v[184:187], v[192:195], v[48:51]
	v_mfma_f32_16x16x32_bf16 v[36:39], v[176:179], v[200:203], v[36:39]
	v_mfma_f32_16x16x32_bf16 v[32:35], v[184:187], v[200:203], v[32:35]
	v_mfma_f32_16x16x32_bf16 v[20:23], v[176:179], v[212:215], v[20:23]
	v_mfma_f32_16x16x32_bf16 v[16:19], v[184:187], v[212:215], v[16:19]
	v_mfma_f32_16x16x32_bf16 v[4:7], v[176:179], v[220:223], v[4:7]
	v_mfma_f32_16x16x32_bf16 v[0:3], v[184:187], v[220:223], v[0:3]
	s_barrier
; #define PG8_STAGE(bufoff, gbase, voff) do { _Pragma("unroll") for (int _i = 0; _i < 2; ++_i) \
;         __builtin_amdgcn_global_load_lds((const unsigned*)((const char*)(gbase) + (voff)[_i]), (PG8_LAS unsigned*)(lds + (bufoff) + ldsw + _i * 8192), 16, 0, 0); } while (0)
; #define PG8_LDA(dst, b, h) do { _Pragma("unroll") for (int m = 0; m < 4; ++m) _Pragma("unroll") for (int k = 0; k < 2; ++k) dst[m][k] = *(const PG8_LAS bf16x8*)(lds + PG8_SA(b, h) + aoff + m * 2048 + k * 1024); } while (0)
; #define PG8_LDB(dst, b, h) do { _Pragma("unroll") for (int n = 0; n < 2; ++n) _Pragma("unroll") for (int k = 0; k < 2; ++k) dst[n][k] = *(const PG8_LAS bf16x8*)(lds + PG8_SB(b, h) + boff + n * 2048 + k * 1024); } while (0)
; #define PG8_MMA(ai, bj, At, Bt) do { __builtin_amdgcn_s_setprio(1); _Pragma("unroll") for (int m = 0; m < 4; ++m) _Pragma("unroll") for (int n = 0; n < 2; ++n) _Pragma("unroll") for (int k = 0; k < 2; ++k) \
;         acc[ai][bj][m][n] = __builtin_amdgcn_mfma_f32_16x16x32_bf16(Bt[n][k], At[m][k], acc[ai][bj][m][n], 0, 0, 0); __builtin_amdgcn_s_setprio(0); } while (0)
; #define PG8_WAIT_V(n) asm volatile("s_waitcnt vmcnt(" #n ")" ::: "memory")
; #define PG8_WAIT_L(n) asm volatile("s_waitcnt lgkmcnt(" #n ")" ::: "memory")
; #define PG8_BAR __builtin_amdgcn_s_barrier()
; #define PG8_SCHED __builtin_amdgcn_sched_barrier(0)
; template <class Epi, class Sched, bool ALIGN_EPI = false, bool SP2 = false>
; __device__ __forceinline__ void gemm_phase(PG8_LAS unsigned char* lds, const Gemm g, const Sched& S, const Epi& E, int tid_in) {
;     ...
;             PG8_LDB(B0, 1, 0); PG8_LDB(B1, 1, 1); PG8_SCHED; PG8_LDA(At, 1, 0); PG8_STAGE(PG8_SA(0, 1), a2 + hstep, voffA);
;             PG8_WAIT_V(8); PG8_WAIT_L(0); PG8_BAR; PG8_MMA(0, 0, At, B0); PG8_MMA(0, 1, At, B1); PG8_BAR; PG8_SCHED;
;             PG8_LDA(At, 1, 1); PG8_STAGE(PG8_SB(1, 0), b3, voffB); PG8_STAGE(PG8_SB(1, 1), b3 + hstepB, voffB); PG8_STAGE(PG8_SA(1, 0), a3, voffA);
;             PG8_WAIT_V(8); PG8_WAIT_L(0); PG8_BAR; PG8_MMA(1, 0, At, B0); PG8_MMA(1, 1, At, B1); PG8_BAR; PG8_SCHED;
;     ...
;         if constexpr (ALIGN_EPI) { if (wr == 0) PG8_BAR; }
	s_add_i32 s33, 0, 0x18000
	v_add_u32_e32 v155, s33, v146
	s_add_i32 s77, 0, 0x1c000
	ds_read_b128 v[156:159], v155
	ds_read_b128 v[160:163], v155 offset:1024
	ds_read_b128 v[164:167], v155 offset:2048
	ds_read_b128 v[168:171], v155 offset:3072
	v_add_u32_e32 v155, s77, v146
	ds_read_b128 v[172:175], v155
	ds_read_b128 v[176:179], v155 offset:1024
	ds_read_b128 v[180:183], v155 offset:2048
	ds_read_b128 v[184:187], v155 offset:3072
	s_add_u32 s26, s56, 0x80000
	s_addc_u32 s27, s57, 0
	s_mov_b32 m0, s62
	ds_read_b128 v[188:191], v152 offset:32768
	ds_read_b128 v[192:195], v152 offset:33792
	ds_read_b128 v[196:199], v152 offset:34816
	ds_read_b128 v[200:203], v152 offset:35840
	ds_read_b128 v[204:207], v152 offset:36864
	ds_read_b128 v[212:215], v152 offset:37888
	ds_read_b128 v[216:219], v152 offset:38912
	ds_read_b128 v[220:223], v152 offset:39936
	global_load_lds_dwordx4 v128, s[26:27]
	s_mov_b32 m0, s63
	s_nop 0
	global_load_lds_dwordx4 v132, s[26:27]
	s_waitcnt vmcnt(8)
	s_waitcnt lgkmcnt(0)
	s_barrier
	s_waitcnt lgkmcnt(0)
	v_mfma_f32_16x16x32_bf16 v[124:127], v[156:159], v[188:191], v[124:127]
	v_mfma_f32_16x16x32_bf16 v[120:123], v[164:167], v[188:191], v[120:123]
	v_mfma_f32_16x16x32_bf16 v[108:111], v[156:159], v[196:199], v[108:111]
	v_mfma_f32_16x16x32_bf16 v[104:107], v[164:167], v[196:199], v[104:107]
	v_mfma_f32_16x16x32_bf16 v[92:95], v[156:159], v[204:207], v[92:95]
	v_mfma_f32_16x16x32_bf16 v[88:91], v[164:167], v[204:207], v[88:91]
	v_mfma_f32_16x16x32_bf16 v[76:79], v[156:159], v[216:219], v[76:79]
	v_mfma_f32_16x16x32_bf16 v[72:75], v[164:167], v[216:219], v[72:75]
	v_mfma_f32_16x16x32_bf16 v[124:127], v[160:163], v[192:195], v[124:127]
	v_mfma_f32_16x16x32_bf16 v[120:123], v[168:171], v[192:195], v[120:123]
	v_mfma_f32_16x16x32_bf16 v[108:111], v[160:163], v[200:203], v[108:111]
	v_mfma_f32_16x16x32_bf16 v[104:107], v[168:171], v[200:203], v[104:107]
	v_mfma_f32_16x16x32_bf16 v[92:95], v[160:163], v[212:215], v[92:95]
	v_mfma_f32_16x16x32_bf16 v[88:91], v[168:171], v[212:215], v[88:91]
	v_mfma_f32_16x16x32_bf16 v[76:79], v[160:163], v[220:223], v[76:79]
	v_mfma_f32_16x16x32_bf16 v[72:75], v[168:171], v[220:223], v[72:75]
	v_mfma_f32_16x16x32_bf16 v[116:119], v[172:175], v[188:191], v[116:119]
	v_mfma_f32_16x16x32_bf16 v[112:115], v[180:183], v[188:191], v[112:115]
	v_mfma_f32_16x16x32_bf16 v[100:103], v[172:175], v[196:199], v[100:103]
	v_mfma_f32_16x16x32_bf16 v[96:99], v[180:183], v[196:199], v[96:99]
	v_mfma_f32_16x16x32_bf16 v[84:87], v[172:175], v[204:207], v[84:87]
	v_mfma_f32_16x16x32_bf16 v[80:83], v[180:183], v[204:207], v[80:83]
	v_mfma_f32_16x16x32_bf16 v[68:71], v[172:175], v[216:219], v[68:71]
	v_mfma_f32_16x16x32_bf16 v[64:67], v[180:183], v[216:219], v[64:67]
	v_mfma_f32_16x16x32_bf16 v[116:119], v[176:179], v[192:195], v[116:119]
	v_mfma_f32_16x16x32_bf16 v[112:115], v[184:187], v[192:195], v[112:115]
	v_mfma_f32_16x16x32_bf16 v[100:103], v[176:179], v[200:203], v[100:103]
	v_mfma_f32_16x16x32_bf16 v[96:99], v[184:187], v[200:203], v[96:99]
	v_mfma_f32_16x16x32_bf16 v[84:87], v[176:179], v[212:215], v[84:87]
	v_mfma_f32_16x16x32_bf16 v[80:83], v[184:187], v[212:215], v[80:83]
	v_mfma_f32_16x16x32_bf16 v[68:71], v[176:179], v[220:223], v[68:71]
	v_mfma_f32_16x16x32_bf16 v[64:67], v[184:187], v[220:223], v[64:67]
	s_barrier
	s_add_i32 s26, s33, s60
	s_add_i32 m0, s26, 0xffffff80
	ds_read_b128 v[188:191], v152 offset:49152
	ds_read_b128 v[192:195], v152 offset:50176
	ds_read_b128 v[196:199], v152 offset:51200
	ds_read_b128 v[200:203], v152 offset:52224
	ds_read_b128 v[204:207], v152 offset:53248
	ds_read_b128 v[212:215], v152 offset:54272
	ds_read_b128 v[216:219], v152 offset:55296
	ds_read_b128 v[220:223], v152 offset:56320
	global_load_lds_dwordx4 v130, s[54:55] offset:128
	s_add_i32 m0, s26, 0x1f80
	s_add_u32 s26, s54, 0x20080
	s_addc_u32 s27, s55, 0
	s_add_i32 s33, s77, s60
	global_load_lds_dwordx4 v134, s[54:55] offset:128
	s_mov_b32 m0, s33
	s_nop 0
	global_load_lds_dwordx4 v130, s[26:27]
	s_add_i32 m0, s33, 0x2000
	s_nop 0
	global_load_lds_dwordx4 v134, s[26:27]
	s_add_i32 m0, s66, 0xffffff80
	s_nop 0
	global_load_lds_dwordx4 v128, s[56:57] offset:128
	s_add_i32 m0, s67, 0xffffff80
	s_nop 0
	global_load_lds_dwordx4 v132, s[56:57] offset:128
	s_waitcnt vmcnt(8)
	s_waitcnt lgkmcnt(0)
	s_barrier
	s_waitcnt lgkmcnt(0)
	v_mfma_f32_16x16x32_bf16 v[60:63], v[156:159], v[188:191], v[60:63]
	v_mfma_f32_16x16x32_bf16 v[56:59], v[164:167], v[188:191], v[56:59]
	v_mfma_f32_16x16x32_bf16 v[44:47], v[156:159], v[196:199], v[44:47]
	v_mfma_f32_16x16x32_bf16 v[40:43], v[164:167], v[196:199], v[40:43]
	v_mfma_f32_16x16x32_bf16 v[28:31], v[156:159], v[204:207], v[28:31]
	v_mfma_f32_16x16x32_bf16 v[24:27], v[164:167], v[204:207], v[24:27]
	v_mfma_f32_16x16x32_bf16 v[12:15], v[156:159], v[216:219], v[12:15]
	v_mfma_f32_16x16x32_bf16 v[8:11], v[164:167], v[216:219], v[8:11]
	v_mfma_f32_16x16x32_bf16 v[60:63], v[160:163], v[192:195], v[60:63]
	v_mfma_f32_16x16x32_bf16 v[56:59], v[168:171], v[192:195], v[56:59]
	v_mfma_f32_16x16x32_bf16 v[44:47], v[160:163], v[200:203], v[44:47]
	v_mfma_f32_16x16x32_bf16 v[40:43], v[168:171], v[200:203], v[40:43]
	v_mfma_f32_16x16x32_bf16 v[28:31], v[160:163], v[212:215], v[28:31]
	v_mfma_f32_16x16x32_bf16 v[24:27], v[168:171], v[212:215], v[24:27]
	v_mfma_f32_16x16x32_bf16 v[12:15], v[160:163], v[220:223], v[12:15]
	v_mfma_f32_16x16x32_bf16 v[8:11], v[168:171], v[220:223], v[8:11]
	v_mfma_f32_16x16x32_bf16 v[52:55], v[172:175], v[188:191], v[52:55]
	v_mfma_f32_16x16x32_bf16 v[48:51], v[180:183], v[188:191], v[48:51]
	v_mfma_f32_16x16x32_bf16 v[36:39], v[172:175], v[196:199], v[36:39]
	v_mfma_f32_16x16x32_bf16 v[32:35], v[180:183], v[196:199], v[32:35]
	v_mfma_f32_16x16x32_bf16 v[20:23], v[172:175], v[204:207], v[20:23]
	v_mfma_f32_16x16x32_bf16 v[16:19], v[180:183], v[204:207], v[16:19]
	v_mfma_f32_16x16x32_bf16 v[4:7], v[172:175], v[216:219], v[4:7]
	v_mfma_f32_16x16x32_bf16 v[0:3], v[180:183], v[216:219], v[0:3]
	v_mfma_f32_16x16x32_bf16 v[52:55], v[176:179], v[192:195], v[52:55]
	v_mfma_f32_16x16x32_bf16 v[48:51], v[184:187], v[192:195], v[48:51]
	v_mfma_f32_16x16x32_bf16 v[36:39], v[176:179], v[200:203], v[36:39]
	v_mfma_f32_16x16x32_bf16 v[32:35], v[184:187], v[200:203], v[32:35]
	v_mfma_f32_16x16x32_bf16 v[20:23], v[176:179], v[212:215], v[20:23]
	v_mfma_f32_16x16x32_bf16 v[16:19], v[184:187], v[212:215], v[16:19]
	v_mfma_f32_16x16x32_bf16 v[4:7], v[176:179], v[220:223], v[4:7]
	v_mfma_f32_16x16x32_bf16 v[0:3], v[184:187], v[220:223], v[0:3]
	s_barrier
	s_add_i32 s76, s76, 2
	s_add_u32 s52, s52, 0x100
	s_addc_u32 s53, s53, 0
	s_add_u32 s74, s74, 0x100
	s_addc_u32 s75, s75, 0
	s_cmp_gt_u32 s76, 29
	s_cbranch_scc0 .LBB0_394
	s_and_b64 vcc, exec, s[14:15]
	s_cbranch_vccz .LBB0_397
	s_barrier

; #define PG8_STAGE(bufoff, gbase, voff) do { _Pragma("unroll") for (int _i = 0; _i < 2; ++_i) \
;         __builtin_amdgcn_global_load_lds((const unsigned*)((const char*)(gbase) + (voff)[_i]), (PG8_LAS unsigned*)(lds + (bufoff) + ldsw + _i * 8192), 16, 0, 0); } while (0)
; #define PG8_LDA(dst, b, h) do { _Pragma("unroll") for (int m = 0; m < 4; ++m) _Pragma("unroll") for (int k = 0; k < 2; ++k) dst[m][k] = *(const PG8_LAS bf16x8*)(lds + PG8_SA(b, h) + aoff + m * 2048 + k * 1024); } while (0)
; #define PG8_LDB(dst, b, h) do { _Pragma("unroll") for (int n = 0; n < 2; ++n) _Pragma("unroll") for (int k = 0; k < 2; ++k) dst[n][k] = *(const PG8_LAS bf16x8*)(lds + PG8_SB(b, h) + boff + n * 2048 + k * 1024); } while (0)
; #define PG8_MMA(ai, bj, At, Bt) do { __builtin_amdgcn_s_setprio(1); _Pragma("unroll") for (int m = 0; m < 4; ++m) _Pragma("unroll") for (int n = 0; n < 2; ++n) _Pragma("unroll") for (int k = 0; k < 2; ++k) \
;         acc[ai][bj][m][n] = __builtin_amdgcn_mfma_f32_16x16x32_bf16(Bt[n][k], At[m][k], acc[ai][bj][m][n], 0, 0, 0); __builtin_amdgcn_s_setprio(0); } while (0)
; #define PG8_WAIT_V(n) asm volatile("s_waitcnt vmcnt(" #n ")" ::: "memory")
; #define PG8_BAR __builtin_amdgcn_s_barrier()
; template <class Epi, class Sched, bool ALIGN_EPI = false, bool SP2 = false>
; __device__ __forceinline__ void gemm_phase(PG8_LAS unsigned char* lds, const Gemm g, const Sched& S, const Epi& E, int tid_in) {
;     ...
;         for (int t = 0; t < nt; t += 2) {
;             const bool last = (t == nt - 2);
;             const char* a1 = cA + (size_t)(t + 1) * kstep;
;             const char* a2 = last ? nA : cA + (size_t)(t + 2) * kstep; const char* b2 = last ? nB : cB + (size_t)(t + 2) * kstep;
;             const char* a3 = a2 + kstep; const char* b3 = b2 + kstep;
;             if (last && has_next) S.a_ready(nxt);
;             if constexpr (SP2) {
;             PG8_LDB(B0, 0, 0); PG8_LDB(B1, 0, 1); PG8_SCHED; PG8_LDA(At, 0, 0); PG8_STAGE(PG8_SA(1, 1), a1 + hstep, voffA);
;             PG8_WAIT_V(8); PG8_WAIT_L(0); PG8_BAR; PG8_MMA(0, 0, At, B0); PG8_MMA(0, 1, At, B1); PG8_BAR; PG8_SCHED;
;             PG8_LDA(At, 0, 1); PG8_STAGE(PG8_SB(0, 0), b2, voffB); PG8_STAGE(PG8_SB(0, 1), b2 + hstepB, voffB); PG8_STAGE(PG8_SA(0, 0), a2, voffA);
;             PG8_WAIT_V(8); PG8_WAIT_L(0); PG8_BAR; PG8_MMA(1, 0, At, B0); PG8_MMA(1, 1, At, B1); PG8_BAR; PG8_SCHED;
.Lkb_skip_3:
	ds_read_b128 v[146:149], v153
	ds_read_b128 v[158:161], v153 offset:1024
	ds_read_b128 v[162:165], v153 offset:2048
	ds_read_b128 v[166:169], v153 offset:3072
	ds_read_b128 v[170:173], v154
	ds_read_b128 v[174:177], v154 offset:1024
	ds_read_b128 v[178:181], v154 offset:2048
	ds_read_b128 v[182:185], v154 offset:3072
	s_add_u32 s12, s56, 0x100
	s_addc_u32 s13, s57, 0
	s_cmpk_eq_i32 s79, 0x7c
	s_cselect_b32 s61, s51, s13
	s_cselect_b32 s60, s50, s12
	s_cselect_b32 s59, s49, s77
	s_cselect_b32 s58, s75, s76
	s_add_i32 m0, s55, 0xc000
	ds_read_b128 v[186:189], v155
	ds_read_b128 v[190:193], v155 offset:1024
	ds_read_b128 v[194:197], v155 offset:2048
	ds_read_b128 v[198:201], v155 offset:3072
	ds_read_b128 v[202:205], v155 offset:4096
	ds_read_b128 v[206:209], v155 offset:5120
	ds_read_b128 v[212:215], v155 offset:6144
	ds_read_b128 v[216:219], v155 offset:7168
	global_load_lds_dwordx4 v138, s[56:57]
	s_add_i32 m0, s55, 0xe000
	s_nop 0
	global_load_lds_dwordx4 v140, s[56:57]
	s_waitcnt vmcnt(8)
	s_waitcnt lgkmcnt(0)
	s_barrier
	s_waitcnt lgkmcnt(0)
	v_mfma_f32_16x16x32_bf16 v[124:127], v[146:149], v[186:189], 0
	v_mfma_f32_16x16x32_bf16 v[120:123], v[162:165], v[186:189], 0
	v_mfma_f32_16x16x32_bf16 v[108:111], v[146:149], v[194:197], 0
	v_mfma_f32_16x16x32_bf16 v[104:107], v[162:165], v[194:197], 0
	v_mfma_f32_16x16x32_bf16 v[92:95], v[146:149], v[202:205], 0
	v_mfma_f32_16x16x32_bf16 v[88:91], v[162:165], v[202:205], 0
	v_mfma_f32_16x16x32_bf16 v[76:79], v[146:149], v[212:215], 0
	v_mfma_f32_16x16x32_bf16 v[72:75], v[162:165], v[212:215], 0
	v_mfma_f32_16x16x32_bf16 v[124:127], v[158:161], v[190:193], v[124:127]
	v_mfma_f32_16x16x32_bf16 v[120:123], v[166:169], v[190:193], v[120:123]
	v_mfma_f32_16x16x32_bf16 v[108:111], v[158:161], v[198:201], v[108:111]
	v_mfma_f32_16x16x32_bf16 v[104:107], v[166:169], v[198:201], v[104:107]
	v_mfma_f32_16x16x32_bf16 v[92:95], v[158:161], v[206:209], v[92:95]
	v_mfma_f32_16x16x32_bf16 v[88:91], v[166:169], v[206:209], v[88:91]
	v_mfma_f32_16x16x32_bf16 v[76:79], v[158:161], v[216:219], v[76:79]
	v_mfma_f32_16x16x32_bf16 v[72:75], v[166:169], v[216:219], v[72:75]
	v_mfma_f32_16x16x32_bf16 v[116:119], v[170:173], v[186:189], 0
	v_mfma_f32_16x16x32_bf16 v[112:115], v[178:181], v[186:189], 0
	v_mfma_f32_16x16x32_bf16 v[100:103], v[170:173], v[194:197], 0
	v_mfma_f32_16x16x32_bf16 v[96:99], v[178:181], v[194:197], 0
	v_mfma_f32_16x16x32_bf16 v[84:87], v[170:173], v[202:205], 0
	v_mfma_f32_16x16x32_bf16 v[80:83], v[178:181], v[202:205], 0
	v_mfma_f32_16x16x32_bf16 v[68:71], v[170:173], v[212:215], 0
	v_mfma_f32_16x16x32_bf16 v[64:67], v[178:181], v[212:215], 0
	v_mfma_f32_16x16x32_bf16 v[116:119], v[174:177], v[190:193], v[116:119]
	v_mfma_f32_16x16x32_bf16 v[112:115], v[182:185], v[190:193], v[112:115]
	v_mfma_f32_16x16x32_bf16 v[100:103], v[174:177], v[198:201], v[100:103]
	v_mfma_f32_16x16x32_bf16 v[96:99], v[182:185], v[198:201], v[96:99]
	v_mfma_f32_16x16x32_bf16 v[84:87], v[174:177], v[206:209], v[84:87]
	v_mfma_f32_16x16x32_bf16 v[80:83], v[182:185], v[206:209], v[80:83]
	v_mfma_f32_16x16x32_bf16 v[68:71], v[174:177], v[216:219], v[68:71]
	v_mfma_f32_16x16x32_bf16 v[64:67], v[182:185], v[216:219], v[64:67]
	s_barrier
	s_add_i32 s26, s71, s64
	s_mov_b32 m0, s26
	ds_read_b128 v[186:189], v155 offset:16384
	ds_read_b128 v[190:193], v155 offset:17408
	ds_read_b128 v[194:197], v155 offset:18432
	ds_read_b128 v[198:201], v155 offset:19456
	ds_read_b128 v[202:205], v155 offset:20480
	ds_read_b128 v[206:209], v155 offset:21504
	ds_read_b128 v[212:215], v155 offset:22528
	ds_read_b128 v[216:219], v155 offset:23552
	global_load_lds_dwordx4 v130, s[58:59]
	s_add_i32 m0, s26, 0x2000
	s_add_u32 s26, s58, 0x80000
	s_addc_u32 s27, s59, 0
	s_add_i32 s33, s72, s64
	global_load_lds_dwordx4 v134, s[58:59]
	s_mov_b32 m0, s33
	s_nop 0
	global_load_lds_dwordx4 v130, s[26:27]
	s_add_i32 m0, s33, 0x2000
	s_nop 0
	global_load_lds_dwordx4 v134, s[26:27]
	s_mov_b32 m0, s55
	s_nop 0
	global_load_lds_dwordx4 v128, s[60:61]
	s_mov_b32 m0, s65
	s_nop 0
	global_load_lds_dwordx4 v132, s[60:61]
	s_waitcnt vmcnt(8)
	s_waitcnt lgkmcnt(0)
	s_barrier
	s_waitcnt lgkmcnt(0)
	v_mfma_f32_16x16x32_bf16 v[60:63], v[146:149], v[186:189], 0
	v_mfma_f32_16x16x32_bf16 v[56:59], v[162:165], v[186:189], 0
	v_mfma_f32_16x16x32_bf16 v[44:47], v[146:149], v[194:197], 0
	v_mfma_f32_16x16x32_bf16 v[40:43], v[162:165], v[194:197], 0
	v_mfma_f32_16x16x32_bf16 v[28:31], v[146:149], v[202:205], 0
	v_mfma_f32_16x16x32_bf16 v[24:27], v[162:165], v[202:205], 0
	v_mfma_f32_16x16x32_bf16 v[12:15], v[146:149], v[212:215], 0
	v_mfma_f32_16x16x32_bf16 v[8:11], v[162:165], v[212:215], 0
	v_mfma_f32_16x16x32_bf16 v[60:63], v[158:161], v[190:193], v[60:63]
	v_mfma_f32_16x16x32_bf16 v[56:59], v[166:169], v[190:193], v[56:59]
	v_mfma_f32_16x16x32_bf16 v[44:47], v[158:161], v[198:201], v[44:47]
	v_mfma_f32_16x16x32_bf16 v[40:43], v[166:169], v[198:201], v[40:43]
	v_mfma_f32_16x16x32_bf16 v[28:31], v[158:161], v[206:209], v[28:31]
	v_mfma_f32_16x16x32_bf16 v[24:27], v[166:169], v[206:209], v[24:27]
	v_mfma_f32_16x16x32_bf16 v[12:15], v[158:161], v[216:219], v[12:15]
	v_mfma_f32_16x16x32_bf16 v[8:11], v[166:169], v[216:219], v[8:11]
	v_mfma_f32_16x16x32_bf16 v[52:55], v[170:173], v[186:189], 0
	v_mfma_f32_16x16x32_bf16 v[48:51], v[178:181], v[186:189], 0
	v_mfma_f32_16x16x32_bf16 v[36:39], v[170:173], v[194:197], 0
	v_mfma_f32_16x16x32_bf16 v[32:35], v[178:181], v[194:197], 0
	v_mfma_f32_16x16x32_bf16 v[20:23], v[170:173], v[202:205], 0
	v_mfma_f32_16x16x32_bf16 v[16:19], v[178:181], v[202:205], 0
	v_mfma_f32_16x16x32_bf16 v[4:7], v[170:173], v[212:215], 0
	v_mfma_f32_16x16x32_bf16 v[0:3], v[178:181], v[212:215], 0
	v_mfma_f32_16x16x32_bf16 v[52:55], v[174:177], v[190:193], v[52:55]
	v_mfma_f32_16x16x32_bf16 v[48:51], v[182:185], v[190:193], v[48:51]
	v_mfma_f32_16x16x32_bf16 v[36:39], v[174:177], v[198:201], v[36:39]
	v_mfma_f32_16x16x32_bf16 v[32:35], v[182:185], v[198:201], v[32:35]
	v_mfma_f32_16x16x32_bf16 v[20:23], v[174:177], v[206:209], v[20:23]
	v_mfma_f32_16x16x32_bf16 v[16:19], v[182:185], v[206:209], v[16:19]
	v_mfma_f32_16x16x32_bf16 v[4:7], v[174:177], v[216:219], v[4:7]
	v_mfma_f32_16x16x32_bf16 v[0:3], v[182:185], v[216:219], v[0:3]
	s_barrier
; #define PG8_STAGE(bufoff, gbase, voff) do { _Pragma("unroll") for (int _i = 0; _i < 2; ++_i) \
;         __builtin_amdgcn_global_load_lds((const unsigned*)((const char*)(gbase) + (voff)[_i]), (PG8_LAS unsigned*)(lds + (bufoff) + ldsw + _i * 8192), 16, 0, 0); } while (0)
; #define PG8_LDA(dst, b, h) do { _Pragma("unroll") for (int m = 0; m < 4; ++m) _Pragma("unroll") for (int k = 0; k < 2; ++k) dst[m][k] = *(const PG8_LAS bf16x8*)(lds + PG8_SA(b, h) + aoff + m * 2048 + k * 1024); } while (0)
; #define PG8_LDB(dst, b, h) do { _Pragma("unroll") for (int n = 0; n < 2; ++n) _Pragma("unroll") for (int k = 0; k < 2; ++k) dst[n][k] = *(const PG8_LAS bf16x8*)(lds + PG8_SB(b, h) + boff + n * 2048 + k * 1024); } while (0)
; #define PG8_MMA(ai, bj, At, Bt) do { __builtin_amdgcn_s_setprio(1); _Pragma("unroll") for (int m = 0; m < 4; ++m) _Pragma("unroll") for (int n = 0; n < 2; ++n) _Pragma("unroll") for (int k = 0; k < 2; ++k) \
;         acc[ai][bj][m][n] = __builtin_amdgcn_mfma_f32_16x16x32_bf16(Bt[n][k], At[m][k], acc[ai][bj][m][n], 0, 0, 0); __builtin_amdgcn_s_setprio(0); } while (0)
; #define PG8_WAIT_V(n) asm volatile("s_waitcnt vmcnt(" #n ")" ::: "memory")
; #define PG8_WAIT_L(n) asm volatile("s_waitcnt lgkmcnt(" #n ")" ::: "memory")
; #define PG8_BAR __builtin_amdgcn_s_barrier()
; #define PG8_SCHED __builtin_amdgcn_sched_barrier(0)
; template <class Epi, class Sched, bool ALIGN_EPI = false, bool SP2 = false>
; __device__ __forceinline__ void gemm_phase(PG8_LAS unsigned char* lds, const Gemm g, const Sched& S, const Epi& E, int tid_in) {
;     ...
;             PG8_LDB(B0, 1, 0); PG8_LDB(B1, 1, 1); PG8_SCHED; PG8_LDA(At, 1, 0); PG8_STAGE(PG8_SA(0, 1), a2 + hstep, voffA);
;             PG8_WAIT_V(8); PG8_WAIT_L(0); PG8_BAR; PG8_MMA(0, 0, At, B0); PG8_MMA(0, 1, At, B1); PG8_BAR; PG8_SCHED;
;             PG8_LDA(At, 1, 1); PG8_STAGE(PG8_SB(1, 0), b3, voffB); PG8_STAGE(PG8_SB(1, 1), b3 + hstepB, voffB); PG8_STAGE(PG8_SA(1, 0), a3, voffA);
;             PG8_WAIT_V(8); PG8_WAIT_L(0); PG8_BAR; PG8_MMA(1, 0, At, B0); PG8_MMA(1, 1, At, B1); PG8_BAR; PG8_SCHED;
	s_add_i32 s33, 0, 0x18000
	s_add_i32 s56, 0, 0x1c000
	v_add_u32_e32 v166, s33, v137
	v_add_u32_e32 v182, s56, v137
	ds_read_b128 v[146:149], v166
	ds_read_b128 v[158:161], v166 offset:1024
	ds_read_b128 v[162:165], v166 offset:2048
	ds_read_b128 v[166:169], v166 offset:3072
	ds_read_b128 v[170:173], v182
	ds_read_b128 v[174:177], v182 offset:1024
	ds_read_b128 v[178:181], v182 offset:2048
	ds_read_b128 v[182:185], v182 offset:3072
	s_add_u32 s26, s60, 0x204000
	s_addc_u32 s27, s61, 0
	s_mov_b32 m0, s66
	ds_read_b128 v[186:189], v155 offset:32768
	ds_read_b128 v[190:193], v155 offset:33792
	ds_read_b128 v[194:197], v155 offset:34816
	ds_read_b128 v[198:201], v155 offset:35840
	ds_read_b128 v[202:205], v155 offset:36864
	ds_read_b128 v[206:209], v155 offset:37888
	ds_read_b128 v[212:215], v155 offset:38912
	ds_read_b128 v[216:219], v155 offset:39936
	global_load_lds_dwordx4 v128, s[26:27]
	s_mov_b32 m0, s67
	s_nop 0
	global_load_lds_dwordx4 v132, s[26:27]
	s_waitcnt vmcnt(8)
	s_waitcnt lgkmcnt(0)
	s_barrier
	s_waitcnt lgkmcnt(0)
	v_mfma_f32_16x16x32_bf16 v[124:127], v[146:149], v[186:189], v[124:127]
	v_mfma_f32_16x16x32_bf16 v[120:123], v[162:165], v[186:189], v[120:123]
	v_mfma_f32_16x16x32_bf16 v[108:111], v[146:149], v[194:197], v[108:111]
	v_mfma_f32_16x16x32_bf16 v[104:107], v[162:165], v[194:197], v[104:107]
	v_mfma_f32_16x16x32_bf16 v[92:95], v[146:149], v[202:205], v[92:95]
	v_mfma_f32_16x16x32_bf16 v[88:91], v[162:165], v[202:205], v[88:91]
	v_mfma_f32_16x16x32_bf16 v[76:79], v[146:149], v[212:215], v[76:79]
	v_mfma_f32_16x16x32_bf16 v[72:75], v[162:165], v[212:215], v[72:75]
	v_mfma_f32_16x16x32_bf16 v[124:127], v[158:161], v[190:193], v[124:127]
	v_mfma_f32_16x16x32_bf16 v[120:123], v[166:169], v[190:193], v[120:123]
	v_mfma_f32_16x16x32_bf16 v[108:111], v[158:161], v[198:201], v[108:111]
	v_mfma_f32_16x16x32_bf16 v[104:107], v[166:169], v[198:201], v[104:107]
	v_mfma_f32_16x16x32_bf16 v[92:95], v[158:161], v[206:209], v[92:95]
	v_mfma_f32_16x16x32_bf16 v[88:91], v[166:169], v[206:209], v[88:91]
	v_mfma_f32_16x16x32_bf16 v[76:79], v[158:161], v[216:219], v[76:79]
	v_mfma_f32_16x16x32_bf16 v[72:75], v[166:169], v[216:219], v[72:75]
	v_mfma_f32_16x16x32_bf16 v[116:119], v[170:173], v[186:189], v[116:119]
	v_mfma_f32_16x16x32_bf16 v[112:115], v[178:181], v[186:189], v[112:115]
	v_mfma_f32_16x16x32_bf16 v[100:103], v[170:173], v[194:197], v[100:103]
	v_mfma_f32_16x16x32_bf16 v[96:99], v[178:181], v[194:197], v[96:99]
	v_mfma_f32_16x16x32_bf16 v[84:87], v[170:173], v[202:205], v[84:87]
	v_mfma_f32_16x16x32_bf16 v[80:83], v[178:181], v[202:205], v[80:83]
	v_mfma_f32_16x16x32_bf16 v[68:71], v[170:173], v[212:215], v[68:71]
	v_mfma_f32_16x16x32_bf16 v[64:67], v[178:181], v[212:215], v[64:67]
	v_mfma_f32_16x16x32_bf16 v[116:119], v[174:177], v[190:193], v[116:119]
	v_mfma_f32_16x16x32_bf16 v[112:115], v[182:185], v[190:193], v[112:115]
	v_mfma_f32_16x16x32_bf16 v[100:103], v[174:177], v[198:201], v[100:103]
	v_mfma_f32_16x16x32_bf16 v[96:99], v[182:185], v[198:201], v[96:99]
	v_mfma_f32_16x16x32_bf16 v[84:87], v[174:177], v[206:209], v[84:87]
	v_mfma_f32_16x16x32_bf16 v[80:83], v[182:185], v[206:209], v[80:83]
	v_mfma_f32_16x16x32_bf16 v[68:71], v[174:177], v[216:219], v[68:71]
	v_mfma_f32_16x16x32_bf16 v[64:67], v[182:185], v[216:219], v[64:67]
	s_barrier
	s_add_i32 s26, s33, s64
	s_add_i32 m0, s26, 0xffffff80
	ds_read_b128 v[186:189], v155 offset:49152
	ds_read_b128 v[190:193], v155 offset:50176
	ds_read_b128 v[194:197], v155 offset:51200
	ds_read_b128 v[198:201], v155 offset:52224
	ds_read_b128 v[202:205], v155 offset:53248
	ds_read_b128 v[206:209], v155 offset:54272
	ds_read_b128 v[212:215], v155 offset:55296
	ds_read_b128 v[216:219], v155 offset:56320
	global_load_lds_dwordx4 v130, s[58:59] offset:128
	s_add_i32 m0, s26, 0x1f80
	s_add_u32 s26, s58, 0x80080
	s_addc_u32 s27, s59, 0
	s_add_i32 s33, s56, s64
	global_load_lds_dwordx4 v134, s[58:59] offset:128
	s_mov_b32 m0, s33
	s_nop 0
	global_load_lds_dwordx4 v130, s[26:27]
	s_add_i32 m0, s33, 0x2000
	s_nop 0
	global_load_lds_dwordx4 v134, s[26:27]
	s_add_i32 m0, s69, 0xffffff80
	s_nop 0
	global_load_lds_dwordx4 v128, s[60:61] offset:128
	s_add_i32 m0, s70, 0xffffff80
	s_nop 0
	global_load_lds_dwordx4 v132, s[60:61] offset:128
	s_waitcnt vmcnt(8)
	s_waitcnt lgkmcnt(0)
	s_barrier
	s_waitcnt lgkmcnt(0)
	v_mfma_f32_16x16x32_bf16 v[60:63], v[146:149], v[186:189], v[60:63]
	v_mfma_f32_16x16x32_bf16 v[56:59], v[162:165], v[186:189], v[56:59]
	v_mfma_f32_16x16x32_bf16 v[44:47], v[146:149], v[194:197], v[44:47]
	v_mfma_f32_16x16x32_bf16 v[40:43], v[162:165], v[194:197], v[40:43]
	v_mfma_f32_16x16x32_bf16 v[28:31], v[146:149], v[202:205], v[28:31]
	v_mfma_f32_16x16x32_bf16 v[24:27], v[162:165], v[202:205], v[24:27]
	v_mfma_f32_16x16x32_bf16 v[12:15], v[146:149], v[212:215], v[12:15]
	v_mfma_f32_16x16x32_bf16 v[8:11], v[162:165], v[212:215], v[8:11]
	v_mfma_f32_16x16x32_bf16 v[60:63], v[158:161], v[190:193], v[60:63]
	v_mfma_f32_16x16x32_bf16 v[56:59], v[166:169], v[190:193], v[56:59]
	v_mfma_f32_16x16x32_bf16 v[44:47], v[158:161], v[198:201], v[44:47]
	v_mfma_f32_16x16x32_bf16 v[40:43], v[166:169], v[198:201], v[40:43]
	v_mfma_f32_16x16x32_bf16 v[28:31], v[158:161], v[206:209], v[28:31]
	v_mfma_f32_16x16x32_bf16 v[24:27], v[166:169], v[206:209], v[24:27]
	v_mfma_f32_16x16x32_bf16 v[12:15], v[158:161], v[216:219], v[12:15]
	v_mfma_f32_16x16x32_bf16 v[8:11], v[166:169], v[216:219], v[8:11]
	v_mfma_f32_16x16x32_bf16 v[52:55], v[170:173], v[186:189], v[52:55]
	v_mfma_f32_16x16x32_bf16 v[48:51], v[178:181], v[186:189], v[48:51]
	v_mfma_f32_16x16x32_bf16 v[36:39], v[170:173], v[194:197], v[36:39]
	v_mfma_f32_16x16x32_bf16 v[32:35], v[178:181], v[194:197], v[32:35]
	v_mfma_f32_16x16x32_bf16 v[20:23], v[170:173], v[202:205], v[20:23]
	v_mfma_f32_16x16x32_bf16 v[16:19], v[178:181], v[202:205], v[16:19]
	v_mfma_f32_16x16x32_bf16 v[4:7], v[170:173], v[212:215], v[4:7]
	v_mfma_f32_16x16x32_bf16 v[0:3], v[178:181], v[212:215], v[0:3]
	v_mfma_f32_16x16x32_bf16 v[52:55], v[174:177], v[190:193], v[52:55]
	v_mfma_f32_16x16x32_bf16 v[48:51], v[182:185], v[190:193], v[48:51]
	v_mfma_f32_16x16x32_bf16 v[36:39], v[174:177], v[198:201], v[36:39]
	v_mfma_f32_16x16x32_bf16 v[32:35], v[182:185], v[198:201], v[32:35]
	v_mfma_f32_16x16x32_bf16 v[20:23], v[174:177], v[206:209], v[20:23]
	v_mfma_f32_16x16x32_bf16 v[16:19], v[182:185], v[206:209], v[16:19]
	v_mfma_f32_16x16x32_bf16 v[4:7], v[174:177], v[216:219], v[4:7]
	v_mfma_f32_16x16x32_bf16 v[0:3], v[182:185], v[216:219], v[0:3]
	s_barrier
	s_add_i32 s79, s79, 2
	s_add_u32 s76, s76, 0x100
	s_addc_u32 s77, s77, 0
	s_cmpk_gt_u32 s79, 0x7d
	s_mov_b64 s[56:57], s[12:13]
; #define PG8_STAGE(bufoff, gbase, voff) do { _Pragma("unroll") for (int _i = 0; _i < 2; ++_i) \
;         __builtin_amdgcn_global_load_lds((const unsigned*)((const char*)(gbase) + (voff)[_i]), (PG8_LAS unsigned*)(lds + (bufoff) + ldsw + _i * 8192), 16, 0, 0); } while (0)
; #define PG8_LDA(dst, b, h) do { _Pragma("unroll") for (int m = 0; m < 4; ++m) _Pragma("unroll") for (int k = 0; k < 2; ++k) dst[m][k] = *(const PG8_LAS bf16x8*)(lds + PG8_SA(b, h) + aoff + m * 2048 + k * 1024); } while (0)
; #define PG8_LDB(dst, b, h) do { _Pragma("unroll") for (int n = 0; n < 2; ++n) _Pragma("unroll") for (int k = 0; k < 2; ++k) dst[n][k] = *(const PG8_LAS bf16x8*)(lds + PG8_SB(b, h) + boff + n * 2048 + k * 1024); } while (0)
; #define PG8_MMA(ai, bj, At, Bt) do { __builtin_amdgcn_s_setprio(1); _Pragma("unroll") for (int m = 0; m < 4; ++m) _Pragma("unroll") for (int n = 0; n < 2; ++n) _Pragma("unroll") for (int k = 0; k < 2; ++k) \
;         acc[ai][bj][m][n] = __builtin_amdgcn_mfma_f32_16x16x32_bf16(Bt[n][k], At[m][k], acc[ai][bj][m][n], 0, 0, 0); __builtin_amdgcn_s_setprio(0); } while (0)
; #define PG8_WAIT_V(n) asm volatile("s_waitcnt vmcnt(" #n ")" ::: "memory")
; #define PG8_BAR __builtin_amdgcn_s_barrier()
; template <class Epi, class Sched, bool ALIGN_EPI = false, bool SP2 = false>
; __device__ __forceinline__ void gemm_phase(PG8_LAS unsigned char* lds, const Gemm g, const Sched& S, const Epi& E, int tid_in) {
;     ...
;         for (int t = 0; t < nt; t += 2) {
;             const bool last = (t == nt - 2);
;             const char* a1 = cA + (size_t)(t + 1) * kstep;
;             const char* a2 = last ? nA : cA + (size_t)(t + 2) * kstep; const char* b2 = last ? nB : cB + (size_t)(t + 2) * kstep;
;             const char* a3 = a2 + kstep; const char* b3 = b2 + kstep;
;             if (last && has_next) S.a_ready(nxt);
;             if constexpr (SP2) {
;             PG8_LDB(B0, 0, 0); PG8_LDB(B1, 0, 1); PG8_SCHED; PG8_LDA(At, 0, 0); PG8_STAGE(PG8_SA(1, 1), a1 + hstep, voffA);
;             PG8_WAIT_V(8); PG8_WAIT_L(0); PG8_BAR; PG8_MMA(0, 0, At, B0); PG8_MMA(0, 1, At, B1); PG8_BAR; PG8_SCHED;
;             PG8_LDA(At, 0, 1); PG8_STAGE(PG8_SB(0, 0), b2, voffB); PG8_STAGE(PG8_SB(0, 1), b2 + hstepB, voffB); PG8_STAGE(PG8_SA(0, 0), a2, voffA);
;             PG8_WAIT_V(8); PG8_WAIT_L(0); PG8_BAR; PG8_MMA(1, 0, At, B0); PG8_MMA(1, 1, At, B1); PG8_BAR; PG8_SCHED;
.LBB0_474:
	ds_read_b128 v[146:149], v153
	ds_read_b128 v[158:161], v153 offset:1024
	ds_read_b128 v[162:165], v153 offset:2048
	ds_read_b128 v[166:169], v153 offset:3072
	ds_read_b128 v[170:173], v154
	ds_read_b128 v[174:177], v154 offset:1024
	ds_read_b128 v[178:181], v154 offset:2048
	ds_read_b128 v[182:185], v154 offset:3072
	s_add_u32 s12, s56, 0x100
	s_addc_u32 s13, s57, 0
	s_cmpk_eq_i32 s79, 0x7c
	s_cselect_b32 s61, s51, s13
	s_cselect_b32 s60, s50, s12
	s_cselect_b32 s59, s49, s77
	s_cselect_b32 s58, s75, s76
	s_add_i32 m0, s55, 0xc000
	ds_read_b128 v[186:189], v155
	ds_read_b128 v[190:193], v155 offset:1024
	ds_read_b128 v[194:197], v155 offset:2048
	ds_read_b128 v[198:201], v155 offset:3072
	ds_read_b128 v[202:205], v155 offset:4096
	ds_read_b128 v[206:209], v155 offset:5120
	ds_read_b128 v[212:215], v155 offset:6144
	ds_read_b128 v[216:219], v155 offset:7168
	global_load_lds_dwordx4 v138, s[56:57]
	s_add_i32 m0, s55, 0xe000
	s_nop 0
	global_load_lds_dwordx4 v140, s[56:57]
	s_waitcnt vmcnt(8)
	s_waitcnt lgkmcnt(0)
	s_barrier
	s_waitcnt lgkmcnt(0)
	v_mfma_f32_16x16x32_bf16 v[124:127], v[146:149], v[186:189], v[124:127]
	v_mfma_f32_16x16x32_bf16 v[120:123], v[162:165], v[186:189], v[120:123]
	v_mfma_f32_16x16x32_bf16 v[108:111], v[146:149], v[194:197], v[108:111]
	v_mfma_f32_16x16x32_bf16 v[104:107], v[162:165], v[194:197], v[104:107]
	v_mfma_f32_16x16x32_bf16 v[92:95], v[146:149], v[202:205], v[92:95]
	v_mfma_f32_16x16x32_bf16 v[88:91], v[162:165], v[202:205], v[88:91]
	v_mfma_f32_16x16x32_bf16 v[76:79], v[146:149], v[212:215], v[76:79]
	v_mfma_f32_16x16x32_bf16 v[72:75], v[162:165], v[212:215], v[72:75]
	v_mfma_f32_16x16x32_bf16 v[124:127], v[158:161], v[190:193], v[124:127]
	v_mfma_f32_16x16x32_bf16 v[120:123], v[166:169], v[190:193], v[120:123]
	v_mfma_f32_16x16x32_bf16 v[108:111], v[158:161], v[198:201], v[108:111]
	v_mfma_f32_16x16x32_bf16 v[104:107], v[166:169], v[198:201], v[104:107]
	v_mfma_f32_16x16x32_bf16 v[92:95], v[158:161], v[206:209], v[92:95]
	v_mfma_f32_16x16x32_bf16 v[88:91], v[166:169], v[206:209], v[88:91]
	v_mfma_f32_16x16x32_bf16 v[76:79], v[158:161], v[216:219], v[76:79]
	v_mfma_f32_16x16x32_bf16 v[72:75], v[166:169], v[216:219], v[72:75]
	v_mfma_f32_16x16x32_bf16 v[116:119], v[170:173], v[186:189], v[116:119]
	v_mfma_f32_16x16x32_bf16 v[112:115], v[178:181], v[186:189], v[112:115]
	v_mfma_f32_16x16x32_bf16 v[100:103], v[170:173], v[194:197], v[100:103]
	v_mfma_f32_16x16x32_bf16 v[96:99], v[178:181], v[194:197], v[96:99]
	v_mfma_f32_16x16x32_bf16 v[84:87], v[170:173], v[202:205], v[84:87]
	v_mfma_f32_16x16x32_bf16 v[80:83], v[178:181], v[202:205], v[80:83]
	v_mfma_f32_16x16x32_bf16 v[68:71], v[170:173], v[212:215], v[68:71]
	v_mfma_f32_16x16x32_bf16 v[64:67], v[178:181], v[212:215], v[64:67]
	v_mfma_f32_16x16x32_bf16 v[116:119], v[174:177], v[190:193], v[116:119]
	v_mfma_f32_16x16x32_bf16 v[112:115], v[182:185], v[190:193], v[112:115]
	v_mfma_f32_16x16x32_bf16 v[100:103], v[174:177], v[198:201], v[100:103]
	v_mfma_f32_16x16x32_bf16 v[96:99], v[182:185], v[198:201], v[96:99]
	v_mfma_f32_16x16x32_bf16 v[84:87], v[174:177], v[206:209], v[84:87]
	v_mfma_f32_16x16x32_bf16 v[80:83], v[182:185], v[206:209], v[80:83]
	v_mfma_f32_16x16x32_bf16 v[68:71], v[174:177], v[216:219], v[68:71]
	v_mfma_f32_16x16x32_bf16 v[64:67], v[182:185], v[216:219], v[64:67]
	s_barrier
	s_add_i32 s26, s71, s64
	s_mov_b32 m0, s26
	ds_read_b128 v[186:189], v155 offset:16384
	ds_read_b128 v[190:193], v155 offset:17408
	ds_read_b128 v[194:197], v155 offset:18432
	ds_read_b128 v[198:201], v155 offset:19456
	ds_read_b128 v[202:205], v155 offset:20480
	ds_read_b128 v[206:209], v155 offset:21504
	ds_read_b128 v[212:215], v155 offset:22528
	ds_read_b128 v[216:219], v155 offset:23552
	global_load_lds_dwordx4 v130, s[58:59]
	s_add_i32 m0, s26, 0x2000
	s_add_u32 s26, s58, 0x80000
	s_addc_u32 s27, s59, 0
	s_add_i32 s33, s72, s64
	global_load_lds_dwordx4 v134, s[58:59]
	s_mov_b32 m0, s33
	s_nop 0
	global_load_lds_dwordx4 v130, s[26:27]
	s_add_i32 m0, s33, 0x2000
	s_nop 0
	global_load_lds_dwordx4 v134, s[26:27]
	s_mov_b32 m0, s55
	s_nop 0
	global_load_lds_dwordx4 v128, s[60:61]
	s_mov_b32 m0, s65
	s_nop 0
	global_load_lds_dwordx4 v132, s[60:61]
	s_waitcnt vmcnt(8)
	s_waitcnt lgkmcnt(0)
	s_barrier
	s_waitcnt lgkmcnt(0)
	v_mfma_f32_16x16x32_bf16 v[60:63], v[146:149], v[186:189], v[60:63]
	v_mfma_f32_16x16x32_bf16 v[56:59], v[162:165], v[186:189], v[56:59]
	v_mfma_f32_16x16x32_bf16 v[44:47], v[146:149], v[194:197], v[44:47]
	v_mfma_f32_16x16x32_bf16 v[40:43], v[162:165], v[194:197], v[40:43]
	v_mfma_f32_16x16x32_bf16 v[28:31], v[146:149], v[202:205], v[28:31]
	v_mfma_f32_16x16x32_bf16 v[24:27], v[162:165], v[202:205], v[24:27]
	v_mfma_f32_16x16x32_bf16 v[12:15], v[146:149], v[212:215], v[12:15]
	v_mfma_f32_16x16x32_bf16 v[8:11], v[162:165], v[212:215], v[8:11]
	v_mfma_f32_16x16x32_bf16 v[60:63], v[158:161], v[190:193], v[60:63]
	v_mfma_f32_16x16x32_bf16 v[56:59], v[166:169], v[190:193], v[56:59]
	v_mfma_f32_16x16x32_bf16 v[44:47], v[158:161], v[198:201], v[44:47]
	v_mfma_f32_16x16x32_bf16 v[40:43], v[166:169], v[198:201], v[40:43]
	v_mfma_f32_16x16x32_bf16 v[28:31], v[158:161], v[206:209], v[28:31]
	v_mfma_f32_16x16x32_bf16 v[24:27], v[166:169], v[206:209], v[24:27]
	v_mfma_f32_16x16x32_bf16 v[12:15], v[158:161], v[216:219], v[12:15]
	v_mfma_f32_16x16x32_bf16 v[8:11], v[166:169], v[216:219], v[8:11]
	v_mfma_f32_16x16x32_bf16 v[52:55], v[170:173], v[186:189], v[52:55]
	v_mfma_f32_16x16x32_bf16 v[48:51], v[178:181], v[186:189], v[48:51]
	v_mfma_f32_16x16x32_bf16 v[36:39], v[170:173], v[194:197], v[36:39]
	v_mfma_f32_16x16x32_bf16 v[32:35], v[178:181], v[194:197], v[32:35]
	v_mfma_f32_16x16x32_bf16 v[20:23], v[170:173], v[202:205], v[20:23]
	v_mfma_f32_16x16x32_bf16 v[16:19], v[178:181], v[202:205], v[16:19]
	v_mfma_f32_16x16x32_bf16 v[4:7], v[170:173], v[212:215], v[4:7]
	v_mfma_f32_16x16x32_bf16 v[0:3], v[178:181], v[212:215], v[0:3]
	v_mfma_f32_16x16x32_bf16 v[52:55], v[174:177], v[190:193], v[52:55]
	v_mfma_f32_16x16x32_bf16 v[48:51], v[182:185], v[190:193], v[48:51]
	v_mfma_f32_16x16x32_bf16 v[36:39], v[174:177], v[198:201], v[36:39]
	v_mfma_f32_16x16x32_bf16 v[32:35], v[182:185], v[198:201], v[32:35]
	v_mfma_f32_16x16x32_bf16 v[20:23], v[174:177], v[206:209], v[20:23]
	v_mfma_f32_16x16x32_bf16 v[16:19], v[182:185], v[206:209], v[16:19]
	v_mfma_f32_16x16x32_bf16 v[4:7], v[174:177], v[216:219], v[4:7]
	v_mfma_f32_16x16x32_bf16 v[0:3], v[182:185], v[216:219], v[0:3]
	s_barrier
; #define PG8_STAGE(bufoff, gbase, voff) do { _Pragma("unroll") for (int _i = 0; _i < 2; ++_i) \
;         __builtin_amdgcn_global_load_lds((const unsigned*)((const char*)(gbase) + (voff)[_i]), (PG8_LAS unsigned*)(lds + (bufoff) + ldsw + _i * 8192), 16, 0, 0); } while (0)
; #define PG8_LDA(dst, b, h) do { _Pragma("unroll") for (int m = 0; m < 4; ++m) _Pragma("unroll") for (int k = 0; k < 2; ++k) dst[m][k] = *(const PG8_LAS bf16x8*)(lds + PG8_SA(b, h) + aoff + m * 2048 + k * 1024); } while (0)
; #define PG8_LDB(dst, b, h) do { _Pragma("unroll") for (int n = 0; n < 2; ++n) _Pragma("unroll") for (int k = 0; k < 2; ++k) dst[n][k] = *(const PG8_LAS bf16x8*)(lds + PG8_SB(b, h) + boff + n * 2048 + k * 1024); } while (0)
; #define PG8_MMA(ai, bj, At, Bt) do { __builtin_amdgcn_s_setprio(1); _Pragma("unroll") for (int m = 0; m < 4; ++m) _Pragma("unroll") for (int n = 0; n < 2; ++n) _Pragma("unroll") for (int k = 0; k < 2; ++k) \
;         acc[ai][bj][m][n] = __builtin_amdgcn_mfma_f32_16x16x32_bf16(Bt[n][k], At[m][k], acc[ai][bj][m][n], 0, 0, 0); __builtin_amdgcn_s_setprio(0); } while (0)
; #define PG8_WAIT_V(n) asm volatile("s_waitcnt vmcnt(" #n ")" ::: "memory")
; #define PG8_WAIT_L(n) asm volatile("s_waitcnt lgkmcnt(" #n ")" ::: "memory")
; #define PG8_BAR __builtin_amdgcn_s_barrier()
; #define PG8_SCHED __builtin_amdgcn_sched_barrier(0)
; template <class Epi, class Sched, bool ALIGN_EPI = false, bool SP2 = false>
; __device__ __forceinline__ void gemm_phase(PG8_LAS unsigned char* lds, const Gemm g, const Sched& S, const Epi& E, int tid_in) {
;     ...
;             PG8_LDB(B0, 1, 0); PG8_LDB(B1, 1, 1); PG8_SCHED; PG8_LDA(At, 1, 0); PG8_STAGE(PG8_SA(0, 1), a2 + hstep, voffA);
;             PG8_WAIT_V(8); PG8_WAIT_L(0); PG8_BAR; PG8_MMA(0, 0, At, B0); PG8_MMA(0, 1, At, B1); PG8_BAR; PG8_SCHED;
;             PG8_LDA(At, 1, 1); PG8_STAGE(PG8_SB(1, 0), b3, voffB); PG8_STAGE(PG8_SB(1, 1), b3 + hstepB, voffB); PG8_STAGE(PG8_SA(1, 0), a3, voffA);
	s_add_i32 s33, 0, 0x18000
	s_add_i32 s56, 0, 0x1c000
	v_add_u32_e32 v166, s33, v137
	v_add_u32_e32 v182, s56, v137
	ds_read_b128 v[146:149], v166
	ds_read_b128 v[158:161], v166 offset:1024
	ds_read_b128 v[162:165], v166 offset:2048
	ds_read_b128 v[166:169], v166 offset:3072
	ds_read_b128 v[170:173], v182
	ds_read_b128 v[174:177], v182 offset:1024
	ds_read_b128 v[178:181], v182 offset:2048
	ds_read_b128 v[182:185], v182 offset:3072
	s_add_u32 s26, s60, 0x204000
	s_addc_u32 s27, s61, 0
	s_mov_b32 m0, s66
	ds_read_b128 v[186:189], v155 offset:32768
	ds_read_b128 v[190:193], v155 offset:33792
	ds_read_b128 v[194:197], v155 offset:34816
	ds_read_b128 v[198:201], v155 offset:35840
	ds_read_b128 v[202:205], v155 offset:36864
	ds_read_b128 v[206:209], v155 offset:37888
	ds_read_b128 v[212:215], v155 offset:38912
	ds_read_b128 v[216:219], v155 offset:39936
	global_load_lds_dwordx4 v128, s[26:27]
	s_mov_b32 m0, s67
	s_nop 0
	global_load_lds_dwordx4 v132, s[26:27]
	s_waitcnt vmcnt(8)
	s_waitcnt lgkmcnt(0)
	s_barrier
	s_waitcnt lgkmcnt(0)
	v_mfma_f32_16x16x32_bf16 v[124:127], v[146:149], v[186:189], v[124:127]
	v_mfma_f32_16x16x32_bf16 v[120:123], v[162:165], v[186:189], v[120:123]
	v_mfma_f32_16x16x32_bf16 v[108:111], v[146:149], v[194:197], v[108:111]
	v_mfma_f32_16x16x32_bf16 v[104:107], v[162:165], v[194:197], v[104:107]
	v_mfma_f32_16x16x32_bf16 v[92:95], v[146:149], v[202:205], v[92:95]
	v_mfma_f32_16x16x32_bf16 v[88:91], v[162:165], v[202:205], v[88:91]
	v_mfma_f32_16x16x32_bf16 v[76:79], v[146:149], v[212:215], v[76:79]
	v_mfma_f32_16x16x32_bf16 v[72:75], v[162:165], v[212:215], v[72:75]
	v_mfma_f32_16x16x32_bf16 v[124:127], v[158:161], v[190:193], v[124:127]
	v_mfma_f32_16x16x32_bf16 v[120:123], v[166:169], v[190:193], v[120:123]
	v_mfma_f32_16x16x32_bf16 v[108:111], v[158:161], v[198:201], v[108:111]
	v_mfma_f32_16x16x32_bf16 v[104:107], v[166:169], v[198:201], v[104:107]
	v_mfma_f32_16x16x32_bf16 v[92:95], v[158:161], v[206:209], v[92:95]
	v_mfma_f32_16x16x32_bf16 v[88:91], v[166:169], v[206:209], v[88:91]
	v_mfma_f32_16x16x32_bf16 v[76:79], v[158:161], v[216:219], v[76:79]
	v_mfma_f32_16x16x32_bf16 v[72:75], v[166:169], v[216:219], v[72:75]
	v_mfma_f32_16x16x32_bf16 v[116:119], v[170:173], v[186:189], v[116:119]
	v_mfma_f32_16x16x32_bf16 v[112:115], v[178:181], v[186:189], v[112:115]
	v_mfma_f32_16x16x32_bf16 v[100:103], v[170:173], v[194:197], v[100:103]
	v_mfma_f32_16x16x32_bf16 v[96:99], v[178:181], v[194:197], v[96:99]
	v_mfma_f32_16x16x32_bf16 v[84:87], v[170:173], v[202:205], v[84:87]
	v_mfma_f32_16x16x32_bf16 v[80:83], v[178:181], v[202:205], v[80:83]
	v_mfma_f32_16x16x32_bf16 v[68:71], v[170:173], v[212:215], v[68:71]
	v_mfma_f32_16x16x32_bf16 v[64:67], v[178:181], v[212:215], v[64:67]
	v_mfma_f32_16x16x32_bf16 v[116:119], v[174:177], v[190:193], v[116:119]
	v_mfma_f32_16x16x32_bf16 v[112:115], v[182:185], v[190:193], v[112:115]
	v_mfma_f32_16x16x32_bf16 v[100:103], v[174:177], v[198:201], v[100:103]
	v_mfma_f32_16x16x32_bf16 v[96:99], v[182:185], v[198:201], v[96:99]
	v_mfma_f32_16x16x32_bf16 v[84:87], v[174:177], v[206:209], v[84:87]
	v_mfma_f32_16x16x32_bf16 v[80:83], v[182:185], v[206:209], v[80:83]
	v_mfma_f32_16x16x32_bf16 v[68:71], v[174:177], v[216:219], v[68:71]
	v_mfma_f32_16x16x32_bf16 v[64:67], v[182:185], v[216:219], v[64:67]
	s_barrier
	s_add_i32 s26, s33, s64
	s_add_i32 m0, s26, 0xffffff80
	ds_read_b128 v[186:189], v155 offset:49152
	ds_read_b128 v[190:193], v155 offset:50176
	ds_read_b128 v[194:197], v155 offset:51200
	ds_read_b128 v[198:201], v155 offset:52224
	ds_read_b128 v[202:205], v155 offset:53248
	ds_read_b128 v[206:209], v155 offset:54272
	ds_read_b128 v[212:215], v155 offset:55296
	ds_read_b128 v[216:219], v155 offset:56320
	global_load_lds_dwordx4 v130, s[58:59] offset:128
	s_add_i32 m0, s26, 0x1f80
	s_add_u32 s26, s58, 0x80080
	s_addc_u32 s27, s59, 0
	s_add_i32 s33, s56, s64
	global_load_lds_dwordx4 v134, s[58:59] offset:128
	s_mov_b32 m0, s33
	s_nop 0
	global_load_lds_dwordx4 v130, s[26:27]
	s_add_i32 m0, s33, 0x2000
	s_nop 0
	global_load_lds_dwordx4 v134, s[26:27]
	s_add_i32 m0, s69, 0xffffff80
	s_nop 0
	global_load_lds_dwordx4 v128, s[60:61] offset:128
	s_add_i32 m0, s70, 0xffffff80
	s_nop 0
	global_load_lds_dwordx4 v132, s[60:61] offset:128
	s_waitcnt vmcnt(8)
	s_waitcnt lgkmcnt(0)
	s_barrier
; #define PG8_BAR __builtin_amdgcn_s_barrier()
; template <class Epi, class Sched, bool ALIGN_EPI = false, bool SP2 = false>
; __device__ __forceinline__ void gemm_phase(PG8_LAS unsigned char* lds, const Gemm g, const Sched& S, const Epi& E, int tid_in) {
;     ...
;             PG8_WAIT_V(8); PG8_WAIT_L(0); PG8_BAR; PG8_MMA(1, 0, At, B0); PG8_MMA(1, 1, At, B1); PG8_BAR; PG8_SCHED;
;             } else {
;             PG8_LDB(B0, 0, 0); PG8_SCHED; PG8_LDA(At, 0, 0); PG8_STAGE(PG8_SA(1, 1), a1 + hstep, voffA);
;             PG8_WAIT_L(8); PG8_BAR; PG8_WAIT_L(0); PG8_MMA(0, 0, At, B0); PG8_BAR; PG8_SCHED;
;             PG8_LDB(B1, 0, 1); PG8_STAGE(PG8_SB(0, 0), b2, voffB);
;             PG8_BAR; PG8_WAIT_L(0); PG8_MMA(0, 1, At, B1); PG8_BAR;
;             PG8_LDA(At, 0, 1); PG8_STAGE(PG8_SA(0, 0), a2, voffA);
;             PG8_BAR; PG8_WAIT_L(0); PG8_MMA(1, 0, At, B0); PG8_BAR; PG8_SCHED;
;             PG8_STAGE(PG8_SB(0, 1), b2 + hstepB, voffB);
;             PG8_WAIT_V(6); PG8_BAR; PG8_MMA(1, 1, At, B1); PG8_BAR;
;             PG8_LDB(B0, 1, 0); PG8_SCHED; PG8_LDA(At, 1, 0); PG8_STAGE(PG8_SA(0, 1), a2 + hstep, voffA);
;             PG8_WAIT_L(8); PG8_BAR; PG8_WAIT_L(0); PG8_MMA(0, 0, At, B0); PG8_BAR; PG8_SCHED;
;             PG8_LDB(B1, 1, 1); PG8_STAGE(PG8_SB(1, 0), b3, voffB);
;             PG8_BAR; PG8_WAIT_L(0); PG8_MMA(0, 1, At, B1); PG8_BAR;
;             PG8_LDA(At, 1, 1); PG8_STAGE(PG8_SA(1, 0), a3, voffA);
;             PG8_BAR; PG8_WAIT_L(0); PG8_MMA(1, 0, At, B0); PG8_BAR; PG8_SCHED;
;             PG8_STAGE(PG8_SB(1, 1), b3 + hstepB, voffB);
;             PG8_WAIT_V(6); PG8_BAR; PG8_MMA(1, 1, At, B1); PG8_BAR;
;             }
;         }
;         if constexpr (ALIGN_EPI) { if (wr == 0) PG8_BAR; }
;     __device__ __forceinline__ void operator()(const f32x4 (&acc)[2][2][4][2], const Unit& u, int wr, int wc, int fr, int fq) const {
;     ...
;                 const int row = u.pm * BM + ai * HALF + wr * 64 + m * 16 + r; float q = 0.f;
; #pragma unroll
;                 for (int bj = 0; bj < 2; ++bj) {
;                     const size_t off = (size_t)row * 2048 + u.pn * BM + wc * 64 + bj * 32 + 8 * p;
;                     f32x4 b0, b1;
;                     if (BASE_F32) { b0 = *(const f32x4*)((const float*)base + off); b1 = *(const f32x4*)((const float*)base + off + 4); }
;                     else { const u32x4 bb = *(const u32x4*)((const bf16_t*)base + off);
	s_waitcnt lgkmcnt(0)
	v_mfma_f32_16x16x32_bf16 v[60:63], v[146:149], v[186:189], v[60:63]
	v_mfma_f32_16x16x32_bf16 v[56:59], v[162:165], v[186:189], v[56:59]
	v_mfma_f32_16x16x32_bf16 v[44:47], v[146:149], v[194:197], v[44:47]
	v_mfma_f32_16x16x32_bf16 v[40:43], v[162:165], v[194:197], v[40:43]
	v_mfma_f32_16x16x32_bf16 v[28:31], v[146:149], v[202:205], v[28:31]
	v_mfma_f32_16x16x32_bf16 v[24:27], v[162:165], v[202:205], v[24:27]
	v_mfma_f32_16x16x32_bf16 v[12:15], v[146:149], v[212:215], v[12:15]
	v_mfma_f32_16x16x32_bf16 v[8:11], v[162:165], v[212:215], v[8:11]
	v_mfma_f32_16x16x32_bf16 v[60:63], v[158:161], v[190:193], v[60:63]
	v_mfma_f32_16x16x32_bf16 v[56:59], v[166:169], v[190:193], v[56:59]
	v_mfma_f32_16x16x32_bf16 v[44:47], v[158:161], v[198:201], v[44:47]
	v_mfma_f32_16x16x32_bf16 v[40:43], v[166:169], v[198:201], v[40:43]
	v_mfma_f32_16x16x32_bf16 v[28:31], v[158:161], v[206:209], v[28:31]
	v_mfma_f32_16x16x32_bf16 v[24:27], v[166:169], v[206:209], v[24:27]
	v_mfma_f32_16x16x32_bf16 v[12:15], v[158:161], v[216:219], v[12:15]
	v_mfma_f32_16x16x32_bf16 v[8:11], v[166:169], v[216:219], v[8:11]
	v_mfma_f32_16x16x32_bf16 v[52:55], v[170:173], v[186:189], v[52:55]
	v_mfma_f32_16x16x32_bf16 v[48:51], v[178:181], v[186:189], v[48:51]
	v_mfma_f32_16x16x32_bf16 v[36:39], v[170:173], v[194:197], v[36:39]
	v_mfma_f32_16x16x32_bf16 v[32:35], v[178:181], v[194:197], v[32:35]
	v_mfma_f32_16x16x32_bf16 v[20:23], v[170:173], v[202:205], v[20:23]
	v_mfma_f32_16x16x32_bf16 v[16:19], v[178:181], v[202:205], v[16:19]
	v_mfma_f32_16x16x32_bf16 v[4:7], v[170:173], v[212:215], v[4:7]
	v_mfma_f32_16x16x32_bf16 v[0:3], v[178:181], v[212:215], v[0:3]
	v_mfma_f32_16x16x32_bf16 v[52:55], v[174:177], v[190:193], v[52:55]
	v_mfma_f32_16x16x32_bf16 v[48:51], v[182:185], v[190:193], v[48:51]
	v_mfma_f32_16x16x32_bf16 v[36:39], v[174:177], v[198:201], v[36:39]
	v_mfma_f32_16x16x32_bf16 v[32:35], v[182:185], v[198:201], v[32:35]
	v_mfma_f32_16x16x32_bf16 v[20:23], v[174:177], v[206:209], v[20:23]
	v_mfma_f32_16x16x32_bf16 v[16:19], v[182:185], v[206:209], v[16:19]
	v_mfma_f32_16x16x32_bf16 v[4:7], v[174:177], v[216:219], v[4:7]
	v_mfma_f32_16x16x32_bf16 v[0:3], v[182:185], v[216:219], v[0:3]
	s_barrier
	s_add_i32 s79, s79, 2
	s_add_u32 s76, s76, 0x100
	s_addc_u32 s77, s77, 0
	s_cmpk_gt_u32 s79, 0x7d
	s_mov_b64 s[56:57], s[12:13]
	s_cbranch_scc0 .LBB0_474
	v_lshl_add_u32 v148, s74, 8, v150
	v_lshl_or_b32 v146, s54, 8, v136
	v_lshl_add_u32 v147, v148, 11, v146
	v_lshlrev_b32_e32 v159, 1, v147
	v_lshlrev_b32_e32 v208, 3, v148
	global_load_dwordx4 v[160:163], v159, s[38:39]
	global_load_dwordx4 v[164:167], v159, s[38:39] offset:64
	v_add_u32_e32 v149, 0x10000, v159
	global_load_dwordx4 v[168:171], v149, s[38:39]
	global_load_dwordx4 v[172:175], v149, s[38:39] offset:64
	v_add_u32_e32 v209, 0x20000, v159
	global_load_dwordx4 v[176:179], v209, s[38:39]
	global_load_dwordx4 v[180:183], v209, s[38:39] offset:64
	v_add_u32_e32 v149, 0x30000, v159
	global_load_dwordx4 v[184:187], v149, s[38:39]
	global_load_dwordx4 v[188:191], v149, s[38:39] offset:64
	v_add_u32_e32 v209, 0x80000, v159
	global_load_dwordx4 v[192:195], v209, s[38:39]
	global_load_dwordx4 v[196:199], v209, s[38:39] offset:64
	v_add_u32_e32 v149, 0x90000, v159
	global_load_dwordx4 v[200:203], v149, s[38:39]
	global_load_dwordx4 v[204:207], v149, s[38:39] offset:64
	v_add_u32_e32 v209, 0xa0000, v159
	global_load_dwordx4 v[212:215], v209, s[38:39]
	global_load_dwordx4 v[216:219], v209, s[38:39] offset:64
	v_add_u32_e32 v149, 0xb0000, v159
	global_load_dwordx4 v[220:223], v149, s[38:39]
	global_load_dwordx4 v[224:227], v149, s[38:39] offset:64
	s_and_b64 vcc, exec, s[46:47]
	s_cbranch_vccz .LBB0_477
	s_barrier

; #define PG8_STAGE(bufoff, gbase, voff) do { _Pragma("unroll") for (int _i = 0; _i < 2; ++_i) \
;         __builtin_amdgcn_global_load_lds((const unsigned*)((const char*)(gbase) + (voff)[_i]), (PG8_LAS unsigned*)(lds + (bufoff) + ldsw + _i * 8192), 16, 0, 0); } while (0)
; #define PG8_LDA(dst, b, h) do { _Pragma("unroll") for (int m = 0; m < 4; ++m) _Pragma("unroll") for (int k = 0; k < 2; ++k) dst[m][k] = *(const PG8_LAS bf16x8*)(lds + PG8_SA(b, h) + aoff + m * 2048 + k * 1024); } while (0)
; #define PG8_LDB(dst, b, h) do { _Pragma("unroll") for (int n = 0; n < 2; ++n) _Pragma("unroll") for (int k = 0; k < 2; ++k) dst[n][k] = *(const PG8_LAS bf16x8*)(lds + PG8_SB(b, h) + boff + n * 2048 + k * 1024); } while (0)
; #define PG8_MMA(ai, bj, At, Bt) do { __builtin_amdgcn_s_setprio(1); _Pragma("unroll") for (int m = 0; m < 4; ++m) _Pragma("unroll") for (int n = 0; n < 2; ++n) _Pragma("unroll") for (int k = 0; k < 2; ++k) \
;         acc[ai][bj][m][n] = __builtin_amdgcn_mfma_f32_16x16x32_bf16(Bt[n][k], At[m][k], acc[ai][bj][m][n], 0, 0, 0); __builtin_amdgcn_s_setprio(0); } while (0)
; #define PG8_WAIT_V(n) asm volatile("s_waitcnt vmcnt(" #n ")" ::: "memory")
; #define PG8_WAIT_L(n) asm volatile("s_waitcnt lgkmcnt(" #n ")" ::: "memory")
; #define PG8_BAR __builtin_amdgcn_s_barrier()
; #define PG8_SCHED __builtin_amdgcn_sched_barrier(0)
; template <class Epi, class Sched, bool ALIGN_EPI = false, bool SP2 = false>
; __device__ __forceinline__ void gemm_phase(PG8_LAS unsigned char* lds, const Gemm g, const Sched& S, const Epi& E, int tid_in) {
;     ...
;             PG8_LDB(B0, 0, 0); PG8_LDB(B1, 0, 1); PG8_SCHED; PG8_LDA(At, 0, 0); PG8_STAGE(PG8_SA(1, 1), a1 + hstep, voffA);
;             PG8_WAIT_V(8); PG8_WAIT_L(0); PG8_BAR; PG8_MMA(0, 0, At, B0); PG8_MMA(0, 1, At, B1); PG8_BAR; PG8_SCHED;
;             PG8_LDA(At, 0, 1); PG8_STAGE(PG8_SB(0, 0), b2, voffB); PG8_STAGE(PG8_SB(0, 1), b2 + hstepB, voffB); PG8_STAGE(PG8_SA(0, 0), a2, voffA);
;             PG8_WAIT_V(8); PG8_WAIT_L(0); PG8_BAR; PG8_MMA(1, 0, At, B0); PG8_MMA(1, 1, At, B1); PG8_BAR; PG8_SCHED;
.Lkb_skip_4:
	ds_read_b128 v[128:131], v171
	ds_read_b128 v[132:135], v171 offset:1024
	ds_read_b128 v[136:139], v171 offset:2048
	ds_read_b128 v[184:187], v171 offset:3072
	ds_read_b128 v[188:191], v172
	ds_read_b128 v[192:195], v172 offset:1024
	ds_read_b128 v[196:199], v172 offset:2048
	ds_read_b128 v[200:203], v172 offset:3072
	s_add_u32 s26, s60, 0xfff80080
	s_addc_u32 s27, s61, -1
	s_cmp_eq_u32 s88, 28
	s_cselect_b32 s65, s11, s27
	s_cselect_b32 s64, s53, s26
	s_cselect_b32 s63, s51, s87
	s_cselect_b32 s62, s85, s86
	s_add_i32 m0, s59, 0xc000
	ds_read_b128 v[204:207], v173
	ds_read_b128 v[212:215], v173 offset:1024
	ds_read_b128 v[216:219], v173 offset:2048
	ds_read_b128 v[220:223], v173 offset:3072
	ds_read_b128 v[224:227], v173 offset:4096
	ds_read_b128 v[228:231], v173 offset:5120
	ds_read_b128 v[232:235], v173 offset:6144
	ds_read_b128 v[236:239], v173 offset:7168
	global_load_lds_dwordx4 v158, s[60:61]
	s_add_i32 m0, s59, 0xe000
	s_nop 0
	global_load_lds_dwordx4 v160, s[60:61]
	s_waitcnt vmcnt(8)
	s_waitcnt lgkmcnt(0)
	s_barrier
	s_waitcnt lgkmcnt(0)
	v_mfma_f32_16x16x32_bf16 v[124:127], v[128:131], v[204:207], 0
	v_mfma_f32_16x16x32_bf16 v[120:123], v[136:139], v[204:207], 0
	v_mfma_f32_16x16x32_bf16 v[108:111], v[128:131], v[216:219], 0
	v_mfma_f32_16x16x32_bf16 v[104:107], v[136:139], v[216:219], 0
	v_mfma_f32_16x16x32_bf16 v[92:95], v[128:131], v[224:227], 0
	v_mfma_f32_16x16x32_bf16 v[88:91], v[136:139], v[224:227], 0
	v_mfma_f32_16x16x32_bf16 v[76:79], v[128:131], v[232:235], 0
	v_mfma_f32_16x16x32_bf16 v[72:75], v[136:139], v[232:235], 0
	v_mfma_f32_16x16x32_bf16 v[124:127], v[132:135], v[212:215], v[124:127]
	v_mfma_f32_16x16x32_bf16 v[120:123], v[184:187], v[212:215], v[120:123]
	v_mfma_f32_16x16x32_bf16 v[108:111], v[132:135], v[220:223], v[108:111]
	v_mfma_f32_16x16x32_bf16 v[104:107], v[184:187], v[220:223], v[104:107]
	v_mfma_f32_16x16x32_bf16 v[92:95], v[132:135], v[228:231], v[92:95]
	v_mfma_f32_16x16x32_bf16 v[88:91], v[184:187], v[228:231], v[88:91]
	v_mfma_f32_16x16x32_bf16 v[76:79], v[132:135], v[236:239], v[76:79]
	v_mfma_f32_16x16x32_bf16 v[72:75], v[184:187], v[236:239], v[72:75]
	v_mfma_f32_16x16x32_bf16 v[116:119], v[188:191], v[204:207], 0
	v_mfma_f32_16x16x32_bf16 v[112:115], v[196:199], v[204:207], 0
	v_mfma_f32_16x16x32_bf16 v[100:103], v[188:191], v[216:219], 0
	v_mfma_f32_16x16x32_bf16 v[96:99], v[196:199], v[216:219], 0
	v_mfma_f32_16x16x32_bf16 v[84:87], v[188:191], v[224:227], 0
	v_mfma_f32_16x16x32_bf16 v[80:83], v[196:199], v[224:227], 0
	v_mfma_f32_16x16x32_bf16 v[68:71], v[188:191], v[232:235], 0
	v_mfma_f32_16x16x32_bf16 v[64:67], v[196:199], v[232:235], 0
	v_mfma_f32_16x16x32_bf16 v[116:119], v[192:195], v[212:215], v[116:119]
	v_mfma_f32_16x16x32_bf16 v[112:115], v[200:203], v[212:215], v[112:115]
	v_mfma_f32_16x16x32_bf16 v[100:103], v[192:195], v[220:223], v[100:103]
	v_mfma_f32_16x16x32_bf16 v[96:99], v[200:203], v[220:223], v[96:99]
	v_mfma_f32_16x16x32_bf16 v[84:87], v[192:195], v[228:231], v[84:87]
	v_mfma_f32_16x16x32_bf16 v[80:83], v[200:203], v[228:231], v[80:83]
	v_mfma_f32_16x16x32_bf16 v[68:71], v[192:195], v[236:239], v[68:71]
	v_mfma_f32_16x16x32_bf16 v[64:67], v[200:203], v[236:239], v[64:67]
	s_barrier
	s_add_i32 s26, s78, s68
	s_mov_b32 m0, s26
	ds_read_b128 v[204:207], v173 offset:16384
	ds_read_b128 v[212:215], v173 offset:17408
	ds_read_b128 v[216:219], v173 offset:18432
	ds_read_b128 v[220:223], v173 offset:19456
	ds_read_b128 v[224:227], v173 offset:20480
	ds_read_b128 v[228:231], v173 offset:21504
	ds_read_b128 v[232:235], v173 offset:22528
	ds_read_b128 v[236:239], v173 offset:23552
	global_load_lds_dwordx4 v144, s[62:63]
	s_add_i32 m0, s26, 0x2000
	s_add_u32 s26, s62, 0x20000
	s_addc_u32 s27, s63, 0
	s_add_i32 s33, s79, s68
	global_load_lds_dwordx4 v148, s[62:63]
	s_mov_b32 m0, s33
	s_nop 0
	global_load_lds_dwordx4 v144, s[26:27]
	s_add_i32 m0, s33, 0x2000
	s_nop 0
	global_load_lds_dwordx4 v148, s[26:27]
	s_mov_b32 m0, s59
	s_nop 0
	global_load_lds_dwordx4 v142, s[64:65]
	s_mov_b32 m0, s69
	s_nop 0
	global_load_lds_dwordx4 v146, s[64:65]
	s_waitcnt vmcnt(8)
	s_waitcnt lgkmcnt(0)
	s_barrier
	s_waitcnt lgkmcnt(0)
	v_mfma_f32_16x16x32_bf16 v[60:63], v[128:131], v[204:207], 0
	v_mfma_f32_16x16x32_bf16 v[56:59], v[136:139], v[204:207], 0
	v_mfma_f32_16x16x32_bf16 v[44:47], v[128:131], v[216:219], 0
	v_mfma_f32_16x16x32_bf16 v[40:43], v[136:139], v[216:219], 0
	v_mfma_f32_16x16x32_bf16 v[28:31], v[128:131], v[224:227], 0
	v_mfma_f32_16x16x32_bf16 v[24:27], v[136:139], v[224:227], 0
	v_mfma_f32_16x16x32_bf16 v[12:15], v[128:131], v[232:235], 0
	v_mfma_f32_16x16x32_bf16 v[8:11], v[136:139], v[232:235], 0
	v_mfma_f32_16x16x32_bf16 v[60:63], v[132:135], v[212:215], v[60:63]
	v_mfma_f32_16x16x32_bf16 v[56:59], v[184:187], v[212:215], v[56:59]
	v_mfma_f32_16x16x32_bf16 v[44:47], v[132:135], v[220:223], v[44:47]
	v_mfma_f32_16x16x32_bf16 v[40:43], v[184:187], v[220:223], v[40:43]
	v_mfma_f32_16x16x32_bf16 v[28:31], v[132:135], v[228:231], v[28:31]
	v_mfma_f32_16x16x32_bf16 v[24:27], v[184:187], v[228:231], v[24:27]
	v_mfma_f32_16x16x32_bf16 v[12:15], v[132:135], v[236:239], v[12:15]
	v_mfma_f32_16x16x32_bf16 v[8:11], v[184:187], v[236:239], v[8:11]
	v_mfma_f32_16x16x32_bf16 v[52:55], v[188:191], v[204:207], 0
	v_mfma_f32_16x16x32_bf16 v[48:51], v[196:199], v[204:207], 0
	v_mfma_f32_16x16x32_bf16 v[36:39], v[188:191], v[216:219], 0
	v_mfma_f32_16x16x32_bf16 v[32:35], v[196:199], v[216:219], 0
	v_mfma_f32_16x16x32_bf16 v[20:23], v[188:191], v[224:227], 0
	v_mfma_f32_16x16x32_bf16 v[16:19], v[196:199], v[224:227], 0
	v_mfma_f32_16x16x32_bf16 v[4:7], v[188:191], v[232:235], 0
	v_mfma_f32_16x16x32_bf16 v[0:3], v[196:199], v[232:235], 0
	v_mfma_f32_16x16x32_bf16 v[52:55], v[192:195], v[212:215], v[52:55]
	v_mfma_f32_16x16x32_bf16 v[48:51], v[200:203], v[212:215], v[48:51]
	v_mfma_f32_16x16x32_bf16 v[36:39], v[192:195], v[220:223], v[36:39]
	v_mfma_f32_16x16x32_bf16 v[32:35], v[200:203], v[220:223], v[32:35]
	v_mfma_f32_16x16x32_bf16 v[20:23], v[192:195], v[228:231], v[20:23]
	v_mfma_f32_16x16x32_bf16 v[16:19], v[200:203], v[228:231], v[16:19]
	v_mfma_f32_16x16x32_bf16 v[4:7], v[192:195], v[236:239], v[4:7]
	v_mfma_f32_16x16x32_bf16 v[0:3], v[200:203], v[236:239], v[0:3]
	s_barrier
; #define PG8_STAGE(bufoff, gbase, voff) do { _Pragma("unroll") for (int _i = 0; _i < 2; ++_i) \
;         __builtin_amdgcn_global_load_lds((const unsigned*)((const char*)(gbase) + (voff)[_i]), (PG8_LAS unsigned*)(lds + (bufoff) + ldsw + _i * 8192), 16, 0, 0); } while (0)
; #define PG8_LDA(dst, b, h) do { _Pragma("unroll") for (int m = 0; m < 4; ++m) _Pragma("unroll") for (int k = 0; k < 2; ++k) dst[m][k] = *(const PG8_LAS bf16x8*)(lds + PG8_SA(b, h) + aoff + m * 2048 + k * 1024); } while (0)
; #define PG8_LDB(dst, b, h) do { _Pragma("unroll") for (int n = 0; n < 2; ++n) _Pragma("unroll") for (int k = 0; k < 2; ++k) dst[n][k] = *(const PG8_LAS bf16x8*)(lds + PG8_SB(b, h) + boff + n * 2048 + k * 1024); } while (0)
; #define PG8_MMA(ai, bj, At, Bt) do { __builtin_amdgcn_s_setprio(1); _Pragma("unroll") for (int m = 0; m < 4; ++m) _Pragma("unroll") for (int n = 0; n < 2; ++n) _Pragma("unroll") for (int k = 0; k < 2; ++k) \
;         acc[ai][bj][m][n] = __builtin_amdgcn_mfma_f32_16x16x32_bf16(Bt[n][k], At[m][k], acc[ai][bj][m][n], 0, 0, 0); __builtin_amdgcn_s_setprio(0); } while (0)
; #define PG8_WAIT_V(n) asm volatile("s_waitcnt vmcnt(" #n ")" ::: "memory")
; #define PG8_WAIT_L(n) asm volatile("s_waitcnt lgkmcnt(" #n ")" ::: "memory")
; #define PG8_BAR __builtin_amdgcn_s_barrier()
; #define PG8_SCHED __builtin_amdgcn_sched_barrier(0)
; template <class Epi, class Sched, bool ALIGN_EPI = false, bool SP2 = false>
; __device__ __forceinline__ void gemm_phase(PG8_LAS unsigned char* lds, const Gemm g, const Sched& S, const Epi& E, int tid_in) {
;     ...
;             PG8_LDB(B0, 1, 0); PG8_LDB(B1, 1, 1); PG8_SCHED; PG8_LDA(At, 1, 0); PG8_STAGE(PG8_SA(0, 1), a2 + hstep, voffA);
;             PG8_WAIT_V(8); PG8_WAIT_L(0); PG8_BAR; PG8_MMA(0, 0, At, B0); PG8_MMA(0, 1, At, B1); PG8_BAR; PG8_SCHED;
;             PG8_LDA(At, 1, 1); PG8_STAGE(PG8_SB(1, 0), b3, voffB); PG8_STAGE(PG8_SB(1, 1), b3 + hstepB, voffB); PG8_STAGE(PG8_SA(1, 0), a3, voffA);
;             PG8_WAIT_V(8); PG8_WAIT_L(0); PG8_BAR; PG8_MMA(1, 0, At, B0); PG8_MMA(1, 1, At, B1); PG8_BAR; PG8_SCHED;
;     ...
;         }
;         if constexpr (ALIGN_EPI) { if (wr == 0) PG8_BAR; }
	s_add_i32 s33, 0, 0x18000
	v_add_u32_e32 v150, s33, v167
	s_add_i32 s89, 0, 0x1c000
	ds_read_b128 v[128:131], v150
	ds_read_b128 v[132:135], v150 offset:1024
	ds_read_b128 v[136:139], v150 offset:2048
	ds_read_b128 v[184:187], v150 offset:3072
	v_add_u32_e32 v150, s89, v167
	ds_read_b128 v[188:191], v150
	ds_read_b128 v[192:195], v150 offset:1024
	ds_read_b128 v[196:199], v150 offset:2048
	ds_read_b128 v[200:203], v150 offset:3072
	s_add_u32 s26, s64, 0x80000
	s_addc_u32 s27, s65, 0
	s_mov_b32 m0, s70
	ds_read_b128 v[204:207], v173 offset:32768
	ds_read_b128 v[212:215], v173 offset:33792
	ds_read_b128 v[216:219], v173 offset:34816
	ds_read_b128 v[220:223], v173 offset:35840
	ds_read_b128 v[224:227], v173 offset:36864
	ds_read_b128 v[228:231], v173 offset:37888
	ds_read_b128 v[232:235], v173 offset:38912
	ds_read_b128 v[236:239], v173 offset:39936
	global_load_lds_dwordx4 v142, s[26:27]
	s_mov_b32 m0, s71
	s_nop 0
	global_load_lds_dwordx4 v146, s[26:27]
	s_waitcnt vmcnt(8)
	s_waitcnt lgkmcnt(0)
	s_barrier
	s_waitcnt lgkmcnt(0)
	v_mfma_f32_16x16x32_bf16 v[124:127], v[128:131], v[204:207], v[124:127]
	v_mfma_f32_16x16x32_bf16 v[120:123], v[136:139], v[204:207], v[120:123]
	v_mfma_f32_16x16x32_bf16 v[108:111], v[128:131], v[216:219], v[108:111]
	v_mfma_f32_16x16x32_bf16 v[104:107], v[136:139], v[216:219], v[104:107]
	v_mfma_f32_16x16x32_bf16 v[92:95], v[128:131], v[224:227], v[92:95]
	v_mfma_f32_16x16x32_bf16 v[88:91], v[136:139], v[224:227], v[88:91]
	v_mfma_f32_16x16x32_bf16 v[76:79], v[128:131], v[232:235], v[76:79]
	v_mfma_f32_16x16x32_bf16 v[72:75], v[136:139], v[232:235], v[72:75]
	v_mfma_f32_16x16x32_bf16 v[124:127], v[132:135], v[212:215], v[124:127]
	v_mfma_f32_16x16x32_bf16 v[120:123], v[184:187], v[212:215], v[120:123]
	v_mfma_f32_16x16x32_bf16 v[108:111], v[132:135], v[220:223], v[108:111]
	v_mfma_f32_16x16x32_bf16 v[104:107], v[184:187], v[220:223], v[104:107]
	v_mfma_f32_16x16x32_bf16 v[92:95], v[132:135], v[228:231], v[92:95]
	v_mfma_f32_16x16x32_bf16 v[88:91], v[184:187], v[228:231], v[88:91]
	v_mfma_f32_16x16x32_bf16 v[76:79], v[132:135], v[236:239], v[76:79]
	v_mfma_f32_16x16x32_bf16 v[72:75], v[184:187], v[236:239], v[72:75]
	v_mfma_f32_16x16x32_bf16 v[116:119], v[188:191], v[204:207], v[116:119]
	v_mfma_f32_16x16x32_bf16 v[112:115], v[196:199], v[204:207], v[112:115]
	v_mfma_f32_16x16x32_bf16 v[100:103], v[188:191], v[216:219], v[100:103]
	v_mfma_f32_16x16x32_bf16 v[96:99], v[196:199], v[216:219], v[96:99]
	v_mfma_f32_16x16x32_bf16 v[84:87], v[188:191], v[224:227], v[84:87]
	v_mfma_f32_16x16x32_bf16 v[80:83], v[196:199], v[224:227], v[80:83]
	v_mfma_f32_16x16x32_bf16 v[68:71], v[188:191], v[232:235], v[68:71]
	v_mfma_f32_16x16x32_bf16 v[64:67], v[196:199], v[232:235], v[64:67]
	v_mfma_f32_16x16x32_bf16 v[116:119], v[192:195], v[212:215], v[116:119]
	v_mfma_f32_16x16x32_bf16 v[112:115], v[200:203], v[212:215], v[112:115]
	v_mfma_f32_16x16x32_bf16 v[100:103], v[192:195], v[220:223], v[100:103]
	v_mfma_f32_16x16x32_bf16 v[96:99], v[200:203], v[220:223], v[96:99]
	v_mfma_f32_16x16x32_bf16 v[84:87], v[192:195], v[228:231], v[84:87]
	v_mfma_f32_16x16x32_bf16 v[80:83], v[200:203], v[228:231], v[80:83]
	v_mfma_f32_16x16x32_bf16 v[68:71], v[192:195], v[236:239], v[68:71]
	v_mfma_f32_16x16x32_bf16 v[64:67], v[200:203], v[236:239], v[64:67]
	s_barrier
	s_add_i32 s26, s33, s68
	s_add_i32 m0, s26, 0xffffff80
	ds_read_b128 v[204:207], v173 offset:49152
	ds_read_b128 v[212:215], v173 offset:50176
	ds_read_b128 v[216:219], v173 offset:51200
	ds_read_b128 v[220:223], v173 offset:52224
	ds_read_b128 v[224:227], v173 offset:53248
	ds_read_b128 v[228:231], v173 offset:54272
	ds_read_b128 v[232:235], v173 offset:55296
	ds_read_b128 v[236:239], v173 offset:56320
	global_load_lds_dwordx4 v144, s[62:63] offset:128
	s_add_i32 m0, s26, 0x1f80
	s_add_u32 s26, s62, 0x20080
	s_addc_u32 s27, s63, 0
	s_add_i32 s33, s89, s68
	global_load_lds_dwordx4 v148, s[62:63] offset:128
	s_mov_b32 m0, s33
	s_nop 0
	global_load_lds_dwordx4 v144, s[26:27]
	s_add_i32 m0, s33, 0x2000
	s_nop 0
	global_load_lds_dwordx4 v148, s[26:27]
	s_add_i32 m0, s74, 0xffffff80
	s_nop 0
	global_load_lds_dwordx4 v142, s[64:65] offset:128
	s_add_i32 m0, s75, 0xffffff80
	s_nop 0
	global_load_lds_dwordx4 v146, s[64:65] offset:128
	s_waitcnt vmcnt(8)
	s_waitcnt lgkmcnt(0)
	s_barrier
	s_waitcnt lgkmcnt(0)
	v_mfma_f32_16x16x32_bf16 v[60:63], v[128:131], v[204:207], v[60:63]
	v_mfma_f32_16x16x32_bf16 v[56:59], v[136:139], v[204:207], v[56:59]
	v_mfma_f32_16x16x32_bf16 v[44:47], v[128:131], v[216:219], v[44:47]
	v_mfma_f32_16x16x32_bf16 v[40:43], v[136:139], v[216:219], v[40:43]
	v_mfma_f32_16x16x32_bf16 v[28:31], v[128:131], v[224:227], v[28:31]
	v_mfma_f32_16x16x32_bf16 v[24:27], v[136:139], v[224:227], v[24:27]
	v_mfma_f32_16x16x32_bf16 v[12:15], v[128:131], v[232:235], v[12:15]
	v_mfma_f32_16x16x32_bf16 v[8:11], v[136:139], v[232:235], v[8:11]
	v_mfma_f32_16x16x32_bf16 v[60:63], v[132:135], v[212:215], v[60:63]
	v_mfma_f32_16x16x32_bf16 v[56:59], v[184:187], v[212:215], v[56:59]
	v_mfma_f32_16x16x32_bf16 v[44:47], v[132:135], v[220:223], v[44:47]
	v_mfma_f32_16x16x32_bf16 v[40:43], v[184:187], v[220:223], v[40:43]
	v_mfma_f32_16x16x32_bf16 v[28:31], v[132:135], v[228:231], v[28:31]
	v_mfma_f32_16x16x32_bf16 v[24:27], v[184:187], v[228:231], v[24:27]
	v_mfma_f32_16x16x32_bf16 v[12:15], v[132:135], v[236:239], v[12:15]
	v_mfma_f32_16x16x32_bf16 v[8:11], v[184:187], v[236:239], v[8:11]
	v_mfma_f32_16x16x32_bf16 v[52:55], v[188:191], v[204:207], v[52:55]
	v_mfma_f32_16x16x32_bf16 v[48:51], v[196:199], v[204:207], v[48:51]
	v_mfma_f32_16x16x32_bf16 v[36:39], v[188:191], v[216:219], v[36:39]
	v_mfma_f32_16x16x32_bf16 v[32:35], v[196:199], v[216:219], v[32:35]
	v_mfma_f32_16x16x32_bf16 v[20:23], v[188:191], v[224:227], v[20:23]
	v_mfma_f32_16x16x32_bf16 v[16:19], v[196:199], v[224:227], v[16:19]
	v_mfma_f32_16x16x32_bf16 v[4:7], v[188:191], v[232:235], v[4:7]
	v_mfma_f32_16x16x32_bf16 v[0:3], v[196:199], v[232:235], v[0:3]
	v_mfma_f32_16x16x32_bf16 v[52:55], v[192:195], v[212:215], v[52:55]
	v_mfma_f32_16x16x32_bf16 v[48:51], v[200:203], v[212:215], v[48:51]
	v_mfma_f32_16x16x32_bf16 v[36:39], v[192:195], v[220:223], v[36:39]
	v_mfma_f32_16x16x32_bf16 v[32:35], v[200:203], v[220:223], v[32:35]
	v_mfma_f32_16x16x32_bf16 v[20:23], v[192:195], v[228:231], v[20:23]
	v_mfma_f32_16x16x32_bf16 v[16:19], v[200:203], v[228:231], v[16:19]
	v_mfma_f32_16x16x32_bf16 v[4:7], v[192:195], v[236:239], v[4:7]
	v_mfma_f32_16x16x32_bf16 v[0:3], v[200:203], v[236:239], v[0:3]
	s_barrier
	s_add_i32 s88, s88, 2
	s_add_u32 s60, s60, 0x100
	s_addc_u32 s61, s61, 0
	s_add_u32 s86, s86, 0x100
	s_addc_u32 s87, s87, 0
	s_cmp_gt_u32 s88, 29
; #define PG8_STAGE(bufoff, gbase, voff) do { _Pragma("unroll") for (int _i = 0; _i < 2; ++_i) \
;         __builtin_amdgcn_global_load_lds((const unsigned*)((const char*)(gbase) + (voff)[_i]), (PG8_LAS unsigned*)(lds + (bufoff) + ldsw + _i * 8192), 16, 0, 0); } while (0)
; #define PG8_LDA(dst, b, h) do { _Pragma("unroll") for (int m = 0; m < 4; ++m) _Pragma("unroll") for (int k = 0; k < 2; ++k) dst[m][k] = *(const PG8_LAS bf16x8*)(lds + PG8_SA(b, h) + aoff + m * 2048 + k * 1024); } while (0)
; #define PG8_LDB(dst, b, h) do { _Pragma("unroll") for (int n = 0; n < 2; ++n) _Pragma("unroll") for (int k = 0; k < 2; ++k) dst[n][k] = *(const PG8_LAS bf16x8*)(lds + PG8_SB(b, h) + boff + n * 2048 + k * 1024); } while (0)
; #define PG8_MMA(ai, bj, At, Bt) do { __builtin_amdgcn_s_setprio(1); _Pragma("unroll") for (int m = 0; m < 4; ++m) _Pragma("unroll") for (int n = 0; n < 2; ++n) _Pragma("unroll") for (int k = 0; k < 2; ++k) \
;         acc[ai][bj][m][n] = __builtin_amdgcn_mfma_f32_16x16x32_bf16(Bt[n][k], At[m][k], acc[ai][bj][m][n], 0, 0, 0); __builtin_amdgcn_s_setprio(0); } while (0)
; #define PG8_WAIT_V(n) asm volatile("s_waitcnt vmcnt(" #n ")" ::: "memory")
; #define PG8_WAIT_L(n) asm volatile("s_waitcnt lgkmcnt(" #n ")" ::: "memory")
; #define PG8_BAR __builtin_amdgcn_s_barrier()
; #define PG8_SCHED __builtin_amdgcn_sched_barrier(0)
; template <class Epi, class Sched, bool ALIGN_EPI = false, bool SP2 = false>
; __device__ __forceinline__ void gemm_phase(PG8_LAS unsigned char* lds, const Gemm g, const Sched& S, const Epi& E, int tid_in) {
;     ...
;             PG8_LDB(B0, 0, 0); PG8_LDB(B1, 0, 1); PG8_SCHED; PG8_LDA(At, 0, 0); PG8_STAGE(PG8_SA(1, 1), a1 + hstep, voffA);
;             PG8_WAIT_V(8); PG8_WAIT_L(0); PG8_BAR; PG8_MMA(0, 0, At, B0); PG8_MMA(0, 1, At, B1); PG8_BAR; PG8_SCHED;
;             PG8_LDA(At, 0, 1); PG8_STAGE(PG8_SB(0, 0), b2, voffB); PG8_STAGE(PG8_SB(0, 1), b2 + hstepB, voffB); PG8_STAGE(PG8_SA(0, 0), a2, voffA);
;             PG8_WAIT_V(8); PG8_WAIT_L(0); PG8_BAR; PG8_MMA(1, 0, At, B0); PG8_MMA(1, 1, At, B1); PG8_BAR; PG8_SCHED;
.LBB0_597:
	ds_read_b128 v[128:131], v171
	ds_read_b128 v[132:135], v171 offset:1024
	ds_read_b128 v[136:139], v171 offset:2048
	ds_read_b128 v[184:187], v171 offset:3072
	ds_read_b128 v[188:191], v172
	ds_read_b128 v[192:195], v172 offset:1024
	ds_read_b128 v[196:199], v172 offset:2048
	ds_read_b128 v[200:203], v172 offset:3072
	s_add_u32 s26, s60, 0xfff80080
	s_addc_u32 s27, s61, -1
	s_cmp_eq_u32 s88, 28
	s_cselect_b32 s65, s11, s27
	s_cselect_b32 s64, s53, s26
	s_cselect_b32 s63, s51, s87
	s_cselect_b32 s62, s85, s86
	s_add_i32 m0, s59, 0xc000
	ds_read_b128 v[204:207], v173
	ds_read_b128 v[212:215], v173 offset:1024
	ds_read_b128 v[216:219], v173 offset:2048
	ds_read_b128 v[220:223], v173 offset:3072
	ds_read_b128 v[224:227], v173 offset:4096
	ds_read_b128 v[228:231], v173 offset:5120
	ds_read_b128 v[232:235], v173 offset:6144
	ds_read_b128 v[236:239], v173 offset:7168
	global_load_lds_dwordx4 v158, s[60:61]
	s_add_i32 m0, s59, 0xe000
	s_nop 0
	global_load_lds_dwordx4 v160, s[60:61]
	s_waitcnt vmcnt(8)
	s_waitcnt lgkmcnt(0)
	s_barrier
	s_waitcnt lgkmcnt(0)
	v_mfma_f32_16x16x32_bf16 v[124:127], v[128:131], v[204:207], v[124:127]
	v_mfma_f32_16x16x32_bf16 v[120:123], v[136:139], v[204:207], v[120:123]
	v_mfma_f32_16x16x32_bf16 v[108:111], v[128:131], v[216:219], v[108:111]
	v_mfma_f32_16x16x32_bf16 v[104:107], v[136:139], v[216:219], v[104:107]
	v_mfma_f32_16x16x32_bf16 v[92:95], v[128:131], v[224:227], v[92:95]
	v_mfma_f32_16x16x32_bf16 v[88:91], v[136:139], v[224:227], v[88:91]
	v_mfma_f32_16x16x32_bf16 v[76:79], v[128:131], v[232:235], v[76:79]
	v_mfma_f32_16x16x32_bf16 v[72:75], v[136:139], v[232:235], v[72:75]
	v_mfma_f32_16x16x32_bf16 v[124:127], v[132:135], v[212:215], v[124:127]
	v_mfma_f32_16x16x32_bf16 v[120:123], v[184:187], v[212:215], v[120:123]
	v_mfma_f32_16x16x32_bf16 v[108:111], v[132:135], v[220:223], v[108:111]
	v_mfma_f32_16x16x32_bf16 v[104:107], v[184:187], v[220:223], v[104:107]
	v_mfma_f32_16x16x32_bf16 v[92:95], v[132:135], v[228:231], v[92:95]
	v_mfma_f32_16x16x32_bf16 v[88:91], v[184:187], v[228:231], v[88:91]
	v_mfma_f32_16x16x32_bf16 v[76:79], v[132:135], v[236:239], v[76:79]
	v_mfma_f32_16x16x32_bf16 v[72:75], v[184:187], v[236:239], v[72:75]
	v_mfma_f32_16x16x32_bf16 v[116:119], v[188:191], v[204:207], v[116:119]
	v_mfma_f32_16x16x32_bf16 v[112:115], v[196:199], v[204:207], v[112:115]
	v_mfma_f32_16x16x32_bf16 v[100:103], v[188:191], v[216:219], v[100:103]
	v_mfma_f32_16x16x32_bf16 v[96:99], v[196:199], v[216:219], v[96:99]
	v_mfma_f32_16x16x32_bf16 v[84:87], v[188:191], v[224:227], v[84:87]
	v_mfma_f32_16x16x32_bf16 v[80:83], v[196:199], v[224:227], v[80:83]
	v_mfma_f32_16x16x32_bf16 v[68:71], v[188:191], v[232:235], v[68:71]
	v_mfma_f32_16x16x32_bf16 v[64:67], v[196:199], v[232:235], v[64:67]
	v_mfma_f32_16x16x32_bf16 v[116:119], v[192:195], v[212:215], v[116:119]
	v_mfma_f32_16x16x32_bf16 v[112:115], v[200:203], v[212:215], v[112:115]
	v_mfma_f32_16x16x32_bf16 v[100:103], v[192:195], v[220:223], v[100:103]
	v_mfma_f32_16x16x32_bf16 v[96:99], v[200:203], v[220:223], v[96:99]
	v_mfma_f32_16x16x32_bf16 v[84:87], v[192:195], v[228:231], v[84:87]
	v_mfma_f32_16x16x32_bf16 v[80:83], v[200:203], v[228:231], v[80:83]
	v_mfma_f32_16x16x32_bf16 v[68:71], v[192:195], v[236:239], v[68:71]
	v_mfma_f32_16x16x32_bf16 v[64:67], v[200:203], v[236:239], v[64:67]
	s_barrier
	s_add_i32 s26, s78, s68
	s_mov_b32 m0, s26
	ds_read_b128 v[204:207], v173 offset:16384
	ds_read_b128 v[212:215], v173 offset:17408
	ds_read_b128 v[216:219], v173 offset:18432
	ds_read_b128 v[220:223], v173 offset:19456
	ds_read_b128 v[224:227], v173 offset:20480
	ds_read_b128 v[228:231], v173 offset:21504
	ds_read_b128 v[232:235], v173 offset:22528
	ds_read_b128 v[236:239], v173 offset:23552
	global_load_lds_dwordx4 v144, s[62:63]
	s_add_i32 m0, s26, 0x2000
	s_add_u32 s26, s62, 0x20000
	s_addc_u32 s27, s63, 0
	s_add_i32 s33, s79, s68
	global_load_lds_dwordx4 v148, s[62:63]
	s_mov_b32 m0, s33
	s_nop 0
	global_load_lds_dwordx4 v144, s[26:27]
	s_add_i32 m0, s33, 0x2000
	s_nop 0
	global_load_lds_dwordx4 v148, s[26:27]
	s_mov_b32 m0, s59
	s_nop 0
	global_load_lds_dwordx4 v142, s[64:65]
	s_mov_b32 m0, s69
	s_nop 0
	global_load_lds_dwordx4 v146, s[64:65]
	s_waitcnt vmcnt(8)
	s_waitcnt lgkmcnt(0)
	s_barrier
	s_waitcnt lgkmcnt(0)
	v_mfma_f32_16x16x32_bf16 v[60:63], v[128:131], v[204:207], v[60:63]
	v_mfma_f32_16x16x32_bf16 v[56:59], v[136:139], v[204:207], v[56:59]
	v_mfma_f32_16x16x32_bf16 v[44:47], v[128:131], v[216:219], v[44:47]
	v_mfma_f32_16x16x32_bf16 v[40:43], v[136:139], v[216:219], v[40:43]
	v_mfma_f32_16x16x32_bf16 v[28:31], v[128:131], v[224:227], v[28:31]
	v_mfma_f32_16x16x32_bf16 v[24:27], v[136:139], v[224:227], v[24:27]
	v_mfma_f32_16x16x32_bf16 v[12:15], v[128:131], v[232:235], v[12:15]
	v_mfma_f32_16x16x32_bf16 v[8:11], v[136:139], v[232:235], v[8:11]
	v_mfma_f32_16x16x32_bf16 v[60:63], v[132:135], v[212:215], v[60:63]
	v_mfma_f32_16x16x32_bf16 v[56:59], v[184:187], v[212:215], v[56:59]
	v_mfma_f32_16x16x32_bf16 v[44:47], v[132:135], v[220:223], v[44:47]
	v_mfma_f32_16x16x32_bf16 v[40:43], v[184:187], v[220:223], v[40:43]
	v_mfma_f32_16x16x32_bf16 v[28:31], v[132:135], v[228:231], v[28:31]
	v_mfma_f32_16x16x32_bf16 v[24:27], v[184:187], v[228:231], v[24:27]
	v_mfma_f32_16x16x32_bf16 v[12:15], v[132:135], v[236:239], v[12:15]
	v_mfma_f32_16x16x32_bf16 v[8:11], v[184:187], v[236:239], v[8:11]
	v_mfma_f32_16x16x32_bf16 v[52:55], v[188:191], v[204:207], v[52:55]
	v_mfma_f32_16x16x32_bf16 v[48:51], v[196:199], v[204:207], v[48:51]
	v_mfma_f32_16x16x32_bf16 v[36:39], v[188:191], v[216:219], v[36:39]
	v_mfma_f32_16x16x32_bf16 v[32:35], v[196:199], v[216:219], v[32:35]
	v_mfma_f32_16x16x32_bf16 v[20:23], v[188:191], v[224:227], v[20:23]
	v_mfma_f32_16x16x32_bf16 v[16:19], v[196:199], v[224:227], v[16:19]
	v_mfma_f32_16x16x32_bf16 v[4:7], v[188:191], v[232:235], v[4:7]
	v_mfma_f32_16x16x32_bf16 v[0:3], v[196:199], v[232:235], v[0:3]
	v_mfma_f32_16x16x32_bf16 v[52:55], v[192:195], v[212:215], v[52:55]
	v_mfma_f32_16x16x32_bf16 v[48:51], v[200:203], v[212:215], v[48:51]
	v_mfma_f32_16x16x32_bf16 v[36:39], v[192:195], v[220:223], v[36:39]
	v_mfma_f32_16x16x32_bf16 v[32:35], v[200:203], v[220:223], v[32:35]
	v_mfma_f32_16x16x32_bf16 v[20:23], v[192:195], v[228:231], v[20:23]
	v_mfma_f32_16x16x32_bf16 v[16:19], v[200:203], v[228:231], v[16:19]
	v_mfma_f32_16x16x32_bf16 v[4:7], v[192:195], v[236:239], v[4:7]
	v_mfma_f32_16x16x32_bf16 v[0:3], v[200:203], v[236:239], v[0:3]
	s_barrier
; #define PG8_STAGE(bufoff, gbase, voff) do { _Pragma("unroll") for (int _i = 0; _i < 2; ++_i) \
;         __builtin_amdgcn_global_load_lds((const unsigned*)((const char*)(gbase) + (voff)[_i]), (PG8_LAS unsigned*)(lds + (bufoff) + ldsw + _i * 8192), 16, 0, 0); } while (0)
; #define PG8_LDA(dst, b, h) do { _Pragma("unroll") for (int m = 0; m < 4; ++m) _Pragma("unroll") for (int k = 0; k < 2; ++k) dst[m][k] = *(const PG8_LAS bf16x8*)(lds + PG8_SA(b, h) + aoff + m * 2048 + k * 1024); } while (0)
; #define PG8_LDB(dst, b, h) do { _Pragma("unroll") for (int n = 0; n < 2; ++n) _Pragma("unroll") for (int k = 0; k < 2; ++k) dst[n][k] = *(const PG8_LAS bf16x8*)(lds + PG8_SB(b, h) + boff + n * 2048 + k * 1024); } while (0)
; #define PG8_MMA(ai, bj, At, Bt) do { __builtin_amdgcn_s_setprio(1); _Pragma("unroll") for (int m = 0; m < 4; ++m) _Pragma("unroll") for (int n = 0; n < 2; ++n) _Pragma("unroll") for (int k = 0; k < 2; ++k) \
;         acc[ai][bj][m][n] = __builtin_amdgcn_mfma_f32_16x16x32_bf16(Bt[n][k], At[m][k], acc[ai][bj][m][n], 0, 0, 0); __builtin_amdgcn_s_setprio(0); } while (0)
; #define PG8_WAIT_V(n) asm volatile("s_waitcnt vmcnt(" #n ")" ::: "memory")
; #define PG8_WAIT_L(n) asm volatile("s_waitcnt lgkmcnt(" #n ")" ::: "memory")
; #define PG8_BAR __builtin_amdgcn_s_barrier()
; #define PG8_SCHED __builtin_amdgcn_sched_barrier(0)
; template <class Epi, class Sched, bool ALIGN_EPI = false, bool SP2 = false>
; __device__ __forceinline__ void gemm_phase(PG8_LAS unsigned char* lds, const Gemm g, const Sched& S, const Epi& E, int tid_in) {
;     ...
;             PG8_LDB(B0, 1, 0); PG8_LDB(B1, 1, 1); PG8_SCHED; PG8_LDA(At, 1, 0); PG8_STAGE(PG8_SA(0, 1), a2 + hstep, voffA);
;             PG8_WAIT_V(8); PG8_WAIT_L(0); PG8_BAR; PG8_MMA(0, 0, At, B0); PG8_MMA(0, 1, At, B1); PG8_BAR; PG8_SCHED;
;             PG8_LDA(At, 1, 1); PG8_STAGE(PG8_SB(1, 0), b3, voffB); PG8_STAGE(PG8_SB(1, 1), b3 + hstepB, voffB); PG8_STAGE(PG8_SA(1, 0), a3, voffA);
;             PG8_WAIT_V(8); PG8_WAIT_L(0); PG8_BAR; PG8_MMA(1, 0, At, B0); PG8_MMA(1, 1, At, B1); PG8_BAR; PG8_SCHED;
;     ...
;         }
;         if constexpr (ALIGN_EPI) { if (wr == 0) PG8_BAR; }
	s_add_i32 s33, 0, 0x18000
	v_add_u32_e32 v150, s33, v167
	s_add_i32 s89, 0, 0x1c000
	ds_read_b128 v[128:131], v150
	ds_read_b128 v[132:135], v150 offset:1024
	ds_read_b128 v[136:139], v150 offset:2048
	ds_read_b128 v[184:187], v150 offset:3072
	v_add_u32_e32 v150, s89, v167
	ds_read_b128 v[188:191], v150
	ds_read_b128 v[192:195], v150 offset:1024
	ds_read_b128 v[196:199], v150 offset:2048
	ds_read_b128 v[200:203], v150 offset:3072
	s_add_u32 s26, s64, 0x80000
	s_addc_u32 s27, s65, 0
	s_mov_b32 m0, s70
	ds_read_b128 v[204:207], v173 offset:32768
	ds_read_b128 v[212:215], v173 offset:33792
	ds_read_b128 v[216:219], v173 offset:34816
	ds_read_b128 v[220:223], v173 offset:35840
	ds_read_b128 v[224:227], v173 offset:36864
	ds_read_b128 v[228:231], v173 offset:37888
	ds_read_b128 v[232:235], v173 offset:38912
	ds_read_b128 v[236:239], v173 offset:39936
	global_load_lds_dwordx4 v142, s[26:27]
	s_mov_b32 m0, s71
	s_nop 0
	global_load_lds_dwordx4 v146, s[26:27]
	s_waitcnt vmcnt(8)
	s_waitcnt lgkmcnt(0)
	s_barrier
	s_waitcnt lgkmcnt(0)
	v_mfma_f32_16x16x32_bf16 v[124:127], v[128:131], v[204:207], v[124:127]
	v_mfma_f32_16x16x32_bf16 v[120:123], v[136:139], v[204:207], v[120:123]
	v_mfma_f32_16x16x32_bf16 v[108:111], v[128:131], v[216:219], v[108:111]
	v_mfma_f32_16x16x32_bf16 v[104:107], v[136:139], v[216:219], v[104:107]
	v_mfma_f32_16x16x32_bf16 v[92:95], v[128:131], v[224:227], v[92:95]
	v_mfma_f32_16x16x32_bf16 v[88:91], v[136:139], v[224:227], v[88:91]
	v_mfma_f32_16x16x32_bf16 v[76:79], v[128:131], v[232:235], v[76:79]
	v_mfma_f32_16x16x32_bf16 v[72:75], v[136:139], v[232:235], v[72:75]
	v_mfma_f32_16x16x32_bf16 v[124:127], v[132:135], v[212:215], v[124:127]
	v_mfma_f32_16x16x32_bf16 v[120:123], v[184:187], v[212:215], v[120:123]
	v_mfma_f32_16x16x32_bf16 v[108:111], v[132:135], v[220:223], v[108:111]
	v_mfma_f32_16x16x32_bf16 v[104:107], v[184:187], v[220:223], v[104:107]
	v_mfma_f32_16x16x32_bf16 v[92:95], v[132:135], v[228:231], v[92:95]
	v_mfma_f32_16x16x32_bf16 v[88:91], v[184:187], v[228:231], v[88:91]
	v_mfma_f32_16x16x32_bf16 v[76:79], v[132:135], v[236:239], v[76:79]
	v_mfma_f32_16x16x32_bf16 v[72:75], v[184:187], v[236:239], v[72:75]
	v_mfma_f32_16x16x32_bf16 v[116:119], v[188:191], v[204:207], v[116:119]
	v_mfma_f32_16x16x32_bf16 v[112:115], v[196:199], v[204:207], v[112:115]
	v_mfma_f32_16x16x32_bf16 v[100:103], v[188:191], v[216:219], v[100:103]
	v_mfma_f32_16x16x32_bf16 v[96:99], v[196:199], v[216:219], v[96:99]
	v_mfma_f32_16x16x32_bf16 v[84:87], v[188:191], v[224:227], v[84:87]
	v_mfma_f32_16x16x32_bf16 v[80:83], v[196:199], v[224:227], v[80:83]
	v_mfma_f32_16x16x32_bf16 v[68:71], v[188:191], v[232:235], v[68:71]
	v_mfma_f32_16x16x32_bf16 v[64:67], v[196:199], v[232:235], v[64:67]
	v_mfma_f32_16x16x32_bf16 v[116:119], v[192:195], v[212:215], v[116:119]
	v_mfma_f32_16x16x32_bf16 v[112:115], v[200:203], v[212:215], v[112:115]
	v_mfma_f32_16x16x32_bf16 v[100:103], v[192:195], v[220:223], v[100:103]
	v_mfma_f32_16x16x32_bf16 v[96:99], v[200:203], v[220:223], v[96:99]
	v_mfma_f32_16x16x32_bf16 v[84:87], v[192:195], v[228:231], v[84:87]
	v_mfma_f32_16x16x32_bf16 v[80:83], v[200:203], v[228:231], v[80:83]
	v_mfma_f32_16x16x32_bf16 v[68:71], v[192:195], v[236:239], v[68:71]
	v_mfma_f32_16x16x32_bf16 v[64:67], v[200:203], v[236:239], v[64:67]
	s_barrier
	s_add_i32 s26, s33, s68
	s_add_i32 m0, s26, 0xffffff80
	ds_read_b128 v[204:207], v173 offset:49152
	ds_read_b128 v[212:215], v173 offset:50176
	ds_read_b128 v[216:219], v173 offset:51200
	ds_read_b128 v[220:223], v173 offset:52224
	ds_read_b128 v[224:227], v173 offset:53248
	ds_read_b128 v[228:231], v173 offset:54272
	ds_read_b128 v[232:235], v173 offset:55296
	ds_read_b128 v[236:239], v173 offset:56320
	global_load_lds_dwordx4 v144, s[62:63] offset:128
	s_add_i32 m0, s26, 0x1f80
	s_add_u32 s26, s62, 0x20080
	s_addc_u32 s27, s63, 0
	s_add_i32 s33, s89, s68
	global_load_lds_dwordx4 v148, s[62:63] offset:128
	s_mov_b32 m0, s33
	s_nop 0
	global_load_lds_dwordx4 v144, s[26:27]
	s_add_i32 m0, s33, 0x2000
	s_nop 0
	global_load_lds_dwordx4 v148, s[26:27]
	s_add_i32 m0, s74, 0xffffff80
	s_nop 0
	global_load_lds_dwordx4 v142, s[64:65] offset:128
	s_add_i32 m0, s75, 0xffffff80
	s_nop 0
	global_load_lds_dwordx4 v146, s[64:65] offset:128
	s_waitcnt vmcnt(8)
	s_waitcnt lgkmcnt(0)
	s_barrier
	s_waitcnt lgkmcnt(0)
	v_mfma_f32_16x16x32_bf16 v[60:63], v[128:131], v[204:207], v[60:63]
	v_mfma_f32_16x16x32_bf16 v[56:59], v[136:139], v[204:207], v[56:59]
	v_mfma_f32_16x16x32_bf16 v[44:47], v[128:131], v[216:219], v[44:47]
	v_mfma_f32_16x16x32_bf16 v[40:43], v[136:139], v[216:219], v[40:43]
	v_mfma_f32_16x16x32_bf16 v[28:31], v[128:131], v[224:227], v[28:31]
	v_mfma_f32_16x16x32_bf16 v[24:27], v[136:139], v[224:227], v[24:27]
	v_mfma_f32_16x16x32_bf16 v[12:15], v[128:131], v[232:235], v[12:15]
	v_mfma_f32_16x16x32_bf16 v[8:11], v[136:139], v[232:235], v[8:11]
	v_mfma_f32_16x16x32_bf16 v[60:63], v[132:135], v[212:215], v[60:63]
	v_mfma_f32_16x16x32_bf16 v[56:59], v[184:187], v[212:215], v[56:59]
	v_mfma_f32_16x16x32_bf16 v[44:47], v[132:135], v[220:223], v[44:47]
	v_mfma_f32_16x16x32_bf16 v[40:43], v[184:187], v[220:223], v[40:43]
	v_mfma_f32_16x16x32_bf16 v[28:31], v[132:135], v[228:231], v[28:31]
	v_mfma_f32_16x16x32_bf16 v[24:27], v[184:187], v[228:231], v[24:27]
	v_mfma_f32_16x16x32_bf16 v[12:15], v[132:135], v[236:239], v[12:15]
	v_mfma_f32_16x16x32_bf16 v[8:11], v[184:187], v[236:239], v[8:11]
	v_mfma_f32_16x16x32_bf16 v[52:55], v[188:191], v[204:207], v[52:55]
	v_mfma_f32_16x16x32_bf16 v[48:51], v[196:199], v[204:207], v[48:51]
	v_mfma_f32_16x16x32_bf16 v[36:39], v[188:191], v[216:219], v[36:39]
	v_mfma_f32_16x16x32_bf16 v[32:35], v[196:199], v[216:219], v[32:35]
	v_mfma_f32_16x16x32_bf16 v[20:23], v[188:191], v[224:227], v[20:23]
	v_mfma_f32_16x16x32_bf16 v[16:19], v[196:199], v[224:227], v[16:19]
	v_mfma_f32_16x16x32_bf16 v[4:7], v[188:191], v[232:235], v[4:7]
	v_mfma_f32_16x16x32_bf16 v[0:3], v[196:199], v[232:235], v[0:3]
	v_mfma_f32_16x16x32_bf16 v[52:55], v[192:195], v[212:215], v[52:55]
	v_mfma_f32_16x16x32_bf16 v[48:51], v[200:203], v[212:215], v[48:51]
	v_mfma_f32_16x16x32_bf16 v[36:39], v[192:195], v[220:223], v[36:39]
	v_mfma_f32_16x16x32_bf16 v[32:35], v[200:203], v[220:223], v[32:35]
	v_mfma_f32_16x16x32_bf16 v[20:23], v[192:195], v[228:231], v[20:23]
	v_mfma_f32_16x16x32_bf16 v[16:19], v[200:203], v[228:231], v[16:19]
	v_mfma_f32_16x16x32_bf16 v[4:7], v[192:195], v[236:239], v[4:7]
	v_mfma_f32_16x16x32_bf16 v[0:3], v[200:203], v[236:239], v[0:3]
	s_barrier
	s_add_i32 s88, s88, 2
	s_add_u32 s60, s60, 0x100
	s_addc_u32 s61, s61, 0
	s_add_u32 s86, s86, 0x100
	s_addc_u32 s87, s87, 0
	s_cmp_gt_u32 s88, 29
	s_cbranch_scc0 .LBB0_597
	s_and_b64 vcc, exec, s[46:47]
	s_cbranch_vccz .LBB0_600
	s_barrier

; #define PG8_STAGE(bufoff, gbase, voff) do { _Pragma("unroll") for (int _i = 0; _i < 2; ++_i) \
;         __builtin_amdgcn_global_load_lds((const unsigned*)((const char*)(gbase) + (voff)[_i]), (PG8_LAS unsigned*)(lds + (bufoff) + ldsw + _i * 8192), 16, 0, 0); } while (0)
; #define PG8_LDA(dst, b, h) do { _Pragma("unroll") for (int m = 0; m < 4; ++m) _Pragma("unroll") for (int k = 0; k < 2; ++k) dst[m][k] = *(const PG8_LAS bf16x8*)(lds + PG8_SA(b, h) + aoff + m * 2048 + k * 1024); } while (0)
; #define PG8_LDB(dst, b, h) do { _Pragma("unroll") for (int n = 0; n < 2; ++n) _Pragma("unroll") for (int k = 0; k < 2; ++k) dst[n][k] = *(const PG8_LAS bf16x8*)(lds + PG8_SB(b, h) + boff + n * 2048 + k * 1024); } while (0)
; #define PG8_MMA(ai, bj, At, Bt) do { __builtin_amdgcn_s_setprio(1); _Pragma("unroll") for (int m = 0; m < 4; ++m) _Pragma("unroll") for (int n = 0; n < 2; ++n) _Pragma("unroll") for (int k = 0; k < 2; ++k) \
;         acc[ai][bj][m][n] = __builtin_amdgcn_mfma_f32_16x16x32_bf16(Bt[n][k], At[m][k], acc[ai][bj][m][n], 0, 0, 0); __builtin_amdgcn_s_setprio(0); } while (0)
; #define PG8_WAIT_V(n) asm volatile("s_waitcnt vmcnt(" #n ")" ::: "memory")
; #define PG8_WAIT_L(n) asm volatile("s_waitcnt lgkmcnt(" #n ")" ::: "memory")
; #define PG8_BAR __builtin_amdgcn_s_barrier()
; #define PG8_SCHED __builtin_amdgcn_sched_barrier(0)
; template <class Epi, class Sched, bool ALIGN_EPI = false, bool SP2 = false>
; __device__ __forceinline__ void gemm_phase(PG8_LAS unsigned char* lds, const Gemm g, const Sched& S, const Epi& E, int tid_in) {
;     ...
;             PG8_LDB(B0, 0, 0); PG8_LDB(B1, 0, 1); PG8_SCHED; PG8_LDA(At, 0, 0); PG8_STAGE(PG8_SA(1, 1), a1 + hstep, voffA);
;             PG8_WAIT_V(8); PG8_WAIT_L(0); PG8_BAR; PG8_MMA(0, 0, At, B0); PG8_MMA(0, 1, At, B1); PG8_BAR; PG8_SCHED;
;             PG8_LDA(At, 0, 1); PG8_STAGE(PG8_SB(0, 0), b2, voffB); PG8_STAGE(PG8_SB(0, 1), b2 + hstepB, voffB); PG8_STAGE(PG8_SA(0, 0), a2, voffA);
;             PG8_WAIT_V(8); PG8_WAIT_L(0); PG8_BAR; PG8_MMA(1, 0, At, B0); PG8_MMA(1, 1, At, B1); PG8_BAR; PG8_SCHED;
.Lkb_skip_5:
	ds_read_b128 v[146:149], v153
	ds_read_b128 v[158:161], v153 offset:1024
	ds_read_b128 v[162:165], v153 offset:2048
	ds_read_b128 v[166:169], v153 offset:3072
	ds_read_b128 v[170:173], v154
	ds_read_b128 v[174:177], v154 offset:1024
	ds_read_b128 v[178:181], v154 offset:2048
	ds_read_b128 v[182:185], v154 offset:3072
	s_add_u32 s26, s62, 0xfffc0080
	s_addc_u32 s27, s63, -1
	s_cmp_eq_u32 s83, 12
	s_cselect_b32 s67, s53, s27
	s_cselect_b32 s66, s59, s26
	s_cselect_b32 s65, s51, s79
	s_cselect_b32 s64, s77, s78
	s_add_i32 m0, s61, 0xc000
	ds_read_b128 v[186:189], v155
	ds_read_b128 v[190:193], v155 offset:1024
	ds_read_b128 v[194:197], v155 offset:2048
	ds_read_b128 v[198:201], v155 offset:3072
	ds_read_b128 v[202:205], v155 offset:4096
	ds_read_b128 v[206:209], v155 offset:5120
	ds_read_b128 v[210:213], v155 offset:6144
	ds_read_b128 v[214:217], v155 offset:7168
	global_load_lds_dwordx4 v138, s[62:63]
	s_add_i32 m0, s61, 0xe000
	s_nop 0
	global_load_lds_dwordx4 v140, s[62:63]
	s_waitcnt vmcnt(8)
	s_waitcnt lgkmcnt(0)
	s_barrier
	s_waitcnt lgkmcnt(0)
	v_mfma_f32_16x16x32_bf16 v[124:127], v[146:149], v[186:189], 0
	v_mfma_f32_16x16x32_bf16 v[120:123], v[162:165], v[186:189], 0
	v_mfma_f32_16x16x32_bf16 v[108:111], v[146:149], v[194:197], 0
	v_mfma_f32_16x16x32_bf16 v[104:107], v[162:165], v[194:197], 0
	v_mfma_f32_16x16x32_bf16 v[92:95], v[146:149], v[202:205], 0
	v_mfma_f32_16x16x32_bf16 v[88:91], v[162:165], v[202:205], 0
	v_mfma_f32_16x16x32_bf16 v[76:79], v[146:149], v[210:213], 0
	v_mfma_f32_16x16x32_bf16 v[72:75], v[162:165], v[210:213], 0
	v_mfma_f32_16x16x32_bf16 v[124:127], v[158:161], v[190:193], v[124:127]
	v_mfma_f32_16x16x32_bf16 v[120:123], v[166:169], v[190:193], v[120:123]
	v_mfma_f32_16x16x32_bf16 v[108:111], v[158:161], v[198:201], v[108:111]
	v_mfma_f32_16x16x32_bf16 v[104:107], v[166:169], v[198:201], v[104:107]
	v_mfma_f32_16x16x32_bf16 v[92:95], v[158:161], v[206:209], v[92:95]
	v_mfma_f32_16x16x32_bf16 v[88:91], v[166:169], v[206:209], v[88:91]
	v_mfma_f32_16x16x32_bf16 v[76:79], v[158:161], v[214:217], v[76:79]
	v_mfma_f32_16x16x32_bf16 v[72:75], v[166:169], v[214:217], v[72:75]
	v_mfma_f32_16x16x32_bf16 v[116:119], v[170:173], v[186:189], 0
	v_mfma_f32_16x16x32_bf16 v[112:115], v[178:181], v[186:189], 0
	v_mfma_f32_16x16x32_bf16 v[100:103], v[170:173], v[194:197], 0
	v_mfma_f32_16x16x32_bf16 v[96:99], v[178:181], v[194:197], 0
	v_mfma_f32_16x16x32_bf16 v[84:87], v[170:173], v[202:205], 0
	v_mfma_f32_16x16x32_bf16 v[80:83], v[178:181], v[202:205], 0
	v_mfma_f32_16x16x32_bf16 v[68:71], v[170:173], v[210:213], 0
	v_mfma_f32_16x16x32_bf16 v[64:67], v[178:181], v[210:213], 0
	v_mfma_f32_16x16x32_bf16 v[116:119], v[174:177], v[190:193], v[116:119]
	v_mfma_f32_16x16x32_bf16 v[112:115], v[182:185], v[190:193], v[112:115]
	v_mfma_f32_16x16x32_bf16 v[100:103], v[174:177], v[198:201], v[100:103]
	v_mfma_f32_16x16x32_bf16 v[96:99], v[182:185], v[198:201], v[96:99]
	v_mfma_f32_16x16x32_bf16 v[84:87], v[174:177], v[206:209], v[84:87]
	v_mfma_f32_16x16x32_bf16 v[80:83], v[182:185], v[206:209], v[80:83]
	v_mfma_f32_16x16x32_bf16 v[68:71], v[174:177], v[214:217], v[68:71]
	v_mfma_f32_16x16x32_bf16 v[64:67], v[182:185], v[214:217], v[64:67]
	s_barrier
	s_add_i32 s26, s75, s68
	s_mov_b32 m0, s26
	ds_read_b128 v[186:189], v155 offset:16384
	ds_read_b128 v[190:193], v155 offset:17408
	ds_read_b128 v[194:197], v155 offset:18432
	ds_read_b128 v[198:201], v155 offset:19456
	ds_read_b128 v[202:205], v155 offset:20480
	ds_read_b128 v[206:209], v155 offset:21504
	ds_read_b128 v[210:213], v155 offset:22528
	ds_read_b128 v[214:217], v155 offset:23552
	global_load_lds_dwordx4 v130, s[64:65]
	s_add_i32 m0, s26, 0x2000
	s_add_u32 s26, s64, 0x10000
	s_addc_u32 s27, s65, 0
	s_add_i32 s33, s76, s68
	global_load_lds_dwordx4 v134, s[64:65]
	s_mov_b32 m0, s33
	s_nop 0
	global_load_lds_dwordx4 v130, s[26:27]
	s_add_i32 m0, s33, 0x2000
	s_nop 0
	global_load_lds_dwordx4 v134, s[26:27]
	s_mov_b32 m0, s61
	s_nop 0
	global_load_lds_dwordx4 v128, s[66:67]
	s_mov_b32 m0, s69
	s_nop 0
	global_load_lds_dwordx4 v132, s[66:67]
	s_waitcnt vmcnt(8)
	s_waitcnt lgkmcnt(0)
	s_barrier
	s_waitcnt lgkmcnt(0)
	v_mfma_f32_16x16x32_bf16 v[60:63], v[146:149], v[186:189], 0
	v_mfma_f32_16x16x32_bf16 v[56:59], v[162:165], v[186:189], 0
	v_mfma_f32_16x16x32_bf16 v[44:47], v[146:149], v[194:197], 0
	v_mfma_f32_16x16x32_bf16 v[40:43], v[162:165], v[194:197], 0
	v_mfma_f32_16x16x32_bf16 v[28:31], v[146:149], v[202:205], 0
	v_mfma_f32_16x16x32_bf16 v[24:27], v[162:165], v[202:205], 0
	v_mfma_f32_16x16x32_bf16 v[12:15], v[146:149], v[210:213], 0
	v_mfma_f32_16x16x32_bf16 v[8:11], v[162:165], v[210:213], 0
	v_mfma_f32_16x16x32_bf16 v[60:63], v[158:161], v[190:193], v[60:63]
	v_mfma_f32_16x16x32_bf16 v[56:59], v[166:169], v[190:193], v[56:59]
	v_mfma_f32_16x16x32_bf16 v[44:47], v[158:161], v[198:201], v[44:47]
	v_mfma_f32_16x16x32_bf16 v[40:43], v[166:169], v[198:201], v[40:43]
	v_mfma_f32_16x16x32_bf16 v[28:31], v[158:161], v[206:209], v[28:31]
	v_mfma_f32_16x16x32_bf16 v[24:27], v[166:169], v[206:209], v[24:27]
	v_mfma_f32_16x16x32_bf16 v[12:15], v[158:161], v[214:217], v[12:15]
	v_mfma_f32_16x16x32_bf16 v[8:11], v[166:169], v[214:217], v[8:11]
	v_mfma_f32_16x16x32_bf16 v[52:55], v[170:173], v[186:189], 0
	v_mfma_f32_16x16x32_bf16 v[48:51], v[178:181], v[186:189], 0
	v_mfma_f32_16x16x32_bf16 v[36:39], v[170:173], v[194:197], 0
	v_mfma_f32_16x16x32_bf16 v[32:35], v[178:181], v[194:197], 0
	v_mfma_f32_16x16x32_bf16 v[20:23], v[170:173], v[202:205], 0
	v_mfma_f32_16x16x32_bf16 v[16:19], v[178:181], v[202:205], 0
	v_mfma_f32_16x16x32_bf16 v[4:7], v[170:173], v[210:213], 0
	v_mfma_f32_16x16x32_bf16 v[0:3], v[178:181], v[210:213], 0
	v_mfma_f32_16x16x32_bf16 v[52:55], v[174:177], v[190:193], v[52:55]
	v_mfma_f32_16x16x32_bf16 v[48:51], v[182:185], v[190:193], v[48:51]
	v_mfma_f32_16x16x32_bf16 v[36:39], v[174:177], v[198:201], v[36:39]
	v_mfma_f32_16x16x32_bf16 v[32:35], v[182:185], v[198:201], v[32:35]
	v_mfma_f32_16x16x32_bf16 v[20:23], v[174:177], v[206:209], v[20:23]
	v_mfma_f32_16x16x32_bf16 v[16:19], v[182:185], v[206:209], v[16:19]
	v_mfma_f32_16x16x32_bf16 v[4:7], v[174:177], v[214:217], v[4:7]
	v_mfma_f32_16x16x32_bf16 v[0:3], v[182:185], v[214:217], v[0:3]
	s_barrier
; #define PG8_STAGE(bufoff, gbase, voff) do { _Pragma("unroll") for (int _i = 0; _i < 2; ++_i) \
;         __builtin_amdgcn_global_load_lds((const unsigned*)((const char*)(gbase) + (voff)[_i]), (PG8_LAS unsigned*)(lds + (bufoff) + ldsw + _i * 8192), 16, 0, 0); } while (0)
; #define PG8_LDA(dst, b, h) do { _Pragma("unroll") for (int m = 0; m < 4; ++m) _Pragma("unroll") for (int k = 0; k < 2; ++k) dst[m][k] = *(const PG8_LAS bf16x8*)(lds + PG8_SA(b, h) + aoff + m * 2048 + k * 1024); } while (0)
; #define PG8_LDB(dst, b, h) do { _Pragma("unroll") for (int n = 0; n < 2; ++n) _Pragma("unroll") for (int k = 0; k < 2; ++k) dst[n][k] = *(const PG8_LAS bf16x8*)(lds + PG8_SB(b, h) + boff + n * 2048 + k * 1024); } while (0)
; #define PG8_MMA(ai, bj, At, Bt) do { __builtin_amdgcn_s_setprio(1); _Pragma("unroll") for (int m = 0; m < 4; ++m) _Pragma("unroll") for (int n = 0; n < 2; ++n) _Pragma("unroll") for (int k = 0; k < 2; ++k) \
;         acc[ai][bj][m][n] = __builtin_amdgcn_mfma_f32_16x16x32_bf16(Bt[n][k], At[m][k], acc[ai][bj][m][n], 0, 0, 0); __builtin_amdgcn_s_setprio(0); } while (0)
; #define PG8_WAIT_V(n) asm volatile("s_waitcnt vmcnt(" #n ")" ::: "memory")
; #define PG8_WAIT_L(n) asm volatile("s_waitcnt lgkmcnt(" #n ")" ::: "memory")
; #define PG8_BAR __builtin_amdgcn_s_barrier()
; #define PG8_SCHED __builtin_amdgcn_sched_barrier(0)
; template <class Epi, class Sched, bool ALIGN_EPI = false, bool SP2 = false>
; __device__ __forceinline__ void gemm_phase(PG8_LAS unsigned char* lds, const Gemm g, const Sched& S, const Epi& E, int tid_in) {
;     ...
;             PG8_LDB(B0, 1, 0); PG8_LDB(B1, 1, 1); PG8_SCHED; PG8_LDA(At, 1, 0); PG8_STAGE(PG8_SA(0, 1), a2 + hstep, voffA);
;             PG8_WAIT_V(8); PG8_WAIT_L(0); PG8_BAR; PG8_MMA(0, 0, At, B0); PG8_MMA(0, 1, At, B1); PG8_BAR; PG8_SCHED;
;             PG8_LDA(At, 1, 1); PG8_STAGE(PG8_SB(1, 0), b3, voffB); PG8_STAGE(PG8_SB(1, 1), b3 + hstepB, voffB); PG8_STAGE(PG8_SA(1, 0), a3, voffA);
;             PG8_WAIT_V(8); PG8_WAIT_L(0); PG8_BAR; PG8_MMA(1, 0, At, B0); PG8_MMA(1, 1, At, B1); PG8_BAR; PG8_SCHED;
	s_add_i32 s33, 0, 0x18000
	s_add_i32 s84, 0, 0x1c000
	v_add_u32_e32 v166, s33, v137
	v_add_u32_e32 v182, s84, v137
	ds_read_b128 v[146:149], v166
	ds_read_b128 v[158:161], v166 offset:1024
	ds_read_b128 v[162:165], v166 offset:2048
	ds_read_b128 v[166:169], v166 offset:3072
	ds_read_b128 v[170:173], v182
	ds_read_b128 v[174:177], v182 offset:1024
	ds_read_b128 v[178:181], v182 offset:2048
	ds_read_b128 v[182:185], v182 offset:3072
	s_add_u32 s26, s66, 0x40000
	s_addc_u32 s27, s67, 0
	s_mov_b32 m0, s70
	ds_read_b128 v[186:189], v155 offset:32768
	ds_read_b128 v[190:193], v155 offset:33792
	ds_read_b128 v[194:197], v155 offset:34816
	ds_read_b128 v[198:201], v155 offset:35840
	ds_read_b128 v[202:205], v155 offset:36864
	ds_read_b128 v[206:209], v155 offset:37888
	ds_read_b128 v[210:213], v155 offset:38912
	ds_read_b128 v[214:217], v155 offset:39936
	global_load_lds_dwordx4 v128, s[26:27]
	s_mov_b32 m0, s71
	s_nop 0
	global_load_lds_dwordx4 v132, s[26:27]
	s_waitcnt vmcnt(8)
	s_waitcnt lgkmcnt(0)
	s_barrier
	s_waitcnt lgkmcnt(0)
	v_mfma_f32_16x16x32_bf16 v[124:127], v[146:149], v[186:189], v[124:127]
	v_mfma_f32_16x16x32_bf16 v[120:123], v[162:165], v[186:189], v[120:123]
	v_mfma_f32_16x16x32_bf16 v[108:111], v[146:149], v[194:197], v[108:111]
	v_mfma_f32_16x16x32_bf16 v[104:107], v[162:165], v[194:197], v[104:107]
	v_mfma_f32_16x16x32_bf16 v[92:95], v[146:149], v[202:205], v[92:95]
	v_mfma_f32_16x16x32_bf16 v[88:91], v[162:165], v[202:205], v[88:91]
	v_mfma_f32_16x16x32_bf16 v[76:79], v[146:149], v[210:213], v[76:79]
	v_mfma_f32_16x16x32_bf16 v[72:75], v[162:165], v[210:213], v[72:75]
	v_mfma_f32_16x16x32_bf16 v[124:127], v[158:161], v[190:193], v[124:127]
	v_mfma_f32_16x16x32_bf16 v[120:123], v[166:169], v[190:193], v[120:123]
	v_mfma_f32_16x16x32_bf16 v[108:111], v[158:161], v[198:201], v[108:111]
	v_mfma_f32_16x16x32_bf16 v[104:107], v[166:169], v[198:201], v[104:107]
	v_mfma_f32_16x16x32_bf16 v[92:95], v[158:161], v[206:209], v[92:95]
	v_mfma_f32_16x16x32_bf16 v[88:91], v[166:169], v[206:209], v[88:91]
	v_mfma_f32_16x16x32_bf16 v[76:79], v[158:161], v[214:217], v[76:79]
	v_mfma_f32_16x16x32_bf16 v[72:75], v[166:169], v[214:217], v[72:75]
	v_mfma_f32_16x16x32_bf16 v[116:119], v[170:173], v[186:189], v[116:119]
	v_mfma_f32_16x16x32_bf16 v[112:115], v[178:181], v[186:189], v[112:115]
	v_mfma_f32_16x16x32_bf16 v[100:103], v[170:173], v[194:197], v[100:103]
	v_mfma_f32_16x16x32_bf16 v[96:99], v[178:181], v[194:197], v[96:99]
	v_mfma_f32_16x16x32_bf16 v[84:87], v[170:173], v[202:205], v[84:87]
	v_mfma_f32_16x16x32_bf16 v[80:83], v[178:181], v[202:205], v[80:83]
	v_mfma_f32_16x16x32_bf16 v[68:71], v[170:173], v[210:213], v[68:71]
	v_mfma_f32_16x16x32_bf16 v[64:67], v[178:181], v[210:213], v[64:67]
	v_mfma_f32_16x16x32_bf16 v[116:119], v[174:177], v[190:193], v[116:119]
	v_mfma_f32_16x16x32_bf16 v[112:115], v[182:185], v[190:193], v[112:115]
	v_mfma_f32_16x16x32_bf16 v[100:103], v[174:177], v[198:201], v[100:103]
	v_mfma_f32_16x16x32_bf16 v[96:99], v[182:185], v[198:201], v[96:99]
	v_mfma_f32_16x16x32_bf16 v[84:87], v[174:177], v[206:209], v[84:87]
	v_mfma_f32_16x16x32_bf16 v[80:83], v[182:185], v[206:209], v[80:83]
	v_mfma_f32_16x16x32_bf16 v[68:71], v[174:177], v[214:217], v[68:71]
	v_mfma_f32_16x16x32_bf16 v[64:67], v[182:185], v[214:217], v[64:67]
	s_barrier
	s_add_i32 s26, s33, s68
	s_add_i32 m0, s26, 0xffffff80
	ds_read_b128 v[186:189], v155 offset:49152
	ds_read_b128 v[190:193], v155 offset:50176
	ds_read_b128 v[194:197], v155 offset:51200
	ds_read_b128 v[198:201], v155 offset:52224
	ds_read_b128 v[202:205], v155 offset:53248
	ds_read_b128 v[206:209], v155 offset:54272
	ds_read_b128 v[210:213], v155 offset:55296
	ds_read_b128 v[214:217], v155 offset:56320
	global_load_lds_dwordx4 v130, s[64:65] offset:128
	s_add_i32 m0, s26, 0x1f80
	s_add_u32 s26, s64, 0x10080
	s_addc_u32 s27, s65, 0
	s_add_i32 s33, s84, s68
	global_load_lds_dwordx4 v134, s[64:65] offset:128
	s_mov_b32 m0, s33
	s_nop 0
	global_load_lds_dwordx4 v130, s[26:27]
	s_add_i32 m0, s33, 0x2000
	s_nop 0
	global_load_lds_dwordx4 v134, s[26:27]
	s_add_i32 m0, s73, 0xffffff80
	s_nop 0
	global_load_lds_dwordx4 v128, s[66:67] offset:128
	s_add_i32 m0, s74, 0xffffff80
	s_nop 0
	global_load_lds_dwordx4 v132, s[66:67] offset:128
	s_waitcnt vmcnt(8)
	s_waitcnt lgkmcnt(0)
	s_barrier
	s_waitcnt lgkmcnt(0)
	v_mfma_f32_16x16x32_bf16 v[60:63], v[146:149], v[186:189], v[60:63]
	v_mfma_f32_16x16x32_bf16 v[56:59], v[162:165], v[186:189], v[56:59]
	v_mfma_f32_16x16x32_bf16 v[44:47], v[146:149], v[194:197], v[44:47]
	v_mfma_f32_16x16x32_bf16 v[40:43], v[162:165], v[194:197], v[40:43]
	v_mfma_f32_16x16x32_bf16 v[28:31], v[146:149], v[202:205], v[28:31]
	v_mfma_f32_16x16x32_bf16 v[24:27], v[162:165], v[202:205], v[24:27]
	v_mfma_f32_16x16x32_bf16 v[12:15], v[146:149], v[210:213], v[12:15]
	v_mfma_f32_16x16x32_bf16 v[8:11], v[162:165], v[210:213], v[8:11]
	v_mfma_f32_16x16x32_bf16 v[60:63], v[158:161], v[190:193], v[60:63]
	v_mfma_f32_16x16x32_bf16 v[56:59], v[166:169], v[190:193], v[56:59]
	v_mfma_f32_16x16x32_bf16 v[44:47], v[158:161], v[198:201], v[44:47]
	v_mfma_f32_16x16x32_bf16 v[40:43], v[166:169], v[198:201], v[40:43]
	v_mfma_f32_16x16x32_bf16 v[28:31], v[158:161], v[206:209], v[28:31]
	v_mfma_f32_16x16x32_bf16 v[24:27], v[166:169], v[206:209], v[24:27]
	v_mfma_f32_16x16x32_bf16 v[12:15], v[158:161], v[214:217], v[12:15]
	v_mfma_f32_16x16x32_bf16 v[8:11], v[166:169], v[214:217], v[8:11]
	v_mfma_f32_16x16x32_bf16 v[52:55], v[170:173], v[186:189], v[52:55]
	v_mfma_f32_16x16x32_bf16 v[48:51], v[178:181], v[186:189], v[48:51]
	v_mfma_f32_16x16x32_bf16 v[36:39], v[170:173], v[194:197], v[36:39]
	v_mfma_f32_16x16x32_bf16 v[32:35], v[178:181], v[194:197], v[32:35]
	v_mfma_f32_16x16x32_bf16 v[20:23], v[170:173], v[202:205], v[20:23]
	v_mfma_f32_16x16x32_bf16 v[16:19], v[178:181], v[202:205], v[16:19]
	v_mfma_f32_16x16x32_bf16 v[4:7], v[170:173], v[210:213], v[4:7]
	v_mfma_f32_16x16x32_bf16 v[0:3], v[178:181], v[210:213], v[0:3]
	v_mfma_f32_16x16x32_bf16 v[52:55], v[174:177], v[190:193], v[52:55]
	v_mfma_f32_16x16x32_bf16 v[48:51], v[182:185], v[190:193], v[48:51]
	v_mfma_f32_16x16x32_bf16 v[36:39], v[174:177], v[198:201], v[36:39]
	v_mfma_f32_16x16x32_bf16 v[32:35], v[182:185], v[198:201], v[32:35]
	v_mfma_f32_16x16x32_bf16 v[20:23], v[174:177], v[206:209], v[20:23]
	v_mfma_f32_16x16x32_bf16 v[16:19], v[182:185], v[206:209], v[16:19]
	v_mfma_f32_16x16x32_bf16 v[4:7], v[174:177], v[214:217], v[4:7]
	v_mfma_f32_16x16x32_bf16 v[0:3], v[182:185], v[214:217], v[0:3]
	s_barrier
	s_add_i32 s83, s83, 2
	s_add_u32 s62, s62, 0x100
	s_addc_u32 s63, s63, 0
	s_add_u32 s78, s78, 0x100
	s_addc_u32 s79, s79, 0
	s_cmp_gt_u32 s83, 13
; #define PG8_STAGE(bufoff, gbase, voff) do { _Pragma("unroll") for (int _i = 0; _i < 2; ++_i) \
;         __builtin_amdgcn_global_load_lds((const unsigned*)((const char*)(gbase) + (voff)[_i]), (PG8_LAS unsigned*)(lds + (bufoff) + ldsw + _i * 8192), 16, 0, 0); } while (0)
; #define PG8_LDA(dst, b, h) do { _Pragma("unroll") for (int m = 0; m < 4; ++m) _Pragma("unroll") for (int k = 0; k < 2; ++k) dst[m][k] = *(const PG8_LAS bf16x8*)(lds + PG8_SA(b, h) + aoff + m * 2048 + k * 1024); } while (0)
; #define PG8_LDB(dst, b, h) do { _Pragma("unroll") for (int n = 0; n < 2; ++n) _Pragma("unroll") for (int k = 0; k < 2; ++k) dst[n][k] = *(const PG8_LAS bf16x8*)(lds + PG8_SB(b, h) + boff + n * 2048 + k * 1024); } while (0)
; #define PG8_MMA(ai, bj, At, Bt) do { __builtin_amdgcn_s_setprio(1); _Pragma("unroll") for (int m = 0; m < 4; ++m) _Pragma("unroll") for (int n = 0; n < 2; ++n) _Pragma("unroll") for (int k = 0; k < 2; ++k) \
;         acc[ai][bj][m][n] = __builtin_amdgcn_mfma_f32_16x16x32_bf16(Bt[n][k], At[m][k], acc[ai][bj][m][n], 0, 0, 0); __builtin_amdgcn_s_setprio(0); } while (0)
; #define PG8_WAIT_V(n) asm volatile("s_waitcnt vmcnt(" #n ")" ::: "memory")
; #define PG8_WAIT_L(n) asm volatile("s_waitcnt lgkmcnt(" #n ")" ::: "memory")
; #define PG8_BAR __builtin_amdgcn_s_barrier()
; #define PG8_SCHED __builtin_amdgcn_sched_barrier(0)
; template <class Epi, class Sched, bool ALIGN_EPI = false, bool SP2 = false>
; __device__ __forceinline__ void gemm_phase(PG8_LAS unsigned char* lds, const Gemm g, const Sched& S, const Epi& E, int tid_in) {
;     ...
;             PG8_LDB(B0, 0, 0); PG8_LDB(B1, 0, 1); PG8_SCHED; PG8_LDA(At, 0, 0); PG8_STAGE(PG8_SA(1, 1), a1 + hstep, voffA);
;             PG8_WAIT_V(8); PG8_WAIT_L(0); PG8_BAR; PG8_MMA(0, 0, At, B0); PG8_MMA(0, 1, At, B1); PG8_BAR; PG8_SCHED;
;             PG8_LDA(At, 0, 1); PG8_STAGE(PG8_SB(0, 0), b2, voffB); PG8_STAGE(PG8_SB(0, 1), b2 + hstepB, voffB); PG8_STAGE(PG8_SA(0, 0), a2, voffA);
;             PG8_WAIT_V(8); PG8_WAIT_L(0); PG8_BAR; PG8_MMA(1, 0, At, B0); PG8_MMA(1, 1, At, B1); PG8_BAR; PG8_SCHED;
.LBB0_767:
	ds_read_b128 v[146:149], v153
	ds_read_b128 v[158:161], v153 offset:1024
	ds_read_b128 v[162:165], v153 offset:2048
	ds_read_b128 v[166:169], v153 offset:3072
	ds_read_b128 v[170:173], v154
	ds_read_b128 v[174:177], v154 offset:1024
	ds_read_b128 v[178:181], v154 offset:2048
	ds_read_b128 v[182:185], v154 offset:3072
	s_add_u32 s26, s62, 0xfffc0080
	s_addc_u32 s27, s63, -1
	s_cmp_eq_u32 s83, 12
	s_cselect_b32 s67, s53, s27
	s_cselect_b32 s66, s59, s26
	s_cselect_b32 s65, s51, s79
	s_cselect_b32 s64, s77, s78
	s_add_i32 m0, s61, 0xc000
	ds_read_b128 v[186:189], v155
	ds_read_b128 v[190:193], v155 offset:1024
	ds_read_b128 v[194:197], v155 offset:2048
	ds_read_b128 v[198:201], v155 offset:3072
	ds_read_b128 v[202:205], v155 offset:4096
	ds_read_b128 v[206:209], v155 offset:5120
	ds_read_b128 v[210:213], v155 offset:6144
	ds_read_b128 v[214:217], v155 offset:7168
	global_load_lds_dwordx4 v138, s[62:63]
	s_add_i32 m0, s61, 0xe000
	s_nop 0
	global_load_lds_dwordx4 v140, s[62:63]
	s_waitcnt vmcnt(8)
	s_waitcnt lgkmcnt(0)
	s_barrier
	s_waitcnt lgkmcnt(0)
	v_mfma_f32_16x16x32_bf16 v[124:127], v[146:149], v[186:189], v[124:127]
	v_mfma_f32_16x16x32_bf16 v[120:123], v[162:165], v[186:189], v[120:123]
	v_mfma_f32_16x16x32_bf16 v[108:111], v[146:149], v[194:197], v[108:111]
	v_mfma_f32_16x16x32_bf16 v[104:107], v[162:165], v[194:197], v[104:107]
	v_mfma_f32_16x16x32_bf16 v[92:95], v[146:149], v[202:205], v[92:95]
	v_mfma_f32_16x16x32_bf16 v[88:91], v[162:165], v[202:205], v[88:91]
	v_mfma_f32_16x16x32_bf16 v[76:79], v[146:149], v[210:213], v[76:79]
	v_mfma_f32_16x16x32_bf16 v[72:75], v[162:165], v[210:213], v[72:75]
	v_mfma_f32_16x16x32_bf16 v[124:127], v[158:161], v[190:193], v[124:127]
	v_mfma_f32_16x16x32_bf16 v[120:123], v[166:169], v[190:193], v[120:123]
	v_mfma_f32_16x16x32_bf16 v[108:111], v[158:161], v[198:201], v[108:111]
	v_mfma_f32_16x16x32_bf16 v[104:107], v[166:169], v[198:201], v[104:107]
	v_mfma_f32_16x16x32_bf16 v[92:95], v[158:161], v[206:209], v[92:95]
	v_mfma_f32_16x16x32_bf16 v[88:91], v[166:169], v[206:209], v[88:91]
	v_mfma_f32_16x16x32_bf16 v[76:79], v[158:161], v[214:217], v[76:79]
	v_mfma_f32_16x16x32_bf16 v[72:75], v[166:169], v[214:217], v[72:75]
	v_mfma_f32_16x16x32_bf16 v[116:119], v[170:173], v[186:189], v[116:119]
	v_mfma_f32_16x16x32_bf16 v[112:115], v[178:181], v[186:189], v[112:115]
	v_mfma_f32_16x16x32_bf16 v[100:103], v[170:173], v[194:197], v[100:103]
	v_mfma_f32_16x16x32_bf16 v[96:99], v[178:181], v[194:197], v[96:99]
	v_mfma_f32_16x16x32_bf16 v[84:87], v[170:173], v[202:205], v[84:87]
	v_mfma_f32_16x16x32_bf16 v[80:83], v[178:181], v[202:205], v[80:83]
	v_mfma_f32_16x16x32_bf16 v[68:71], v[170:173], v[210:213], v[68:71]
	v_mfma_f32_16x16x32_bf16 v[64:67], v[178:181], v[210:213], v[64:67]
	v_mfma_f32_16x16x32_bf16 v[116:119], v[174:177], v[190:193], v[116:119]
	v_mfma_f32_16x16x32_bf16 v[112:115], v[182:185], v[190:193], v[112:115]
	v_mfma_f32_16x16x32_bf16 v[100:103], v[174:177], v[198:201], v[100:103]
	v_mfma_f32_16x16x32_bf16 v[96:99], v[182:185], v[198:201], v[96:99]
	v_mfma_f32_16x16x32_bf16 v[84:87], v[174:177], v[206:209], v[84:87]
	v_mfma_f32_16x16x32_bf16 v[80:83], v[182:185], v[206:209], v[80:83]
	v_mfma_f32_16x16x32_bf16 v[68:71], v[174:177], v[214:217], v[68:71]
	v_mfma_f32_16x16x32_bf16 v[64:67], v[182:185], v[214:217], v[64:67]
	s_barrier
	s_add_i32 s26, s75, s68
	s_mov_b32 m0, s26
	ds_read_b128 v[186:189], v155 offset:16384
	ds_read_b128 v[190:193], v155 offset:17408
	ds_read_b128 v[194:197], v155 offset:18432
	ds_read_b128 v[198:201], v155 offset:19456
	ds_read_b128 v[202:205], v155 offset:20480
	ds_read_b128 v[206:209], v155 offset:21504
	ds_read_b128 v[210:213], v155 offset:22528
	ds_read_b128 v[214:217], v155 offset:23552
	global_load_lds_dwordx4 v130, s[64:65]
	s_add_i32 m0, s26, 0x2000
	s_add_u32 s26, s64, 0x10000
	s_addc_u32 s27, s65, 0
	s_add_i32 s33, s76, s68
	global_load_lds_dwordx4 v134, s[64:65]
	s_mov_b32 m0, s33
	s_nop 0
	global_load_lds_dwordx4 v130, s[26:27]
	s_add_i32 m0, s33, 0x2000
	s_nop 0
	global_load_lds_dwordx4 v134, s[26:27]
	s_mov_b32 m0, s61
	s_nop 0
	global_load_lds_dwordx4 v128, s[66:67]
	s_mov_b32 m0, s69
	s_nop 0
	global_load_lds_dwordx4 v132, s[66:67]
	s_waitcnt vmcnt(8)
	s_waitcnt lgkmcnt(0)
	s_barrier
	s_waitcnt lgkmcnt(0)
	v_mfma_f32_16x16x32_bf16 v[60:63], v[146:149], v[186:189], v[60:63]
	v_mfma_f32_16x16x32_bf16 v[56:59], v[162:165], v[186:189], v[56:59]
	v_mfma_f32_16x16x32_bf16 v[44:47], v[146:149], v[194:197], v[44:47]
	v_mfma_f32_16x16x32_bf16 v[40:43], v[162:165], v[194:197], v[40:43]
	v_mfma_f32_16x16x32_bf16 v[28:31], v[146:149], v[202:205], v[28:31]
	v_mfma_f32_16x16x32_bf16 v[24:27], v[162:165], v[202:205], v[24:27]
	v_mfma_f32_16x16x32_bf16 v[12:15], v[146:149], v[210:213], v[12:15]
	v_mfma_f32_16x16x32_bf16 v[8:11], v[162:165], v[210:213], v[8:11]
	v_mfma_f32_16x16x32_bf16 v[60:63], v[158:161], v[190:193], v[60:63]
	v_mfma_f32_16x16x32_bf16 v[56:59], v[166:169], v[190:193], v[56:59]
	v_mfma_f32_16x16x32_bf16 v[44:47], v[158:161], v[198:201], v[44:47]
	v_mfma_f32_16x16x32_bf16 v[40:43], v[166:169], v[198:201], v[40:43]
	v_mfma_f32_16x16x32_bf16 v[28:31], v[158:161], v[206:209], v[28:31]
	v_mfma_f32_16x16x32_bf16 v[24:27], v[166:169], v[206:209], v[24:27]
	v_mfma_f32_16x16x32_bf16 v[12:15], v[158:161], v[214:217], v[12:15]
	v_mfma_f32_16x16x32_bf16 v[8:11], v[166:169], v[214:217], v[8:11]
	v_mfma_f32_16x16x32_bf16 v[52:55], v[170:173], v[186:189], v[52:55]
	v_mfma_f32_16x16x32_bf16 v[48:51], v[178:181], v[186:189], v[48:51]
	v_mfma_f32_16x16x32_bf16 v[36:39], v[170:173], v[194:197], v[36:39]
	v_mfma_f32_16x16x32_bf16 v[32:35], v[178:181], v[194:197], v[32:35]
	v_mfma_f32_16x16x32_bf16 v[20:23], v[170:173], v[202:205], v[20:23]
	v_mfma_f32_16x16x32_bf16 v[16:19], v[178:181], v[202:205], v[16:19]
	v_mfma_f32_16x16x32_bf16 v[4:7], v[170:173], v[210:213], v[4:7]
	v_mfma_f32_16x16x32_bf16 v[0:3], v[178:181], v[210:213], v[0:3]
	v_mfma_f32_16x16x32_bf16 v[52:55], v[174:177], v[190:193], v[52:55]
	v_mfma_f32_16x16x32_bf16 v[48:51], v[182:185], v[190:193], v[48:51]
	v_mfma_f32_16x16x32_bf16 v[36:39], v[174:177], v[198:201], v[36:39]
	v_mfma_f32_16x16x32_bf16 v[32:35], v[182:185], v[198:201], v[32:35]
	v_mfma_f32_16x16x32_bf16 v[20:23], v[174:177], v[206:209], v[20:23]
	v_mfma_f32_16x16x32_bf16 v[16:19], v[182:185], v[206:209], v[16:19]
	v_mfma_f32_16x16x32_bf16 v[4:7], v[174:177], v[214:217], v[4:7]
	v_mfma_f32_16x16x32_bf16 v[0:3], v[182:185], v[214:217], v[0:3]
	s_barrier
; #define PG8_STAGE(bufoff, gbase, voff) do { _Pragma("unroll") for (int _i = 0; _i < 2; ++_i) \
;         __builtin_amdgcn_global_load_lds((const unsigned*)((const char*)(gbase) + (voff)[_i]), (PG8_LAS unsigned*)(lds + (bufoff) + ldsw + _i * 8192), 16, 0, 0); } while (0)
; #define PG8_LDA(dst, b, h) do { _Pragma("unroll") for (int m = 0; m < 4; ++m) _Pragma("unroll") for (int k = 0; k < 2; ++k) dst[m][k] = *(const PG8_LAS bf16x8*)(lds + PG8_SA(b, h) + aoff + m * 2048 + k * 1024); } while (0)
; #define PG8_LDB(dst, b, h) do { _Pragma("unroll") for (int n = 0; n < 2; ++n) _Pragma("unroll") for (int k = 0; k < 2; ++k) dst[n][k] = *(const PG8_LAS bf16x8*)(lds + PG8_SB(b, h) + boff + n * 2048 + k * 1024); } while (0)
; #define PG8_MMA(ai, bj, At, Bt) do { __builtin_amdgcn_s_setprio(1); _Pragma("unroll") for (int m = 0; m < 4; ++m) _Pragma("unroll") for (int n = 0; n < 2; ++n) _Pragma("unroll") for (int k = 0; k < 2; ++k) \
;         acc[ai][bj][m][n] = __builtin_amdgcn_mfma_f32_16x16x32_bf16(Bt[n][k], At[m][k], acc[ai][bj][m][n], 0, 0, 0); __builtin_amdgcn_s_setprio(0); } while (0)
; #define PG8_WAIT_V(n) asm volatile("s_waitcnt vmcnt(" #n ")" ::: "memory")
; #define PG8_WAIT_L(n) asm volatile("s_waitcnt lgkmcnt(" #n ")" ::: "memory")
; #define PG8_BAR __builtin_amdgcn_s_barrier()
; #define PG8_SCHED __builtin_amdgcn_sched_barrier(0)
; template <class Epi, class Sched, bool ALIGN_EPI = false, bool SP2 = false>
; __device__ __forceinline__ void gemm_phase(PG8_LAS unsigned char* lds, const Gemm g, const Sched& S, const Epi& E, int tid_in) {
;     ...
;             PG8_LDB(B0, 1, 0); PG8_LDB(B1, 1, 1); PG8_SCHED; PG8_LDA(At, 1, 0); PG8_STAGE(PG8_SA(0, 1), a2 + hstep, voffA);
;             PG8_WAIT_V(8); PG8_WAIT_L(0); PG8_BAR; PG8_MMA(0, 0, At, B0); PG8_MMA(0, 1, At, B1); PG8_BAR; PG8_SCHED;
;             PG8_LDA(At, 1, 1); PG8_STAGE(PG8_SB(1, 0), b3, voffB); PG8_STAGE(PG8_SB(1, 1), b3 + hstepB, voffB); PG8_STAGE(PG8_SA(1, 0), a3, voffA);
;             PG8_WAIT_V(8); PG8_WAIT_L(0); PG8_BAR; PG8_MMA(1, 0, At, B0); PG8_MMA(1, 1, At, B1); PG8_BAR; PG8_SCHED;
	s_add_i32 s33, 0, 0x18000
	s_add_i32 s84, 0, 0x1c000
	v_add_u32_e32 v166, s33, v137
	v_add_u32_e32 v182, s84, v137
	ds_read_b128 v[146:149], v166
	ds_read_b128 v[158:161], v166 offset:1024
	ds_read_b128 v[162:165], v166 offset:2048
	ds_read_b128 v[166:169], v166 offset:3072
	ds_read_b128 v[170:173], v182
	ds_read_b128 v[174:177], v182 offset:1024
	ds_read_b128 v[178:181], v182 offset:2048
	ds_read_b128 v[182:185], v182 offset:3072
	s_add_u32 s26, s66, 0x40000
	s_addc_u32 s27, s67, 0
	s_mov_b32 m0, s70
	ds_read_b128 v[186:189], v155 offset:32768
	ds_read_b128 v[190:193], v155 offset:33792
	ds_read_b128 v[194:197], v155 offset:34816
	ds_read_b128 v[198:201], v155 offset:35840
	ds_read_b128 v[202:205], v155 offset:36864
	ds_read_b128 v[206:209], v155 offset:37888
	ds_read_b128 v[210:213], v155 offset:38912
	ds_read_b128 v[214:217], v155 offset:39936
	global_load_lds_dwordx4 v128, s[26:27]
	s_mov_b32 m0, s71
	s_nop 0
	global_load_lds_dwordx4 v132, s[26:27]
	s_waitcnt vmcnt(8)
	s_waitcnt lgkmcnt(0)
	s_barrier
	s_waitcnt lgkmcnt(0)
	v_mfma_f32_16x16x32_bf16 v[124:127], v[146:149], v[186:189], v[124:127]
	v_mfma_f32_16x16x32_bf16 v[120:123], v[162:165], v[186:189], v[120:123]
	v_mfma_f32_16x16x32_bf16 v[108:111], v[146:149], v[194:197], v[108:111]
	v_mfma_f32_16x16x32_bf16 v[104:107], v[162:165], v[194:197], v[104:107]
	v_mfma_f32_16x16x32_bf16 v[92:95], v[146:149], v[202:205], v[92:95]
	v_mfma_f32_16x16x32_bf16 v[88:91], v[162:165], v[202:205], v[88:91]
	v_mfma_f32_16x16x32_bf16 v[76:79], v[146:149], v[210:213], v[76:79]
	v_mfma_f32_16x16x32_bf16 v[72:75], v[162:165], v[210:213], v[72:75]
	v_mfma_f32_16x16x32_bf16 v[124:127], v[158:161], v[190:193], v[124:127]
	v_mfma_f32_16x16x32_bf16 v[120:123], v[166:169], v[190:193], v[120:123]
	v_mfma_f32_16x16x32_bf16 v[108:111], v[158:161], v[198:201], v[108:111]
	v_mfma_f32_16x16x32_bf16 v[104:107], v[166:169], v[198:201], v[104:107]
	v_mfma_f32_16x16x32_bf16 v[92:95], v[158:161], v[206:209], v[92:95]
	v_mfma_f32_16x16x32_bf16 v[88:91], v[166:169], v[206:209], v[88:91]
	v_mfma_f32_16x16x32_bf16 v[76:79], v[158:161], v[214:217], v[76:79]
	v_mfma_f32_16x16x32_bf16 v[72:75], v[166:169], v[214:217], v[72:75]
	v_mfma_f32_16x16x32_bf16 v[116:119], v[170:173], v[186:189], v[116:119]
	v_mfma_f32_16x16x32_bf16 v[112:115], v[178:181], v[186:189], v[112:115]
	v_mfma_f32_16x16x32_bf16 v[100:103], v[170:173], v[194:197], v[100:103]
	v_mfma_f32_16x16x32_bf16 v[96:99], v[178:181], v[194:197], v[96:99]
	v_mfma_f32_16x16x32_bf16 v[84:87], v[170:173], v[202:205], v[84:87]
	v_mfma_f32_16x16x32_bf16 v[80:83], v[178:181], v[202:205], v[80:83]
	v_mfma_f32_16x16x32_bf16 v[68:71], v[170:173], v[210:213], v[68:71]
	v_mfma_f32_16x16x32_bf16 v[64:67], v[178:181], v[210:213], v[64:67]
	v_mfma_f32_16x16x32_bf16 v[116:119], v[174:177], v[190:193], v[116:119]
	v_mfma_f32_16x16x32_bf16 v[112:115], v[182:185], v[190:193], v[112:115]
	v_mfma_f32_16x16x32_bf16 v[100:103], v[174:177], v[198:201], v[100:103]
	v_mfma_f32_16x16x32_bf16 v[96:99], v[182:185], v[198:201], v[96:99]
	v_mfma_f32_16x16x32_bf16 v[84:87], v[174:177], v[206:209], v[84:87]
	v_mfma_f32_16x16x32_bf16 v[80:83], v[182:185], v[206:209], v[80:83]
	v_mfma_f32_16x16x32_bf16 v[68:71], v[174:177], v[214:217], v[68:71]
	v_mfma_f32_16x16x32_bf16 v[64:67], v[182:185], v[214:217], v[64:67]
	s_barrier
	s_add_i32 s26, s33, s68
	s_add_i32 m0, s26, 0xffffff80
	ds_read_b128 v[186:189], v155 offset:49152
	ds_read_b128 v[190:193], v155 offset:50176
	ds_read_b128 v[194:197], v155 offset:51200
	ds_read_b128 v[198:201], v155 offset:52224
	ds_read_b128 v[202:205], v155 offset:53248
	ds_read_b128 v[206:209], v155 offset:54272
	ds_read_b128 v[210:213], v155 offset:55296
	ds_read_b128 v[214:217], v155 offset:56320
	global_load_lds_dwordx4 v130, s[64:65] offset:128
	s_add_i32 m0, s26, 0x1f80
	s_add_u32 s26, s64, 0x10080
	s_addc_u32 s27, s65, 0
	s_add_i32 s33, s84, s68
	global_load_lds_dwordx4 v134, s[64:65] offset:128
	s_mov_b32 m0, s33
	s_nop 0
	global_load_lds_dwordx4 v130, s[26:27]
	s_add_i32 m0, s33, 0x2000
	s_nop 0
	global_load_lds_dwordx4 v134, s[26:27]
	s_add_i32 m0, s73, 0xffffff80
	s_nop 0
	global_load_lds_dwordx4 v128, s[66:67] offset:128
	s_add_i32 m0, s74, 0xffffff80
	s_nop 0
	global_load_lds_dwordx4 v132, s[66:67] offset:128
	s_waitcnt vmcnt(8)
	s_waitcnt lgkmcnt(0)
	s_barrier
; #define PG8_MMA(ai, bj, At, Bt) do { __builtin_amdgcn_s_setprio(1); _Pragma("unroll") for (int m = 0; m < 4; ++m) _Pragma("unroll") for (int n = 0; n < 2; ++n) _Pragma("unroll") for (int k = 0; k < 2; ++k) \
;         acc[ai][bj][m][n] = __builtin_amdgcn_mfma_f32_16x16x32_bf16(Bt[n][k], At[m][k], acc[ai][bj][m][n], 0, 0, 0); __builtin_amdgcn_s_setprio(0); } while (0)
; #define PG8_WAIT_V(n) asm volatile("s_waitcnt vmcnt(" #n ")" ::: "memory")
; #define PG8_WAIT_L(n) asm volatile("s_waitcnt lgkmcnt(" #n ")" ::: "memory")
; #define PG8_BAR __builtin_amdgcn_s_barrier()
; #define PG8_SCHED __builtin_amdgcn_sched_barrier(0)
; template <class Epi, class Sched, bool ALIGN_EPI = false, bool SP2 = false>
; __device__ __forceinline__ void gemm_phase(PG8_LAS unsigned char* lds, const Gemm g, const Sched& S, const Epi& E, int tid_in) {
;     ...
;             PG8_WAIT_V(8); PG8_WAIT_L(0); PG8_BAR; PG8_MMA(1, 0, At, B0); PG8_MMA(1, 1, At, B1); PG8_BAR; PG8_SCHED;
;     __device__ __forceinline__ void operator()(const f32x4 (&acc)[2][2][4][2], const Unit& u, int wr, int wc, int fr, int fq) const {
;     ...
;                 const int row = u.pm * BM + ai * HALF + wr * 64 + m * 16 + r; float q = 0.f;
; #pragma unroll
;                 for (int bj = 0; bj < 2; ++bj) {
;                     const size_t off = (size_t)row * 2048 + u.pn * BM + wc * 64 + bj * 32 + 8 * p;
;                     f32x4 b0, b1;
;                     if (BASE_F32) { b0 = *(const f32x4*)((const float*)base + off); b1 = *(const f32x4*)((const float*)base + off + 4); }
;                     else { const u32x4 bb = *(const u32x4*)((const bf16_t*)base + off);
;                         b0 = (f32x4){__uint_as_float(bb.x << 16), __uint_as_float(bb.x & 0xffff0000u), __uint_as_float(bb.y << 16), __uint_as_float(bb.y & 0xffff0000u)};
;                         b1 = (f32x4){__uint_as_float(bb.z << 16), __uint_as_float(bb.z & 0xffff0000u), __uint_as_float(bb.w << 16), __uint_as_float(bb.w & 0xffff0000u)}; }
	s_waitcnt lgkmcnt(0)
	v_mfma_f32_16x16x32_bf16 v[60:63], v[146:149], v[186:189], v[60:63]
	v_mfma_f32_16x16x32_bf16 v[56:59], v[162:165], v[186:189], v[56:59]
	v_mfma_f32_16x16x32_bf16 v[44:47], v[146:149], v[194:197], v[44:47]
	v_mfma_f32_16x16x32_bf16 v[40:43], v[162:165], v[194:197], v[40:43]
	v_mfma_f32_16x16x32_bf16 v[28:31], v[146:149], v[202:205], v[28:31]
	v_mfma_f32_16x16x32_bf16 v[24:27], v[162:165], v[202:205], v[24:27]
	v_mfma_f32_16x16x32_bf16 v[12:15], v[146:149], v[210:213], v[12:15]
	v_mfma_f32_16x16x32_bf16 v[8:11], v[162:165], v[210:213], v[8:11]
	v_mfma_f32_16x16x32_bf16 v[60:63], v[158:161], v[190:193], v[60:63]
	v_mfma_f32_16x16x32_bf16 v[56:59], v[166:169], v[190:193], v[56:59]
	v_mfma_f32_16x16x32_bf16 v[44:47], v[158:161], v[198:201], v[44:47]
	v_mfma_f32_16x16x32_bf16 v[40:43], v[166:169], v[198:201], v[40:43]
	v_mfma_f32_16x16x32_bf16 v[28:31], v[158:161], v[206:209], v[28:31]
	v_mfma_f32_16x16x32_bf16 v[24:27], v[166:169], v[206:209], v[24:27]
	v_mfma_f32_16x16x32_bf16 v[12:15], v[158:161], v[214:217], v[12:15]
	v_mfma_f32_16x16x32_bf16 v[8:11], v[166:169], v[214:217], v[8:11]
	v_mfma_f32_16x16x32_bf16 v[52:55], v[170:173], v[186:189], v[52:55]
	v_mfma_f32_16x16x32_bf16 v[48:51], v[178:181], v[186:189], v[48:51]
	v_mfma_f32_16x16x32_bf16 v[36:39], v[170:173], v[194:197], v[36:39]
	v_mfma_f32_16x16x32_bf16 v[32:35], v[178:181], v[194:197], v[32:35]
	v_mfma_f32_16x16x32_bf16 v[20:23], v[170:173], v[202:205], v[20:23]
	v_mfma_f32_16x16x32_bf16 v[16:19], v[178:181], v[202:205], v[16:19]
	v_mfma_f32_16x16x32_bf16 v[4:7], v[170:173], v[210:213], v[4:7]
	v_mfma_f32_16x16x32_bf16 v[0:3], v[178:181], v[210:213], v[0:3]
	v_mfma_f32_16x16x32_bf16 v[52:55], v[174:177], v[190:193], v[52:55]
	v_mfma_f32_16x16x32_bf16 v[48:51], v[182:185], v[190:193], v[48:51]
	v_mfma_f32_16x16x32_bf16 v[36:39], v[174:177], v[198:201], v[36:39]
	v_mfma_f32_16x16x32_bf16 v[32:35], v[182:185], v[198:201], v[32:35]
	v_mfma_f32_16x16x32_bf16 v[20:23], v[174:177], v[206:209], v[20:23]
	v_mfma_f32_16x16x32_bf16 v[16:19], v[182:185], v[206:209], v[16:19]
	v_mfma_f32_16x16x32_bf16 v[4:7], v[174:177], v[214:217], v[4:7]
	v_mfma_f32_16x16x32_bf16 v[0:3], v[182:185], v[214:217], v[0:3]
	s_barrier
	s_add_i32 s83, s83, 2
	s_add_u32 s62, s62, 0x100
	s_addc_u32 s63, s63, 0
	s_add_u32 s78, s78, 0x100
	s_addc_u32 s79, s79, 0
	s_cmp_gt_u32 s83, 13
	s_cbranch_scc0 .LBB0_767
	v_lshl_add_u32 v148, s58, 8, v150
	v_lshl_or_b32 v146, s60, 8, v136
	v_lshl_add_u32 v147, v148, 11, v146
	v_lshlrev_b32_e32 v159, 1, v147
	v_lshlrev_b32_e32 v208, 3, v148
	global_load_dwordx4 v[160:163], v159, s[28:29]
	global_load_dwordx4 v[164:167], v159, s[28:29] offset:64
	v_add_u32_e32 v149, 0x10000, v159
	global_load_dwordx4 v[168:171], v149, s[28:29]
	global_load_dwordx4 v[172:175], v149, s[28:29] offset:64
	v_add_u32_e32 v209, 0x20000, v159
	global_load_dwordx4 v[176:179], v209, s[28:29]
	global_load_dwordx4 v[180:183], v209, s[28:29] offset:64
	v_add_u32_e32 v149, 0x30000, v159
	global_load_dwordx4 v[184:187], v149, s[28:29]
	global_load_dwordx4 v[188:191], v149, s[28:29] offset:64
	v_add_u32_e32 v209, 0x80000, v159
	global_load_dwordx4 v[192:195], v209, s[28:29]
	global_load_dwordx4 v[196:199], v209, s[28:29] offset:64
	v_add_u32_e32 v149, 0x90000, v159
	global_load_dwordx4 v[200:203], v149, s[28:29]
	global_load_dwordx4 v[204:207], v149, s[28:29] offset:64
	v_add_u32_e32 v209, 0xa0000, v159
	global_load_dwordx4 v[212:215], v209, s[28:29]
	global_load_dwordx4 v[216:219], v209, s[28:29] offset:64
	v_add_u32_e32 v149, 0xb0000, v159
	global_load_dwordx4 v[220:223], v149, s[28:29]
	global_load_dwordx4 v[224:227], v149, s[28:29] offset:64
	s_and_b64 vcc, exec, s[48:49]
	s_cbranch_vccz .LBB0_770
	s_barrier

; #define PG8_STAGE(bufoff, gbase, voff) do { _Pragma("unroll") for (int _i = 0; _i < 2; ++_i) \
;         __builtin_amdgcn_global_load_lds((const unsigned*)((const char*)(gbase) + (voff)[_i]), (PG8_LAS unsigned*)(lds + (bufoff) + ldsw + _i * 8192), 16, 0, 0); } while (0)
; #define PG8_LDA(dst, b, h) do { _Pragma("unroll") for (int m = 0; m < 4; ++m) _Pragma("unroll") for (int k = 0; k < 2; ++k) dst[m][k] = *(const PG8_LAS bf16x8*)(lds + PG8_SA(b, h) + aoff + m * 2048 + k * 1024); } while (0)
; #define PG8_LDB(dst, b, h) do { _Pragma("unroll") for (int n = 0; n < 2; ++n) _Pragma("unroll") for (int k = 0; k < 2; ++k) dst[n][k] = *(const PG8_LAS bf16x8*)(lds + PG8_SB(b, h) + boff + n * 2048 + k * 1024); } while (0)
; #define PG8_MMA(ai, bj, At, Bt) do { __builtin_amdgcn_s_setprio(1); _Pragma("unroll") for (int m = 0; m < 4; ++m) _Pragma("unroll") for (int n = 0; n < 2; ++n) _Pragma("unroll") for (int k = 0; k < 2; ++k) \
;         acc[ai][bj][m][n] = __builtin_amdgcn_mfma_f32_16x16x32_bf16(Bt[n][k], At[m][k], acc[ai][bj][m][n], 0, 0, 0); __builtin_amdgcn_s_setprio(0); } while (0)
; #define PG8_WAIT_V(n) asm volatile("s_waitcnt vmcnt(" #n ")" ::: "memory")
; #define PG8_WAIT_L(n) asm volatile("s_waitcnt lgkmcnt(" #n ")" ::: "memory")
; #define PG8_BAR __builtin_amdgcn_s_barrier()
; #define PG8_SCHED __builtin_amdgcn_sched_barrier(0)
; template <class Epi, class Sched, bool ALIGN_EPI = false, bool SP2 = false>
; __device__ __forceinline__ void gemm_phase(PG8_LAS unsigned char* lds, const Gemm g, const Sched& S, const Epi& E, int tid_in) {
;     ...
;             PG8_LDB(B0, 0, 0); PG8_LDB(B1, 0, 1); PG8_SCHED; PG8_LDA(At, 0, 0); PG8_STAGE(PG8_SA(1, 1), a1 + hstep, voffA);
;             PG8_WAIT_V(8); PG8_WAIT_L(0); PG8_BAR; PG8_MMA(0, 0, At, B0); PG8_MMA(0, 1, At, B1); PG8_BAR; PG8_SCHED;
;             PG8_LDA(At, 0, 1); PG8_STAGE(PG8_SB(0, 0), b2, voffB); PG8_STAGE(PG8_SB(0, 1), b2 + hstepB, voffB); PG8_STAGE(PG8_SA(0, 0), a2, voffA);
;             PG8_WAIT_V(8); PG8_WAIT_L(0); PG8_BAR; PG8_MMA(1, 0, At, B0); PG8_MMA(1, 1, At, B1); PG8_BAR; PG8_SCHED;
.Lkb_skip_6:
	ds_read_b128 v[156:159], v150
	ds_read_b128 v[160:163], v150 offset:1024
	ds_read_b128 v[164:167], v150 offset:2048
	ds_read_b128 v[168:171], v150 offset:3072
	ds_read_b128 v[172:175], v151
	ds_read_b128 v[176:179], v151 offset:1024
	ds_read_b128 v[180:183], v151 offset:2048
	ds_read_b128 v[184:187], v151 offset:3072
	s_add_u32 s26, s50, 0xfff80080
	s_addc_u32 s27, s51, -1
	s_cmp_eq_u32 s72, 28
	s_cselect_b32 s55, s41, s27
	s_cselect_b32 s54, s68, s26
	s_cselect_b32 s53, s39, s71
	s_cselect_b32 s52, s69, s70
	s_add_i32 m0, s49, 0xc000
	ds_read_b128 v[188:191], v152
	ds_read_b128 v[192:195], v152 offset:1024
	ds_read_b128 v[196:199], v152 offset:2048
	ds_read_b128 v[200:203], v152 offset:3072
	ds_read_b128 v[204:207], v152 offset:4096
	ds_read_b128 v[208:211], v152 offset:5120
	ds_read_b128 v[212:215], v152 offset:6144
	ds_read_b128 v[216:219], v152 offset:7168
	global_load_lds_dwordx4 v138, s[50:51]
	s_add_i32 m0, s49, 0xe000
	s_nop 0
	global_load_lds_dwordx4 v140, s[50:51]
	s_waitcnt vmcnt(8)
	s_waitcnt lgkmcnt(0)
	s_barrier
	s_waitcnt lgkmcnt(0)
	v_mfma_f32_16x16x32_bf16 v[124:127], v[156:159], v[188:191], 0
	v_mfma_f32_16x16x32_bf16 v[120:123], v[164:167], v[188:191], 0
	v_mfma_f32_16x16x32_bf16 v[108:111], v[156:159], v[196:199], 0
	v_mfma_f32_16x16x32_bf16 v[104:107], v[164:167], v[196:199], 0
	v_mfma_f32_16x16x32_bf16 v[92:95], v[156:159], v[204:207], 0
	v_mfma_f32_16x16x32_bf16 v[88:91], v[164:167], v[204:207], 0
	v_mfma_f32_16x16x32_bf16 v[76:79], v[156:159], v[212:215], 0
	v_mfma_f32_16x16x32_bf16 v[72:75], v[164:167], v[212:215], 0
	v_mfma_f32_16x16x32_bf16 v[124:127], v[160:163], v[192:195], v[124:127]
	v_mfma_f32_16x16x32_bf16 v[120:123], v[168:171], v[192:195], v[120:123]
	v_mfma_f32_16x16x32_bf16 v[108:111], v[160:163], v[200:203], v[108:111]
	v_mfma_f32_16x16x32_bf16 v[104:107], v[168:171], v[200:203], v[104:107]
	v_mfma_f32_16x16x32_bf16 v[92:95], v[160:163], v[208:211], v[92:95]
	v_mfma_f32_16x16x32_bf16 v[88:91], v[168:171], v[208:211], v[88:91]
	v_mfma_f32_16x16x32_bf16 v[76:79], v[160:163], v[216:219], v[76:79]
	v_mfma_f32_16x16x32_bf16 v[72:75], v[168:171], v[216:219], v[72:75]
	v_mfma_f32_16x16x32_bf16 v[116:119], v[172:175], v[188:191], 0
	v_mfma_f32_16x16x32_bf16 v[112:115], v[180:183], v[188:191], 0
	v_mfma_f32_16x16x32_bf16 v[100:103], v[172:175], v[196:199], 0
	v_mfma_f32_16x16x32_bf16 v[96:99], v[180:183], v[196:199], 0
	v_mfma_f32_16x16x32_bf16 v[84:87], v[172:175], v[204:207], 0
	v_mfma_f32_16x16x32_bf16 v[80:83], v[180:183], v[204:207], 0
	v_mfma_f32_16x16x32_bf16 v[68:71], v[172:175], v[212:215], 0
	v_mfma_f32_16x16x32_bf16 v[64:67], v[180:183], v[212:215], 0
	v_mfma_f32_16x16x32_bf16 v[116:119], v[176:179], v[192:195], v[116:119]
	v_mfma_f32_16x16x32_bf16 v[112:115], v[184:187], v[192:195], v[112:115]
	v_mfma_f32_16x16x32_bf16 v[100:103], v[176:179], v[200:203], v[100:103]
	v_mfma_f32_16x16x32_bf16 v[96:99], v[184:187], v[200:203], v[96:99]
	v_mfma_f32_16x16x32_bf16 v[84:87], v[176:179], v[208:211], v[84:87]
	v_mfma_f32_16x16x32_bf16 v[80:83], v[184:187], v[208:211], v[80:83]
	v_mfma_f32_16x16x32_bf16 v[68:71], v[176:179], v[216:219], v[68:71]
	v_mfma_f32_16x16x32_bf16 v[64:67], v[184:187], v[216:219], v[64:67]
	s_barrier
	s_add_i32 s26, s64, s56
	s_mov_b32 m0, s26
	ds_read_b128 v[188:191], v152 offset:16384
	ds_read_b128 v[192:195], v152 offset:17408
	ds_read_b128 v[196:199], v152 offset:18432
	ds_read_b128 v[200:203], v152 offset:19456
	ds_read_b128 v[204:207], v152 offset:20480
	ds_read_b128 v[208:211], v152 offset:21504
	ds_read_b128 v[212:215], v152 offset:22528
	ds_read_b128 v[216:219], v152 offset:23552
	global_load_lds_dwordx4 v130, s[52:53]
	s_add_i32 m0, s26, 0x2000
	s_add_u32 s26, s52, 0x20000
	s_addc_u32 s27, s53, 0
	s_add_i32 s33, s65, s56
	global_load_lds_dwordx4 v134, s[52:53]
	s_mov_b32 m0, s33
	s_nop 0
	global_load_lds_dwordx4 v130, s[26:27]
	s_add_i32 m0, s33, 0x2000
	s_nop 0
	global_load_lds_dwordx4 v134, s[26:27]
	s_mov_b32 m0, s49
	s_nop 0
	global_load_lds_dwordx4 v128, s[54:55]
	s_mov_b32 m0, s57
	s_nop 0
	global_load_lds_dwordx4 v132, s[54:55]
	s_waitcnt vmcnt(8)
	s_waitcnt lgkmcnt(0)
	s_barrier
	s_waitcnt lgkmcnt(0)
	v_mfma_f32_16x16x32_bf16 v[60:63], v[156:159], v[188:191], 0
	v_mfma_f32_16x16x32_bf16 v[56:59], v[164:167], v[188:191], 0
	v_mfma_f32_16x16x32_bf16 v[44:47], v[156:159], v[196:199], 0
	v_mfma_f32_16x16x32_bf16 v[40:43], v[164:167], v[196:199], 0
	v_mfma_f32_16x16x32_bf16 v[28:31], v[156:159], v[204:207], 0
	v_mfma_f32_16x16x32_bf16 v[24:27], v[164:167], v[204:207], 0
	v_mfma_f32_16x16x32_bf16 v[12:15], v[156:159], v[212:215], 0
	v_mfma_f32_16x16x32_bf16 v[8:11], v[164:167], v[212:215], 0
	v_mfma_f32_16x16x32_bf16 v[60:63], v[160:163], v[192:195], v[60:63]
	v_mfma_f32_16x16x32_bf16 v[56:59], v[168:171], v[192:195], v[56:59]
	v_mfma_f32_16x16x32_bf16 v[44:47], v[160:163], v[200:203], v[44:47]
	v_mfma_f32_16x16x32_bf16 v[40:43], v[168:171], v[200:203], v[40:43]
	v_mfma_f32_16x16x32_bf16 v[28:31], v[160:163], v[208:211], v[28:31]
	v_mfma_f32_16x16x32_bf16 v[24:27], v[168:171], v[208:211], v[24:27]
	v_mfma_f32_16x16x32_bf16 v[12:15], v[160:163], v[216:219], v[12:15]
	v_mfma_f32_16x16x32_bf16 v[8:11], v[168:171], v[216:219], v[8:11]
	v_mfma_f32_16x16x32_bf16 v[52:55], v[172:175], v[188:191], 0
	v_mfma_f32_16x16x32_bf16 v[48:51], v[180:183], v[188:191], 0
	v_mfma_f32_16x16x32_bf16 v[36:39], v[172:175], v[196:199], 0
	v_mfma_f32_16x16x32_bf16 v[32:35], v[180:183], v[196:199], 0
	v_mfma_f32_16x16x32_bf16 v[20:23], v[172:175], v[204:207], 0
	v_mfma_f32_16x16x32_bf16 v[16:19], v[180:183], v[204:207], 0
	v_mfma_f32_16x16x32_bf16 v[4:7], v[172:175], v[212:215], 0
	v_mfma_f32_16x16x32_bf16 v[0:3], v[180:183], v[212:215], 0
	v_mfma_f32_16x16x32_bf16 v[52:55], v[176:179], v[192:195], v[52:55]
	v_mfma_f32_16x16x32_bf16 v[48:51], v[184:187], v[192:195], v[48:51]
	v_mfma_f32_16x16x32_bf16 v[36:39], v[176:179], v[200:203], v[36:39]
	v_mfma_f32_16x16x32_bf16 v[32:35], v[184:187], v[200:203], v[32:35]
	v_mfma_f32_16x16x32_bf16 v[20:23], v[176:179], v[208:211], v[20:23]
	v_mfma_f32_16x16x32_bf16 v[16:19], v[184:187], v[208:211], v[16:19]
	v_mfma_f32_16x16x32_bf16 v[4:7], v[176:179], v[216:219], v[4:7]
	v_mfma_f32_16x16x32_bf16 v[0:3], v[184:187], v[216:219], v[0:3]
	s_barrier
; #define PG8_STAGE(bufoff, gbase, voff) do { _Pragma("unroll") for (int _i = 0; _i < 2; ++_i) \
;         __builtin_amdgcn_global_load_lds((const unsigned*)((const char*)(gbase) + (voff)[_i]), (PG8_LAS unsigned*)(lds + (bufoff) + ldsw + _i * 8192), 16, 0, 0); } while (0)
; #define PG8_LDA(dst, b, h) do { _Pragma("unroll") for (int m = 0; m < 4; ++m) _Pragma("unroll") for (int k = 0; k < 2; ++k) dst[m][k] = *(const PG8_LAS bf16x8*)(lds + PG8_SA(b, h) + aoff + m * 2048 + k * 1024); } while (0)
; #define PG8_LDB(dst, b, h) do { _Pragma("unroll") for (int n = 0; n < 2; ++n) _Pragma("unroll") for (int k = 0; k < 2; ++k) dst[n][k] = *(const PG8_LAS bf16x8*)(lds + PG8_SB(b, h) + boff + n * 2048 + k * 1024); } while (0)
; #define PG8_MMA(ai, bj, At, Bt) do { __builtin_amdgcn_s_setprio(1); _Pragma("unroll") for (int m = 0; m < 4; ++m) _Pragma("unroll") for (int n = 0; n < 2; ++n) _Pragma("unroll") for (int k = 0; k < 2; ++k) \
;         acc[ai][bj][m][n] = __builtin_amdgcn_mfma_f32_16x16x32_bf16(Bt[n][k], At[m][k], acc[ai][bj][m][n], 0, 0, 0); __builtin_amdgcn_s_setprio(0); } while (0)
; #define PG8_WAIT_V(n) asm volatile("s_waitcnt vmcnt(" #n ")" ::: "memory")
; #define PG8_WAIT_L(n) asm volatile("s_waitcnt lgkmcnt(" #n ")" ::: "memory")
; #define PG8_BAR __builtin_amdgcn_s_barrier()
; #define PG8_SCHED __builtin_amdgcn_sched_barrier(0)
; template <class Epi, class Sched, bool ALIGN_EPI = false, bool SP2 = false>
; __device__ __forceinline__ void gemm_phase(PG8_LAS unsigned char* lds, const Gemm g, const Sched& S, const Epi& E, int tid_in) {
;     ...
;             PG8_LDB(B0, 1, 0); PG8_LDB(B1, 1, 1); PG8_SCHED; PG8_LDA(At, 1, 0); PG8_STAGE(PG8_SA(0, 1), a2 + hstep, voffA);
;             PG8_WAIT_V(8); PG8_WAIT_L(0); PG8_BAR; PG8_MMA(0, 0, At, B0); PG8_MMA(0, 1, At, B1); PG8_BAR; PG8_SCHED;
;             PG8_LDA(At, 1, 1); PG8_STAGE(PG8_SB(1, 0), b3, voffB); PG8_STAGE(PG8_SB(1, 1), b3 + hstepB, voffB); PG8_STAGE(PG8_SA(1, 0), a3, voffA);
;             PG8_WAIT_V(8); PG8_WAIT_L(0); PG8_BAR; PG8_MMA(1, 0, At, B0); PG8_MMA(1, 1, At, B1); PG8_BAR; PG8_SCHED;
;     ...
;         }
;         if constexpr (ALIGN_EPI) { if (wr == 0) PG8_BAR; }
	s_add_i32 s33, 0, 0x18000
	v_add_u32_e32 v155, s33, v146
	s_add_i32 s73, 0, 0x1c000
	ds_read_b128 v[156:159], v155
	ds_read_b128 v[160:163], v155 offset:1024
	ds_read_b128 v[164:167], v155 offset:2048
	ds_read_b128 v[168:171], v155 offset:3072
	v_add_u32_e32 v155, s73, v146
	ds_read_b128 v[172:175], v155
	ds_read_b128 v[176:179], v155 offset:1024
	ds_read_b128 v[180:183], v155 offset:2048
	ds_read_b128 v[184:187], v155 offset:3072
	s_add_u32 s26, s54, 0x80000
	s_addc_u32 s27, s55, 0
	s_mov_b32 m0, s58
	ds_read_b128 v[188:191], v152 offset:32768
	ds_read_b128 v[192:195], v152 offset:33792
	ds_read_b128 v[196:199], v152 offset:34816
	ds_read_b128 v[200:203], v152 offset:35840
	ds_read_b128 v[204:207], v152 offset:36864
	ds_read_b128 v[208:211], v152 offset:37888
	ds_read_b128 v[212:215], v152 offset:38912
	ds_read_b128 v[216:219], v152 offset:39936
	global_load_lds_dwordx4 v128, s[26:27]
	s_mov_b32 m0, s59
	s_nop 0
	global_load_lds_dwordx4 v132, s[26:27]
	s_waitcnt vmcnt(8)
	s_waitcnt lgkmcnt(0)
	s_barrier
	s_waitcnt lgkmcnt(0)
	v_mfma_f32_16x16x32_bf16 v[124:127], v[156:159], v[188:191], v[124:127]
	v_mfma_f32_16x16x32_bf16 v[120:123], v[164:167], v[188:191], v[120:123]
	v_mfma_f32_16x16x32_bf16 v[108:111], v[156:159], v[196:199], v[108:111]
	v_mfma_f32_16x16x32_bf16 v[104:107], v[164:167], v[196:199], v[104:107]
	v_mfma_f32_16x16x32_bf16 v[92:95], v[156:159], v[204:207], v[92:95]
	v_mfma_f32_16x16x32_bf16 v[88:91], v[164:167], v[204:207], v[88:91]
	v_mfma_f32_16x16x32_bf16 v[76:79], v[156:159], v[212:215], v[76:79]
	v_mfma_f32_16x16x32_bf16 v[72:75], v[164:167], v[212:215], v[72:75]
	v_mfma_f32_16x16x32_bf16 v[124:127], v[160:163], v[192:195], v[124:127]
	v_mfma_f32_16x16x32_bf16 v[120:123], v[168:171], v[192:195], v[120:123]
	v_mfma_f32_16x16x32_bf16 v[108:111], v[160:163], v[200:203], v[108:111]
	v_mfma_f32_16x16x32_bf16 v[104:107], v[168:171], v[200:203], v[104:107]
	v_mfma_f32_16x16x32_bf16 v[92:95], v[160:163], v[208:211], v[92:95]
	v_mfma_f32_16x16x32_bf16 v[88:91], v[168:171], v[208:211], v[88:91]
	v_mfma_f32_16x16x32_bf16 v[76:79], v[160:163], v[216:219], v[76:79]
	v_mfma_f32_16x16x32_bf16 v[72:75], v[168:171], v[216:219], v[72:75]
	v_mfma_f32_16x16x32_bf16 v[116:119], v[172:175], v[188:191], v[116:119]
	v_mfma_f32_16x16x32_bf16 v[112:115], v[180:183], v[188:191], v[112:115]
	v_mfma_f32_16x16x32_bf16 v[100:103], v[172:175], v[196:199], v[100:103]
	v_mfma_f32_16x16x32_bf16 v[96:99], v[180:183], v[196:199], v[96:99]
	v_mfma_f32_16x16x32_bf16 v[84:87], v[172:175], v[204:207], v[84:87]
	v_mfma_f32_16x16x32_bf16 v[80:83], v[180:183], v[204:207], v[80:83]
	v_mfma_f32_16x16x32_bf16 v[68:71], v[172:175], v[212:215], v[68:71]
	v_mfma_f32_16x16x32_bf16 v[64:67], v[180:183], v[212:215], v[64:67]
	v_mfma_f32_16x16x32_bf16 v[116:119], v[176:179], v[192:195], v[116:119]
	v_mfma_f32_16x16x32_bf16 v[112:115], v[184:187], v[192:195], v[112:115]
	v_mfma_f32_16x16x32_bf16 v[100:103], v[176:179], v[200:203], v[100:103]
	v_mfma_f32_16x16x32_bf16 v[96:99], v[184:187], v[200:203], v[96:99]
	v_mfma_f32_16x16x32_bf16 v[84:87], v[176:179], v[208:211], v[84:87]
	v_mfma_f32_16x16x32_bf16 v[80:83], v[184:187], v[208:211], v[80:83]
	v_mfma_f32_16x16x32_bf16 v[68:71], v[176:179], v[216:219], v[68:71]
	v_mfma_f32_16x16x32_bf16 v[64:67], v[184:187], v[216:219], v[64:67]
	s_barrier
	s_add_i32 s26, s33, s56
	s_add_i32 m0, s26, 0xffffff80
	ds_read_b128 v[188:191], v152 offset:49152
	ds_read_b128 v[192:195], v152 offset:50176
	ds_read_b128 v[196:199], v152 offset:51200
	ds_read_b128 v[200:203], v152 offset:52224
	ds_read_b128 v[204:207], v152 offset:53248
	ds_read_b128 v[208:211], v152 offset:54272
	ds_read_b128 v[212:215], v152 offset:55296
	ds_read_b128 v[216:219], v152 offset:56320
	global_load_lds_dwordx4 v130, s[52:53] offset:128
	s_add_i32 m0, s26, 0x1f80
	s_add_u32 s26, s52, 0x20080
	s_addc_u32 s27, s53, 0
	s_add_i32 s33, s73, s56
	global_load_lds_dwordx4 v134, s[52:53] offset:128
	s_mov_b32 m0, s33
	s_nop 0
	global_load_lds_dwordx4 v130, s[26:27]
	s_add_i32 m0, s33, 0x2000
	s_nop 0
	global_load_lds_dwordx4 v134, s[26:27]
	s_add_i32 m0, s62, 0xffffff80
	s_nop 0
	global_load_lds_dwordx4 v128, s[54:55] offset:128
	s_add_i32 m0, s63, 0xffffff80
	s_nop 0
	global_load_lds_dwordx4 v132, s[54:55] offset:128
	s_waitcnt vmcnt(8)
	s_waitcnt lgkmcnt(0)
	s_barrier
	s_waitcnt lgkmcnt(0)
	v_mfma_f32_16x16x32_bf16 v[60:63], v[156:159], v[188:191], v[60:63]
	v_mfma_f32_16x16x32_bf16 v[56:59], v[164:167], v[188:191], v[56:59]
	v_mfma_f32_16x16x32_bf16 v[44:47], v[156:159], v[196:199], v[44:47]
	v_mfma_f32_16x16x32_bf16 v[40:43], v[164:167], v[196:199], v[40:43]
	v_mfma_f32_16x16x32_bf16 v[28:31], v[156:159], v[204:207], v[28:31]
	v_mfma_f32_16x16x32_bf16 v[24:27], v[164:167], v[204:207], v[24:27]
	v_mfma_f32_16x16x32_bf16 v[12:15], v[156:159], v[212:215], v[12:15]
	v_mfma_f32_16x16x32_bf16 v[8:11], v[164:167], v[212:215], v[8:11]
	v_mfma_f32_16x16x32_bf16 v[60:63], v[160:163], v[192:195], v[60:63]
	v_mfma_f32_16x16x32_bf16 v[56:59], v[168:171], v[192:195], v[56:59]
	v_mfma_f32_16x16x32_bf16 v[44:47], v[160:163], v[200:203], v[44:47]
	v_mfma_f32_16x16x32_bf16 v[40:43], v[168:171], v[200:203], v[40:43]
	v_mfma_f32_16x16x32_bf16 v[28:31], v[160:163], v[208:211], v[28:31]
	v_mfma_f32_16x16x32_bf16 v[24:27], v[168:171], v[208:211], v[24:27]
	v_mfma_f32_16x16x32_bf16 v[12:15], v[160:163], v[216:219], v[12:15]
	v_mfma_f32_16x16x32_bf16 v[8:11], v[168:171], v[216:219], v[8:11]
	v_mfma_f32_16x16x32_bf16 v[52:55], v[172:175], v[188:191], v[52:55]
	v_mfma_f32_16x16x32_bf16 v[48:51], v[180:183], v[188:191], v[48:51]
	v_mfma_f32_16x16x32_bf16 v[36:39], v[172:175], v[196:199], v[36:39]
	v_mfma_f32_16x16x32_bf16 v[32:35], v[180:183], v[196:199], v[32:35]
	v_mfma_f32_16x16x32_bf16 v[20:23], v[172:175], v[204:207], v[20:23]
	v_mfma_f32_16x16x32_bf16 v[16:19], v[180:183], v[204:207], v[16:19]
	v_mfma_f32_16x16x32_bf16 v[4:7], v[172:175], v[212:215], v[4:7]
	v_mfma_f32_16x16x32_bf16 v[0:3], v[180:183], v[212:215], v[0:3]
	v_mfma_f32_16x16x32_bf16 v[52:55], v[176:179], v[192:195], v[52:55]
	v_mfma_f32_16x16x32_bf16 v[48:51], v[184:187], v[192:195], v[48:51]
	v_mfma_f32_16x16x32_bf16 v[36:39], v[176:179], v[200:203], v[36:39]
	v_mfma_f32_16x16x32_bf16 v[32:35], v[184:187], v[200:203], v[32:35]
	v_mfma_f32_16x16x32_bf16 v[20:23], v[176:179], v[208:211], v[20:23]
	v_mfma_f32_16x16x32_bf16 v[16:19], v[184:187], v[208:211], v[16:19]
	v_mfma_f32_16x16x32_bf16 v[4:7], v[176:179], v[216:219], v[4:7]
	v_mfma_f32_16x16x32_bf16 v[0:3], v[184:187], v[216:219], v[0:3]
	s_barrier
	s_add_i32 s72, s72, 2
	s_add_u32 s50, s50, 0x100
	s_addc_u32 s51, s51, 0
	s_add_u32 s70, s70, 0x100
	s_addc_u32 s71, s71, 0
	s_cmp_gt_u32 s72, 29
; #define PG8_STAGE(bufoff, gbase, voff) do { _Pragma("unroll") for (int _i = 0; _i < 2; ++_i) \
;         __builtin_amdgcn_global_load_lds((const unsigned*)((const char*)(gbase) + (voff)[_i]), (PG8_LAS unsigned*)(lds + (bufoff) + ldsw + _i * 8192), 16, 0, 0); } while (0)
; #define PG8_LDA(dst, b, h) do { _Pragma("unroll") for (int m = 0; m < 4; ++m) _Pragma("unroll") for (int k = 0; k < 2; ++k) dst[m][k] = *(const PG8_LAS bf16x8*)(lds + PG8_SA(b, h) + aoff + m * 2048 + k * 1024); } while (0)
; #define PG8_LDB(dst, b, h) do { _Pragma("unroll") for (int n = 0; n < 2; ++n) _Pragma("unroll") for (int k = 0; k < 2; ++k) dst[n][k] = *(const PG8_LAS bf16x8*)(lds + PG8_SB(b, h) + boff + n * 2048 + k * 1024); } while (0)
; #define PG8_MMA(ai, bj, At, Bt) do { __builtin_amdgcn_s_setprio(1); _Pragma("unroll") for (int m = 0; m < 4; ++m) _Pragma("unroll") for (int n = 0; n < 2; ++n) _Pragma("unroll") for (int k = 0; k < 2; ++k) \
;         acc[ai][bj][m][n] = __builtin_amdgcn_mfma_f32_16x16x32_bf16(Bt[n][k], At[m][k], acc[ai][bj][m][n], 0, 0, 0); __builtin_amdgcn_s_setprio(0); } while (0)
; #define PG8_WAIT_V(n) asm volatile("s_waitcnt vmcnt(" #n ")" ::: "memory")
; #define PG8_WAIT_L(n) asm volatile("s_waitcnt lgkmcnt(" #n ")" ::: "memory")
; #define PG8_BAR __builtin_amdgcn_s_barrier()
; #define PG8_SCHED __builtin_amdgcn_sched_barrier(0)
; template <class Epi, class Sched, bool ALIGN_EPI = false, bool SP2 = false>
; __device__ __forceinline__ void gemm_phase(PG8_LAS unsigned char* lds, const Gemm g, const Sched& S, const Epi& E, int tid_in) {
;     ...
;             PG8_LDB(B0, 0, 0); PG8_LDB(B1, 0, 1); PG8_SCHED; PG8_LDA(At, 0, 0); PG8_STAGE(PG8_SA(1, 1), a1 + hstep, voffA);
;             PG8_WAIT_V(8); PG8_WAIT_L(0); PG8_BAR; PG8_MMA(0, 0, At, B0); PG8_MMA(0, 1, At, B1); PG8_BAR; PG8_SCHED;
;             PG8_LDA(At, 0, 1); PG8_STAGE(PG8_SB(0, 0), b2, voffB); PG8_STAGE(PG8_SB(0, 1), b2 + hstepB, voffB); PG8_STAGE(PG8_SA(0, 0), a2, voffA);
;             PG8_WAIT_V(8); PG8_WAIT_L(0); PG8_BAR; PG8_MMA(1, 0, At, B0); PG8_MMA(1, 1, At, B1); PG8_BAR; PG8_SCHED;
.LBB0_869:
	ds_read_b128 v[156:159], v150
	ds_read_b128 v[160:163], v150 offset:1024
	ds_read_b128 v[164:167], v150 offset:2048
	ds_read_b128 v[168:171], v150 offset:3072
	ds_read_b128 v[172:175], v151
	ds_read_b128 v[176:179], v151 offset:1024
	ds_read_b128 v[180:183], v151 offset:2048
	ds_read_b128 v[184:187], v151 offset:3072
	s_add_u32 s26, s50, 0xfff80080
	s_addc_u32 s27, s51, -1
	s_cmp_eq_u32 s72, 28
	s_cselect_b32 s55, s41, s27
	s_cselect_b32 s54, s68, s26
	s_cselect_b32 s53, s39, s71
	s_cselect_b32 s52, s69, s70
	s_add_i32 m0, s49, 0xc000
	ds_read_b128 v[188:191], v152
	ds_read_b128 v[192:195], v152 offset:1024
	ds_read_b128 v[196:199], v152 offset:2048
	ds_read_b128 v[200:203], v152 offset:3072
	ds_read_b128 v[204:207], v152 offset:4096
	ds_read_b128 v[208:211], v152 offset:5120
	ds_read_b128 v[212:215], v152 offset:6144
	ds_read_b128 v[216:219], v152 offset:7168
	global_load_lds_dwordx4 v138, s[50:51]
	s_add_i32 m0, s49, 0xe000
	s_nop 0
	global_load_lds_dwordx4 v140, s[50:51]
	s_waitcnt vmcnt(8)
	s_waitcnt lgkmcnt(0)
	s_barrier
	s_waitcnt lgkmcnt(0)
	v_mfma_f32_16x16x32_bf16 v[124:127], v[156:159], v[188:191], v[124:127]
	v_mfma_f32_16x16x32_bf16 v[120:123], v[164:167], v[188:191], v[120:123]
	v_mfma_f32_16x16x32_bf16 v[108:111], v[156:159], v[196:199], v[108:111]
	v_mfma_f32_16x16x32_bf16 v[104:107], v[164:167], v[196:199], v[104:107]
	v_mfma_f32_16x16x32_bf16 v[92:95], v[156:159], v[204:207], v[92:95]
	v_mfma_f32_16x16x32_bf16 v[88:91], v[164:167], v[204:207], v[88:91]
	v_mfma_f32_16x16x32_bf16 v[76:79], v[156:159], v[212:215], v[76:79]
	v_mfma_f32_16x16x32_bf16 v[72:75], v[164:167], v[212:215], v[72:75]
	v_mfma_f32_16x16x32_bf16 v[124:127], v[160:163], v[192:195], v[124:127]
	v_mfma_f32_16x16x32_bf16 v[120:123], v[168:171], v[192:195], v[120:123]
	v_mfma_f32_16x16x32_bf16 v[108:111], v[160:163], v[200:203], v[108:111]
	v_mfma_f32_16x16x32_bf16 v[104:107], v[168:171], v[200:203], v[104:107]
	v_mfma_f32_16x16x32_bf16 v[92:95], v[160:163], v[208:211], v[92:95]
	v_mfma_f32_16x16x32_bf16 v[88:91], v[168:171], v[208:211], v[88:91]
	v_mfma_f32_16x16x32_bf16 v[76:79], v[160:163], v[216:219], v[76:79]
	v_mfma_f32_16x16x32_bf16 v[72:75], v[168:171], v[216:219], v[72:75]
	v_mfma_f32_16x16x32_bf16 v[116:119], v[172:175], v[188:191], v[116:119]
	v_mfma_f32_16x16x32_bf16 v[112:115], v[180:183], v[188:191], v[112:115]
	v_mfma_f32_16x16x32_bf16 v[100:103], v[172:175], v[196:199], v[100:103]
	v_mfma_f32_16x16x32_bf16 v[96:99], v[180:183], v[196:199], v[96:99]
	v_mfma_f32_16x16x32_bf16 v[84:87], v[172:175], v[204:207], v[84:87]
	v_mfma_f32_16x16x32_bf16 v[80:83], v[180:183], v[204:207], v[80:83]
	v_mfma_f32_16x16x32_bf16 v[68:71], v[172:175], v[212:215], v[68:71]
	v_mfma_f32_16x16x32_bf16 v[64:67], v[180:183], v[212:215], v[64:67]
	v_mfma_f32_16x16x32_bf16 v[116:119], v[176:179], v[192:195], v[116:119]
	v_mfma_f32_16x16x32_bf16 v[112:115], v[184:187], v[192:195], v[112:115]
	v_mfma_f32_16x16x32_bf16 v[100:103], v[176:179], v[200:203], v[100:103]
	v_mfma_f32_16x16x32_bf16 v[96:99], v[184:187], v[200:203], v[96:99]
	v_mfma_f32_16x16x32_bf16 v[84:87], v[176:179], v[208:211], v[84:87]
	v_mfma_f32_16x16x32_bf16 v[80:83], v[184:187], v[208:211], v[80:83]
	v_mfma_f32_16x16x32_bf16 v[68:71], v[176:179], v[216:219], v[68:71]
	v_mfma_f32_16x16x32_bf16 v[64:67], v[184:187], v[216:219], v[64:67]
	s_barrier
	s_add_i32 s26, s64, s56
	s_mov_b32 m0, s26
	ds_read_b128 v[188:191], v152 offset:16384
	ds_read_b128 v[192:195], v152 offset:17408
	ds_read_b128 v[196:199], v152 offset:18432
	ds_read_b128 v[200:203], v152 offset:19456
	ds_read_b128 v[204:207], v152 offset:20480
	ds_read_b128 v[208:211], v152 offset:21504
	ds_read_b128 v[212:215], v152 offset:22528
	ds_read_b128 v[216:219], v152 offset:23552
	global_load_lds_dwordx4 v130, s[52:53]
	s_add_i32 m0, s26, 0x2000
	s_add_u32 s26, s52, 0x20000
	s_addc_u32 s27, s53, 0
	s_add_i32 s33, s65, s56
	global_load_lds_dwordx4 v134, s[52:53]
	s_mov_b32 m0, s33
	s_nop 0
	global_load_lds_dwordx4 v130, s[26:27]
	s_add_i32 m0, s33, 0x2000
	s_nop 0
	global_load_lds_dwordx4 v134, s[26:27]
	s_mov_b32 m0, s49
	s_nop 0
	global_load_lds_dwordx4 v128, s[54:55]
	s_mov_b32 m0, s57
	s_nop 0
	global_load_lds_dwordx4 v132, s[54:55]
	s_waitcnt vmcnt(8)
	s_waitcnt lgkmcnt(0)
	s_barrier
	s_waitcnt lgkmcnt(0)
	v_mfma_f32_16x16x32_bf16 v[60:63], v[156:159], v[188:191], v[60:63]
	v_mfma_f32_16x16x32_bf16 v[56:59], v[164:167], v[188:191], v[56:59]
	v_mfma_f32_16x16x32_bf16 v[44:47], v[156:159], v[196:199], v[44:47]
	v_mfma_f32_16x16x32_bf16 v[40:43], v[164:167], v[196:199], v[40:43]
	v_mfma_f32_16x16x32_bf16 v[28:31], v[156:159], v[204:207], v[28:31]
	v_mfma_f32_16x16x32_bf16 v[24:27], v[164:167], v[204:207], v[24:27]
	v_mfma_f32_16x16x32_bf16 v[12:15], v[156:159], v[212:215], v[12:15]
	v_mfma_f32_16x16x32_bf16 v[8:11], v[164:167], v[212:215], v[8:11]
	v_mfma_f32_16x16x32_bf16 v[60:63], v[160:163], v[192:195], v[60:63]
	v_mfma_f32_16x16x32_bf16 v[56:59], v[168:171], v[192:195], v[56:59]
	v_mfma_f32_16x16x32_bf16 v[44:47], v[160:163], v[200:203], v[44:47]
	v_mfma_f32_16x16x32_bf16 v[40:43], v[168:171], v[200:203], v[40:43]
	v_mfma_f32_16x16x32_bf16 v[28:31], v[160:163], v[208:211], v[28:31]
	v_mfma_f32_16x16x32_bf16 v[24:27], v[168:171], v[208:211], v[24:27]
	v_mfma_f32_16x16x32_bf16 v[12:15], v[160:163], v[216:219], v[12:15]
	v_mfma_f32_16x16x32_bf16 v[8:11], v[168:171], v[216:219], v[8:11]
	v_mfma_f32_16x16x32_bf16 v[52:55], v[172:175], v[188:191], v[52:55]
	v_mfma_f32_16x16x32_bf16 v[48:51], v[180:183], v[188:191], v[48:51]
	v_mfma_f32_16x16x32_bf16 v[36:39], v[172:175], v[196:199], v[36:39]
	v_mfma_f32_16x16x32_bf16 v[32:35], v[180:183], v[196:199], v[32:35]
	v_mfma_f32_16x16x32_bf16 v[20:23], v[172:175], v[204:207], v[20:23]
	v_mfma_f32_16x16x32_bf16 v[16:19], v[180:183], v[204:207], v[16:19]
	v_mfma_f32_16x16x32_bf16 v[4:7], v[172:175], v[212:215], v[4:7]
	v_mfma_f32_16x16x32_bf16 v[0:3], v[180:183], v[212:215], v[0:3]
	v_mfma_f32_16x16x32_bf16 v[52:55], v[176:179], v[192:195], v[52:55]
	v_mfma_f32_16x16x32_bf16 v[48:51], v[184:187], v[192:195], v[48:51]
	v_mfma_f32_16x16x32_bf16 v[36:39], v[176:179], v[200:203], v[36:39]
	v_mfma_f32_16x16x32_bf16 v[32:35], v[184:187], v[200:203], v[32:35]
	v_mfma_f32_16x16x32_bf16 v[20:23], v[176:179], v[208:211], v[20:23]
	v_mfma_f32_16x16x32_bf16 v[16:19], v[184:187], v[208:211], v[16:19]
	v_mfma_f32_16x16x32_bf16 v[4:7], v[176:179], v[216:219], v[4:7]
	v_mfma_f32_16x16x32_bf16 v[0:3], v[184:187], v[216:219], v[0:3]
	s_barrier
; #define PG8_STAGE(bufoff, gbase, voff) do { _Pragma("unroll") for (int _i = 0; _i < 2; ++_i) \
;         __builtin_amdgcn_global_load_lds((const unsigned*)((const char*)(gbase) + (voff)[_i]), (PG8_LAS unsigned*)(lds + (bufoff) + ldsw + _i * 8192), 16, 0, 0); } while (0)
; #define PG8_LDA(dst, b, h) do { _Pragma("unroll") for (int m = 0; m < 4; ++m) _Pragma("unroll") for (int k = 0; k < 2; ++k) dst[m][k] = *(const PG8_LAS bf16x8*)(lds + PG8_SA(b, h) + aoff + m * 2048 + k * 1024); } while (0)
; #define PG8_LDB(dst, b, h) do { _Pragma("unroll") for (int n = 0; n < 2; ++n) _Pragma("unroll") for (int k = 0; k < 2; ++k) dst[n][k] = *(const PG8_LAS bf16x8*)(lds + PG8_SB(b, h) + boff + n * 2048 + k * 1024); } while (0)
; #define PG8_MMA(ai, bj, At, Bt) do { __builtin_amdgcn_s_setprio(1); _Pragma("unroll") for (int m = 0; m < 4; ++m) _Pragma("unroll") for (int n = 0; n < 2; ++n) _Pragma("unroll") for (int k = 0; k < 2; ++k) \
;         acc[ai][bj][m][n] = __builtin_amdgcn_mfma_f32_16x16x32_bf16(Bt[n][k], At[m][k], acc[ai][bj][m][n], 0, 0, 0); __builtin_amdgcn_s_setprio(0); } while (0)
; #define PG8_WAIT_V(n) asm volatile("s_waitcnt vmcnt(" #n ")" ::: "memory")
; #define PG8_WAIT_L(n) asm volatile("s_waitcnt lgkmcnt(" #n ")" ::: "memory")
; #define PG8_BAR __builtin_amdgcn_s_barrier()
; #define PG8_SCHED __builtin_amdgcn_sched_barrier(0)
; template <class Epi, class Sched, bool ALIGN_EPI = false, bool SP2 = false>
; __device__ __forceinline__ void gemm_phase(PG8_LAS unsigned char* lds, const Gemm g, const Sched& S, const Epi& E, int tid_in) {
;     ...
;             PG8_LDB(B0, 1, 0); PG8_LDB(B1, 1, 1); PG8_SCHED; PG8_LDA(At, 1, 0); PG8_STAGE(PG8_SA(0, 1), a2 + hstep, voffA);
;             PG8_WAIT_V(8); PG8_WAIT_L(0); PG8_BAR; PG8_MMA(0, 0, At, B0); PG8_MMA(0, 1, At, B1); PG8_BAR; PG8_SCHED;
;             PG8_LDA(At, 1, 1); PG8_STAGE(PG8_SB(1, 0), b3, voffB); PG8_STAGE(PG8_SB(1, 1), b3 + hstepB, voffB); PG8_STAGE(PG8_SA(1, 0), a3, voffA);
;             PG8_WAIT_V(8); PG8_WAIT_L(0); PG8_BAR; PG8_MMA(1, 0, At, B0); PG8_MMA(1, 1, At, B1); PG8_BAR; PG8_SCHED;
;     ...
;         }
;         if constexpr (ALIGN_EPI) { if (wr == 0) PG8_BAR; }
	s_add_i32 s33, 0, 0x18000
	v_add_u32_e32 v155, s33, v146
	s_add_i32 s73, 0, 0x1c000
	ds_read_b128 v[156:159], v155
	ds_read_b128 v[160:163], v155 offset:1024
	ds_read_b128 v[164:167], v155 offset:2048
	ds_read_b128 v[168:171], v155 offset:3072
	v_add_u32_e32 v155, s73, v146
	ds_read_b128 v[172:175], v155
	ds_read_b128 v[176:179], v155 offset:1024
	ds_read_b128 v[180:183], v155 offset:2048
	ds_read_b128 v[184:187], v155 offset:3072
	s_add_u32 s26, s54, 0x80000
	s_addc_u32 s27, s55, 0
	s_mov_b32 m0, s58
	ds_read_b128 v[188:191], v152 offset:32768
	ds_read_b128 v[192:195], v152 offset:33792
	ds_read_b128 v[196:199], v152 offset:34816
	ds_read_b128 v[200:203], v152 offset:35840
	ds_read_b128 v[204:207], v152 offset:36864
	ds_read_b128 v[208:211], v152 offset:37888
	ds_read_b128 v[212:215], v152 offset:38912
	ds_read_b128 v[216:219], v152 offset:39936
	global_load_lds_dwordx4 v128, s[26:27]
	s_mov_b32 m0, s59
	s_nop 0
	global_load_lds_dwordx4 v132, s[26:27]
	s_waitcnt vmcnt(8)
	s_waitcnt lgkmcnt(0)
	s_barrier
	s_waitcnt lgkmcnt(0)
	v_mfma_f32_16x16x32_bf16 v[124:127], v[156:159], v[188:191], v[124:127]
	v_mfma_f32_16x16x32_bf16 v[120:123], v[164:167], v[188:191], v[120:123]
	v_mfma_f32_16x16x32_bf16 v[108:111], v[156:159], v[196:199], v[108:111]
	v_mfma_f32_16x16x32_bf16 v[104:107], v[164:167], v[196:199], v[104:107]
	v_mfma_f32_16x16x32_bf16 v[92:95], v[156:159], v[204:207], v[92:95]
	v_mfma_f32_16x16x32_bf16 v[88:91], v[164:167], v[204:207], v[88:91]
	v_mfma_f32_16x16x32_bf16 v[76:79], v[156:159], v[212:215], v[76:79]
	v_mfma_f32_16x16x32_bf16 v[72:75], v[164:167], v[212:215], v[72:75]
	v_mfma_f32_16x16x32_bf16 v[124:127], v[160:163], v[192:195], v[124:127]
	v_mfma_f32_16x16x32_bf16 v[120:123], v[168:171], v[192:195], v[120:123]
	v_mfma_f32_16x16x32_bf16 v[108:111], v[160:163], v[200:203], v[108:111]
	v_mfma_f32_16x16x32_bf16 v[104:107], v[168:171], v[200:203], v[104:107]
	v_mfma_f32_16x16x32_bf16 v[92:95], v[160:163], v[208:211], v[92:95]
	v_mfma_f32_16x16x32_bf16 v[88:91], v[168:171], v[208:211], v[88:91]
	v_mfma_f32_16x16x32_bf16 v[76:79], v[160:163], v[216:219], v[76:79]
	v_mfma_f32_16x16x32_bf16 v[72:75], v[168:171], v[216:219], v[72:75]
	v_mfma_f32_16x16x32_bf16 v[116:119], v[172:175], v[188:191], v[116:119]
	v_mfma_f32_16x16x32_bf16 v[112:115], v[180:183], v[188:191], v[112:115]
	v_mfma_f32_16x16x32_bf16 v[100:103], v[172:175], v[196:199], v[100:103]
	v_mfma_f32_16x16x32_bf16 v[96:99], v[180:183], v[196:199], v[96:99]
	v_mfma_f32_16x16x32_bf16 v[84:87], v[172:175], v[204:207], v[84:87]
	v_mfma_f32_16x16x32_bf16 v[80:83], v[180:183], v[204:207], v[80:83]
	v_mfma_f32_16x16x32_bf16 v[68:71], v[172:175], v[212:215], v[68:71]
	v_mfma_f32_16x16x32_bf16 v[64:67], v[180:183], v[212:215], v[64:67]
	v_mfma_f32_16x16x32_bf16 v[116:119], v[176:179], v[192:195], v[116:119]
	v_mfma_f32_16x16x32_bf16 v[112:115], v[184:187], v[192:195], v[112:115]
	v_mfma_f32_16x16x32_bf16 v[100:103], v[176:179], v[200:203], v[100:103]
	v_mfma_f32_16x16x32_bf16 v[96:99], v[184:187], v[200:203], v[96:99]
	v_mfma_f32_16x16x32_bf16 v[84:87], v[176:179], v[208:211], v[84:87]
	v_mfma_f32_16x16x32_bf16 v[80:83], v[184:187], v[208:211], v[80:83]
	v_mfma_f32_16x16x32_bf16 v[68:71], v[176:179], v[216:219], v[68:71]
	v_mfma_f32_16x16x32_bf16 v[64:67], v[184:187], v[216:219], v[64:67]
	s_barrier
	s_add_i32 s26, s33, s56
	s_add_i32 m0, s26, 0xffffff80
	ds_read_b128 v[188:191], v152 offset:49152
	ds_read_b128 v[192:195], v152 offset:50176
	ds_read_b128 v[196:199], v152 offset:51200
	ds_read_b128 v[200:203], v152 offset:52224
	ds_read_b128 v[204:207], v152 offset:53248
	ds_read_b128 v[208:211], v152 offset:54272
	ds_read_b128 v[212:215], v152 offset:55296
	ds_read_b128 v[216:219], v152 offset:56320
	global_load_lds_dwordx4 v130, s[52:53] offset:128
	s_add_i32 m0, s26, 0x1f80
	s_add_u32 s26, s52, 0x20080
	s_addc_u32 s27, s53, 0
	s_add_i32 s33, s73, s56
	global_load_lds_dwordx4 v134, s[52:53] offset:128
	s_mov_b32 m0, s33
	s_nop 0
	global_load_lds_dwordx4 v130, s[26:27]
	s_add_i32 m0, s33, 0x2000
	s_nop 0
	global_load_lds_dwordx4 v134, s[26:27]
	s_add_i32 m0, s62, 0xffffff80
	s_nop 0
	global_load_lds_dwordx4 v128, s[54:55] offset:128
	s_add_i32 m0, s63, 0xffffff80
	s_nop 0
	global_load_lds_dwordx4 v132, s[54:55] offset:128
	s_waitcnt vmcnt(8)
	s_waitcnt lgkmcnt(0)
	s_barrier
	s_waitcnt lgkmcnt(0)
	v_mfma_f32_16x16x32_bf16 v[60:63], v[156:159], v[188:191], v[60:63]
	v_mfma_f32_16x16x32_bf16 v[56:59], v[164:167], v[188:191], v[56:59]
	v_mfma_f32_16x16x32_bf16 v[44:47], v[156:159], v[196:199], v[44:47]
	v_mfma_f32_16x16x32_bf16 v[40:43], v[164:167], v[196:199], v[40:43]
	v_mfma_f32_16x16x32_bf16 v[28:31], v[156:159], v[204:207], v[28:31]
	v_mfma_f32_16x16x32_bf16 v[24:27], v[164:167], v[204:207], v[24:27]
	v_mfma_f32_16x16x32_bf16 v[12:15], v[156:159], v[212:215], v[12:15]
	v_mfma_f32_16x16x32_bf16 v[8:11], v[164:167], v[212:215], v[8:11]
	v_mfma_f32_16x16x32_bf16 v[60:63], v[160:163], v[192:195], v[60:63]
	v_mfma_f32_16x16x32_bf16 v[56:59], v[168:171], v[192:195], v[56:59]
	v_mfma_f32_16x16x32_bf16 v[44:47], v[160:163], v[200:203], v[44:47]
	v_mfma_f32_16x16x32_bf16 v[40:43], v[168:171], v[200:203], v[40:43]
	v_mfma_f32_16x16x32_bf16 v[28:31], v[160:163], v[208:211], v[28:31]
	v_mfma_f32_16x16x32_bf16 v[24:27], v[168:171], v[208:211], v[24:27]
	v_mfma_f32_16x16x32_bf16 v[12:15], v[160:163], v[216:219], v[12:15]
	v_mfma_f32_16x16x32_bf16 v[8:11], v[168:171], v[216:219], v[8:11]
	v_mfma_f32_16x16x32_bf16 v[52:55], v[172:175], v[188:191], v[52:55]
	v_mfma_f32_16x16x32_bf16 v[48:51], v[180:183], v[188:191], v[48:51]
	v_mfma_f32_16x16x32_bf16 v[36:39], v[172:175], v[196:199], v[36:39]
	v_mfma_f32_16x16x32_bf16 v[32:35], v[180:183], v[196:199], v[32:35]
	v_mfma_f32_16x16x32_bf16 v[20:23], v[172:175], v[204:207], v[20:23]
	v_mfma_f32_16x16x32_bf16 v[16:19], v[180:183], v[204:207], v[16:19]
	v_mfma_f32_16x16x32_bf16 v[4:7], v[172:175], v[212:215], v[4:7]
	v_mfma_f32_16x16x32_bf16 v[0:3], v[180:183], v[212:215], v[0:3]
	v_mfma_f32_16x16x32_bf16 v[52:55], v[176:179], v[192:195], v[52:55]
	v_mfma_f32_16x16x32_bf16 v[48:51], v[184:187], v[192:195], v[48:51]
	v_mfma_f32_16x16x32_bf16 v[36:39], v[176:179], v[200:203], v[36:39]
	v_mfma_f32_16x16x32_bf16 v[32:35], v[184:187], v[200:203], v[32:35]
	v_mfma_f32_16x16x32_bf16 v[20:23], v[176:179], v[208:211], v[20:23]
	v_mfma_f32_16x16x32_bf16 v[16:19], v[184:187], v[208:211], v[16:19]
	v_mfma_f32_16x16x32_bf16 v[4:7], v[176:179], v[216:219], v[4:7]
	v_mfma_f32_16x16x32_bf16 v[0:3], v[184:187], v[216:219], v[0:3]
	s_barrier
	s_add_i32 s72, s72, 2
	s_add_u32 s50, s50, 0x100
	s_addc_u32 s51, s51, 0
	s_add_u32 s70, s70, 0x100
	s_addc_u32 s71, s71, 0
	s_cmp_gt_u32 s72, 29
	s_cbranch_scc0 .LBB0_869
	s_and_b64 vcc, exec, s[36:37]
	s_cbranch_vccz .LBB0_872
	s_barrier

; #define PG8_STAGE(bufoff, gbase, voff) do { _Pragma("unroll") for (int _i = 0; _i < 2; ++_i) \
;         __builtin_amdgcn_global_load_lds((const unsigned*)((const char*)(gbase) + (voff)[_i]), (PG8_LAS unsigned*)(lds + (bufoff) + ldsw + _i * 8192), 16, 0, 0); } while (0)
; #define PG8_LDA(dst, b, h) do { _Pragma("unroll") for (int m = 0; m < 4; ++m) _Pragma("unroll") for (int k = 0; k < 2; ++k) dst[m][k] = *(const PG8_LAS bf16x8*)(lds + PG8_SA(b, h) + aoff + m * 2048 + k * 1024); } while (0)
; #define PG8_LDB(dst, b, h) do { _Pragma("unroll") for (int n = 0; n < 2; ++n) _Pragma("unroll") for (int k = 0; k < 2; ++k) dst[n][k] = *(const PG8_LAS bf16x8*)(lds + PG8_SB(b, h) + boff + n * 2048 + k * 1024); } while (0)
; #define PG8_MMA(ai, bj, At, Bt) do { __builtin_amdgcn_s_setprio(1); _Pragma("unroll") for (int m = 0; m < 4; ++m) _Pragma("unroll") for (int n = 0; n < 2; ++n) _Pragma("unroll") for (int k = 0; k < 2; ++k) \
;         acc[ai][bj][m][n] = __builtin_amdgcn_mfma_f32_16x16x32_bf16(Bt[n][k], At[m][k], acc[ai][bj][m][n], 0, 0, 0); __builtin_amdgcn_s_setprio(0); } while (0)
; #define PG8_WAIT_V(n) asm volatile("s_waitcnt vmcnt(" #n ")" ::: "memory")
; #define PG8_WAIT_L(n) asm volatile("s_waitcnt lgkmcnt(" #n ")" ::: "memory")
; #define PG8_BAR __builtin_amdgcn_s_barrier()
; #define PG8_SCHED __builtin_amdgcn_sched_barrier(0)
; template <class Epi, class Sched, bool ALIGN_EPI = false, bool SP2 = false>
; __device__ __forceinline__ void gemm_phase(PG8_LAS unsigned char* lds, const Gemm g, const Sched& S, const Epi& E, int tid_in) {
;     ...
;             PG8_LDB(B0, 0, 0); PG8_LDB(B1, 0, 1); PG8_SCHED; PG8_LDA(At, 0, 0); PG8_STAGE(PG8_SA(1, 1), a1 + hstep, voffA);
;             PG8_WAIT_V(8); PG8_WAIT_L(0); PG8_BAR; PG8_MMA(0, 0, At, B0); PG8_MMA(0, 1, At, B1); PG8_BAR; PG8_SCHED;
;             PG8_LDA(At, 0, 1); PG8_STAGE(PG8_SB(0, 0), b2, voffB); PG8_STAGE(PG8_SB(0, 1), b2 + hstepB, voffB); PG8_STAGE(PG8_SA(0, 0), a2, voffA);
;             PG8_WAIT_V(8); PG8_WAIT_L(0); PG8_BAR; PG8_MMA(1, 0, At, B0); PG8_MMA(1, 1, At, B1); PG8_BAR; PG8_SCHED;
.Lkb_skip_7:
	ds_read_b128 v[146:149], v153
	ds_read_b128 v[158:161], v153 offset:1024
	ds_read_b128 v[162:165], v153 offset:2048
	ds_read_b128 v[166:169], v153 offset:3072
	ds_read_b128 v[170:173], v154
	ds_read_b128 v[174:177], v154 offset:1024
	ds_read_b128 v[178:181], v154 offset:2048
	ds_read_b128 v[182:185], v154 offset:3072
	s_add_u32 s10, s50, 0x100
	s_addc_u32 s11, s51, 0
	s_cmpk_eq_i32 s70, 0x7c
	s_cselect_b32 s55, s45, s11
	s_cselect_b32 s54, s44, s10
	s_cselect_b32 s53, s43, s69
	s_cselect_b32 s52, s67, s68
	s_add_i32 m0, s49, 0xc000
	ds_read_b128 v[186:189], v155
	ds_read_b128 v[190:193], v155 offset:1024
	ds_read_b128 v[194:197], v155 offset:2048
	ds_read_b128 v[198:201], v155 offset:3072
	ds_read_b128 v[202:205], v155 offset:4096
	ds_read_b128 v[206:209], v155 offset:5120
	ds_read_b128 v[210:213], v155 offset:6144
	ds_read_b128 v[214:217], v155 offset:7168
	global_load_lds_dwordx4 v138, s[50:51]
	s_add_i32 m0, s49, 0xe000
	s_nop 0
	global_load_lds_dwordx4 v140, s[50:51]
	s_waitcnt vmcnt(8)
	s_waitcnt lgkmcnt(0)
	s_barrier
	s_waitcnt lgkmcnt(0)
	v_mfma_f32_16x16x32_bf16 v[124:127], v[146:149], v[186:189], 0
	v_mfma_f32_16x16x32_bf16 v[120:123], v[162:165], v[186:189], 0
	v_mfma_f32_16x16x32_bf16 v[108:111], v[146:149], v[194:197], 0
	v_mfma_f32_16x16x32_bf16 v[104:107], v[162:165], v[194:197], 0
	v_mfma_f32_16x16x32_bf16 v[92:95], v[146:149], v[202:205], 0
	v_mfma_f32_16x16x32_bf16 v[88:91], v[162:165], v[202:205], 0
	v_mfma_f32_16x16x32_bf16 v[76:79], v[146:149], v[210:213], 0
	v_mfma_f32_16x16x32_bf16 v[72:75], v[162:165], v[210:213], 0
	v_mfma_f32_16x16x32_bf16 v[124:127], v[158:161], v[190:193], v[124:127]
	v_mfma_f32_16x16x32_bf16 v[120:123], v[166:169], v[190:193], v[120:123]
	v_mfma_f32_16x16x32_bf16 v[108:111], v[158:161], v[198:201], v[108:111]
	v_mfma_f32_16x16x32_bf16 v[104:107], v[166:169], v[198:201], v[104:107]
	v_mfma_f32_16x16x32_bf16 v[92:95], v[158:161], v[206:209], v[92:95]
	v_mfma_f32_16x16x32_bf16 v[88:91], v[166:169], v[206:209], v[88:91]
	v_mfma_f32_16x16x32_bf16 v[76:79], v[158:161], v[214:217], v[76:79]
	v_mfma_f32_16x16x32_bf16 v[72:75], v[166:169], v[214:217], v[72:75]
	v_mfma_f32_16x16x32_bf16 v[116:119], v[170:173], v[186:189], 0
	v_mfma_f32_16x16x32_bf16 v[112:115], v[178:181], v[186:189], 0
	v_mfma_f32_16x16x32_bf16 v[100:103], v[170:173], v[194:197], 0
	v_mfma_f32_16x16x32_bf16 v[96:99], v[178:181], v[194:197], 0
	v_mfma_f32_16x16x32_bf16 v[84:87], v[170:173], v[202:205], 0
	v_mfma_f32_16x16x32_bf16 v[80:83], v[178:181], v[202:205], 0
	v_mfma_f32_16x16x32_bf16 v[68:71], v[170:173], v[210:213], 0
	v_mfma_f32_16x16x32_bf16 v[64:67], v[178:181], v[210:213], 0
	v_mfma_f32_16x16x32_bf16 v[116:119], v[174:177], v[190:193], v[116:119]
	v_mfma_f32_16x16x32_bf16 v[112:115], v[182:185], v[190:193], v[112:115]
	v_mfma_f32_16x16x32_bf16 v[100:103], v[174:177], v[198:201], v[100:103]
	v_mfma_f32_16x16x32_bf16 v[96:99], v[182:185], v[198:201], v[96:99]
	v_mfma_f32_16x16x32_bf16 v[84:87], v[174:177], v[206:209], v[84:87]
	v_mfma_f32_16x16x32_bf16 v[80:83], v[182:185], v[206:209], v[80:83]
	v_mfma_f32_16x16x32_bf16 v[68:71], v[174:177], v[214:217], v[68:71]
	v_mfma_f32_16x16x32_bf16 v[64:67], v[182:185], v[214:217], v[64:67]
	s_barrier
	s_add_i32 s26, s63, s56
	s_mov_b32 m0, s26
	ds_read_b128 v[186:189], v155 offset:16384
	ds_read_b128 v[190:193], v155 offset:17408
	ds_read_b128 v[194:197], v155 offset:18432
	ds_read_b128 v[198:201], v155 offset:19456
	ds_read_b128 v[202:205], v155 offset:20480
	ds_read_b128 v[206:209], v155 offset:21504
	ds_read_b128 v[210:213], v155 offset:22528
	ds_read_b128 v[214:217], v155 offset:23552
	global_load_lds_dwordx4 v130, s[52:53]
	s_add_i32 m0, s26, 0x2000
	s_add_u32 s26, s52, 0x80000
	s_addc_u32 s27, s53, 0
	s_add_i32 s33, s64, s56
	global_load_lds_dwordx4 v134, s[52:53]
	s_mov_b32 m0, s33
	s_nop 0
	global_load_lds_dwordx4 v130, s[26:27]
	s_add_i32 m0, s33, 0x2000
	s_nop 0
	global_load_lds_dwordx4 v134, s[26:27]
	s_mov_b32 m0, s49
	s_nop 0
	global_load_lds_dwordx4 v128, s[54:55]
	s_mov_b32 m0, s57
	s_nop 0
	global_load_lds_dwordx4 v132, s[54:55]
	s_waitcnt vmcnt(8)
	s_waitcnt lgkmcnt(0)
	s_barrier
	s_waitcnt lgkmcnt(0)
	v_mfma_f32_16x16x32_bf16 v[60:63], v[146:149], v[186:189], 0
	v_mfma_f32_16x16x32_bf16 v[56:59], v[162:165], v[186:189], 0
	v_mfma_f32_16x16x32_bf16 v[44:47], v[146:149], v[194:197], 0
	v_mfma_f32_16x16x32_bf16 v[40:43], v[162:165], v[194:197], 0
	v_mfma_f32_16x16x32_bf16 v[28:31], v[146:149], v[202:205], 0
	v_mfma_f32_16x16x32_bf16 v[24:27], v[162:165], v[202:205], 0
	v_mfma_f32_16x16x32_bf16 v[12:15], v[146:149], v[210:213], 0
	v_mfma_f32_16x16x32_bf16 v[8:11], v[162:165], v[210:213], 0
	v_mfma_f32_16x16x32_bf16 v[60:63], v[158:161], v[190:193], v[60:63]
	v_mfma_f32_16x16x32_bf16 v[56:59], v[166:169], v[190:193], v[56:59]
	v_mfma_f32_16x16x32_bf16 v[44:47], v[158:161], v[198:201], v[44:47]
	v_mfma_f32_16x16x32_bf16 v[40:43], v[166:169], v[198:201], v[40:43]
	v_mfma_f32_16x16x32_bf16 v[28:31], v[158:161], v[206:209], v[28:31]
	v_mfma_f32_16x16x32_bf16 v[24:27], v[166:169], v[206:209], v[24:27]
	v_mfma_f32_16x16x32_bf16 v[12:15], v[158:161], v[214:217], v[12:15]
	v_mfma_f32_16x16x32_bf16 v[8:11], v[166:169], v[214:217], v[8:11]
	v_mfma_f32_16x16x32_bf16 v[52:55], v[170:173], v[186:189], 0
	v_mfma_f32_16x16x32_bf16 v[48:51], v[178:181], v[186:189], 0
	v_mfma_f32_16x16x32_bf16 v[36:39], v[170:173], v[194:197], 0
	v_mfma_f32_16x16x32_bf16 v[32:35], v[178:181], v[194:197], 0
	v_mfma_f32_16x16x32_bf16 v[20:23], v[170:173], v[202:205], 0
	v_mfma_f32_16x16x32_bf16 v[16:19], v[178:181], v[202:205], 0
	v_mfma_f32_16x16x32_bf16 v[4:7], v[170:173], v[210:213], 0
	v_mfma_f32_16x16x32_bf16 v[0:3], v[178:181], v[210:213], 0
	v_mfma_f32_16x16x32_bf16 v[52:55], v[174:177], v[190:193], v[52:55]
	v_mfma_f32_16x16x32_bf16 v[48:51], v[182:185], v[190:193], v[48:51]
	v_mfma_f32_16x16x32_bf16 v[36:39], v[174:177], v[198:201], v[36:39]
	v_mfma_f32_16x16x32_bf16 v[32:35], v[182:185], v[198:201], v[32:35]
	v_mfma_f32_16x16x32_bf16 v[20:23], v[174:177], v[206:209], v[20:23]
	v_mfma_f32_16x16x32_bf16 v[16:19], v[182:185], v[206:209], v[16:19]
	v_mfma_f32_16x16x32_bf16 v[4:7], v[174:177], v[214:217], v[4:7]
	v_mfma_f32_16x16x32_bf16 v[0:3], v[182:185], v[214:217], v[0:3]
	s_barrier
; #define PG8_STAGE(bufoff, gbase, voff) do { _Pragma("unroll") for (int _i = 0; _i < 2; ++_i) \
;         __builtin_amdgcn_global_load_lds((const unsigned*)((const char*)(gbase) + (voff)[_i]), (PG8_LAS unsigned*)(lds + (bufoff) + ldsw + _i * 8192), 16, 0, 0); } while (0)
; #define PG8_LDA(dst, b, h) do { _Pragma("unroll") for (int m = 0; m < 4; ++m) _Pragma("unroll") for (int k = 0; k < 2; ++k) dst[m][k] = *(const PG8_LAS bf16x8*)(lds + PG8_SA(b, h) + aoff + m * 2048 + k * 1024); } while (0)
; #define PG8_LDB(dst, b, h) do { _Pragma("unroll") for (int n = 0; n < 2; ++n) _Pragma("unroll") for (int k = 0; k < 2; ++k) dst[n][k] = *(const PG8_LAS bf16x8*)(lds + PG8_SB(b, h) + boff + n * 2048 + k * 1024); } while (0)
; #define PG8_MMA(ai, bj, At, Bt) do { __builtin_amdgcn_s_setprio(1); _Pragma("unroll") for (int m = 0; m < 4; ++m) _Pragma("unroll") for (int n = 0; n < 2; ++n) _Pragma("unroll") for (int k = 0; k < 2; ++k) \
;         acc[ai][bj][m][n] = __builtin_amdgcn_mfma_f32_16x16x32_bf16(Bt[n][k], At[m][k], acc[ai][bj][m][n], 0, 0, 0); __builtin_amdgcn_s_setprio(0); } while (0)
; #define PG8_WAIT_V(n) asm volatile("s_waitcnt vmcnt(" #n ")" ::: "memory")
; #define PG8_WAIT_L(n) asm volatile("s_waitcnt lgkmcnt(" #n ")" ::: "memory")
; #define PG8_BAR __builtin_amdgcn_s_barrier()
; #define PG8_SCHED __builtin_amdgcn_sched_barrier(0)
; template <class Epi, class Sched, bool ALIGN_EPI = false, bool SP2 = false>
; __device__ __forceinline__ void gemm_phase(PG8_LAS unsigned char* lds, const Gemm g, const Sched& S, const Epi& E, int tid_in) {
;     ...
;             PG8_LDB(B0, 1, 0); PG8_LDB(B1, 1, 1); PG8_SCHED; PG8_LDA(At, 1, 0); PG8_STAGE(PG8_SA(0, 1), a2 + hstep, voffA);
;             PG8_WAIT_V(8); PG8_WAIT_L(0); PG8_BAR; PG8_MMA(0, 0, At, B0); PG8_MMA(0, 1, At, B1); PG8_BAR; PG8_SCHED;
;             PG8_LDA(At, 1, 1); PG8_STAGE(PG8_SB(1, 0), b3, voffB); PG8_STAGE(PG8_SB(1, 1), b3 + hstepB, voffB); PG8_STAGE(PG8_SA(1, 0), a3, voffA);
;             PG8_WAIT_V(8); PG8_WAIT_L(0); PG8_BAR; PG8_MMA(1, 0, At, B0); PG8_MMA(1, 1, At, B1); PG8_BAR; PG8_SCHED;
	s_add_i32 s33, 0, 0x18000
	s_add_i32 s50, 0, 0x1c000
	v_add_u32_e32 v166, s33, v137
	v_add_u32_e32 v182, s50, v137
	ds_read_b128 v[146:149], v166
	ds_read_b128 v[158:161], v166 offset:1024
	ds_read_b128 v[162:165], v166 offset:2048
	ds_read_b128 v[166:169], v166 offset:3072
	ds_read_b128 v[170:173], v182
	ds_read_b128 v[174:177], v182 offset:1024
	ds_read_b128 v[178:181], v182 offset:2048
	ds_read_b128 v[182:185], v182 offset:3072
	s_add_u32 s26, s54, 0x204000
	s_addc_u32 s27, s55, 0
	s_mov_b32 m0, s58
	ds_read_b128 v[186:189], v155 offset:32768
	ds_read_b128 v[190:193], v155 offset:33792
	ds_read_b128 v[194:197], v155 offset:34816
	ds_read_b128 v[198:201], v155 offset:35840
	ds_read_b128 v[202:205], v155 offset:36864
	ds_read_b128 v[206:209], v155 offset:37888
	ds_read_b128 v[210:213], v155 offset:38912
	ds_read_b128 v[214:217], v155 offset:39936
	global_load_lds_dwordx4 v128, s[26:27]
	s_mov_b32 m0, s59
	s_nop 0
	global_load_lds_dwordx4 v132, s[26:27]
	s_waitcnt vmcnt(8)
	s_waitcnt lgkmcnt(0)
	s_barrier
	s_waitcnt lgkmcnt(0)
	v_mfma_f32_16x16x32_bf16 v[124:127], v[146:149], v[186:189], v[124:127]
	v_mfma_f32_16x16x32_bf16 v[120:123], v[162:165], v[186:189], v[120:123]
	v_mfma_f32_16x16x32_bf16 v[108:111], v[146:149], v[194:197], v[108:111]
	v_mfma_f32_16x16x32_bf16 v[104:107], v[162:165], v[194:197], v[104:107]
	v_mfma_f32_16x16x32_bf16 v[92:95], v[146:149], v[202:205], v[92:95]
	v_mfma_f32_16x16x32_bf16 v[88:91], v[162:165], v[202:205], v[88:91]
	v_mfma_f32_16x16x32_bf16 v[76:79], v[146:149], v[210:213], v[76:79]
	v_mfma_f32_16x16x32_bf16 v[72:75], v[162:165], v[210:213], v[72:75]
	v_mfma_f32_16x16x32_bf16 v[124:127], v[158:161], v[190:193], v[124:127]
	v_mfma_f32_16x16x32_bf16 v[120:123], v[166:169], v[190:193], v[120:123]
	v_mfma_f32_16x16x32_bf16 v[108:111], v[158:161], v[198:201], v[108:111]
	v_mfma_f32_16x16x32_bf16 v[104:107], v[166:169], v[198:201], v[104:107]
	v_mfma_f32_16x16x32_bf16 v[92:95], v[158:161], v[206:209], v[92:95]
	v_mfma_f32_16x16x32_bf16 v[88:91], v[166:169], v[206:209], v[88:91]
	v_mfma_f32_16x16x32_bf16 v[76:79], v[158:161], v[214:217], v[76:79]
	v_mfma_f32_16x16x32_bf16 v[72:75], v[166:169], v[214:217], v[72:75]
	v_mfma_f32_16x16x32_bf16 v[116:119], v[170:173], v[186:189], v[116:119]
	v_mfma_f32_16x16x32_bf16 v[112:115], v[178:181], v[186:189], v[112:115]
	v_mfma_f32_16x16x32_bf16 v[100:103], v[170:173], v[194:197], v[100:103]
	v_mfma_f32_16x16x32_bf16 v[96:99], v[178:181], v[194:197], v[96:99]
	v_mfma_f32_16x16x32_bf16 v[84:87], v[170:173], v[202:205], v[84:87]
	v_mfma_f32_16x16x32_bf16 v[80:83], v[178:181], v[202:205], v[80:83]
	v_mfma_f32_16x16x32_bf16 v[68:71], v[170:173], v[210:213], v[68:71]
	v_mfma_f32_16x16x32_bf16 v[64:67], v[178:181], v[210:213], v[64:67]
	v_mfma_f32_16x16x32_bf16 v[116:119], v[174:177], v[190:193], v[116:119]
	v_mfma_f32_16x16x32_bf16 v[112:115], v[182:185], v[190:193], v[112:115]
	v_mfma_f32_16x16x32_bf16 v[100:103], v[174:177], v[198:201], v[100:103]
	v_mfma_f32_16x16x32_bf16 v[96:99], v[182:185], v[198:201], v[96:99]
	v_mfma_f32_16x16x32_bf16 v[84:87], v[174:177], v[206:209], v[84:87]
	v_mfma_f32_16x16x32_bf16 v[80:83], v[182:185], v[206:209], v[80:83]
	v_mfma_f32_16x16x32_bf16 v[68:71], v[174:177], v[214:217], v[68:71]
	v_mfma_f32_16x16x32_bf16 v[64:67], v[182:185], v[214:217], v[64:67]
	s_barrier
	s_add_i32 s26, s33, s56
	s_add_i32 m0, s26, 0xffffff80
	ds_read_b128 v[186:189], v155 offset:49152
	ds_read_b128 v[190:193], v155 offset:50176
	ds_read_b128 v[194:197], v155 offset:51200
	ds_read_b128 v[198:201], v155 offset:52224
	ds_read_b128 v[202:205], v155 offset:53248
	ds_read_b128 v[206:209], v155 offset:54272
	ds_read_b128 v[210:213], v155 offset:55296
	ds_read_b128 v[214:217], v155 offset:56320
	global_load_lds_dwordx4 v130, s[52:53] offset:128
	s_add_i32 m0, s26, 0x1f80
	s_add_u32 s26, s52, 0x80080
	s_addc_u32 s27, s53, 0
	s_add_i32 s33, s50, s56
	global_load_lds_dwordx4 v134, s[52:53] offset:128
	s_mov_b32 m0, s33
	s_nop 0
	global_load_lds_dwordx4 v130, s[26:27]
	s_add_i32 m0, s33, 0x2000
	s_nop 0
	global_load_lds_dwordx4 v134, s[26:27]
	s_add_i32 m0, s61, 0xffffff80
	s_nop 0
	global_load_lds_dwordx4 v128, s[54:55] offset:128
	s_add_i32 m0, s62, 0xffffff80
	s_nop 0
	global_load_lds_dwordx4 v132, s[54:55] offset:128
	s_waitcnt vmcnt(8)
	s_waitcnt lgkmcnt(0)
	s_barrier
	s_waitcnt lgkmcnt(0)
	v_mfma_f32_16x16x32_bf16 v[60:63], v[146:149], v[186:189], v[60:63]
	v_mfma_f32_16x16x32_bf16 v[56:59], v[162:165], v[186:189], v[56:59]
	v_mfma_f32_16x16x32_bf16 v[44:47], v[146:149], v[194:197], v[44:47]
	v_mfma_f32_16x16x32_bf16 v[40:43], v[162:165], v[194:197], v[40:43]
	v_mfma_f32_16x16x32_bf16 v[28:31], v[146:149], v[202:205], v[28:31]
	v_mfma_f32_16x16x32_bf16 v[24:27], v[162:165], v[202:205], v[24:27]
	v_mfma_f32_16x16x32_bf16 v[12:15], v[146:149], v[210:213], v[12:15]
	v_mfma_f32_16x16x32_bf16 v[8:11], v[162:165], v[210:213], v[8:11]
	v_mfma_f32_16x16x32_bf16 v[60:63], v[158:161], v[190:193], v[60:63]
	v_mfma_f32_16x16x32_bf16 v[56:59], v[166:169], v[190:193], v[56:59]
	v_mfma_f32_16x16x32_bf16 v[44:47], v[158:161], v[198:201], v[44:47]
	v_mfma_f32_16x16x32_bf16 v[40:43], v[166:169], v[198:201], v[40:43]
	v_mfma_f32_16x16x32_bf16 v[28:31], v[158:161], v[206:209], v[28:31]
	v_mfma_f32_16x16x32_bf16 v[24:27], v[166:169], v[206:209], v[24:27]
	v_mfma_f32_16x16x32_bf16 v[12:15], v[158:161], v[214:217], v[12:15]
	v_mfma_f32_16x16x32_bf16 v[8:11], v[166:169], v[214:217], v[8:11]
	v_mfma_f32_16x16x32_bf16 v[52:55], v[170:173], v[186:189], v[52:55]
	v_mfma_f32_16x16x32_bf16 v[48:51], v[178:181], v[186:189], v[48:51]
	v_mfma_f32_16x16x32_bf16 v[36:39], v[170:173], v[194:197], v[36:39]
	v_mfma_f32_16x16x32_bf16 v[32:35], v[178:181], v[194:197], v[32:35]
	v_mfma_f32_16x16x32_bf16 v[20:23], v[170:173], v[202:205], v[20:23]
	v_mfma_f32_16x16x32_bf16 v[16:19], v[178:181], v[202:205], v[16:19]
	v_mfma_f32_16x16x32_bf16 v[4:7], v[170:173], v[210:213], v[4:7]
	v_mfma_f32_16x16x32_bf16 v[0:3], v[178:181], v[210:213], v[0:3]
	v_mfma_f32_16x16x32_bf16 v[52:55], v[174:177], v[190:193], v[52:55]
	v_mfma_f32_16x16x32_bf16 v[48:51], v[182:185], v[190:193], v[48:51]
	v_mfma_f32_16x16x32_bf16 v[36:39], v[174:177], v[198:201], v[36:39]
	v_mfma_f32_16x16x32_bf16 v[32:35], v[182:185], v[198:201], v[32:35]
	v_mfma_f32_16x16x32_bf16 v[20:23], v[174:177], v[206:209], v[20:23]
	v_mfma_f32_16x16x32_bf16 v[16:19], v[182:185], v[206:209], v[16:19]
	v_mfma_f32_16x16x32_bf16 v[4:7], v[174:177], v[214:217], v[4:7]
	v_mfma_f32_16x16x32_bf16 v[0:3], v[182:185], v[214:217], v[0:3]
	s_barrier
	s_add_i32 s70, s70, 2
	s_add_u32 s68, s68, 0x100
	s_addc_u32 s69, s69, 0
	s_cmpk_gt_u32 s70, 0x7d
	s_mov_b64 s[50:51], s[10:11]
; #define PG8_STAGE(bufoff, gbase, voff) do { _Pragma("unroll") for (int _i = 0; _i < 2; ++_i) \
;         __builtin_amdgcn_global_load_lds((const unsigned*)((const char*)(gbase) + (voff)[_i]), (PG8_LAS unsigned*)(lds + (bufoff) + ldsw + _i * 8192), 16, 0, 0); } while (0)
; #define PG8_LDA(dst, b, h) do { _Pragma("unroll") for (int m = 0; m < 4; ++m) _Pragma("unroll") for (int k = 0; k < 2; ++k) dst[m][k] = *(const PG8_LAS bf16x8*)(lds + PG8_SA(b, h) + aoff + m * 2048 + k * 1024); } while (0)
; #define PG8_LDB(dst, b, h) do { _Pragma("unroll") for (int n = 0; n < 2; ++n) _Pragma("unroll") for (int k = 0; k < 2; ++k) dst[n][k] = *(const PG8_LAS bf16x8*)(lds + PG8_SB(b, h) + boff + n * 2048 + k * 1024); } while (0)
; #define PG8_MMA(ai, bj, At, Bt) do { __builtin_amdgcn_s_setprio(1); _Pragma("unroll") for (int m = 0; m < 4; ++m) _Pragma("unroll") for (int n = 0; n < 2; ++n) _Pragma("unroll") for (int k = 0; k < 2; ++k) \
;         acc[ai][bj][m][n] = __builtin_amdgcn_mfma_f32_16x16x32_bf16(Bt[n][k], At[m][k], acc[ai][bj][m][n], 0, 0, 0); __builtin_amdgcn_s_setprio(0); } while (0)
; #define PG8_WAIT_V(n) asm volatile("s_waitcnt vmcnt(" #n ")" ::: "memory")
; #define PG8_WAIT_L(n) asm volatile("s_waitcnt lgkmcnt(" #n ")" ::: "memory")
; #define PG8_BAR __builtin_amdgcn_s_barrier()
; #define PG8_SCHED __builtin_amdgcn_sched_barrier(0)
; template <class Epi, class Sched, bool ALIGN_EPI = false, bool SP2 = false>
; __device__ __forceinline__ void gemm_phase(PG8_LAS unsigned char* lds, const Gemm g, const Sched& S, const Epi& E, int tid_in) {
;     ...
;             PG8_LDB(B0, 0, 0); PG8_LDB(B1, 0, 1); PG8_SCHED; PG8_LDA(At, 0, 0); PG8_STAGE(PG8_SA(1, 1), a1 + hstep, voffA);
;             PG8_WAIT_V(8); PG8_WAIT_L(0); PG8_BAR; PG8_MMA(0, 0, At, B0); PG8_MMA(0, 1, At, B1); PG8_BAR; PG8_SCHED;
;             PG8_LDA(At, 0, 1); PG8_STAGE(PG8_SB(0, 0), b2, voffB); PG8_STAGE(PG8_SB(0, 1), b2 + hstepB, voffB); PG8_STAGE(PG8_SA(0, 0), a2, voffA);
;             PG8_WAIT_V(8); PG8_WAIT_L(0); PG8_BAR; PG8_MMA(1, 0, At, B0); PG8_MMA(1, 1, At, B1); PG8_BAR; PG8_SCHED;
.LBB0_949:
	ds_read_b128 v[146:149], v153
	ds_read_b128 v[158:161], v153 offset:1024
	ds_read_b128 v[162:165], v153 offset:2048
	ds_read_b128 v[166:169], v153 offset:3072
	ds_read_b128 v[170:173], v154
	ds_read_b128 v[174:177], v154 offset:1024
	ds_read_b128 v[178:181], v154 offset:2048
	ds_read_b128 v[182:185], v154 offset:3072
	s_add_u32 s10, s50, 0x100
	s_addc_u32 s11, s51, 0
	s_cmpk_eq_i32 s70, 0x7c
	s_cselect_b32 s55, s45, s11
	s_cselect_b32 s54, s44, s10
	s_cselect_b32 s53, s43, s69
	s_cselect_b32 s52, s67, s68
	s_add_i32 m0, s49, 0xc000
	ds_read_b128 v[186:189], v155
	ds_read_b128 v[190:193], v155 offset:1024
	ds_read_b128 v[194:197], v155 offset:2048
	ds_read_b128 v[198:201], v155 offset:3072
	ds_read_b128 v[202:205], v155 offset:4096
	ds_read_b128 v[206:209], v155 offset:5120
	ds_read_b128 v[210:213], v155 offset:6144
	ds_read_b128 v[214:217], v155 offset:7168
	global_load_lds_dwordx4 v138, s[50:51]
	s_add_i32 m0, s49, 0xe000
	s_nop 0
	global_load_lds_dwordx4 v140, s[50:51]
	s_waitcnt vmcnt(8)
	s_waitcnt lgkmcnt(0)
	s_barrier
	s_waitcnt lgkmcnt(0)
	v_mfma_f32_16x16x32_bf16 v[124:127], v[146:149], v[186:189], v[124:127]
	v_mfma_f32_16x16x32_bf16 v[120:123], v[162:165], v[186:189], v[120:123]
	v_mfma_f32_16x16x32_bf16 v[108:111], v[146:149], v[194:197], v[108:111]
	v_mfma_f32_16x16x32_bf16 v[104:107], v[162:165], v[194:197], v[104:107]
	v_mfma_f32_16x16x32_bf16 v[92:95], v[146:149], v[202:205], v[92:95]
	v_mfma_f32_16x16x32_bf16 v[88:91], v[162:165], v[202:205], v[88:91]
	v_mfma_f32_16x16x32_bf16 v[76:79], v[146:149], v[210:213], v[76:79]
	v_mfma_f32_16x16x32_bf16 v[72:75], v[162:165], v[210:213], v[72:75]
	v_mfma_f32_16x16x32_bf16 v[124:127], v[158:161], v[190:193], v[124:127]
	v_mfma_f32_16x16x32_bf16 v[120:123], v[166:169], v[190:193], v[120:123]
	v_mfma_f32_16x16x32_bf16 v[108:111], v[158:161], v[198:201], v[108:111]
	v_mfma_f32_16x16x32_bf16 v[104:107], v[166:169], v[198:201], v[104:107]
	v_mfma_f32_16x16x32_bf16 v[92:95], v[158:161], v[206:209], v[92:95]
	v_mfma_f32_16x16x32_bf16 v[88:91], v[166:169], v[206:209], v[88:91]
	v_mfma_f32_16x16x32_bf16 v[76:79], v[158:161], v[214:217], v[76:79]
	v_mfma_f32_16x16x32_bf16 v[72:75], v[166:169], v[214:217], v[72:75]
	v_mfma_f32_16x16x32_bf16 v[116:119], v[170:173], v[186:189], v[116:119]
	v_mfma_f32_16x16x32_bf16 v[112:115], v[178:181], v[186:189], v[112:115]
	v_mfma_f32_16x16x32_bf16 v[100:103], v[170:173], v[194:197], v[100:103]
	v_mfma_f32_16x16x32_bf16 v[96:99], v[178:181], v[194:197], v[96:99]
	v_mfma_f32_16x16x32_bf16 v[84:87], v[170:173], v[202:205], v[84:87]
	v_mfma_f32_16x16x32_bf16 v[80:83], v[178:181], v[202:205], v[80:83]
	v_mfma_f32_16x16x32_bf16 v[68:71], v[170:173], v[210:213], v[68:71]
	v_mfma_f32_16x16x32_bf16 v[64:67], v[178:181], v[210:213], v[64:67]
	v_mfma_f32_16x16x32_bf16 v[116:119], v[174:177], v[190:193], v[116:119]
	v_mfma_f32_16x16x32_bf16 v[112:115], v[182:185], v[190:193], v[112:115]
	v_mfma_f32_16x16x32_bf16 v[100:103], v[174:177], v[198:201], v[100:103]
	v_mfma_f32_16x16x32_bf16 v[96:99], v[182:185], v[198:201], v[96:99]
	v_mfma_f32_16x16x32_bf16 v[84:87], v[174:177], v[206:209], v[84:87]
	v_mfma_f32_16x16x32_bf16 v[80:83], v[182:185], v[206:209], v[80:83]
	v_mfma_f32_16x16x32_bf16 v[68:71], v[174:177], v[214:217], v[68:71]
	v_mfma_f32_16x16x32_bf16 v[64:67], v[182:185], v[214:217], v[64:67]
	s_barrier
	s_add_i32 s26, s63, s56
	s_mov_b32 m0, s26
	ds_read_b128 v[186:189], v155 offset:16384
	ds_read_b128 v[190:193], v155 offset:17408
	ds_read_b128 v[194:197], v155 offset:18432
	ds_read_b128 v[198:201], v155 offset:19456
	ds_read_b128 v[202:205], v155 offset:20480
	ds_read_b128 v[206:209], v155 offset:21504
	ds_read_b128 v[210:213], v155 offset:22528
	ds_read_b128 v[214:217], v155 offset:23552
	global_load_lds_dwordx4 v130, s[52:53]
	s_add_i32 m0, s26, 0x2000
	s_add_u32 s26, s52, 0x80000
	s_addc_u32 s27, s53, 0
	s_add_i32 s33, s64, s56
	global_load_lds_dwordx4 v134, s[52:53]
	s_mov_b32 m0, s33
	s_nop 0
	global_load_lds_dwordx4 v130, s[26:27]
	s_add_i32 m0, s33, 0x2000
	s_nop 0
	global_load_lds_dwordx4 v134, s[26:27]
	s_mov_b32 m0, s49
	s_nop 0
	global_load_lds_dwordx4 v128, s[54:55]
	s_mov_b32 m0, s57
	s_nop 0
	global_load_lds_dwordx4 v132, s[54:55]
	s_waitcnt vmcnt(8)
	s_waitcnt lgkmcnt(0)
	s_barrier
	s_waitcnt lgkmcnt(0)
	v_mfma_f32_16x16x32_bf16 v[60:63], v[146:149], v[186:189], v[60:63]
	v_mfma_f32_16x16x32_bf16 v[56:59], v[162:165], v[186:189], v[56:59]
	v_mfma_f32_16x16x32_bf16 v[44:47], v[146:149], v[194:197], v[44:47]
	v_mfma_f32_16x16x32_bf16 v[40:43], v[162:165], v[194:197], v[40:43]
	v_mfma_f32_16x16x32_bf16 v[28:31], v[146:149], v[202:205], v[28:31]
	v_mfma_f32_16x16x32_bf16 v[24:27], v[162:165], v[202:205], v[24:27]
	v_mfma_f32_16x16x32_bf16 v[12:15], v[146:149], v[210:213], v[12:15]
	v_mfma_f32_16x16x32_bf16 v[8:11], v[162:165], v[210:213], v[8:11]
	v_mfma_f32_16x16x32_bf16 v[60:63], v[158:161], v[190:193], v[60:63]
	v_mfma_f32_16x16x32_bf16 v[56:59], v[166:169], v[190:193], v[56:59]
	v_mfma_f32_16x16x32_bf16 v[44:47], v[158:161], v[198:201], v[44:47]
	v_mfma_f32_16x16x32_bf16 v[40:43], v[166:169], v[198:201], v[40:43]
	v_mfma_f32_16x16x32_bf16 v[28:31], v[158:161], v[206:209], v[28:31]
	v_mfma_f32_16x16x32_bf16 v[24:27], v[166:169], v[206:209], v[24:27]
	v_mfma_f32_16x16x32_bf16 v[12:15], v[158:161], v[214:217], v[12:15]
	v_mfma_f32_16x16x32_bf16 v[8:11], v[166:169], v[214:217], v[8:11]
	v_mfma_f32_16x16x32_bf16 v[52:55], v[170:173], v[186:189], v[52:55]
	v_mfma_f32_16x16x32_bf16 v[48:51], v[178:181], v[186:189], v[48:51]
	v_mfma_f32_16x16x32_bf16 v[36:39], v[170:173], v[194:197], v[36:39]
	v_mfma_f32_16x16x32_bf16 v[32:35], v[178:181], v[194:197], v[32:35]
	v_mfma_f32_16x16x32_bf16 v[20:23], v[170:173], v[202:205], v[20:23]
	v_mfma_f32_16x16x32_bf16 v[16:19], v[178:181], v[202:205], v[16:19]
	v_mfma_f32_16x16x32_bf16 v[4:7], v[170:173], v[210:213], v[4:7]
	v_mfma_f32_16x16x32_bf16 v[0:3], v[178:181], v[210:213], v[0:3]
	v_mfma_f32_16x16x32_bf16 v[52:55], v[174:177], v[190:193], v[52:55]
	v_mfma_f32_16x16x32_bf16 v[48:51], v[182:185], v[190:193], v[48:51]
	v_mfma_f32_16x16x32_bf16 v[36:39], v[174:177], v[198:201], v[36:39]
	v_mfma_f32_16x16x32_bf16 v[32:35], v[182:185], v[198:201], v[32:35]
	v_mfma_f32_16x16x32_bf16 v[20:23], v[174:177], v[206:209], v[20:23]
	v_mfma_f32_16x16x32_bf16 v[16:19], v[182:185], v[206:209], v[16:19]
	v_mfma_f32_16x16x32_bf16 v[4:7], v[174:177], v[214:217], v[4:7]
	v_mfma_f32_16x16x32_bf16 v[0:3], v[182:185], v[214:217], v[0:3]
	s_barrier
; #define PG8_STAGE(bufoff, gbase, voff) do { _Pragma("unroll") for (int _i = 0; _i < 2; ++_i) \
;         __builtin_amdgcn_global_load_lds((const unsigned*)((const char*)(gbase) + (voff)[_i]), (PG8_LAS unsigned*)(lds + (bufoff) + ldsw + _i * 8192), 16, 0, 0); } while (0)
; #define PG8_LDA(dst, b, h) do { _Pragma("unroll") for (int m = 0; m < 4; ++m) _Pragma("unroll") for (int k = 0; k < 2; ++k) dst[m][k] = *(const PG8_LAS bf16x8*)(lds + PG8_SA(b, h) + aoff + m * 2048 + k * 1024); } while (0)
; #define PG8_LDB(dst, b, h) do { _Pragma("unroll") for (int n = 0; n < 2; ++n) _Pragma("unroll") for (int k = 0; k < 2; ++k) dst[n][k] = *(const PG8_LAS bf16x8*)(lds + PG8_SB(b, h) + boff + n * 2048 + k * 1024); } while (0)
; #define PG8_MMA(ai, bj, At, Bt) do { __builtin_amdgcn_s_setprio(1); _Pragma("unroll") for (int m = 0; m < 4; ++m) _Pragma("unroll") for (int n = 0; n < 2; ++n) _Pragma("unroll") for (int k = 0; k < 2; ++k) \
;         acc[ai][bj][m][n] = __builtin_amdgcn_mfma_f32_16x16x32_bf16(Bt[n][k], At[m][k], acc[ai][bj][m][n], 0, 0, 0); __builtin_amdgcn_s_setprio(0); } while (0)
; #define PG8_WAIT_V(n) asm volatile("s_waitcnt vmcnt(" #n ")" ::: "memory")
; #define PG8_WAIT_L(n) asm volatile("s_waitcnt lgkmcnt(" #n ")" ::: "memory")
; #define PG8_BAR __builtin_amdgcn_s_barrier()
; #define PG8_SCHED __builtin_amdgcn_sched_barrier(0)
; template <class Epi, class Sched, bool ALIGN_EPI = false, bool SP2 = false>
; __device__ __forceinline__ void gemm_phase(PG8_LAS unsigned char* lds, const Gemm g, const Sched& S, const Epi& E, int tid_in) {
;     ...
;             PG8_LDB(B0, 1, 0); PG8_LDB(B1, 1, 1); PG8_SCHED; PG8_LDA(At, 1, 0); PG8_STAGE(PG8_SA(0, 1), a2 + hstep, voffA);
;             PG8_WAIT_V(8); PG8_WAIT_L(0); PG8_BAR; PG8_MMA(0, 0, At, B0); PG8_MMA(0, 1, At, B1); PG8_BAR; PG8_SCHED;
;             PG8_LDA(At, 1, 1); PG8_STAGE(PG8_SB(1, 0), b3, voffB); PG8_STAGE(PG8_SB(1, 1), b3 + hstepB, voffB); PG8_STAGE(PG8_SA(1, 0), a3, voffA);
;             PG8_WAIT_V(8); PG8_WAIT_L(0); PG8_BAR; PG8_MMA(1, 0, At, B0); PG8_MMA(1, 1, At, B1); PG8_BAR; PG8_SCHED;
	s_add_i32 s33, 0, 0x18000
	s_add_i32 s50, 0, 0x1c000
	v_add_u32_e32 v166, s33, v137
	v_add_u32_e32 v182, s50, v137
	ds_read_b128 v[146:149], v166
	ds_read_b128 v[158:161], v166 offset:1024
	ds_read_b128 v[162:165], v166 offset:2048
	ds_read_b128 v[166:169], v166 offset:3072
	ds_read_b128 v[170:173], v182
	ds_read_b128 v[174:177], v182 offset:1024
	ds_read_b128 v[178:181], v182 offset:2048
	ds_read_b128 v[182:185], v182 offset:3072
	s_add_u32 s26, s54, 0x204000
	s_addc_u32 s27, s55, 0
	s_mov_b32 m0, s58
	ds_read_b128 v[186:189], v155 offset:32768
	ds_read_b128 v[190:193], v155 offset:33792
	ds_read_b128 v[194:197], v155 offset:34816
	ds_read_b128 v[198:201], v155 offset:35840
	ds_read_b128 v[202:205], v155 offset:36864
	ds_read_b128 v[206:209], v155 offset:37888
	ds_read_b128 v[210:213], v155 offset:38912
	ds_read_b128 v[214:217], v155 offset:39936
	global_load_lds_dwordx4 v128, s[26:27]
	s_mov_b32 m0, s59
	s_nop 0
	global_load_lds_dwordx4 v132, s[26:27]
	s_waitcnt vmcnt(8)
	s_waitcnt lgkmcnt(0)
	s_barrier
	s_waitcnt lgkmcnt(0)
	v_mfma_f32_16x16x32_bf16 v[124:127], v[146:149], v[186:189], v[124:127]
	v_mfma_f32_16x16x32_bf16 v[120:123], v[162:165], v[186:189], v[120:123]
	v_mfma_f32_16x16x32_bf16 v[108:111], v[146:149], v[194:197], v[108:111]
	v_mfma_f32_16x16x32_bf16 v[104:107], v[162:165], v[194:197], v[104:107]
	v_mfma_f32_16x16x32_bf16 v[92:95], v[146:149], v[202:205], v[92:95]
	v_mfma_f32_16x16x32_bf16 v[88:91], v[162:165], v[202:205], v[88:91]
	v_mfma_f32_16x16x32_bf16 v[76:79], v[146:149], v[210:213], v[76:79]
	v_mfma_f32_16x16x32_bf16 v[72:75], v[162:165], v[210:213], v[72:75]
	v_mfma_f32_16x16x32_bf16 v[124:127], v[158:161], v[190:193], v[124:127]
	v_mfma_f32_16x16x32_bf16 v[120:123], v[166:169], v[190:193], v[120:123]
	v_mfma_f32_16x16x32_bf16 v[108:111], v[158:161], v[198:201], v[108:111]
	v_mfma_f32_16x16x32_bf16 v[104:107], v[166:169], v[198:201], v[104:107]
	v_mfma_f32_16x16x32_bf16 v[92:95], v[158:161], v[206:209], v[92:95]
	v_mfma_f32_16x16x32_bf16 v[88:91], v[166:169], v[206:209], v[88:91]
	v_mfma_f32_16x16x32_bf16 v[76:79], v[158:161], v[214:217], v[76:79]
	v_mfma_f32_16x16x32_bf16 v[72:75], v[166:169], v[214:217], v[72:75]
	v_mfma_f32_16x16x32_bf16 v[116:119], v[170:173], v[186:189], v[116:119]
	v_mfma_f32_16x16x32_bf16 v[112:115], v[178:181], v[186:189], v[112:115]
	v_mfma_f32_16x16x32_bf16 v[100:103], v[170:173], v[194:197], v[100:103]
	v_mfma_f32_16x16x32_bf16 v[96:99], v[178:181], v[194:197], v[96:99]
	v_mfma_f32_16x16x32_bf16 v[84:87], v[170:173], v[202:205], v[84:87]
	v_mfma_f32_16x16x32_bf16 v[80:83], v[178:181], v[202:205], v[80:83]
	v_mfma_f32_16x16x32_bf16 v[68:71], v[170:173], v[210:213], v[68:71]
	v_mfma_f32_16x16x32_bf16 v[64:67], v[178:181], v[210:213], v[64:67]
	v_mfma_f32_16x16x32_bf16 v[116:119], v[174:177], v[190:193], v[116:119]
	v_mfma_f32_16x16x32_bf16 v[112:115], v[182:185], v[190:193], v[112:115]
	v_mfma_f32_16x16x32_bf16 v[100:103], v[174:177], v[198:201], v[100:103]
	v_mfma_f32_16x16x32_bf16 v[96:99], v[182:185], v[198:201], v[96:99]
	v_mfma_f32_16x16x32_bf16 v[84:87], v[174:177], v[206:209], v[84:87]
	v_mfma_f32_16x16x32_bf16 v[80:83], v[182:185], v[206:209], v[80:83]
	v_mfma_f32_16x16x32_bf16 v[68:71], v[174:177], v[214:217], v[68:71]
	v_mfma_f32_16x16x32_bf16 v[64:67], v[182:185], v[214:217], v[64:67]
	s_barrier
	s_add_i32 s26, s33, s56
	s_add_i32 m0, s26, 0xffffff80
	ds_read_b128 v[186:189], v155 offset:49152
	ds_read_b128 v[190:193], v155 offset:50176
	ds_read_b128 v[194:197], v155 offset:51200
	ds_read_b128 v[198:201], v155 offset:52224
	ds_read_b128 v[202:205], v155 offset:53248
	ds_read_b128 v[206:209], v155 offset:54272
	ds_read_b128 v[210:213], v155 offset:55296
	ds_read_b128 v[214:217], v155 offset:56320
	global_load_lds_dwordx4 v130, s[52:53] offset:128
	s_add_i32 m0, s26, 0x1f80
	s_add_u32 s26, s52, 0x80080
	s_addc_u32 s27, s53, 0
	s_add_i32 s33, s50, s56
	global_load_lds_dwordx4 v134, s[52:53] offset:128
	s_mov_b32 m0, s33
	s_nop 0
	global_load_lds_dwordx4 v130, s[26:27]
	s_add_i32 m0, s33, 0x2000
	s_nop 0
	global_load_lds_dwordx4 v134, s[26:27]
	s_add_i32 m0, s61, 0xffffff80
	s_nop 0
	global_load_lds_dwordx4 v128, s[54:55] offset:128
	s_add_i32 m0, s62, 0xffffff80
	s_nop 0
	global_load_lds_dwordx4 v132, s[54:55] offset:128
	s_waitcnt vmcnt(8)
	s_waitcnt lgkmcnt(0)
	s_barrier
; #define PG8_MMA(ai, bj, At, Bt) do { __builtin_amdgcn_s_setprio(1); _Pragma("unroll") for (int m = 0; m < 4; ++m) _Pragma("unroll") for (int n = 0; n < 2; ++n) _Pragma("unroll") for (int k = 0; k < 2; ++k) \
;         acc[ai][bj][m][n] = __builtin_amdgcn_mfma_f32_16x16x32_bf16(Bt[n][k], At[m][k], acc[ai][bj][m][n], 0, 0, 0); __builtin_amdgcn_s_setprio(0); } while (0)
; #define PG8_WAIT_V(n) asm volatile("s_waitcnt vmcnt(" #n ")" ::: "memory")
; #define PG8_WAIT_L(n) asm volatile("s_waitcnt lgkmcnt(" #n ")" ::: "memory")
; #define PG8_BAR __builtin_amdgcn_s_barrier()
; #define PG8_SCHED __builtin_amdgcn_sched_barrier(0)
; template <class Epi, class Sched, bool ALIGN_EPI = false, bool SP2 = false>
; __device__ __forceinline__ void gemm_phase(PG8_LAS unsigned char* lds, const Gemm g, const Sched& S, const Epi& E, int tid_in) {
;     ...
;             PG8_WAIT_V(8); PG8_WAIT_L(0); PG8_BAR; PG8_MMA(1, 0, At, B0); PG8_MMA(1, 1, At, B1); PG8_BAR; PG8_SCHED;
;     __device__ __forceinline__ void operator()(const f32x4 (&acc)[2][2][4][2], const Unit& u, int wr, int wc, int fr, int fq) const {
;     ...
;                 const int row = u.pm * BM + ai * HALF + wr * 64 + m * 16 + r; float q = 0.f;
; #pragma unroll
;                 for (int bj = 0; bj < 2; ++bj) {
;                     const size_t off = (size_t)row * 2048 + u.pn * BM + wc * 64 + bj * 32 + 8 * p;
;                     f32x4 b0, b1;
;                     if (BASE_F32) { b0 = *(const f32x4*)((const float*)base + off); b1 = *(const f32x4*)((const float*)base + off + 4); }
;                     else { const u32x4 bb = *(const u32x4*)((const bf16_t*)base + off);
;                         b0 = (f32x4){__uint_as_float(bb.x << 16), __uint_as_float(bb.x & 0xffff0000u), __uint_as_float(bb.y << 16), __uint_as_float(bb.y & 0xffff0000u)};
;                         b1 = (f32x4){__uint_as_float(bb.z << 16), __uint_as_float(bb.z & 0xffff0000u), __uint_as_float(bb.w << 16), __uint_as_float(bb.w & 0xffff0000u)}; }
	s_waitcnt lgkmcnt(0)
	v_mfma_f32_16x16x32_bf16 v[60:63], v[146:149], v[186:189], v[60:63]
	v_mfma_f32_16x16x32_bf16 v[56:59], v[162:165], v[186:189], v[56:59]
	v_mfma_f32_16x16x32_bf16 v[44:47], v[146:149], v[194:197], v[44:47]
	v_mfma_f32_16x16x32_bf16 v[40:43], v[162:165], v[194:197], v[40:43]
	v_mfma_f32_16x16x32_bf16 v[28:31], v[146:149], v[202:205], v[28:31]
	v_mfma_f32_16x16x32_bf16 v[24:27], v[162:165], v[202:205], v[24:27]
	v_mfma_f32_16x16x32_bf16 v[12:15], v[146:149], v[210:213], v[12:15]
	v_mfma_f32_16x16x32_bf16 v[8:11], v[162:165], v[210:213], v[8:11]
	v_mfma_f32_16x16x32_bf16 v[60:63], v[158:161], v[190:193], v[60:63]
	v_mfma_f32_16x16x32_bf16 v[56:59], v[166:169], v[190:193], v[56:59]
	v_mfma_f32_16x16x32_bf16 v[44:47], v[158:161], v[198:201], v[44:47]
	v_mfma_f32_16x16x32_bf16 v[40:43], v[166:169], v[198:201], v[40:43]
	v_mfma_f32_16x16x32_bf16 v[28:31], v[158:161], v[206:209], v[28:31]
	v_mfma_f32_16x16x32_bf16 v[24:27], v[166:169], v[206:209], v[24:27]
	v_mfma_f32_16x16x32_bf16 v[12:15], v[158:161], v[214:217], v[12:15]
	v_mfma_f32_16x16x32_bf16 v[8:11], v[166:169], v[214:217], v[8:11]
	v_mfma_f32_16x16x32_bf16 v[52:55], v[170:173], v[186:189], v[52:55]
	v_mfma_f32_16x16x32_bf16 v[48:51], v[178:181], v[186:189], v[48:51]
	v_mfma_f32_16x16x32_bf16 v[36:39], v[170:173], v[194:197], v[36:39]
	v_mfma_f32_16x16x32_bf16 v[32:35], v[178:181], v[194:197], v[32:35]
	v_mfma_f32_16x16x32_bf16 v[20:23], v[170:173], v[202:205], v[20:23]
	v_mfma_f32_16x16x32_bf16 v[16:19], v[178:181], v[202:205], v[16:19]
	v_mfma_f32_16x16x32_bf16 v[4:7], v[170:173], v[210:213], v[4:7]
	v_mfma_f32_16x16x32_bf16 v[0:3], v[178:181], v[210:213], v[0:3]
	v_mfma_f32_16x16x32_bf16 v[52:55], v[174:177], v[190:193], v[52:55]
	v_mfma_f32_16x16x32_bf16 v[48:51], v[182:185], v[190:193], v[48:51]
	v_mfma_f32_16x16x32_bf16 v[36:39], v[174:177], v[198:201], v[36:39]
	v_mfma_f32_16x16x32_bf16 v[32:35], v[182:185], v[198:201], v[32:35]
	v_mfma_f32_16x16x32_bf16 v[20:23], v[174:177], v[206:209], v[20:23]
	v_mfma_f32_16x16x32_bf16 v[16:19], v[182:185], v[206:209], v[16:19]
	v_mfma_f32_16x16x32_bf16 v[4:7], v[174:177], v[214:217], v[4:7]
	v_mfma_f32_16x16x32_bf16 v[0:3], v[182:185], v[214:217], v[0:3]
	s_barrier
	s_add_i32 s70, s70, 2
	s_add_u32 s68, s68, 0x100
	s_addc_u32 s69, s69, 0
	s_cmpk_gt_u32 s70, 0x7d
	s_mov_b64 s[50:51], s[10:11]
	s_cbranch_scc0 .LBB0_949
	v_lshl_add_u32 v148, s66, 8, v150
	v_lshl_or_b32 v146, s48, 8, v136
	v_lshl_add_u32 v147, v148, 11, v146
	v_lshlrev_b32_e32 v159, 1, v147
	v_lshlrev_b32_e32 v208, 3, v148
	global_load_dwordx4 v[160:163], v159, s[28:29]
	global_load_dwordx4 v[164:167], v159, s[28:29] offset:64
	v_add_u32_e32 v149, 0x10000, v159
	global_load_dwordx4 v[168:171], v149, s[28:29]
	global_load_dwordx4 v[172:175], v149, s[28:29] offset:64
	v_add_u32_e32 v209, 0x20000, v159
	global_load_dwordx4 v[176:179], v209, s[28:29]
	global_load_dwordx4 v[180:183], v209, s[28:29] offset:64
	v_add_u32_e32 v149, 0x30000, v159
	global_load_dwordx4 v[184:187], v149, s[28:29]
	global_load_dwordx4 v[188:191], v149, s[28:29] offset:64
	v_add_u32_e32 v209, 0x80000, v159
	global_load_dwordx4 v[192:195], v209, s[28:29]
	global_load_dwordx4 v[196:199], v209, s[28:29] offset:64
	v_add_u32_e32 v149, 0x90000, v159
	global_load_dwordx4 v[200:203], v149, s[28:29]
	global_load_dwordx4 v[204:207], v149, s[28:29] offset:64
	v_add_u32_e32 v209, 0xa0000, v159
	global_load_dwordx4 v[212:215], v209, s[28:29]
	global_load_dwordx4 v[216:219], v209, s[28:29] offset:64
	v_add_u32_e32 v149, 0xb0000, v159
	global_load_dwordx4 v[220:223], v149, s[28:29]
	global_load_dwordx4 v[224:227], v149, s[28:29] offset:64
	s_and_b64 vcc, exec, s[40:41]
	s_cbranch_vccz .LBB0_952
	s_barrier
